# v12: v9 plus nt cache policy on the large GEMM epilogue output stores
# baseline (speedup 1.0000x reference)
.LBB0_284:
	s_lshl_b32 s0, s28, 8
	s_add_i32 s0, s0, s47
	v_add_u32_e32 v170, s0, v162
	v_mov_b32_e32 v164, v170
	v_lshlrev_b64 v[154:155], 2, v[154:155]
	v_ashrrev_i32_e32 v165, 31, v164
	v_lshlrev_b64 v[164:165], 6, v[164:165]
	v_lshl_add_u64 v[164:165], s[10:11], 0, v[164:165]
	v_lshl_add_u64 v[168:169], v[164:165], 0, v[154:155]
	s_waitcnt vmcnt(0)
	v_pk_add_f32 v[166:167], v[128:129], v[132:133]
	v_pk_add_f32 v[164:165], v[126:127], v[130:131]
	flat_store_dwordx4 v[168:169], v[164:167] nt
	s_nop 1
	v_pk_add_f32 v[166:167], v[124:125], v[136:137]
	v_pk_add_f32 v[164:165], v[122:123], v[134:135]
	flat_store_dwordx4 v[168:169], v[164:167] offset:16 nt
	s_nop 1
	v_add_u32_e32 v164, 16, v170
	v_pk_add_f32 v[166:167], v[120:121], v[132:133]
	v_ashrrev_i32_e32 v165, 31, v164
	v_lshlrev_b64 v[164:165], 6, v[164:165]
	v_lshl_add_u64 v[164:165], s[10:11], 0, v[164:165]
	v_lshl_add_u64 v[168:169], v[164:165], 0, v[154:155]
	v_pk_add_f32 v[164:165], v[118:119], v[130:131]
	flat_store_dwordx4 v[168:169], v[164:167] nt
	s_nop 1
	v_pk_add_f32 v[166:167], v[112:113], v[136:137]
	v_pk_add_f32 v[164:165], v[110:111], v[134:135]
	flat_store_dwordx4 v[168:169], v[164:167] offset:16 nt
	s_nop 1
	v_add_u32_e32 v164, 32, v170
	v_pk_add_f32 v[166:167], v[104:105], v[132:133]
	v_ashrrev_i32_e32 v165, 31, v164
	v_lshlrev_b64 v[164:165], 6, v[164:165]
	v_lshl_add_u64 v[164:165], s[10:11], 0, v[164:165]
	v_lshl_add_u64 v[168:169], v[164:165], 0, v[154:155]
	v_pk_add_f32 v[164:165], v[102:103], v[130:131]
	flat_store_dwordx4 v[168:169], v[164:167] nt
	s_nop 1
	v_pk_add_f32 v[166:167], v[96:97], v[136:137]
	v_pk_add_f32 v[164:165], v[94:95], v[134:135]
	flat_store_dwordx4 v[168:169], v[164:167] offset:16 nt
	s_nop 1
	v_add_u32_e32 v164, 48, v170
	v_pk_add_f32 v[166:167], v[88:89], v[132:133]
	v_ashrrev_i32_e32 v165, 31, v164
	v_lshlrev_b64 v[164:165], 6, v[164:165]
	v_lshl_add_u64 v[164:165], s[10:11], 0, v[164:165]
	v_lshl_add_u64 v[168:169], v[164:165], 0, v[154:155]
	v_pk_add_f32 v[164:165], v[86:87], v[130:131]
	flat_store_dwordx4 v[168:169], v[164:167] nt
	s_nop 1
	v_pk_add_f32 v[166:167], v[80:81], v[136:137]
	v_pk_add_f32 v[164:165], v[78:79], v[134:135]
	flat_store_dwordx4 v[168:169], v[164:167] offset:16 nt
	s_nop 1
	v_add_u32_e32 v164, 0x80, v170
	v_pk_add_f32 v[166:167], v[64:65], v[132:133]
	v_ashrrev_i32_e32 v165, 31, v164
	v_lshlrev_b64 v[164:165], 6, v[164:165]
	v_lshl_add_u64 v[164:165], s[10:11], 0, v[164:165]
	v_lshl_add_u64 v[168:169], v[164:165], 0, v[154:155]
	v_pk_add_f32 v[164:165], v[62:63], v[130:131]
	flat_store_dwordx4 v[168:169], v[164:167] nt
	s_nop 1
	v_pk_add_f32 v[166:167], v[60:61], v[136:137]
	v_pk_add_f32 v[164:165], v[58:59], v[134:135]
	flat_store_dwordx4 v[168:169], v[164:167] offset:16 nt
	s_nop 1
	v_add_u32_e32 v164, 0x90, v170
	v_pk_add_f32 v[166:167], v[56:57], v[132:133]
	v_ashrrev_i32_e32 v165, 31, v164
	v_lshlrev_b64 v[164:165], 6, v[164:165]
	v_lshl_add_u64 v[164:165], s[10:11], 0, v[164:165]
	v_lshl_add_u64 v[168:169], v[164:165], 0, v[154:155]
	v_pk_add_f32 v[164:165], v[54:55], v[130:131]
	flat_store_dwordx4 v[168:169], v[164:167] nt
	s_nop 1
	v_pk_add_f32 v[166:167], v[48:49], v[136:137]
	v_pk_add_f32 v[164:165], v[46:47], v[134:135]
	flat_store_dwordx4 v[168:169], v[164:167] offset:16 nt
	s_nop 1
	v_add_u32_e32 v164, 0xa0, v170
	v_pk_add_f32 v[166:167], v[40:41], v[132:133]
	v_ashrrev_i32_e32 v165, 31, v164
	v_lshlrev_b64 v[164:165], 6, v[164:165]
	v_lshl_add_u64 v[164:165], s[10:11], 0, v[164:165]
	v_lshl_add_u64 v[168:169], v[164:165], 0, v[154:155]
	v_pk_add_f32 v[164:165], v[38:39], v[130:131]
	flat_store_dwordx4 v[168:169], v[164:167] nt
	v_pk_add_f32 v[132:133], v[24:25], v[132:133]
	v_pk_add_f32 v[130:131], v[22:23], v[130:131]
	v_pk_add_f32 v[166:167], v[32:33], v[136:137]
	v_pk_add_f32 v[164:165], v[30:31], v[134:135]
	flat_store_dwordx4 v[168:169], v[164:167] offset:16 nt
	s_nop 1
	v_add_u32_e32 v164, 0xb0, v170
	s_nop 0
	v_ashrrev_i32_e32 v165, 31, v164
	v_lshlrev_b64 v[164:165], 6, v[164:165]
	v_lshl_add_u64 v[164:165], s[10:11], 0, v[164:165]
	v_lshl_add_u64 v[154:155], v[164:165], 0, v[154:155]
	flat_store_dwordx4 v[154:155], v[130:133] nt
	s_nop 1
	v_pk_add_f32 v[132:133], v[16:17], v[136:137]
	v_pk_add_f32 v[130:131], v[14:15], v[134:135]
	flat_store_dwordx4 v[154:155], v[130:133] offset:16 nt

.LBB0_286:
	s_andn2_b64 vcc, exec, s[30:31]
	s_cbranch_vccnz .LBB0_274
	s_lshl_b32 s0, s55, 8
	s_or_b32 s0, s0, s48
	s_cmp_lt_i32 s55, 2
	v_lshl_add_u32 v132, v163, 3, s0
	s_cselect_b64 vcc, -1, 0
	s_lshl_b32 s0, s28, 8
	s_add_i32 s0, s0, s47
	v_add_u32_e32 v131, s0, v162
	v_cndmask_b32_e32 v130, 1.0, v161, vcc
	v_ashrrev_i32_e32 v133, 31, v132
	v_mov_b32_e32 v134, v131
	v_lshl_add_u64 v[132:133], v[132:133], 1, s[14:15]
	v_pk_mul_f32 v[128:129], v[130:131], v[128:129] op_sel_hi:[0,1]
	v_pk_mul_f32 v[126:127], v[130:131], v[126:127] op_sel_hi:[0,1]
	v_pk_mul_f32 v[136:137], v[130:131], v[124:125] op_sel_hi:[0,1]
	v_pk_mul_f32 v[124:125], v[130:131], v[122:123] op_sel_hi:[0,1]
	v_mad_i64_i32 v[134:135], s[0:1], v134, s54, v[132:133]
	v_cvt_pk_bf16_f32 v122, v126, v127
	v_cvt_pk_bf16_f32 v123, v128, v129
	v_cvt_pk_bf16_f32 v124, v124, v125
	v_cvt_pk_bf16_f32 v125, v136, v137
	flat_store_dwordx4 v[134:135], v[122:125] nt
	v_pk_mul_f32 v[116:117], v[130:131], v[116:117] op_sel_hi:[0,1]
	v_pk_mul_f32 v[114:115], v[130:131], v[114:115] op_sel_hi:[0,1]
	v_pk_mul_f32 v[122:123], v[130:131], v[108:109] op_sel_hi:[0,1]
	v_pk_mul_f32 v[108:109], v[130:131], v[106:107] op_sel_hi:[0,1]
	v_cvt_pk_bf16_f32 v106, v114, v115
	v_cvt_pk_bf16_f32 v107, v116, v117
	v_cvt_pk_bf16_f32 v108, v108, v109
	v_cvt_pk_bf16_f32 v109, v122, v123
	flat_store_dwordx4 v[134:135], v[106:109] offset:256 nt
	v_pk_mul_f32 v[112:113], v[130:131], v[112:113] op_sel_hi:[0,1]
	v_pk_mul_f32 v[110:111], v[130:131], v[110:111] op_sel_hi:[0,1]
	v_add_u32_e32 v106, 16, v131
	v_pk_mul_f32 v[108:109], v[130:131], v[120:121] op_sel_hi:[0,1]
	v_mad_i64_i32 v[114:115], s[0:1], v106, s54, v[132:133]
	v_pk_mul_f32 v[106:107], v[130:131], v[118:119] op_sel_hi:[0,1]
	v_cvt_pk_bf16_f32 v106, v106, v107
	v_cvt_pk_bf16_f32 v107, v108, v109
	v_cvt_pk_bf16_f32 v108, v110, v111
	v_cvt_pk_bf16_f32 v109, v112, v113
	flat_store_dwordx4 v[114:115], v[106:109] nt
	v_pk_mul_f32 v[100:101], v[130:131], v[100:101] op_sel_hi:[0,1]
	v_pk_mul_f32 v[98:99], v[130:131], v[98:99] op_sel_hi:[0,1]
	v_pk_mul_f32 v[106:107], v[130:131], v[92:93] op_sel_hi:[0,1]
	v_pk_mul_f32 v[92:93], v[130:131], v[90:91] op_sel_hi:[0,1]
	v_cvt_pk_bf16_f32 v90, v98, v99
	v_cvt_pk_bf16_f32 v91, v100, v101
	v_cvt_pk_bf16_f32 v92, v92, v93
	v_cvt_pk_bf16_f32 v93, v106, v107
	flat_store_dwordx4 v[114:115], v[90:93] offset:256 nt
	v_pk_mul_f32 v[96:97], v[130:131], v[96:97] op_sel_hi:[0,1]
	v_pk_mul_f32 v[94:95], v[130:131], v[94:95] op_sel_hi:[0,1]
	v_add_u32_e32 v90, 32, v131
	v_pk_mul_f32 v[92:93], v[130:131], v[104:105] op_sel_hi:[0,1]
	v_mad_i64_i32 v[98:99], s[0:1], v90, s54, v[132:133]
	v_pk_mul_f32 v[90:91], v[130:131], v[102:103] op_sel_hi:[0,1]
	v_cvt_pk_bf16_f32 v90, v90, v91
	v_cvt_pk_bf16_f32 v91, v92, v93
	v_cvt_pk_bf16_f32 v92, v94, v95
	v_cvt_pk_bf16_f32 v93, v96, v97
	flat_store_dwordx4 v[98:99], v[90:93] nt
	v_pk_mul_f32 v[84:85], v[130:131], v[84:85] op_sel_hi:[0,1]
	v_pk_mul_f32 v[82:83], v[130:131], v[82:83] op_sel_hi:[0,1]
	v_pk_mul_f32 v[90:91], v[130:131], v[76:77] op_sel_hi:[0,1]
	v_pk_mul_f32 v[76:77], v[130:131], v[74:75] op_sel_hi:[0,1]
	v_cvt_pk_bf16_f32 v74, v82, v83
	v_cvt_pk_bf16_f32 v75, v84, v85
	v_cvt_pk_bf16_f32 v76, v76, v77
	v_cvt_pk_bf16_f32 v77, v90, v91
	flat_store_dwordx4 v[98:99], v[74:77] offset:256 nt
	v_pk_mul_f32 v[80:81], v[130:131], v[80:81] op_sel_hi:[0,1]
	v_pk_mul_f32 v[78:79], v[130:131], v[78:79] op_sel_hi:[0,1]
	v_add_u32_e32 v74, 48, v131
	v_pk_mul_f32 v[76:77], v[130:131], v[88:89] op_sel_hi:[0,1]
	v_mad_i64_i32 v[82:83], s[0:1], v74, s54, v[132:133]
	v_pk_mul_f32 v[74:75], v[130:131], v[86:87] op_sel_hi:[0,1]
	v_cvt_pk_bf16_f32 v74, v74, v75
	v_cvt_pk_bf16_f32 v75, v76, v77
	v_cvt_pk_bf16_f32 v76, v78, v79
	v_cvt_pk_bf16_f32 v77, v80, v81
	flat_store_dwordx4 v[82:83], v[74:77] nt
	v_pk_mul_f32 v[72:73], v[130:131], v[72:73] op_sel_hi:[0,1]
	v_pk_mul_f32 v[70:71], v[130:131], v[70:71] op_sel_hi:[0,1]
	v_pk_mul_f32 v[74:75], v[130:131], v[68:69] op_sel_hi:[0,1]
	v_pk_mul_f32 v[68:69], v[130:131], v[66:67] op_sel_hi:[0,1]
	v_cvt_pk_bf16_f32 v66, v70, v71
	v_cvt_pk_bf16_f32 v67, v72, v73
	v_cvt_pk_bf16_f32 v68, v68, v69
	v_cvt_pk_bf16_f32 v69, v74, v75
	flat_store_dwordx4 v[82:83], v[66:69] offset:256 nt
	v_pk_mul_f32 v[64:65], v[130:131], v[64:65] op_sel_hi:[0,1]
	v_pk_mul_f32 v[62:63], v[130:131], v[62:63] op_sel_hi:[0,1]
	v_add_u32_e32 v66, 0x80, v131
	v_pk_mul_f32 v[68:69], v[130:131], v[60:61] op_sel_hi:[0,1]
	v_pk_mul_f32 v[60:61], v[130:131], v[58:59] op_sel_hi:[0,1]
	v_mad_i64_i32 v[66:67], s[0:1], v66, s54, v[132:133]
	v_cvt_pk_bf16_f32 v58, v62, v63
	v_cvt_pk_bf16_f32 v59, v64, v65
	v_cvt_pk_bf16_f32 v60, v60, v61
	v_cvt_pk_bf16_f32 v61, v68, v69
	flat_store_dwordx4 v[66:67], v[58:61] nt
	v_pk_mul_f32 v[52:53], v[130:131], v[52:53] op_sel_hi:[0,1]
	v_pk_mul_f32 v[50:51], v[130:131], v[50:51] op_sel_hi:[0,1]
	v_pk_mul_f32 v[58:59], v[130:131], v[44:45] op_sel_hi:[0,1]
	v_pk_mul_f32 v[44:45], v[130:131], v[42:43] op_sel_hi:[0,1]
	v_cvt_pk_bf16_f32 v42, v50, v51
	v_cvt_pk_bf16_f32 v43, v52, v53
	v_cvt_pk_bf16_f32 v44, v44, v45
	v_cvt_pk_bf16_f32 v45, v58, v59
	flat_store_dwordx4 v[66:67], v[42:45] offset:256 nt
	v_pk_mul_f32 v[48:49], v[130:131], v[48:49] op_sel_hi:[0,1]
	v_pk_mul_f32 v[46:47], v[130:131], v[46:47] op_sel_hi:[0,1]
	v_add_u32_e32 v42, 0x90, v131
	v_pk_mul_f32 v[44:45], v[130:131], v[56:57] op_sel_hi:[0,1]
	v_mad_i64_i32 v[50:51], s[0:1], v42, s54, v[132:133]
	v_pk_mul_f32 v[42:43], v[130:131], v[54:55] op_sel_hi:[0,1]
	v_cvt_pk_bf16_f32 v42, v42, v43
	v_cvt_pk_bf16_f32 v43, v44, v45
	v_cvt_pk_bf16_f32 v44, v46, v47
	v_cvt_pk_bf16_f32 v45, v48, v49
	flat_store_dwordx4 v[50:51], v[42:45] nt
	v_pk_mul_f32 v[36:37], v[130:131], v[36:37] op_sel_hi:[0,1]
	v_pk_mul_f32 v[34:35], v[130:131], v[34:35] op_sel_hi:[0,1]
	v_pk_mul_f32 v[42:43], v[130:131], v[28:29] op_sel_hi:[0,1]
	v_pk_mul_f32 v[28:29], v[130:131], v[26:27] op_sel_hi:[0,1]
	v_cvt_pk_bf16_f32 v26, v34, v35
	v_cvt_pk_bf16_f32 v27, v36, v37
	v_cvt_pk_bf16_f32 v28, v28, v29
	v_cvt_pk_bf16_f32 v29, v42, v43
	flat_store_dwordx4 v[50:51], v[26:29] offset:256 nt
	v_pk_mul_f32 v[32:33], v[130:131], v[32:33] op_sel_hi:[0,1]
	v_pk_mul_f32 v[30:31], v[130:131], v[30:31] op_sel_hi:[0,1]
	v_add_u32_e32 v26, 0xa0, v131
	v_pk_mul_f32 v[28:29], v[130:131], v[40:41] op_sel_hi:[0,1]
	v_mad_i64_i32 v[34:35], s[0:1], v26, s54, v[132:133]
	v_pk_mul_f32 v[26:27], v[130:131], v[38:39] op_sel_hi:[0,1]
	v_cvt_pk_bf16_f32 v26, v26, v27
	v_cvt_pk_bf16_f32 v27, v28, v29
	v_cvt_pk_bf16_f32 v28, v30, v31
	v_cvt_pk_bf16_f32 v29, v32, v33
	flat_store_dwordx4 v[34:35], v[26:29] nt
	v_pk_mul_f32 v[20:21], v[130:131], v[20:21] op_sel_hi:[0,1]
	v_pk_mul_f32 v[18:19], v[130:131], v[18:19] op_sel_hi:[0,1]
	v_pk_mul_f32 v[26:27], v[130:131], v[12:13] op_sel_hi:[0,1]
	v_pk_mul_f32 v[12:13], v[130:131], v[10:11] op_sel_hi:[0,1]
	v_cvt_pk_bf16_f32 v10, v18, v19
	v_cvt_pk_bf16_f32 v11, v20, v21
	v_cvt_pk_bf16_f32 v12, v12, v13
	v_cvt_pk_bf16_f32 v13, v26, v27
	flat_store_dwordx4 v[34:35], v[10:13] offset:256 nt
	v_pk_mul_f32 v[16:17], v[130:131], v[16:17] op_sel_hi:[0,1]
	v_pk_mul_f32 v[14:15], v[130:131], v[14:15] op_sel_hi:[0,1]
	v_add_u32_e32 v10, 0xb0, v131
	v_pk_mul_f32 v[12:13], v[130:131], v[24:25] op_sel_hi:[0,1]
	v_mad_i64_i32 v[18:19], s[0:1], v10, s54, v[132:133]
	v_pk_mul_f32 v[10:11], v[130:131], v[22:23] op_sel_hi:[0,1]
	v_cvt_pk_bf16_f32 v10, v10, v11
	v_cvt_pk_bf16_f32 v11, v12, v13
	v_cvt_pk_bf16_f32 v12, v14, v15
	v_cvt_pk_bf16_f32 v13, v16, v17
	flat_store_dwordx4 v[18:19], v[10:13] nt
	v_pk_mul_f32 v[8:9], v[130:131], v[8:9] op_sel_hi:[0,1]
	v_pk_mul_f32 v[6:7], v[130:131], v[6:7] op_sel_hi:[0,1]
	v_pk_mul_f32 v[10:11], v[130:131], v[4:5] op_sel_hi:[0,1]
	v_pk_mul_f32 v[4:5], v[130:131], v[2:3] op_sel_hi:[0,1]
	v_cvt_pk_bf16_f32 v2, v6, v7
	v_cvt_pk_bf16_f32 v3, v8, v9
	v_cvt_pk_bf16_f32 v4, v4, v5
	v_cvt_pk_bf16_f32 v5, v10, v11
	flat_store_dwordx4 v[18:19], v[2:5] offset:256 nt
	s_branch .LBB0_274

.LBB0_688:
	s_add_u32 s10, s34, 0x100
	s_addc_u32 s11, s35, 0
	s_add_u32 s30, s29, s34
	s_addc_u32 s31, s55, s35
	s_cmpk_eq_i32 s34, 0x300
	s_cselect_b64 vcc, -1, 0
	s_and_b64 s[0:1], vcc, exec
	s_cselect_b32 s1, 0, s10
	s_cselect_b32 s0, 0, s11
	s_cselect_b32 s30, s27, s30
	s_cselect_b32 s31, s25, s31
	s_add_u32 s36, s14, s1
	s_addc_u32 s37, s15, s0
	s_add_i32 s1, 0, 0x10000
	v_add_u32_e32 v14, s1, v197
	ds_read_b128 v[2:5], v14
	ds_read_b128 v[6:9], v14 offset:1024
	ds_read_b128 v[10:13], v14 offset:2048
	ds_read_b128 v[14:17], v14 offset:3072
	v_cndmask_b32_e32 v162, v168, v171, vcc
	v_cndmask_b32_e32 v184, v170, v198, vcc
	v_cndmask_b32_e32 v175, v172, v199, vcc
	v_cndmask_b32_e32 v173, v174, v200, vcc
	v_lshl_add_u64 v[18:19], v[178:179], 0, s[34:35]
	s_add_i32 m0, s45, 0xc000
	ds_read_b128 v[202:205], v169
	ds_read_b128 v[206:209], v169 offset:1024
	ds_read_b128 v[210:213], v169 offset:2048
	ds_read_b128 v[214:217], v169 offset:3072
	ds_read_b128 v[218:221], v169 offset:4096
	ds_read_b128 v[222:225], v169 offset:5120
	ds_read_b128 v[226:229], v169 offset:6144
	ds_read_b128 v[230:233], v169 offset:7168
	global_load_lds_dwordx4 v[18:19], off
	v_lshl_add_u64 v[18:19], v[176:177], 0, s[34:35]
	s_add_i32 m0, s45, 0xe000
	s_nop 0
	global_load_lds_dwordx4 v[18:19], off
	s_waitcnt lgkmcnt(8)
	s_waitcnt vmcnt(10)
	s_barrier
	s_waitcnt lgkmcnt(0)
	s_setprio 1
	s_waitcnt lgkmcnt(0)
	v_mfma_scale_f32_16x16x128_f8f6f4 v[158:161], v[2:9], v[202:209], v[158:161], v188, v188 op_sel_hi:[0,0,0]
	v_mfma_scale_f32_16x16x128_f8f6f4 v[150:153], v[10:17], v[202:209], v[150:153], v188, v188 op_sel_hi:[0,0,0]
	v_mfma_scale_f32_16x16x128_f8f6f4 v[142:145], v[2:9], v[210:217], v[142:145], v188, v188 op_sel_hi:[0,0,0]
	v_mfma_scale_f32_16x16x128_f8f6f4 v[134:137], v[10:17], v[210:217], v[134:137], v188, v188 op_sel_hi:[0,0,0]
	v_mfma_scale_f32_16x16x128_f8f6f4 v[126:129], v[2:9], v[218:225], v[126:129], v188, v188 op_sel_hi:[0,0,0]
	v_mfma_scale_f32_16x16x128_f8f6f4 v[118:121], v[10:17], v[218:225], v[118:121], v188, v188 op_sel_hi:[0,0,0]
	v_mfma_scale_f32_16x16x128_f8f6f4 v[110:113], v[2:9], v[226:233], v[110:113], v188, v188 op_sel_hi:[0,0,0]
	v_mfma_scale_f32_16x16x128_f8f6f4 v[102:105], v[10:17], v[226:233], v[102:105], v188, v188 op_sel_hi:[0,0,0]
	s_setprio 0
	s_barrier
	s_add_i32 s0, 0, 0x14000
	s_add_i32 s1, s1, s43
	v_add_u32_e32 v30, s0, v197
	v_lshl_add_u64 v[180:181], s[30:31], 0, v[164:165]
	s_mov_b32 m0, s1
	ds_read_b128 v[18:21], v30
	ds_read_b128 v[22:25], v30 offset:1024
	ds_read_b128 v[26:29], v30 offset:2048
	ds_read_b128 v[30:33], v30 offset:3072
	global_load_lds_dwordx4 v[180:181], off
	v_lshl_add_u64 v[182:183], s[30:31], 0, v[166:167]
	s_add_i32 m0, s1, 0x2000
	s_nop 0
	global_load_lds_dwordx4 v[182:183], off
	s_waitcnt vmcnt(10)
	s_barrier
	s_waitcnt lgkmcnt(0)
	s_setprio 1
	s_waitcnt lgkmcnt(0)
	v_mfma_scale_f32_16x16x128_f8f6f4 v[154:157], v[18:25], v[202:209], v[154:157], v188, v188 op_sel_hi:[0,0,0]
	v_mfma_scale_f32_16x16x128_f8f6f4 v[146:149], v[26:33], v[202:209], v[146:149], v188, v188 op_sel_hi:[0,0,0]
	v_mfma_scale_f32_16x16x128_f8f6f4 v[138:141], v[18:25], v[210:217], v[138:141], v188, v188 op_sel_hi:[0,0,0]
	v_mfma_scale_f32_16x16x128_f8f6f4 v[130:133], v[26:33], v[210:217], v[130:133], v188, v188 op_sel_hi:[0,0,0]
	v_mfma_scale_f32_16x16x128_f8f6f4 v[122:125], v[18:25], v[218:225], v[122:125], v188, v188 op_sel_hi:[0,0,0]
	v_mfma_scale_f32_16x16x128_f8f6f4 v[114:117], v[26:33], v[218:225], v[114:117], v188, v188 op_sel_hi:[0,0,0]
	v_mfma_scale_f32_16x16x128_f8f6f4 v[106:109], v[18:25], v[226:233], v[106:109], v188, v188 op_sel_hi:[0,0,0]
	v_mfma_scale_f32_16x16x128_f8f6f4 v[98:101], v[26:33], v[226:233], v[98:101], v188, v188 op_sel_hi:[0,0,0]
	s_setprio 0
	s_mov_b32 m0, s45
	s_barrier
	ds_read_b128 v[202:205], v169 offset:16384
	ds_read_b128 v[206:209], v169 offset:17408
	ds_read_b128 v[210:213], v169 offset:18432
	ds_read_b128 v[214:217], v169 offset:19456
	ds_read_b128 v[218:221], v169 offset:20480
	ds_read_b128 v[222:225], v169 offset:21504
	ds_read_b128 v[226:229], v169 offset:22528
	ds_read_b128 v[230:233], v169 offset:23552
	global_load_lds_dwordx4 v162, s[36:37]
	s_mov_b32 m0, s46
	v_mov_b32_e32 v185, v163
	global_load_lds_dwordx4 v184, s[36:37]
	s_waitcnt vmcnt(10)
	s_barrier
	s_waitcnt lgkmcnt(0)
	v_lshl_add_u64 v[186:187], s[36:37], 0, v[162:163]
	v_lshl_add_u64 v[184:185], s[36:37], 0, v[184:185]
	s_setprio 1
	s_waitcnt lgkmcnt(0)
	v_mfma_scale_f32_16x16x128_f8f6f4 v[94:97], v[2:9], v[202:209], v[94:97], v188, v188 op_sel_hi:[0,0,0]
	v_mfma_scale_f32_16x16x128_f8f6f4 v[86:89], v[10:17], v[202:209], v[86:89], v188, v188 op_sel_hi:[0,0,0]
	v_mfma_scale_f32_16x16x128_f8f6f4 v[78:81], v[2:9], v[210:217], v[78:81], v188, v188 op_sel_hi:[0,0,0]
	v_mfma_scale_f32_16x16x128_f8f6f4 v[70:73], v[10:17], v[210:217], v[70:73], v188, v188 op_sel_hi:[0,0,0]
	v_mfma_scale_f32_16x16x128_f8f6f4 v[62:65], v[2:9], v[218:225], v[62:65], v188, v188 op_sel_hi:[0,0,0]
	v_mfma_scale_f32_16x16x128_f8f6f4 v[54:57], v[10:17], v[218:225], v[54:57], v188, v188 op_sel_hi:[0,0,0]
	v_mfma_scale_f32_16x16x128_f8f6f4 v[46:49], v[2:9], v[226:233], v[46:49], v188, v188 op_sel_hi:[0,0,0]
	v_mfma_scale_f32_16x16x128_f8f6f4 v[38:41], v[10:17], v[226:233], v[38:41], v188, v188 op_sel_hi:[0,0,0]
	s_setprio 0
	s_barrier
	s_add_u32 s34, s30, 0x20000
	s_addc_u32 s35, s31, 0
	s_add_i32 s0, s0, s43
	v_lshl_add_u64 v[2:3], s[34:35], 0, v[164:165]
	s_mov_b32 m0, s0
	s_nop 0
	global_load_lds_dwordx4 v[2:3], off
	v_lshl_add_u64 v[2:3], s[34:35], 0, v[166:167]
	s_add_i32 m0, s0, 0x2000
	s_nop 0
	global_load_lds_dwordx4 v[2:3], off
	s_waitcnt vmcnt(10)
	s_barrier
	s_setprio 1
	v_mfma_scale_f32_16x16x128_f8f6f4 v[90:93], v[18:25], v[202:209], v[90:93], v188, v188 op_sel_hi:[0,0,0]
	v_mfma_scale_f32_16x16x128_f8f6f4 v[82:85], v[26:33], v[202:209], v[82:85], v188, v188 op_sel_hi:[0,0,0]
	v_mfma_scale_f32_16x16x128_f8f6f4 v[74:77], v[18:25], v[210:217], v[74:77], v188, v188 op_sel_hi:[0,0,0]
	v_mfma_scale_f32_16x16x128_f8f6f4 v[66:69], v[26:33], v[210:217], v[66:69], v188, v188 op_sel_hi:[0,0,0]
	v_mfma_scale_f32_16x16x128_f8f6f4 v[58:61], v[18:25], v[218:225], v[58:61], v188, v188 op_sel_hi:[0,0,0]
	v_mfma_scale_f32_16x16x128_f8f6f4 v[50:53], v[26:33], v[218:225], v[50:53], v188, v188 op_sel_hi:[0,0,0]
	v_mfma_scale_f32_16x16x128_f8f6f4 v[42:45], v[18:25], v[226:233], v[42:45], v188, v188 op_sel_hi:[0,0,0]
	v_mfma_scale_f32_16x16x128_f8f6f4 v[34:37], v[26:33], v[226:233], v[34:37], v188, v188 op_sel_hi:[0,0,0]
	s_setprio 0
	s_add_i32 s0, 0, 0x18000
	v_add_u32_e32 v14, s0, v197
	s_barrier
	ds_read_b128 v[2:5], v14
	ds_read_b128 v[6:9], v14 offset:1024
	ds_read_b128 v[10:13], v14 offset:2048
	ds_read_b128 v[14:17], v14 offset:3072
	s_mov_b32 m0, s47
	ds_read_b128 v[18:21], v169 offset:32768
	ds_read_b128 v[22:25], v169 offset:33792
	ds_read_b128 v[26:29], v169 offset:34816
	ds_read_b128 v[30:33], v169 offset:35840
	ds_read_b128 v[202:205], v169 offset:36864
	ds_read_b128 v[206:209], v169 offset:37888
	ds_read_b128 v[210:213], v169 offset:38912
	ds_read_b128 v[214:217], v169 offset:39936
	global_load_lds_dwordx4 v175, s[36:37]
	s_mov_b32 m0, s48
	s_nop 0
	global_load_lds_dwordx4 v173, s[36:37]
	s_waitcnt lgkmcnt(8)
	s_waitcnt vmcnt(10)
	s_barrier
	s_waitcnt lgkmcnt(0)
	s_setprio 1
	s_waitcnt lgkmcnt(0)
	v_mfma_scale_f32_16x16x128_f8f6f4 v[158:161], v[2:9], v[18:25], v[158:161], v188, v188 op_sel_hi:[0,0,0]
	v_mfma_scale_f32_16x16x128_f8f6f4 v[150:153], v[10:17], v[18:25], v[150:153], v188, v188 op_sel_hi:[0,0,0]
	v_mfma_scale_f32_16x16x128_f8f6f4 v[142:145], v[2:9], v[26:33], v[142:145], v188, v188 op_sel_hi:[0,0,0]
	v_mfma_scale_f32_16x16x128_f8f6f4 v[134:137], v[10:17], v[26:33], v[134:137], v188, v188 op_sel_hi:[0,0,0]
	v_mfma_scale_f32_16x16x128_f8f6f4 v[126:129], v[2:9], v[202:209], v[126:129], v188, v188 op_sel_hi:[0,0,0]
	v_mfma_scale_f32_16x16x128_f8f6f4 v[118:121], v[10:17], v[202:209], v[118:121], v188, v188 op_sel_hi:[0,0,0]
	v_mfma_scale_f32_16x16x128_f8f6f4 v[110:113], v[2:9], v[210:217], v[110:113], v188, v188 op_sel_hi:[0,0,0]
	v_mfma_scale_f32_16x16x128_f8f6f4 v[102:105], v[10:17], v[210:217], v[102:105], v188, v188 op_sel_hi:[0,0,0]
	s_setprio 0
	s_barrier
	s_add_i32 s34, 0, 0x1c000
	s_add_i32 s0, s0, s43
	v_add_u32_e32 v162, s34, v197
	v_lshl_add_u64 v[180:181], v[180:181], 0, s[20:21]
	s_mov_b32 m0, s0
	ds_read_b128 v[218:221], v162
	ds_read_b128 v[222:225], v162 offset:1024
	ds_read_b128 v[226:229], v162 offset:2048
	ds_read_b128 v[230:233], v162 offset:3072
	global_load_lds_dwordx4 v[180:181], off
	v_lshl_add_u64 v[180:181], v[182:183], 0, s[20:21]
	s_add_i32 m0, s0, 0x2000
	s_nop 0
	global_load_lds_dwordx4 v[180:181], off
	s_waitcnt vmcnt(10)
	s_barrier
	s_waitcnt lgkmcnt(0)
	s_setprio 1
	s_waitcnt lgkmcnt(0)
	v_mfma_scale_f32_16x16x128_f8f6f4 v[154:157], v[218:225], v[18:25], v[154:157], v188, v188 op_sel_hi:[0,0,0]
	v_mfma_scale_f32_16x16x128_f8f6f4 v[146:149], v[226:233], v[18:25], v[146:149], v188, v188 op_sel_hi:[0,0,0]
	v_mfma_scale_f32_16x16x128_f8f6f4 v[138:141], v[218:225], v[26:33], v[138:141], v188, v188 op_sel_hi:[0,0,0]
	v_mfma_scale_f32_16x16x128_f8f6f4 v[130:133], v[226:233], v[26:33], v[130:133], v188, v188 op_sel_hi:[0,0,0]
	v_mfma_scale_f32_16x16x128_f8f6f4 v[122:125], v[218:225], v[202:209], v[122:125], v188, v188 op_sel_hi:[0,0,0]
	v_mfma_scale_f32_16x16x128_f8f6f4 v[114:117], v[226:233], v[202:209], v[114:117], v188, v188 op_sel_hi:[0,0,0]
	v_mfma_scale_f32_16x16x128_f8f6f4 v[106:109], v[218:225], v[210:217], v[106:109], v188, v188 op_sel_hi:[0,0,0]
	v_mfma_scale_f32_16x16x128_f8f6f4 v[98:101], v[226:233], v[210:217], v[98:101], v188, v188 op_sel_hi:[0,0,0]
	s_setprio 0
	s_mov_b32 m0, s51
	v_lshl_add_u64 v[180:181], v[186:187], 0, s[20:21]
	s_barrier
	ds_read_b128 v[18:21], v169 offset:49152
	ds_read_b128 v[22:25], v169 offset:50176
	ds_read_b128 v[26:29], v169 offset:51200
	ds_read_b128 v[30:33], v169 offset:52224
	ds_read_b128 v[202:205], v169 offset:53248
	ds_read_b128 v[206:209], v169 offset:54272
	ds_read_b128 v[210:213], v169 offset:55296
	ds_read_b128 v[214:217], v169 offset:56320
	global_load_lds_dwordx4 v[180:181], off
	v_lshl_add_u64 v[180:181], v[184:185], 0, s[20:21]
	s_mov_b32 m0, s52
	s_nop 0
	global_load_lds_dwordx4 v[180:181], off
	s_waitcnt vmcnt(10)
	s_barrier
	s_waitcnt lgkmcnt(0)
	s_setprio 1
	s_waitcnt lgkmcnt(0)
	v_mfma_scale_f32_16x16x128_f8f6f4 v[94:97], v[2:9], v[18:25], v[94:97], v188, v188 op_sel_hi:[0,0,0]
	v_mfma_scale_f32_16x16x128_f8f6f4 v[86:89], v[10:17], v[18:25], v[86:89], v188, v188 op_sel_hi:[0,0,0]
	v_mfma_scale_f32_16x16x128_f8f6f4 v[78:81], v[2:9], v[26:33], v[78:81], v188, v188 op_sel_hi:[0,0,0]
	v_mfma_scale_f32_16x16x128_f8f6f4 v[70:73], v[10:17], v[26:33], v[70:73], v188, v188 op_sel_hi:[0,0,0]
	v_mfma_scale_f32_16x16x128_f8f6f4 v[62:65], v[2:9], v[202:209], v[62:65], v188, v188 op_sel_hi:[0,0,0]
	v_mfma_scale_f32_16x16x128_f8f6f4 v[54:57], v[10:17], v[202:209], v[54:57], v188, v188 op_sel_hi:[0,0,0]
	v_mfma_scale_f32_16x16x128_f8f6f4 v[46:49], v[2:9], v[210:217], v[46:49], v188, v188 op_sel_hi:[0,0,0]
	v_mfma_scale_f32_16x16x128_f8f6f4 v[38:41], v[10:17], v[210:217], v[38:41], v188, v188 op_sel_hi:[0,0,0]
	s_setprio 0
	s_barrier
	s_add_u32 s0, s30, 0x20080
	s_addc_u32 s1, s31, 0
	s_add_i32 s30, s34, s43
	v_lshl_add_u64 v[2:3], s[0:1], 0, v[164:165]
	s_mov_b32 m0, s30
	s_nop 0
	global_load_lds_dwordx4 v[2:3], off
	v_lshl_add_u64 v[2:3], s[0:1], 0, v[166:167]
	s_add_i32 m0, s30, 0x2000
	s_nop 0
	global_load_lds_dwordx4 v[2:3], off
	s_waitcnt vmcnt(10)
	s_barrier
	s_setprio 1
	v_mfma_scale_f32_16x16x128_f8f6f4 v[90:93], v[218:225], v[18:25], v[90:93], v188, v188 op_sel_hi:[0,0,0]
	v_mfma_scale_f32_16x16x128_f8f6f4 v[82:85], v[226:233], v[18:25], v[82:85], v188, v188 op_sel_hi:[0,0,0]
	v_mfma_scale_f32_16x16x128_f8f6f4 v[74:77], v[218:225], v[26:33], v[74:77], v188, v188 op_sel_hi:[0,0,0]
	v_mfma_scale_f32_16x16x128_f8f6f4 v[66:69], v[226:233], v[26:33], v[66:69], v188, v188 op_sel_hi:[0,0,0]
	v_mfma_scale_f32_16x16x128_f8f6f4 v[58:61], v[218:225], v[202:209], v[58:61], v188, v188 op_sel_hi:[0,0,0]
	v_mfma_scale_f32_16x16x128_f8f6f4 v[50:53], v[226:233], v[202:209], v[50:53], v188, v188 op_sel_hi:[0,0,0]
	v_mfma_scale_f32_16x16x128_f8f6f4 v[42:45], v[218:225], v[210:217], v[42:45], v188, v188 op_sel_hi:[0,0,0]
	v_mfma_scale_f32_16x16x128_f8f6f4 v[34:37], v[226:233], v[210:217], v[34:37], v188, v188 op_sel_hi:[0,0,0]
	s_setprio 0
	s_add_i32 s56, s56, 2
	s_cmp_gt_u32 s56, 5
	s_mov_b64 s[34:35], s[10:11]
	s_barrier
	s_cbranch_scc0 .LBB0_688
	v_mul_f32_e32 v5, 0x3c800000, v158
	v_mul_f32_e32 v6, 0xbfb8aa3b, v5
	v_exp_f32_e32 v6, v6
	s_ashr_i32 s29, s28, 31
	s_ashr_i32 s27, s26, 31
	s_lshl_b64 s[10:11], s[28:29], 18
	v_add_f32_e32 v6, 1.0, v6
	v_rcp_f32_e32 v6, v6
	s_lshl_b64 s[26:27], s[26:27], 15
	v_mov_b32_e32 v3, v195
	s_add_u32 s0, s6, s10
	v_mul_f32_e32 v5, v5, v6
	v_mul_f32_e32 v6, 0x3c800000, v159
	v_mul_f32_e32 v7, 0xbfb8aa3b, v6
	v_exp_f32_e32 v7, v7
	v_mul_f32_e32 v5, v5, v154
	v_mul_f32_e32 v5, 0x3e000000, v5
	v_med3_f32 v5, v5, s40, v190
	v_add_f32_e32 v7, 1.0, v7
	v_rcp_f32_e32 v7, v7
	s_nop 15
	s_nop 15
	v_mov_b32_e32 v2, v196
	v_mul_f32_e32 v6, v6, v7
	v_mul_f32_e32 v7, 0x3c800000, v160
	v_mul_f32_e32 v8, 0xbfb8aa3b, v7
	v_exp_f32_e32 v8, v8
	v_mul_f32_e32 v6, v6, v155
	v_mul_f32_e32 v6, 0x3e000000, v6
	v_add_u32_e32 v4, s49, v3
	v_add_f32_e32 v8, 1.0, v8
	v_rcp_f32_e32 v8, v8
	s_addc_u32 s1, s7, s11
	s_add_u32 s10, s0, s26
	v_mul_f32_e32 v7, v7, v8
	v_mul_f32_e32 v8, 0x3c800000, v161
	v_mul_f32_e32 v9, 0xbfb8aa3b, v8
	v_exp_f32_e32 v9, v9
	v_mul_f32_e32 v7, v7, v156
	v_mul_f32_e32 v7, 0x3e000000, v7
	v_lshl_add_u32 v2, v2, 3, s50
	v_add_f32_e32 v9, 1.0, v9
	v_rcp_f32_e32 v9, v9
	s_addc_u32 s11, s1, s27
	v_ashrrev_i32_e32 v3, 31, v2
	s_and_b64 vcc, exec, s[8:9]
	v_mul_f32_e32 v8, v8, v9
	v_mul_f32_e32 v9, 0x3c800000, v150
	v_mul_f32_e32 v10, 0xbfb8aa3b, v9
	v_exp_f32_e32 v10, v10
	v_mul_f32_e32 v8, v8, v157
	v_mul_f32_e32 v8, 0x3e000000, v8
	v_mov_b32_e32 v174, v200
	v_add_f32_e32 v10, 1.0, v10
	v_rcp_f32_e32 v10, v10
	v_mov_b32_e32 v172, v199
	v_mov_b32_e32 v170, v198
	v_mov_b32_e32 v168, v171
	v_mul_f32_e32 v9, v9, v10
	v_mul_f32_e32 v10, 0x3c800000, v151
	v_mul_f32_e32 v11, 0xbfb8aa3b, v10
	v_exp_f32_e32 v11, v11
	v_mul_f32_e32 v9, v9, v146
	v_mul_f32_e32 v9, 0x3e000000, v9
	s_mov_b32 s26, s24
	v_add_f32_e32 v11, 1.0, v11
	v_rcp_f32_e32 v11, v11
	s_mov_b32 s28, s54
	s_mov_b64 s[30:31], s[12:13]
	v_mul_f32_e32 v10, v10, v11
	v_mul_f32_e32 v11, 0x3c800000, v152
	v_mul_f32_e32 v12, 0xbfb8aa3b, v11
	v_exp_f32_e32 v12, v12
	v_mul_f32_e32 v10, v10, v147
	v_mul_f32_e32 v10, 0x3e000000, v10
	v_add_f32_e32 v12, 1.0, v12
	v_rcp_f32_e32 v12, v12
	s_nop 0
	v_mul_f32_e32 v11, v11, v12
	v_mul_f32_e32 v12, 0x3c800000, v153
	v_mul_f32_e32 v13, 0xbfb8aa3b, v12
	v_exp_f32_e32 v13, v13
	v_mul_f32_e32 v11, v11, v148
	v_mul_f32_e32 v11, 0x3e000000, v11
	v_add_f32_e32 v13, 1.0, v13
	v_rcp_f32_e32 v13, v13
	s_nop 0
	v_mul_f32_e32 v12, v12, v13
	v_med3_f32 v13, v6, s40, v190
	v_mov_b32_e32 v6, v163
	v_cvt_pk_fp8_f32 v6, v5, v13
	v_med3_f32 v5, v7, s40, v190
	v_med3_f32 v7, v8, s40, v190
	v_med3_f32 v8, v10, s40, v190
	v_cvt_pk_fp8_f32 v6, v5, v7 op_sel:[0,0,1]
	v_med3_f32 v5, v9, s40, v190
	v_mov_b32_e32 v7, v163
	v_cvt_pk_fp8_f32 v7, v5, v8
	v_mul_f32_e32 v12, v12, v149
	v_mul_f32_e32 v12, 0x3e000000, v12
	v_med3_f32 v5, v11, s40, v190
	v_med3_f32 v8, v12, s40, v190
	v_cvt_pk_fp8_f32 v7, v5, v8 op_sel:[0,0,1]
	v_ashrrev_i32_e32 v5, 31, v4
	v_lshlrev_b64 v[8:9], 7, v[4:5]
	v_lshl_add_u64 v[8:9], s[10:11], 0, v[8:9]
	v_lshl_add_u64 v[8:9], v[8:9], 0, v[2:3]
	v_mul_f32_e32 v5, 0x3c800000, v142
	flat_store_dwordx2 v[8:9], v[6:7] nt
	v_mul_f32_e32 v6, 0xbfb8aa3b, v5
	v_exp_f32_e32 v6, v6
	s_nop 0
	v_add_f32_e32 v6, 1.0, v6
	v_rcp_f32_e32 v6, v6
	s_nop 0
	v_mul_f32_e32 v5, v5, v6
	v_mul_f32_e32 v6, 0x3c800000, v143
	v_mul_f32_e32 v7, 0xbfb8aa3b, v6
	v_exp_f32_e32 v7, v7
	v_mul_f32_e32 v5, v5, v138
	v_mul_f32_e32 v5, 0x3e000000, v5
	v_med3_f32 v5, v5, s40, v190
	v_add_f32_e32 v7, 1.0, v7
	v_rcp_f32_e32 v7, v7
	s_nop 0
	v_mul_f32_e32 v6, v6, v7
	v_mul_f32_e32 v6, v6, v139
	v_mul_f32_e32 v7, 0x3e000000, v6
	v_mul_f32_e32 v6, 0x3c800000, v144
	v_mul_f32_e32 v8, 0xbfb8aa3b, v6
	v_exp_f32_e32 v8, v8
	v_med3_f32 v7, v7, s40, v190
	v_add_f32_e32 v8, 1.0, v8
	v_rcp_f32_e32 v8, v8
	s_nop 0
	v_mul_f32_e32 v6, v6, v8
	v_mul_f32_e32 v6, v6, v140
	v_mul_f32_e32 v9, 0x3e000000, v6
	v_mul_f32_e32 v6, 0x3c800000, v145
	v_mul_f32_e32 v8, 0xbfb8aa3b, v6
	v_exp_f32_e32 v8, v8
	s_nop 0
	v_add_f32_e32 v8, 1.0, v8
	v_rcp_f32_e32 v8, v8
	s_nop 0
	v_mul_f32_e32 v6, v6, v8
	v_mul_f32_e32 v6, v6, v141
	v_mul_f32_e32 v10, 0x3e000000, v6
	v_mul_f32_e32 v6, 0x3c800000, v134
	v_mul_f32_e32 v8, 0xbfb8aa3b, v6
	v_exp_f32_e32 v8, v8
	s_nop 0
	v_add_f32_e32 v8, 1.0, v8
	v_rcp_f32_e32 v8, v8
	s_nop 0
	v_mul_f32_e32 v6, v6, v8
	v_mul_f32_e32 v6, v6, v130
	v_mul_f32_e32 v11, 0x3e000000, v6
	v_mul_f32_e32 v6, 0x3c800000, v135
	v_mul_f32_e32 v8, 0xbfb8aa3b, v6
	v_exp_f32_e32 v8, v8
	s_nop 0
	v_add_f32_e32 v8, 1.0, v8
	v_rcp_f32_e32 v8, v8
	s_nop 0
	v_mul_f32_e32 v6, v6, v8
	v_mul_f32_e32 v6, v6, v131
	v_mul_f32_e32 v12, 0x3e000000, v6
	v_mul_f32_e32 v6, 0x3c800000, v136
	v_mul_f32_e32 v8, 0xbfb8aa3b, v6
	v_exp_f32_e32 v8, v8
	s_nop 0
	v_add_f32_e32 v8, 1.0, v8
	v_rcp_f32_e32 v8, v8
	s_nop 0
	v_mul_f32_e32 v6, v6, v8
	v_mul_f32_e32 v6, v6, v132
	v_mul_f32_e32 v13, 0x3e000000, v6
	v_mul_f32_e32 v6, 0x3c800000, v137
	v_mul_f32_e32 v8, 0xbfb8aa3b, v6
	v_exp_f32_e32 v8, v8
	s_nop 0
	v_add_f32_e32 v8, 1.0, v8
	v_rcp_f32_e32 v8, v8
	s_nop 0
	v_mul_f32_e32 v6, v6, v8
	v_mov_b32_e32 v8, v163
	v_cvt_pk_fp8_f32 v8, v5, v7
	v_med3_f32 v5, v9, s40, v190
	v_med3_f32 v7, v10, s40, v190
	v_mov_b32_e32 v9, v163
	v_cvt_pk_fp8_f32 v8, v5, v7 op_sel:[0,0,1]
	v_med3_f32 v5, v11, s40, v190
	v_med3_f32 v7, v12, s40, v190
	v_cvt_pk_fp8_f32 v9, v5, v7
	v_mul_f32_e32 v6, v6, v133
	v_mul_f32_e32 v14, 0x3e000000, v6
	v_add_u32_e32 v6, 16, v4
	v_med3_f32 v5, v13, s40, v190
	v_med3_f32 v7, v14, s40, v190
	v_cvt_pk_fp8_f32 v9, v5, v7 op_sel:[0,0,1]
	v_ashrrev_i32_e32 v7, 31, v6
	v_lshlrev_b64 v[6:7], 7, v[6:7]
	v_lshl_add_u64 v[6:7], s[10:11], 0, v[6:7]
	v_lshl_add_u64 v[6:7], v[6:7], 0, v[2:3]
	v_mul_f32_e32 v5, 0x3c800000, v126
	flat_store_dwordx2 v[6:7], v[8:9] nt
	v_mul_f32_e32 v6, 0xbfb8aa3b, v5
	v_exp_f32_e32 v6, v6
	s_nop 0
	v_add_f32_e32 v6, 1.0, v6
	v_rcp_f32_e32 v6, v6
	s_nop 0
	v_mul_f32_e32 v5, v5, v6
	v_mul_f32_e32 v6, 0x3c800000, v127
	v_mul_f32_e32 v7, 0xbfb8aa3b, v6
	v_exp_f32_e32 v7, v7
	v_mul_f32_e32 v5, v5, v122
	v_mul_f32_e32 v5, 0x3e000000, v5
	v_med3_f32 v5, v5, s40, v190
	v_add_f32_e32 v7, 1.0, v7
	v_rcp_f32_e32 v7, v7
	s_nop 0
	v_mul_f32_e32 v6, v6, v7
	v_mul_f32_e32 v6, v6, v123
	v_mul_f32_e32 v7, 0x3e000000, v6
	v_mul_f32_e32 v6, 0x3c800000, v128
	v_mul_f32_e32 v8, 0xbfb8aa3b, v6
	v_exp_f32_e32 v8, v8
	v_med3_f32 v7, v7, s40, v190
	v_add_f32_e32 v8, 1.0, v8
	v_rcp_f32_e32 v8, v8
	s_nop 0
	v_mul_f32_e32 v6, v6, v8
	v_mul_f32_e32 v6, v6, v124
	v_mul_f32_e32 v9, 0x3e000000, v6
	v_mul_f32_e32 v6, 0x3c800000, v129
	v_mul_f32_e32 v8, 0xbfb8aa3b, v6
	v_exp_f32_e32 v8, v8
	s_nop 0
	v_add_f32_e32 v8, 1.0, v8
	v_rcp_f32_e32 v8, v8
	s_nop 0
	v_mul_f32_e32 v6, v6, v8
	v_mul_f32_e32 v6, v6, v125
	v_mul_f32_e32 v10, 0x3e000000, v6
	v_mul_f32_e32 v6, 0x3c800000, v118
	v_mul_f32_e32 v8, 0xbfb8aa3b, v6
	v_exp_f32_e32 v8, v8
	s_nop 0
	v_add_f32_e32 v8, 1.0, v8
	v_rcp_f32_e32 v8, v8
	s_nop 0
	v_mul_f32_e32 v6, v6, v8
	v_mul_f32_e32 v6, v6, v114
	v_mul_f32_e32 v11, 0x3e000000, v6
	v_mul_f32_e32 v6, 0x3c800000, v119
	v_mul_f32_e32 v8, 0xbfb8aa3b, v6
	v_exp_f32_e32 v8, v8
	s_nop 0
	v_add_f32_e32 v8, 1.0, v8
	v_rcp_f32_e32 v8, v8
	s_nop 0
	v_mul_f32_e32 v6, v6, v8
	v_mul_f32_e32 v6, v6, v115
	v_mul_f32_e32 v12, 0x3e000000, v6
	v_mul_f32_e32 v6, 0x3c800000, v120
	v_mul_f32_e32 v8, 0xbfb8aa3b, v6
	v_exp_f32_e32 v8, v8
	s_nop 0
	v_add_f32_e32 v8, 1.0, v8
	v_rcp_f32_e32 v8, v8
	s_nop 0
	v_mul_f32_e32 v6, v6, v8
	v_mul_f32_e32 v6, v6, v116
	v_mul_f32_e32 v13, 0x3e000000, v6
	v_mul_f32_e32 v6, 0x3c800000, v121
	v_mul_f32_e32 v8, 0xbfb8aa3b, v6
	v_exp_f32_e32 v8, v8
	s_nop 0
	v_add_f32_e32 v8, 1.0, v8
	v_rcp_f32_e32 v8, v8
	s_nop 0
	v_mul_f32_e32 v6, v6, v8
	v_mov_b32_e32 v8, v163
	v_cvt_pk_fp8_f32 v8, v5, v7
	v_med3_f32 v5, v9, s40, v190
	v_med3_f32 v7, v10, s40, v190
	v_mov_b32_e32 v9, v163
	v_cvt_pk_fp8_f32 v8, v5, v7 op_sel:[0,0,1]
	v_med3_f32 v5, v11, s40, v190
	v_med3_f32 v7, v12, s40, v190
	v_cvt_pk_fp8_f32 v9, v5, v7
	v_mul_f32_e32 v6, v6, v117
	v_mul_f32_e32 v14, 0x3e000000, v6
	v_add_u32_e32 v6, 32, v4
	v_med3_f32 v5, v13, s40, v190
	v_med3_f32 v7, v14, s40, v190
	v_cvt_pk_fp8_f32 v9, v5, v7 op_sel:[0,0,1]
	v_ashrrev_i32_e32 v7, 31, v6
	v_lshlrev_b64 v[6:7], 7, v[6:7]
	v_lshl_add_u64 v[6:7], s[10:11], 0, v[6:7]
	v_lshl_add_u64 v[6:7], v[6:7], 0, v[2:3]
	v_mul_f32_e32 v5, 0x3c800000, v110
	flat_store_dwordx2 v[6:7], v[8:9] nt
	v_mul_f32_e32 v6, 0xbfb8aa3b, v5
	v_exp_f32_e32 v6, v6
	s_nop 0
	v_add_f32_e32 v6, 1.0, v6
	v_rcp_f32_e32 v6, v6
	s_nop 0
	v_mul_f32_e32 v5, v5, v6
	v_mul_f32_e32 v6, 0x3c800000, v111
	v_mul_f32_e32 v7, 0xbfb8aa3b, v6
	v_exp_f32_e32 v7, v7
	v_mul_f32_e32 v5, v5, v106
	v_mul_f32_e32 v5, 0x3e000000, v5
	v_med3_f32 v5, v5, s40, v190
	v_add_f32_e32 v7, 1.0, v7
	v_rcp_f32_e32 v7, v7
	s_nop 0
	v_mul_f32_e32 v6, v6, v7
	v_mul_f32_e32 v6, v6, v107
	v_mul_f32_e32 v7, 0x3e000000, v6
	v_mul_f32_e32 v6, 0x3c800000, v112
	v_mul_f32_e32 v8, 0xbfb8aa3b, v6
	v_exp_f32_e32 v8, v8
	v_med3_f32 v7, v7, s40, v190
	v_add_f32_e32 v8, 1.0, v8
	v_rcp_f32_e32 v8, v8
	s_nop 0
	v_mul_f32_e32 v6, v6, v8
	v_mul_f32_e32 v6, v6, v108
	v_mul_f32_e32 v9, 0x3e000000, v6
	v_mul_f32_e32 v6, 0x3c800000, v113
	v_mul_f32_e32 v8, 0xbfb8aa3b, v6
	v_exp_f32_e32 v8, v8
	s_nop 0
	v_add_f32_e32 v8, 1.0, v8
	v_rcp_f32_e32 v8, v8
	s_nop 0
	v_mul_f32_e32 v6, v6, v8
	v_mul_f32_e32 v6, v6, v109
	v_mul_f32_e32 v10, 0x3e000000, v6
	v_mul_f32_e32 v6, 0x3c800000, v102
	v_mul_f32_e32 v8, 0xbfb8aa3b, v6
	v_exp_f32_e32 v8, v8
	s_nop 0
	v_add_f32_e32 v8, 1.0, v8
	v_rcp_f32_e32 v8, v8
	s_nop 0
	v_mul_f32_e32 v6, v6, v8
	v_mul_f32_e32 v6, v6, v98
	v_mul_f32_e32 v11, 0x3e000000, v6
	v_mul_f32_e32 v6, 0x3c800000, v103
	v_mul_f32_e32 v8, 0xbfb8aa3b, v6
	v_exp_f32_e32 v8, v8
	s_nop 0
	v_add_f32_e32 v8, 1.0, v8
	v_rcp_f32_e32 v8, v8
	s_nop 0
	v_mul_f32_e32 v6, v6, v8
	v_mul_f32_e32 v6, v6, v99
	v_mul_f32_e32 v12, 0x3e000000, v6
	v_mul_f32_e32 v6, 0x3c800000, v104
	v_mul_f32_e32 v8, 0xbfb8aa3b, v6
	v_exp_f32_e32 v8, v8
	s_nop 0
	v_add_f32_e32 v8, 1.0, v8
	v_rcp_f32_e32 v8, v8
	s_nop 0
	v_mul_f32_e32 v6, v6, v8
	v_mul_f32_e32 v6, v6, v100
	v_mul_f32_e32 v13, 0x3e000000, v6
	v_mul_f32_e32 v6, 0x3c800000, v105
	v_mul_f32_e32 v8, 0xbfb8aa3b, v6
	v_exp_f32_e32 v8, v8
	s_nop 0
	v_add_f32_e32 v8, 1.0, v8
	v_rcp_f32_e32 v8, v8
	s_nop 0
	v_mul_f32_e32 v6, v6, v8
	v_mov_b32_e32 v8, v163
	v_cvt_pk_fp8_f32 v8, v5, v7
	v_med3_f32 v5, v9, s40, v190
	v_med3_f32 v7, v10, s40, v190
	v_mov_b32_e32 v9, v163
	v_cvt_pk_fp8_f32 v8, v5, v7 op_sel:[0,0,1]
	v_med3_f32 v5, v11, s40, v190
	v_med3_f32 v7, v12, s40, v190
	v_cvt_pk_fp8_f32 v9, v5, v7
	v_mul_f32_e32 v6, v6, v101
	v_mul_f32_e32 v14, 0x3e000000, v6
	v_add_u32_e32 v6, 48, v4
	v_med3_f32 v5, v13, s40, v190
	v_med3_f32 v7, v14, s40, v190
	v_cvt_pk_fp8_f32 v9, v5, v7 op_sel:[0,0,1]
	v_ashrrev_i32_e32 v7, 31, v6
	v_lshlrev_b64 v[6:7], 7, v[6:7]
	v_lshl_add_u64 v[6:7], s[10:11], 0, v[6:7]
	v_lshl_add_u64 v[6:7], v[6:7], 0, v[2:3]
	v_mul_f32_e32 v5, 0x3c800000, v94
	flat_store_dwordx2 v[6:7], v[8:9] nt
	v_mul_f32_e32 v7, 0xbfb8aa3b, v5
	v_exp_f32_e32 v7, v7
	v_add_u32_e32 v6, 0x80, v4
	v_add_f32_e32 v7, 1.0, v7
	v_rcp_f32_e32 v7, v7
	s_nop 0
	v_mul_f32_e32 v5, v5, v7
	v_mul_f32_e32 v7, 0x3c800000, v95
	v_mul_f32_e32 v8, 0xbfb8aa3b, v7
	v_exp_f32_e32 v8, v8
	v_mul_f32_e32 v5, v5, v90
	v_mul_f32_e32 v5, 0x3e000000, v5
	v_med3_f32 v5, v5, s40, v190
	v_add_f32_e32 v8, 1.0, v8
	v_rcp_f32_e32 v8, v8
	s_nop 0
	v_mul_f32_e32 v7, v7, v8
	v_mul_f32_e32 v8, 0x3c800000, v96
	v_mul_f32_e32 v9, 0xbfb8aa3b, v8
	v_exp_f32_e32 v9, v9
	v_mul_f32_e32 v7, v7, v91
	v_mul_f32_e32 v7, 0x3e000000, v7
	v_med3_f32 v7, v7, s40, v190
	v_add_f32_e32 v9, 1.0, v9
	v_rcp_f32_e32 v9, v9
	s_nop 0
	v_mul_f32_e32 v8, v8, v9
	v_mul_f32_e32 v8, v8, v92
	v_mul_f32_e32 v9, 0x3e000000, v8
	v_mul_f32_e32 v8, 0x3c800000, v97
	v_mul_f32_e32 v10, 0xbfb8aa3b, v8
	v_exp_f32_e32 v10, v10
	s_nop 0
	v_add_f32_e32 v10, 1.0, v10
	v_rcp_f32_e32 v10, v10
	s_nop 0
	v_mul_f32_e32 v8, v8, v10
	v_mul_f32_e32 v8, v8, v93
	v_mul_f32_e32 v10, 0x3e000000, v8
	v_mul_f32_e32 v8, 0x3c800000, v86
	v_mul_f32_e32 v11, 0xbfb8aa3b, v8
	v_exp_f32_e32 v11, v11
	s_nop 0
	v_add_f32_e32 v11, 1.0, v11
	v_rcp_f32_e32 v11, v11
	s_nop 0
	v_mul_f32_e32 v8, v8, v11
	v_mul_f32_e32 v8, v8, v82
	v_mul_f32_e32 v11, 0x3e000000, v8
	v_mul_f32_e32 v8, 0x3c800000, v87
	v_mul_f32_e32 v12, 0xbfb8aa3b, v8
	v_exp_f32_e32 v12, v12
	s_nop 0
	v_add_f32_e32 v12, 1.0, v12
	v_rcp_f32_e32 v12, v12
	s_nop 0
	v_mul_f32_e32 v8, v8, v12
	v_mul_f32_e32 v8, v8, v83
	v_mul_f32_e32 v12, 0x3e000000, v8
	v_mul_f32_e32 v8, 0x3c800000, v88
	v_mul_f32_e32 v13, 0xbfb8aa3b, v8
	v_exp_f32_e32 v13, v13
	s_nop 0
	v_add_f32_e32 v13, 1.0, v13
	v_rcp_f32_e32 v13, v13
	s_nop 0
	v_mul_f32_e32 v8, v8, v13
	v_mul_f32_e32 v8, v8, v84
	v_mul_f32_e32 v13, 0x3e000000, v8
	v_mul_f32_e32 v8, 0x3c800000, v89
	v_mul_f32_e32 v14, 0xbfb8aa3b, v8
	v_exp_f32_e32 v14, v14
	s_nop 0
	v_add_f32_e32 v14, 1.0, v14
	v_rcp_f32_e32 v14, v14
	s_nop 0
	v_mul_f32_e32 v8, v8, v14
	v_mul_f32_e32 v8, v8, v85
	v_mul_f32_e32 v14, 0x3e000000, v8
	v_mov_b32_e32 v8, v163
	v_cvt_pk_fp8_f32 v8, v5, v7
	v_med3_f32 v5, v9, s40, v190
	v_med3_f32 v7, v10, s40, v190
	v_mov_b32_e32 v9, v163
	v_cvt_pk_fp8_f32 v8, v5, v7 op_sel:[0,0,1]
	v_med3_f32 v5, v11, s40, v190
	v_med3_f32 v7, v12, s40, v190
	v_cvt_pk_fp8_f32 v9, v5, v7
	v_med3_f32 v5, v13, s40, v190
	v_med3_f32 v7, v14, s40, v190
	v_cvt_pk_fp8_f32 v9, v5, v7 op_sel:[0,0,1]
	v_ashrrev_i32_e32 v7, 31, v6
	v_lshlrev_b64 v[6:7], 7, v[6:7]
	v_lshl_add_u64 v[6:7], s[10:11], 0, v[6:7]
	v_lshl_add_u64 v[6:7], v[6:7], 0, v[2:3]
	v_mul_f32_e32 v5, 0x3c800000, v78
	flat_store_dwordx2 v[6:7], v[8:9] nt
	v_mul_f32_e32 v6, 0xbfb8aa3b, v5
	v_exp_f32_e32 v6, v6
	s_nop 0
	v_add_f32_e32 v6, 1.0, v6
	v_rcp_f32_e32 v6, v6
	s_nop 0
	v_mul_f32_e32 v5, v5, v6
	v_mul_f32_e32 v6, 0x3c800000, v79
	v_mul_f32_e32 v7, 0xbfb8aa3b, v6
	v_exp_f32_e32 v7, v7
	v_mul_f32_e32 v5, v5, v74
	v_mul_f32_e32 v5, 0x3e000000, v5
	v_med3_f32 v5, v5, s40, v190
	v_add_f32_e32 v7, 1.0, v7
	v_rcp_f32_e32 v7, v7
	s_nop 0
	v_mul_f32_e32 v6, v6, v7
	v_mul_f32_e32 v6, v6, v75
	v_mul_f32_e32 v7, 0x3e000000, v6
	v_mul_f32_e32 v6, 0x3c800000, v80
	v_mul_f32_e32 v8, 0xbfb8aa3b, v6
	v_exp_f32_e32 v8, v8
	v_med3_f32 v7, v7, s40, v190
	v_add_f32_e32 v8, 1.0, v8
	v_rcp_f32_e32 v8, v8
	s_nop 0
	v_mul_f32_e32 v6, v6, v8
	v_mul_f32_e32 v6, v6, v76
	v_mul_f32_e32 v9, 0x3e000000, v6
	v_mul_f32_e32 v6, 0x3c800000, v81
	v_mul_f32_e32 v8, 0xbfb8aa3b, v6
	v_exp_f32_e32 v8, v8
	s_nop 0
	v_add_f32_e32 v8, 1.0, v8
	v_rcp_f32_e32 v8, v8
	s_nop 0
	v_mul_f32_e32 v6, v6, v8
	v_mul_f32_e32 v6, v6, v77
	v_mul_f32_e32 v10, 0x3e000000, v6
	v_mul_f32_e32 v6, 0x3c800000, v70
	v_mul_f32_e32 v8, 0xbfb8aa3b, v6
	v_exp_f32_e32 v8, v8
	s_nop 0
	v_add_f32_e32 v8, 1.0, v8
	v_rcp_f32_e32 v8, v8
	s_nop 0
	v_mul_f32_e32 v6, v6, v8
	v_mul_f32_e32 v6, v6, v66
	v_mul_f32_e32 v11, 0x3e000000, v6
	v_mul_f32_e32 v6, 0x3c800000, v71
	v_mul_f32_e32 v8, 0xbfb8aa3b, v6
	v_exp_f32_e32 v8, v8
	s_nop 0
	v_add_f32_e32 v8, 1.0, v8
	v_rcp_f32_e32 v8, v8
	s_nop 0
	v_mul_f32_e32 v6, v6, v8
	v_mul_f32_e32 v6, v6, v67
	v_mul_f32_e32 v12, 0x3e000000, v6
	v_mul_f32_e32 v6, 0x3c800000, v72
	v_mul_f32_e32 v8, 0xbfb8aa3b, v6
	v_exp_f32_e32 v8, v8
	s_nop 0
	v_add_f32_e32 v8, 1.0, v8
	v_rcp_f32_e32 v8, v8
	s_nop 0
	v_mul_f32_e32 v6, v6, v8
	v_mul_f32_e32 v6, v6, v68
	v_mul_f32_e32 v13, 0x3e000000, v6
	v_mul_f32_e32 v6, 0x3c800000, v73
	v_mul_f32_e32 v8, 0xbfb8aa3b, v6
	v_exp_f32_e32 v8, v8
	s_nop 0
	v_add_f32_e32 v8, 1.0, v8
	v_rcp_f32_e32 v8, v8
	s_nop 0
	v_mul_f32_e32 v6, v6, v8
	v_mov_b32_e32 v8, v163
	v_cvt_pk_fp8_f32 v8, v5, v7
	v_med3_f32 v5, v9, s40, v190
	v_med3_f32 v7, v10, s40, v190
	v_mov_b32_e32 v9, v163
	v_cvt_pk_fp8_f32 v8, v5, v7 op_sel:[0,0,1]
	v_med3_f32 v5, v11, s40, v190
	v_med3_f32 v7, v12, s40, v190
	v_cvt_pk_fp8_f32 v9, v5, v7
	v_mul_f32_e32 v6, v6, v69
	v_mul_f32_e32 v14, 0x3e000000, v6
	v_add_u32_e32 v6, 0x90, v4
	v_med3_f32 v5, v13, s40, v190
	v_med3_f32 v7, v14, s40, v190
	v_cvt_pk_fp8_f32 v9, v5, v7 op_sel:[0,0,1]
	v_ashrrev_i32_e32 v7, 31, v6
	v_lshlrev_b64 v[6:7], 7, v[6:7]
	v_lshl_add_u64 v[6:7], s[10:11], 0, v[6:7]
	v_lshl_add_u64 v[6:7], v[6:7], 0, v[2:3]
	v_mul_f32_e32 v5, 0x3c800000, v62
	flat_store_dwordx2 v[6:7], v[8:9] nt
	v_mul_f32_e32 v6, 0xbfb8aa3b, v5
	v_exp_f32_e32 v6, v6
	s_nop 0
	v_add_f32_e32 v6, 1.0, v6
	v_rcp_f32_e32 v6, v6
	s_nop 0
	v_mul_f32_e32 v5, v5, v6
	v_mul_f32_e32 v6, 0x3c800000, v63
	v_mul_f32_e32 v7, 0xbfb8aa3b, v6
	v_exp_f32_e32 v7, v7
	v_mul_f32_e32 v5, v5, v58
	v_mul_f32_e32 v5, 0x3e000000, v5
	v_med3_f32 v5, v5, s40, v190
	v_add_f32_e32 v7, 1.0, v7
	v_rcp_f32_e32 v7, v7
	s_nop 0
	v_mul_f32_e32 v6, v6, v7
	v_mul_f32_e32 v6, v6, v59
	v_mul_f32_e32 v7, 0x3e000000, v6
	v_mul_f32_e32 v6, 0x3c800000, v64
	v_mul_f32_e32 v8, 0xbfb8aa3b, v6
	v_exp_f32_e32 v8, v8
	v_med3_f32 v7, v7, s40, v190
	v_add_f32_e32 v8, 1.0, v8
	v_rcp_f32_e32 v8, v8
	s_nop 0
	v_mul_f32_e32 v6, v6, v8
	v_mul_f32_e32 v6, v6, v60
	v_mul_f32_e32 v9, 0x3e000000, v6
	v_mul_f32_e32 v6, 0x3c800000, v65
	v_mul_f32_e32 v8, 0xbfb8aa3b, v6
	v_exp_f32_e32 v8, v8
	s_nop 0
	v_add_f32_e32 v8, 1.0, v8
	v_rcp_f32_e32 v8, v8
	s_nop 0
	v_mul_f32_e32 v6, v6, v8
	v_mul_f32_e32 v6, v6, v61
	v_mul_f32_e32 v10, 0x3e000000, v6
	v_mul_f32_e32 v6, 0x3c800000, v54
	v_mul_f32_e32 v8, 0xbfb8aa3b, v6
	v_exp_f32_e32 v8, v8
	s_nop 0
	v_add_f32_e32 v8, 1.0, v8
	v_rcp_f32_e32 v8, v8
	s_nop 0
	v_mul_f32_e32 v6, v6, v8
	v_mul_f32_e32 v6, v6, v50
	v_mul_f32_e32 v11, 0x3e000000, v6
	v_mul_f32_e32 v6, 0x3c800000, v55
	v_mul_f32_e32 v8, 0xbfb8aa3b, v6
	v_exp_f32_e32 v8, v8
	s_nop 0
	v_add_f32_e32 v8, 1.0, v8
	v_rcp_f32_e32 v8, v8
	s_nop 0
	v_mul_f32_e32 v6, v6, v8
	v_mul_f32_e32 v6, v6, v51
	v_mul_f32_e32 v12, 0x3e000000, v6
	v_mul_f32_e32 v6, 0x3c800000, v56
	v_mul_f32_e32 v8, 0xbfb8aa3b, v6
	v_exp_f32_e32 v8, v8
	s_nop 0
	v_add_f32_e32 v8, 1.0, v8
	v_rcp_f32_e32 v8, v8
	s_nop 0
	v_mul_f32_e32 v6, v6, v8
	v_mul_f32_e32 v6, v6, v52
	v_mul_f32_e32 v13, 0x3e000000, v6
	v_mul_f32_e32 v6, 0x3c800000, v57
	v_mul_f32_e32 v8, 0xbfb8aa3b, v6
	v_exp_f32_e32 v8, v8
	s_nop 0
	v_add_f32_e32 v8, 1.0, v8
	v_rcp_f32_e32 v8, v8
	s_nop 0
	v_mul_f32_e32 v6, v6, v8
	v_mov_b32_e32 v8, v163
	v_cvt_pk_fp8_f32 v8, v5, v7
	v_med3_f32 v5, v9, s40, v190
	v_med3_f32 v7, v10, s40, v190
	v_mov_b32_e32 v9, v163
	v_cvt_pk_fp8_f32 v8, v5, v7 op_sel:[0,0,1]
	v_med3_f32 v5, v11, s40, v190
	v_med3_f32 v7, v12, s40, v190
	v_cvt_pk_fp8_f32 v9, v5, v7
	v_mul_f32_e32 v6, v6, v53
	v_mul_f32_e32 v14, 0x3e000000, v6
	v_add_u32_e32 v6, 0xa0, v4
	v_med3_f32 v5, v13, s40, v190
	v_med3_f32 v7, v14, s40, v190
	v_cvt_pk_fp8_f32 v9, v5, v7 op_sel:[0,0,1]
	v_ashrrev_i32_e32 v7, 31, v6
	v_lshlrev_b64 v[6:7], 7, v[6:7]
	v_lshl_add_u64 v[6:7], s[10:11], 0, v[6:7]
	v_lshl_add_u64 v[6:7], v[6:7], 0, v[2:3]
	v_mul_f32_e32 v5, 0x3c800000, v46
	flat_store_dwordx2 v[6:7], v[8:9] nt
	v_mul_f32_e32 v6, 0xbfb8aa3b, v5
	v_exp_f32_e32 v6, v6
	v_add_u32_e32 v4, 0xb0, v4
	v_add_f32_e32 v6, 1.0, v6
	v_rcp_f32_e32 v6, v6
	s_nop 0
	v_mul_f32_e32 v5, v5, v6
	v_mul_f32_e32 v6, 0x3c800000, v47
	v_mul_f32_e32 v7, 0xbfb8aa3b, v6
	v_exp_f32_e32 v7, v7
	v_mul_f32_e32 v5, v5, v42
	v_mul_f32_e32 v5, 0x3e000000, v5
	v_med3_f32 v5, v5, s40, v190
	v_add_f32_e32 v7, 1.0, v7
	v_rcp_f32_e32 v7, v7
	s_nop 0
	v_mul_f32_e32 v6, v6, v7
	v_mul_f32_e32 v7, 0x3c800000, v48
	v_mul_f32_e32 v8, 0xbfb8aa3b, v7
	v_exp_f32_e32 v8, v8
	v_mul_f32_e32 v6, v6, v43
	v_mul_f32_e32 v6, 0x3e000000, v6
	v_add_f32_e32 v8, 1.0, v8
	v_rcp_f32_e32 v8, v8
	s_nop 0
	v_mul_f32_e32 v7, v7, v8
	v_mul_f32_e32 v8, 0x3c800000, v49
	v_mul_f32_e32 v9, 0xbfb8aa3b, v8
	v_exp_f32_e32 v9, v9
	v_mul_f32_e32 v7, v7, v44
	v_mul_f32_e32 v7, 0x3e000000, v7
	v_add_f32_e32 v9, 1.0, v9
	v_rcp_f32_e32 v9, v9
	s_nop 0
	v_mul_f32_e32 v8, v8, v9
	v_mul_f32_e32 v9, 0x3c800000, v38
	v_mul_f32_e32 v10, 0xbfb8aa3b, v9
	v_exp_f32_e32 v10, v10
	v_mul_f32_e32 v8, v8, v45
	v_mul_f32_e32 v8, 0x3e000000, v8
	v_add_f32_e32 v10, 1.0, v10
	v_rcp_f32_e32 v10, v10
	s_nop 0
	v_mul_f32_e32 v9, v9, v10
	v_mul_f32_e32 v10, 0x3c800000, v39
	v_mul_f32_e32 v11, 0xbfb8aa3b, v10
	v_exp_f32_e32 v11, v11
	v_mul_f32_e32 v9, v9, v34
	v_mul_f32_e32 v9, 0x3e000000, v9
	v_add_f32_e32 v11, 1.0, v11
	v_rcp_f32_e32 v11, v11
	s_nop 0
	v_mul_f32_e32 v10, v10, v11
	v_mul_f32_e32 v11, 0x3c800000, v40
	v_mul_f32_e32 v12, 0xbfb8aa3b, v11
	v_exp_f32_e32 v12, v12
	v_mul_f32_e32 v10, v10, v35
	v_mul_f32_e32 v10, 0x3e000000, v10
	v_add_f32_e32 v12, 1.0, v12
	v_rcp_f32_e32 v12, v12
	s_nop 0
	v_mul_f32_e32 v11, v11, v12
	v_mul_f32_e32 v12, 0x3c800000, v41
	v_mul_f32_e32 v13, 0xbfb8aa3b, v12
	v_exp_f32_e32 v13, v13
	v_mul_f32_e32 v11, v11, v36
	v_mul_f32_e32 v11, 0x3e000000, v11
	v_add_f32_e32 v13, 1.0, v13
	v_rcp_f32_e32 v13, v13
	s_nop 0
	v_mul_f32_e32 v12, v12, v13
	v_med3_f32 v13, v6, s40, v190
	v_mov_b32_e32 v6, v163
	v_cvt_pk_fp8_f32 v6, v5, v13
	v_med3_f32 v5, v7, s40, v190
	v_med3_f32 v7, v8, s40, v190
	v_med3_f32 v8, v10, s40, v190
	v_cvt_pk_fp8_f32 v6, v5, v7 op_sel:[0,0,1]
	v_med3_f32 v5, v9, s40, v190
	v_mov_b32_e32 v7, v163
	v_cvt_pk_fp8_f32 v7, v5, v8
	v_mul_f32_e32 v12, v12, v37
	v_mul_f32_e32 v12, 0x3e000000, v12
	v_med3_f32 v5, v11, s40, v190
	v_med3_f32 v8, v12, s40, v190
	v_cvt_pk_fp8_f32 v7, v5, v8 op_sel:[0,0,1]
	v_ashrrev_i32_e32 v5, 31, v4
	v_lshlrev_b64 v[4:5], 7, v[4:5]
	v_lshl_add_u64 v[4:5], s[10:11], 0, v[4:5]
	v_lshl_add_u64 v[2:3], v[4:5], 0, v[2:3]
	flat_store_dwordx2 v[2:3], v[6:7] nt
	s_cbranch_vccz .LBB0_677
	s_waitcnt vmcnt(0)
	s_cmpk_gt_u32 s42, 0xff
	s_cbranch_scc1 .LBB0_623
	s_barrier
	s_branch .LBB0_623

.LBB0_755:
	ds_read_b128 v[2:5], v169
	ds_read_b128 v[6:9], v169 offset:1024
	ds_read_b128 v[10:13], v169 offset:2048
	ds_read_b128 v[14:17], v169 offset:3072
	s_add_u32 s0, s26, 0x4000
	s_addc_u32 s1, s27, 0
	s_cmp_eq_u32 s53, 4
	s_cselect_b32 s34, s49, s0
	s_cselect_b32 s35, s19, s1
	s_cselect_b32 s28, s50, s51
	s_cselect_b32 s29, s17, s52
	s_add_u32 s30, s34, 0x8000
	s_addc_u32 s31, s35, 0
	v_lshl_add_u64 v[162:163], s[26:27], 0, v[156:157]
	s_add_i32 m0, s25, 0xc000
	ds_read_b128 v[174:177], v170
	ds_read_b128 v[178:181], v170 offset:1024
	ds_read_b128 v[182:185], v170 offset:2048
	ds_read_b128 v[186:189], v170 offset:3072
	ds_read_b128 v[190:193], v170 offset:4096
	ds_read_b128 v[194:197], v170 offset:5120
	ds_read_b128 v[198:201], v170 offset:6144
	ds_read_b128 v[202:205], v170 offset:7168
	global_load_lds_dwordx4 v[162:163], off
	v_lshl_add_u64 v[162:163], s[26:27], 0, v[154:155]
	s_add_i32 m0, s25, 0xe000
	s_nop 0
	global_load_lds_dwordx4 v[162:163], off
	s_waitcnt lgkmcnt(8)
	s_waitcnt vmcnt(10)
	s_barrier
	s_waitcnt lgkmcnt(0)
	s_setprio 1
	s_waitcnt lgkmcnt(0)
	v_mfma_scale_f32_16x16x128_f8f6f4 v[142:145], v[2:9], v[174:181], v[142:145], v171, v171 op_sel_hi:[0,0,0]
	v_mfma_scale_f32_16x16x128_f8f6f4 v[138:141], v[10:17], v[174:181], v[138:141], v171, v171 op_sel_hi:[0,0,0]
	v_mfma_scale_f32_16x16x128_f8f6f4 v[126:129], v[2:9], v[182:189], v[126:129], v171, v171 op_sel_hi:[0,0,0]
	v_mfma_scale_f32_16x16x128_f8f6f4 v[122:125], v[10:17], v[182:189], v[122:125], v171, v171 op_sel_hi:[0,0,0]
	v_mfma_scale_f32_16x16x128_f8f6f4 v[110:113], v[2:9], v[190:197], v[110:113], v171, v171 op_sel_hi:[0,0,0]
	v_mfma_scale_f32_16x16x128_f8f6f4 v[106:109], v[10:17], v[190:197], v[106:109], v171, v171 op_sel_hi:[0,0,0]
	v_mfma_scale_f32_16x16x128_f8f6f4 v[94:97], v[2:9], v[198:205], v[94:97], v171, v171 op_sel_hi:[0,0,0]
	v_mfma_scale_f32_16x16x128_f8f6f4 v[90:93], v[10:17], v[198:205], v[90:93], v171, v171 op_sel_hi:[0,0,0]
	s_setprio 0
	s_barrier
	s_add_i32 s0, s45, s36
	v_lshl_add_u64 v[162:163], s[28:29], 0, v[150:151]
	s_mov_b32 m0, s0
	ds_read_b128 v[206:209], v172
	ds_read_b128 v[210:213], v172 offset:1024
	ds_read_b128 v[214:217], v172 offset:2048
	ds_read_b128 v[218:221], v172 offset:3072
	global_load_lds_dwordx4 v[162:163], off
	v_lshl_add_u64 v[164:165], s[28:29], 0, v[146:147]
	s_add_i32 m0, s0, 0x2000
	s_nop 0
	global_load_lds_dwordx4 v[164:165], off
	s_waitcnt vmcnt(10)
	s_barrier
	s_waitcnt lgkmcnt(0)
	s_setprio 1
	s_waitcnt lgkmcnt(0)
	v_mfma_scale_f32_16x16x128_f8f6f4 v[134:137], v[206:213], v[174:181], v[134:137], v171, v171 op_sel_hi:[0,0,0]
	v_mfma_scale_f32_16x16x128_f8f6f4 v[130:133], v[214:221], v[174:181], v[130:133], v171, v171 op_sel_hi:[0,0,0]
	v_mfma_scale_f32_16x16x128_f8f6f4 v[118:121], v[206:213], v[182:189], v[118:121], v171, v171 op_sel_hi:[0,0,0]
	v_mfma_scale_f32_16x16x128_f8f6f4 v[114:117], v[214:221], v[182:189], v[114:117], v171, v171 op_sel_hi:[0,0,0]
	v_mfma_scale_f32_16x16x128_f8f6f4 v[102:105], v[206:213], v[190:197], v[102:105], v171, v171 op_sel_hi:[0,0,0]
	v_mfma_scale_f32_16x16x128_f8f6f4 v[98:101], v[214:221], v[190:197], v[98:101], v171, v171 op_sel_hi:[0,0,0]
	v_mfma_scale_f32_16x16x128_f8f6f4 v[86:89], v[206:213], v[198:205], v[86:89], v171, v171 op_sel_hi:[0,0,0]
	v_mfma_scale_f32_16x16x128_f8f6f4 v[82:85], v[214:221], v[198:205], v[82:85], v171, v171 op_sel_hi:[0,0,0]
	s_setprio 0
	s_mov_b32 m0, s25
	v_lshl_add_u64 v[222:223], s[34:35], 0, v[152:153]
	s_barrier
	ds_read_b128 v[174:177], v170 offset:16384
	ds_read_b128 v[178:181], v170 offset:17408
	ds_read_b128 v[182:185], v170 offset:18432
	ds_read_b128 v[186:189], v170 offset:19456
	ds_read_b128 v[190:193], v170 offset:20480
	ds_read_b128 v[194:197], v170 offset:21504
	ds_read_b128 v[198:201], v170 offset:22528
	ds_read_b128 v[202:205], v170 offset:23552
	global_load_lds_dwordx4 v[222:223], off
	v_lshl_add_u64 v[222:223], s[34:35], 0, v[148:149]
	s_mov_b32 m0, s37
	s_nop 0
	global_load_lds_dwordx4 v[222:223], off
	s_waitcnt vmcnt(10)
	s_barrier
	s_waitcnt lgkmcnt(0)
	s_setprio 1
	s_waitcnt lgkmcnt(0)
	v_mfma_scale_f32_16x16x128_f8f6f4 v[78:81], v[2:9], v[174:181], v[78:81], v171, v171 op_sel_hi:[0,0,0]
	v_mfma_scale_f32_16x16x128_f8f6f4 v[74:77], v[10:17], v[174:181], v[74:77], v171, v171 op_sel_hi:[0,0,0]
	v_mfma_scale_f32_16x16x128_f8f6f4 v[62:65], v[2:9], v[182:189], v[62:65], v171, v171 op_sel_hi:[0,0,0]
	v_mfma_scale_f32_16x16x128_f8f6f4 v[58:61], v[10:17], v[182:189], v[58:61], v171, v171 op_sel_hi:[0,0,0]
	v_mfma_scale_f32_16x16x128_f8f6f4 v[46:49], v[2:9], v[190:197], v[46:49], v171, v171 op_sel_hi:[0,0,0]
	v_mfma_scale_f32_16x16x128_f8f6f4 v[42:45], v[10:17], v[190:197], v[42:45], v171, v171 op_sel_hi:[0,0,0]
	v_mfma_scale_f32_16x16x128_f8f6f4 v[30:33], v[2:9], v[198:205], v[30:33], v171, v171 op_sel_hi:[0,0,0]
	v_mfma_scale_f32_16x16x128_f8f6f4 v[26:29], v[10:17], v[198:205], v[26:29], v171, v171 op_sel_hi:[0,0,0]
	s_setprio 0
	s_barrier
	s_add_u32 s0, s28, 0x20000
	s_addc_u32 s1, s29, 0
	s_add_i32 s54, s46, s36
	v_lshl_add_u64 v[2:3], s[0:1], 0, v[150:151]
	s_mov_b32 m0, s54
	s_nop 0
	global_load_lds_dwordx4 v[2:3], off
	v_lshl_add_u64 v[2:3], s[0:1], 0, v[146:147]
	s_add_i32 m0, s54, 0x2000
	s_nop 0
	global_load_lds_dwordx4 v[2:3], off
	s_waitcnt vmcnt(10)
	s_barrier
	s_setprio 1
	v_mfma_scale_f32_16x16x128_f8f6f4 v[70:73], v[206:213], v[174:181], v[70:73], v171, v171 op_sel_hi:[0,0,0]
	v_mfma_scale_f32_16x16x128_f8f6f4 v[66:69], v[214:221], v[174:181], v[66:69], v171, v171 op_sel_hi:[0,0,0]
	v_mfma_scale_f32_16x16x128_f8f6f4 v[54:57], v[206:213], v[182:189], v[54:57], v171, v171 op_sel_hi:[0,0,0]
	v_mfma_scale_f32_16x16x128_f8f6f4 v[50:53], v[214:221], v[182:189], v[50:53], v171, v171 op_sel_hi:[0,0,0]
	v_mfma_scale_f32_16x16x128_f8f6f4 v[38:41], v[206:213], v[190:197], v[38:41], v171, v171 op_sel_hi:[0,0,0]
	v_mfma_scale_f32_16x16x128_f8f6f4 v[34:37], v[214:221], v[190:197], v[34:37], v171, v171 op_sel_hi:[0,0,0]
	v_mfma_scale_f32_16x16x128_f8f6f4 v[22:25], v[206:213], v[198:205], v[22:25], v171, v171 op_sel_hi:[0,0,0]
	v_mfma_scale_f32_16x16x128_f8f6f4 v[18:21], v[214:221], v[198:205], v[18:21], v171, v171 op_sel_hi:[0,0,0]
	s_setprio 0
	s_add_i32 s54, 0, 0x18000
	v_add_u32_e32 v14, s54, v168
	s_barrier
	ds_read_b128 v[2:5], v14
	ds_read_b128 v[6:9], v14 offset:1024
	ds_read_b128 v[10:13], v14 offset:2048
	ds_read_b128 v[14:17], v14 offset:3072
	s_add_u32 s0, s34, 0x4000
	s_addc_u32 s1, s35, 0
	s_mov_b32 m0, s38
	v_lshl_add_u64 v[206:207], s[0:1], 0, v[152:153]
	ds_read_b128 v[174:177], v170 offset:32768
	ds_read_b128 v[178:181], v170 offset:33792
	ds_read_b128 v[182:185], v170 offset:34816
	ds_read_b128 v[186:189], v170 offset:35840
	ds_read_b128 v[190:193], v170 offset:36864
	ds_read_b128 v[194:197], v170 offset:37888
	ds_read_b128 v[198:201], v170 offset:38912
	ds_read_b128 v[202:205], v170 offset:39936
	global_load_lds_dwordx4 v[206:207], off
	v_lshl_add_u64 v[206:207], s[0:1], 0, v[148:149]
	s_mov_b32 m0, s39
	s_nop 0
	global_load_lds_dwordx4 v[206:207], off
	s_waitcnt lgkmcnt(8)
	s_waitcnt vmcnt(10)
	s_barrier
	s_waitcnt lgkmcnt(0)
	s_setprio 1
	s_waitcnt lgkmcnt(0)
	v_mfma_scale_f32_16x16x128_f8f6f4 v[142:145], v[2:9], v[174:181], v[142:145], v171, v171 op_sel_hi:[0,0,0]
	v_mfma_scale_f32_16x16x128_f8f6f4 v[138:141], v[10:17], v[174:181], v[138:141], v171, v171 op_sel_hi:[0,0,0]
	v_mfma_scale_f32_16x16x128_f8f6f4 v[126:129], v[2:9], v[182:189], v[126:129], v171, v171 op_sel_hi:[0,0,0]
	v_mfma_scale_f32_16x16x128_f8f6f4 v[122:125], v[10:17], v[182:189], v[122:125], v171, v171 op_sel_hi:[0,0,0]
	v_mfma_scale_f32_16x16x128_f8f6f4 v[110:113], v[2:9], v[190:197], v[110:113], v171, v171 op_sel_hi:[0,0,0]
	v_mfma_scale_f32_16x16x128_f8f6f4 v[106:109], v[10:17], v[190:197], v[106:109], v171, v171 op_sel_hi:[0,0,0]
	v_mfma_scale_f32_16x16x128_f8f6f4 v[94:97], v[2:9], v[198:205], v[94:97], v171, v171 op_sel_hi:[0,0,0]
	v_mfma_scale_f32_16x16x128_f8f6f4 v[90:93], v[10:17], v[198:205], v[90:93], v171, v171 op_sel_hi:[0,0,0]
	s_setprio 0
	s_barrier
	s_add_i32 s34, 0, 0x1c000
	s_add_i32 s0, s54, s36
	v_add_u32_e32 v218, s34, v168
	v_lshl_add_u64 v[162:163], v[162:163], 0, s[12:13]
	s_mov_b32 m0, s0
	ds_read_b128 v[206:209], v218
	ds_read_b128 v[210:213], v218 offset:1024
	ds_read_b128 v[214:217], v218 offset:2048
	ds_read_b128 v[218:221], v218 offset:3072
	global_load_lds_dwordx4 v[162:163], off
	v_lshl_add_u64 v[162:163], v[164:165], 0, s[12:13]
	s_add_i32 m0, s0, 0x2000
	s_nop 0
	global_load_lds_dwordx4 v[162:163], off
	s_waitcnt vmcnt(10)
	s_barrier
	s_waitcnt lgkmcnt(0)
	s_setprio 1
	s_waitcnt lgkmcnt(0)
	v_mfma_scale_f32_16x16x128_f8f6f4 v[134:137], v[206:213], v[174:181], v[134:137], v171, v171 op_sel_hi:[0,0,0]
	v_mfma_scale_f32_16x16x128_f8f6f4 v[130:133], v[214:221], v[174:181], v[130:133], v171, v171 op_sel_hi:[0,0,0]
	v_mfma_scale_f32_16x16x128_f8f6f4 v[118:121], v[206:213], v[182:189], v[118:121], v171, v171 op_sel_hi:[0,0,0]
	v_mfma_scale_f32_16x16x128_f8f6f4 v[114:117], v[214:221], v[182:189], v[114:117], v171, v171 op_sel_hi:[0,0,0]
	v_mfma_scale_f32_16x16x128_f8f6f4 v[102:105], v[206:213], v[190:197], v[102:105], v171, v171 op_sel_hi:[0,0,0]
	v_mfma_scale_f32_16x16x128_f8f6f4 v[98:101], v[214:221], v[190:197], v[98:101], v171, v171 op_sel_hi:[0,0,0]
	v_mfma_scale_f32_16x16x128_f8f6f4 v[86:89], v[206:213], v[198:205], v[86:89], v171, v171 op_sel_hi:[0,0,0]
	v_mfma_scale_f32_16x16x128_f8f6f4 v[82:85], v[214:221], v[198:205], v[82:85], v171, v171 op_sel_hi:[0,0,0]
	s_setprio 0
	s_mov_b32 m0, s43
	v_lshl_add_u64 v[162:163], s[30:31], 0, v[152:153]
	s_barrier
	ds_read_b128 v[174:177], v170 offset:49152
	ds_read_b128 v[178:181], v170 offset:50176
	ds_read_b128 v[182:185], v170 offset:51200
	ds_read_b128 v[186:189], v170 offset:52224
	ds_read_b128 v[190:193], v170 offset:53248
	ds_read_b128 v[194:197], v170 offset:54272
	ds_read_b128 v[198:201], v170 offset:55296
	ds_read_b128 v[202:205], v170 offset:56320
	global_load_lds_dwordx4 v[162:163], off
	v_lshl_add_u64 v[162:163], s[30:31], 0, v[148:149]
	s_mov_b32 m0, s44
	s_nop 0
	global_load_lds_dwordx4 v[162:163], off
	s_waitcnt vmcnt(10)
	s_barrier
	s_waitcnt lgkmcnt(0)
	s_setprio 1
	s_waitcnt lgkmcnt(0)
	v_mfma_scale_f32_16x16x128_f8f6f4 v[78:81], v[2:9], v[174:181], v[78:81], v171, v171 op_sel_hi:[0,0,0]
	v_mfma_scale_f32_16x16x128_f8f6f4 v[74:77], v[10:17], v[174:181], v[74:77], v171, v171 op_sel_hi:[0,0,0]
	v_mfma_scale_f32_16x16x128_f8f6f4 v[62:65], v[2:9], v[182:189], v[62:65], v171, v171 op_sel_hi:[0,0,0]
	v_mfma_scale_f32_16x16x128_f8f6f4 v[58:61], v[10:17], v[182:189], v[58:61], v171, v171 op_sel_hi:[0,0,0]
	v_mfma_scale_f32_16x16x128_f8f6f4 v[46:49], v[2:9], v[190:197], v[46:49], v171, v171 op_sel_hi:[0,0,0]
	v_mfma_scale_f32_16x16x128_f8f6f4 v[42:45], v[10:17], v[190:197], v[42:45], v171, v171 op_sel_hi:[0,0,0]
	v_mfma_scale_f32_16x16x128_f8f6f4 v[30:33], v[2:9], v[198:205], v[30:33], v171, v171 op_sel_hi:[0,0,0]
	v_mfma_scale_f32_16x16x128_f8f6f4 v[26:29], v[10:17], v[198:205], v[26:29], v171, v171 op_sel_hi:[0,0,0]
	s_setprio 0
	s_barrier
	s_add_u32 s0, s28, 0x20080
	s_addc_u32 s1, s29, 0
	s_add_i32 s28, s34, s36
	v_lshl_add_u64 v[2:3], s[0:1], 0, v[150:151]
	s_mov_b32 m0, s28
	s_nop 0
	global_load_lds_dwordx4 v[2:3], off
	v_lshl_add_u64 v[2:3], s[0:1], 0, v[146:147]
	s_add_i32 m0, s28, 0x2000
	s_nop 0
	global_load_lds_dwordx4 v[2:3], off
	s_waitcnt vmcnt(10)
	s_barrier
	s_setprio 1
	v_mfma_scale_f32_16x16x128_f8f6f4 v[70:73], v[206:213], v[174:181], v[70:73], v171, v171 op_sel_hi:[0,0,0]
	v_mfma_scale_f32_16x16x128_f8f6f4 v[66:69], v[214:221], v[174:181], v[66:69], v171, v171 op_sel_hi:[0,0,0]
	v_mfma_scale_f32_16x16x128_f8f6f4 v[54:57], v[206:213], v[182:189], v[54:57], v171, v171 op_sel_hi:[0,0,0]
	v_mfma_scale_f32_16x16x128_f8f6f4 v[50:53], v[214:221], v[182:189], v[50:53], v171, v171 op_sel_hi:[0,0,0]
	v_mfma_scale_f32_16x16x128_f8f6f4 v[38:41], v[206:213], v[190:197], v[38:41], v171, v171 op_sel_hi:[0,0,0]
	v_mfma_scale_f32_16x16x128_f8f6f4 v[34:37], v[214:221], v[190:197], v[34:37], v171, v171 op_sel_hi:[0,0,0]
	v_mfma_scale_f32_16x16x128_f8f6f4 v[22:25], v[206:213], v[198:205], v[22:25], v171, v171 op_sel_hi:[0,0,0]
	v_mfma_scale_f32_16x16x128_f8f6f4 v[18:21], v[214:221], v[198:205], v[18:21], v171, v171 op_sel_hi:[0,0,0]
	s_setprio 0
	s_add_i32 s53, s53, 2
	s_add_u32 s51, s51, 0x100
	s_addc_u32 s52, s52, 0
	s_add_u32 s26, s26, 0x10000
	s_addc_u32 s27, s27, 0
	s_cmp_gt_u32 s53, 5
	s_barrier
	s_cbranch_scc0 .LBB0_755
	v_pk_mul_f32 v[10:11], v[142:143], s[14:15] op_sel_hi:[1,0]
	v_pk_mul_f32 v[8:9], v[144:145], s[14:15] op_sel_hi:[1,0]
	v_med3_f32 v5, v10, s47, v173
	v_med3_f32 v11, v11, s47, v173
	v_mov_b32_e32 v10, 0
	v_cvt_pk_fp8_f32 v10, v5, v11
	v_mov_b32_e32 v3, v166
	v_mov_b32_e32 v2, v167
	s_lshl_b32 s0, s48, 8
	v_pk_mul_f32 v[14:15], v[138:139], s[14:15] op_sel_hi:[1,0]
	v_med3_f32 v5, v8, s47, v173
	v_med3_f32 v8, v9, s47, v173
	s_nop 15
	s_nop 15
	s_or_b32 s0, s0, s42
	v_cvt_pk_fp8_f32 v10, v5, v8 op_sel:[0,0,1]
	v_med3_f32 v5, v14, s47, v173
	v_med3_f32 v8, v15, s47, v173
	v_mov_b32_e32 v11, 0
	v_lshl_add_u32 v2, v2, 3, s0
	s_lshl_b32 s0, s24, 8
	v_cvt_pk_fp8_f32 v11, v5, v8
	s_add_i32 s0, s0, s41
	v_add_u32_e32 v4, s0, v3
	v_pk_mul_f32 v[12:13], v[140:141], s[14:15] op_sel_hi:[1,0]
	v_mov_b32_e32 v6, v4
	v_med3_f32 v5, v12, s47, v173
	v_med3_f32 v8, v13, s47, v173
	v_cvt_pk_fp8_f32 v11, v5, v8 op_sel:[0,0,1]
	v_ashrrev_i32_e32 v7, 31, v6
	v_lshlrev_b64 v[6:7], 10, v[6:7]
	v_ashrrev_i32_e32 v3, 31, v2
	v_lshl_add_u64 v[6:7], s[10:11], 0, v[6:7]
	v_lshl_add_u64 v[6:7], v[6:7], 0, v[2:3]
	flat_store_dwordx2 v[6:7], v[10:11] nt
	v_pk_mul_f32 v[10:11], v[134:135], s[14:15] op_sel_hi:[1,0]
	v_pk_mul_f32 v[8:9], v[136:137], s[14:15] op_sel_hi:[1,0]
	v_med3_f32 v5, v10, s47, v173
	v_med3_f32 v11, v11, s47, v173
	v_mov_b32_e32 v10, 0
	v_cvt_pk_fp8_f32 v10, v5, v11
	v_pk_mul_f32 v[14:15], v[130:131], s[14:15] op_sel_hi:[1,0]
	v_med3_f32 v5, v8, s47, v173
	v_med3_f32 v8, v9, s47, v173
	v_cvt_pk_fp8_f32 v10, v5, v8 op_sel:[0,0,1]
	v_med3_f32 v5, v14, s47, v173
	v_med3_f32 v8, v15, s47, v173
	v_mov_b32_e32 v11, 0
	v_cvt_pk_fp8_f32 v11, v5, v8
	v_pk_mul_f32 v[12:13], v[132:133], s[14:15] op_sel_hi:[1,0]
	v_pk_mul_f32 v[14:15], v[122:123], s[14:15] op_sel_hi:[1,0]
	v_med3_f32 v5, v12, s47, v173
	v_med3_f32 v8, v13, s47, v173
	v_cvt_pk_fp8_f32 v11, v5, v8 op_sel:[0,0,1]
	v_pk_mul_f32 v[8:9], v[128:129], s[14:15] op_sel_hi:[1,0]
	v_pk_mul_f32 v[12:13], v[124:125], s[14:15] op_sel_hi:[1,0]
	s_and_b64 vcc, exec, s[8:9]
	flat_store_dwordx2 v[6:7], v[10:11] offset:128 nt
	v_pk_mul_f32 v[10:11], v[126:127], s[14:15] op_sel_hi:[1,0]
	v_add_u32_e32 v6, 16, v4
	v_med3_f32 v5, v10, s47, v173
	v_med3_f32 v11, v11, s47, v173
	v_mov_b32_e32 v10, 0
	v_cvt_pk_fp8_f32 v10, v5, v11
	v_med3_f32 v5, v8, s47, v173
	v_med3_f32 v8, v9, s47, v173
	v_mov_b32_e32 v11, 0
	v_cvt_pk_fp8_f32 v10, v5, v8 op_sel:[0,0,1]
	v_med3_f32 v5, v14, s47, v173
	v_med3_f32 v8, v15, s47, v173
	v_cvt_pk_fp8_f32 v11, v5, v8
	v_med3_f32 v5, v12, s47, v173
	v_med3_f32 v8, v13, s47, v173
	v_cvt_pk_fp8_f32 v11, v5, v8 op_sel:[0,0,1]
	v_ashrrev_i32_e32 v7, 31, v6
	v_lshlrev_b64 v[6:7], 10, v[6:7]
	v_lshl_add_u64 v[6:7], s[10:11], 0, v[6:7]
	v_lshl_add_u64 v[6:7], v[6:7], 0, v[2:3]
	flat_store_dwordx2 v[6:7], v[10:11] nt
	v_pk_mul_f32 v[10:11], v[118:119], s[14:15] op_sel_hi:[1,0]
	v_pk_mul_f32 v[8:9], v[120:121], s[14:15] op_sel_hi:[1,0]
	v_med3_f32 v5, v10, s47, v173
	v_med3_f32 v11, v11, s47, v173
	v_mov_b32_e32 v10, 0
	v_cvt_pk_fp8_f32 v10, v5, v11
	v_pk_mul_f32 v[14:15], v[114:115], s[14:15] op_sel_hi:[1,0]
	v_med3_f32 v5, v8, s47, v173
	v_med3_f32 v8, v9, s47, v173
	v_cvt_pk_fp8_f32 v10, v5, v8 op_sel:[0,0,1]
	v_med3_f32 v5, v14, s47, v173
	v_med3_f32 v8, v15, s47, v173
	v_mov_b32_e32 v11, 0
	v_cvt_pk_fp8_f32 v11, v5, v8
	v_pk_mul_f32 v[12:13], v[116:117], s[14:15] op_sel_hi:[1,0]
	v_pk_mul_f32 v[14:15], v[106:107], s[14:15] op_sel_hi:[1,0]
	v_med3_f32 v5, v12, s47, v173
	v_med3_f32 v8, v13, s47, v173
	v_cvt_pk_fp8_f32 v11, v5, v8 op_sel:[0,0,1]
	v_pk_mul_f32 v[8:9], v[112:113], s[14:15] op_sel_hi:[1,0]
	v_pk_mul_f32 v[12:13], v[108:109], s[14:15] op_sel_hi:[1,0]
	s_mov_b32 s48, s16
	flat_store_dwordx2 v[6:7], v[10:11] offset:128 nt
	v_pk_mul_f32 v[10:11], v[110:111], s[14:15] op_sel_hi:[1,0]
	v_add_u32_e32 v6, 32, v4
	v_med3_f32 v5, v10, s47, v173
	v_med3_f32 v11, v11, s47, v173
	v_mov_b32_e32 v10, 0
	v_cvt_pk_fp8_f32 v10, v5, v11
	v_med3_f32 v5, v8, s47, v173
	v_med3_f32 v8, v9, s47, v173
	v_mov_b32_e32 v11, 0
	v_cvt_pk_fp8_f32 v10, v5, v8 op_sel:[0,0,1]
	v_med3_f32 v5, v14, s47, v173
	v_med3_f32 v8, v15, s47, v173
	v_cvt_pk_fp8_f32 v11, v5, v8
	v_med3_f32 v5, v12, s47, v173
	v_med3_f32 v8, v13, s47, v173
	v_cvt_pk_fp8_f32 v11, v5, v8 op_sel:[0,0,1]
	v_ashrrev_i32_e32 v7, 31, v6
	v_lshlrev_b64 v[6:7], 10, v[6:7]
	v_lshl_add_u64 v[6:7], s[10:11], 0, v[6:7]
	v_lshl_add_u64 v[6:7], v[6:7], 0, v[2:3]
	flat_store_dwordx2 v[6:7], v[10:11] nt
	v_pk_mul_f32 v[10:11], v[102:103], s[14:15] op_sel_hi:[1,0]
	v_pk_mul_f32 v[8:9], v[104:105], s[14:15] op_sel_hi:[1,0]
	v_med3_f32 v5, v10, s47, v173
	v_med3_f32 v11, v11, s47, v173
	v_mov_b32_e32 v10, 0
	v_cvt_pk_fp8_f32 v10, v5, v11
	v_pk_mul_f32 v[14:15], v[98:99], s[14:15] op_sel_hi:[1,0]
	v_med3_f32 v5, v8, s47, v173
	v_med3_f32 v8, v9, s47, v173
	v_cvt_pk_fp8_f32 v10, v5, v8 op_sel:[0,0,1]
	v_med3_f32 v5, v14, s47, v173
	v_med3_f32 v8, v15, s47, v173
	v_mov_b32_e32 v11, 0
	v_cvt_pk_fp8_f32 v11, v5, v8
	v_pk_mul_f32 v[12:13], v[100:101], s[14:15] op_sel_hi:[1,0]
	v_pk_mul_f32 v[14:15], v[90:91], s[14:15] op_sel_hi:[1,0]
	v_med3_f32 v5, v12, s47, v173
	v_med3_f32 v8, v13, s47, v173
	v_cvt_pk_fp8_f32 v11, v5, v8 op_sel:[0,0,1]
	v_pk_mul_f32 v[8:9], v[96:97], s[14:15] op_sel_hi:[1,0]
	v_pk_mul_f32 v[12:13], v[92:93], s[14:15] op_sel_hi:[1,0]
	s_mov_b32 s24, s18
	flat_store_dwordx2 v[6:7], v[10:11] offset:128 nt
	v_pk_mul_f32 v[10:11], v[94:95], s[14:15] op_sel_hi:[1,0]
	v_add_u32_e32 v6, 48, v4
	v_med3_f32 v5, v10, s47, v173
	v_med3_f32 v11, v11, s47, v173
	v_mov_b32_e32 v10, 0
	v_cvt_pk_fp8_f32 v10, v5, v11
	v_med3_f32 v5, v8, s47, v173
	v_med3_f32 v8, v9, s47, v173
	v_mov_b32_e32 v11, 0
	v_cvt_pk_fp8_f32 v10, v5, v8 op_sel:[0,0,1]
	v_med3_f32 v5, v14, s47, v173
	v_med3_f32 v8, v15, s47, v173
	v_cvt_pk_fp8_f32 v11, v5, v8
	v_med3_f32 v5, v12, s47, v173
	v_med3_f32 v8, v13, s47, v173
	v_cvt_pk_fp8_f32 v11, v5, v8 op_sel:[0,0,1]
	v_ashrrev_i32_e32 v7, 31, v6
	v_lshlrev_b64 v[6:7], 10, v[6:7]
	v_lshl_add_u64 v[6:7], s[10:11], 0, v[6:7]
	v_lshl_add_u64 v[6:7], v[6:7], 0, v[2:3]
	flat_store_dwordx2 v[6:7], v[10:11] nt
	v_pk_mul_f32 v[10:11], v[86:87], s[14:15] op_sel_hi:[1,0]
	v_pk_mul_f32 v[8:9], v[88:89], s[14:15] op_sel_hi:[1,0]
	v_med3_f32 v5, v10, s47, v173
	v_med3_f32 v11, v11, s47, v173
	v_mov_b32_e32 v10, 0
	v_cvt_pk_fp8_f32 v10, v5, v11
	v_pk_mul_f32 v[14:15], v[82:83], s[14:15] op_sel_hi:[1,0]
	v_med3_f32 v5, v8, s47, v173
	v_med3_f32 v8, v9, s47, v173
	v_cvt_pk_fp8_f32 v10, v5, v8 op_sel:[0,0,1]
	v_med3_f32 v5, v14, s47, v173
	v_med3_f32 v8, v15, s47, v173
	v_mov_b32_e32 v11, 0
	v_cvt_pk_fp8_f32 v11, v5, v8
	v_pk_mul_f32 v[12:13], v[84:85], s[14:15] op_sel_hi:[1,0]
	v_pk_mul_f32 v[14:15], v[74:75], s[14:15] op_sel_hi:[1,0]
	v_med3_f32 v5, v12, s47, v173
	v_med3_f32 v8, v13, s47, v173
	v_cvt_pk_fp8_f32 v11, v5, v8 op_sel:[0,0,1]
	v_pk_mul_f32 v[8:9], v[80:81], s[14:15] op_sel_hi:[1,0]
	v_pk_mul_f32 v[12:13], v[76:77], s[14:15] op_sel_hi:[1,0]
	s_mov_b64 s[26:27], s[22:23]
	flat_store_dwordx2 v[6:7], v[10:11] offset:128 nt
	v_pk_mul_f32 v[10:11], v[78:79], s[14:15] op_sel_hi:[1,0]
	v_add_u32_e32 v6, 0x80, v4
	v_med3_f32 v5, v10, s47, v173
	v_med3_f32 v11, v11, s47, v173
	v_mov_b32_e32 v10, 0
	v_cvt_pk_fp8_f32 v10, v5, v11
	v_med3_f32 v5, v8, s47, v173
	v_med3_f32 v8, v9, s47, v173
	v_mov_b32_e32 v11, 0
	v_cvt_pk_fp8_f32 v10, v5, v8 op_sel:[0,0,1]
	v_med3_f32 v5, v14, s47, v173
	v_med3_f32 v8, v15, s47, v173
	v_cvt_pk_fp8_f32 v11, v5, v8
	v_med3_f32 v5, v12, s47, v173
	v_med3_f32 v8, v13, s47, v173
	v_cvt_pk_fp8_f32 v11, v5, v8 op_sel:[0,0,1]
	v_ashrrev_i32_e32 v7, 31, v6
	v_lshlrev_b64 v[6:7], 10, v[6:7]
	v_lshl_add_u64 v[6:7], s[10:11], 0, v[6:7]
	v_lshl_add_u64 v[6:7], v[6:7], 0, v[2:3]
	flat_store_dwordx2 v[6:7], v[10:11] nt
	v_pk_mul_f32 v[10:11], v[70:71], s[14:15] op_sel_hi:[1,0]
	v_pk_mul_f32 v[8:9], v[72:73], s[14:15] op_sel_hi:[1,0]
	v_med3_f32 v5, v10, s47, v173
	v_med3_f32 v11, v11, s47, v173
	v_mov_b32_e32 v10, 0
	v_cvt_pk_fp8_f32 v10, v5, v11
	v_pk_mul_f32 v[14:15], v[66:67], s[14:15] op_sel_hi:[1,0]
	v_med3_f32 v5, v8, s47, v173
	v_med3_f32 v8, v9, s47, v173
	v_cvt_pk_fp8_f32 v10, v5, v8 op_sel:[0,0,1]
	v_med3_f32 v5, v14, s47, v173
	v_med3_f32 v8, v15, s47, v173
	v_mov_b32_e32 v11, 0
	v_cvt_pk_fp8_f32 v11, v5, v8
	v_pk_mul_f32 v[12:13], v[68:69], s[14:15] op_sel_hi:[1,0]
	v_pk_mul_f32 v[14:15], v[58:59], s[14:15] op_sel_hi:[1,0]
	v_med3_f32 v5, v12, s47, v173
	v_med3_f32 v8, v13, s47, v173
	v_cvt_pk_fp8_f32 v11, v5, v8 op_sel:[0,0,1]
	v_pk_mul_f32 v[8:9], v[64:65], s[14:15] op_sel_hi:[1,0]
	v_pk_mul_f32 v[12:13], v[60:61], s[14:15] op_sel_hi:[1,0]
	s_mov_b64 s[28:29], s[20:21]
	flat_store_dwordx2 v[6:7], v[10:11] offset:128 nt
	v_pk_mul_f32 v[10:11], v[62:63], s[14:15] op_sel_hi:[1,0]
	v_add_u32_e32 v6, 0x90, v4
	v_med3_f32 v5, v10, s47, v173
	v_med3_f32 v11, v11, s47, v173
	v_mov_b32_e32 v10, 0
	v_cvt_pk_fp8_f32 v10, v5, v11
	v_med3_f32 v5, v8, s47, v173
	v_med3_f32 v8, v9, s47, v173
	v_mov_b32_e32 v11, 0
	v_cvt_pk_fp8_f32 v10, v5, v8 op_sel:[0,0,1]
	v_med3_f32 v5, v14, s47, v173
	v_med3_f32 v8, v15, s47, v173
	v_cvt_pk_fp8_f32 v11, v5, v8
	v_med3_f32 v5, v12, s47, v173
	v_med3_f32 v8, v13, s47, v173
	v_cvt_pk_fp8_f32 v11, v5, v8 op_sel:[0,0,1]
	v_ashrrev_i32_e32 v7, 31, v6
	v_lshlrev_b64 v[6:7], 10, v[6:7]
	v_lshl_add_u64 v[6:7], s[10:11], 0, v[6:7]
	v_lshl_add_u64 v[6:7], v[6:7], 0, v[2:3]
	flat_store_dwordx2 v[6:7], v[10:11] nt
	v_pk_mul_f32 v[10:11], v[54:55], s[14:15] op_sel_hi:[1,0]
	v_pk_mul_f32 v[8:9], v[56:57], s[14:15] op_sel_hi:[1,0]
	v_med3_f32 v5, v10, s47, v173
	v_med3_f32 v11, v11, s47, v173
	v_mov_b32_e32 v10, 0
	v_cvt_pk_fp8_f32 v10, v5, v11
	v_pk_mul_f32 v[14:15], v[50:51], s[14:15] op_sel_hi:[1,0]
	v_med3_f32 v5, v8, s47, v173
	v_med3_f32 v8, v9, s47, v173
	v_cvt_pk_fp8_f32 v10, v5, v8 op_sel:[0,0,1]
	v_med3_f32 v5, v14, s47, v173
	v_med3_f32 v8, v15, s47, v173
	v_mov_b32_e32 v11, 0
	v_cvt_pk_fp8_f32 v11, v5, v8
	v_pk_mul_f32 v[12:13], v[52:53], s[14:15] op_sel_hi:[1,0]
	v_pk_mul_f32 v[14:15], v[42:43], s[14:15] op_sel_hi:[1,0]
	v_med3_f32 v5, v12, s47, v173
	v_med3_f32 v8, v13, s47, v173
	v_cvt_pk_fp8_f32 v11, v5, v8 op_sel:[0,0,1]
	v_pk_mul_f32 v[8:9], v[48:49], s[14:15] op_sel_hi:[1,0]
	v_pk_mul_f32 v[12:13], v[44:45], s[14:15] op_sel_hi:[1,0]
	flat_store_dwordx2 v[6:7], v[10:11] offset:128 nt
	v_pk_mul_f32 v[10:11], v[46:47], s[14:15] op_sel_hi:[1,0]
	v_add_u32_e32 v6, 0xa0, v4
	v_med3_f32 v5, v10, s47, v173
	v_med3_f32 v11, v11, s47, v173
	v_mov_b32_e32 v10, 0
	v_cvt_pk_fp8_f32 v10, v5, v11
	v_med3_f32 v5, v8, s47, v173
	v_med3_f32 v8, v9, s47, v173
	v_mov_b32_e32 v11, 0
	v_cvt_pk_fp8_f32 v10, v5, v8 op_sel:[0,0,1]
	v_med3_f32 v5, v14, s47, v173
	v_med3_f32 v8, v15, s47, v173
	v_cvt_pk_fp8_f32 v11, v5, v8
	v_med3_f32 v5, v12, s47, v173
	v_med3_f32 v8, v13, s47, v173
	v_cvt_pk_fp8_f32 v11, v5, v8 op_sel:[0,0,1]
	v_ashrrev_i32_e32 v7, 31, v6
	v_lshlrev_b64 v[6:7], 10, v[6:7]
	v_lshl_add_u64 v[6:7], s[10:11], 0, v[6:7]
	v_lshl_add_u64 v[6:7], v[6:7], 0, v[2:3]
	flat_store_dwordx2 v[6:7], v[10:11] nt
	v_pk_mul_f32 v[10:11], v[38:39], s[14:15] op_sel_hi:[1,0]
	v_pk_mul_f32 v[8:9], v[40:41], s[14:15] op_sel_hi:[1,0]
	v_med3_f32 v5, v10, s47, v173
	v_med3_f32 v11, v11, s47, v173
	v_mov_b32_e32 v10, 0
	v_cvt_pk_fp8_f32 v10, v5, v11
	v_pk_mul_f32 v[14:15], v[34:35], s[14:15] op_sel_hi:[1,0]
	v_med3_f32 v5, v8, s47, v173
	v_med3_f32 v8, v9, s47, v173
	v_cvt_pk_fp8_f32 v10, v5, v8 op_sel:[0,0,1]
	v_med3_f32 v5, v14, s47, v173
	v_med3_f32 v8, v15, s47, v173
	v_mov_b32_e32 v11, 0
	v_cvt_pk_fp8_f32 v11, v5, v8
	v_pk_mul_f32 v[12:13], v[36:37], s[14:15] op_sel_hi:[1,0]
	v_add_u32_e32 v4, 0xb0, v4
	v_med3_f32 v5, v12, s47, v173
	v_med3_f32 v8, v13, s47, v173
	v_cvt_pk_fp8_f32 v11, v5, v8 op_sel:[0,0,1]
	v_pk_mul_f32 v[8:9], v[28:29], s[14:15] op_sel_hi:[1,0]
	flat_store_dwordx2 v[6:7], v[10:11] offset:128 nt
	v_pk_mul_f32 v[6:7], v[30:31], s[14:15] op_sel_hi:[1,0]
	v_pk_mul_f32 v[10:11], v[26:27], s[14:15] op_sel_hi:[1,0]
	v_ashrrev_i32_e32 v5, 31, v4
	v_med3_f32 v12, v6, s47, v173
	v_med3_f32 v7, v7, s47, v173
	v_mov_b32_e32 v6, 0
	v_lshlrev_b64 v[4:5], 10, v[4:5]
	v_cvt_pk_fp8_f32 v6, v12, v7
	v_lshl_add_u64 v[4:5], s[10:11], 0, v[4:5]
	v_lshl_add_u64 v[2:3], v[4:5], 0, v[2:3]
	v_pk_mul_f32 v[4:5], v[32:33], s[14:15] op_sel_hi:[1,0]
	v_mov_b32_e32 v7, 0
	v_med3_f32 v4, v4, s47, v173
	v_med3_f32 v5, v5, s47, v173
	v_cvt_pk_fp8_f32 v6, v4, v5 op_sel:[0,0,1]
	v_med3_f32 v4, v10, s47, v173
	v_med3_f32 v5, v11, s47, v173
	v_cvt_pk_fp8_f32 v7, v4, v5
	v_med3_f32 v4, v8, s47, v173
	v_med3_f32 v5, v9, s47, v173
	v_pk_mul_f32 v[10:11], v[18:19], s[14:15] op_sel_hi:[1,0]
	v_cvt_pk_fp8_f32 v7, v4, v5 op_sel:[0,0,1]
	v_pk_mul_f32 v[4:5], v[24:25], s[14:15] op_sel_hi:[1,0]
	v_pk_mul_f32 v[8:9], v[20:21], s[14:15] op_sel_hi:[1,0]
	v_med3_f32 v4, v4, s47, v173
	flat_store_dwordx2 v[2:3], v[6:7] nt
	v_pk_mul_f32 v[6:7], v[22:23], s[14:15] op_sel_hi:[1,0]
	v_med3_f32 v5, v5, s47, v173
	v_med3_f32 v12, v6, s47, v173
	v_med3_f32 v7, v7, s47, v173
	v_mov_b32_e32 v6, 0
	v_cvt_pk_fp8_f32 v6, v12, v7
	v_mov_b32_e32 v7, 0
	v_cvt_pk_fp8_f32 v6, v4, v5 op_sel:[0,0,1]
	v_med3_f32 v4, v10, s47, v173
	v_med3_f32 v5, v11, s47, v173
	v_cvt_pk_fp8_f32 v7, v4, v5
	v_med3_f32 v4, v8, s47, v173
	v_med3_f32 v5, v9, s47, v173
	v_cvt_pk_fp8_f32 v7, v4, v5 op_sel:[0,0,1]
	flat_store_dwordx2 v[2:3], v[6:7] offset:128 nt
	s_cbranch_vccz .LBB0_748
	s_waitcnt vmcnt(0)
	s_cmpk_gt_u32 s4, 0xff
	s_cbranch_scc1 .LBB0_759
	s_barrier

.LBB0_895:
	ds_read_b128 v[156:159], v152
	ds_read_b128 v[160:163], v152 offset:1024
	ds_read_b128 v[164:167], v152 offset:2048
	ds_read_b128 v[168:171], v152 offset:3072
	s_add_u32 s0, s30, 0xfffc0080
	s_addc_u32 s1, s31, -1
	s_cmp_eq_u32 s55, 12
	s_cselect_b32 s37, s23, s1
	s_cselect_b32 s36, s51, s0
	s_cselect_b32 s35, s21, s54
	s_cselect_b32 s34, s52, s53
	v_lshl_add_u64 v[148:149], s[30:31], 0, v[140:141]
	s_add_i32 m0, s25, 0xc000
	ds_read_b128 v[172:175], v153
	ds_read_b128 v[176:179], v153 offset:1024
	ds_read_b128 v[180:183], v153 offset:2048
	ds_read_b128 v[184:187], v153 offset:3072
	ds_read_b128 v[188:191], v153 offset:4096
	ds_read_b128 v[192:195], v153 offset:5120
	ds_read_b128 v[196:199], v153 offset:6144
	ds_read_b128 v[200:203], v153 offset:7168
	global_load_lds_dwordx4 v[148:149], off
	v_lshl_add_u64 v[148:149], s[30:31], 0, v[138:139]
	s_add_i32 m0, s25, 0xe000
	s_nop 0
	global_load_lds_dwordx4 v[148:149], off
	s_waitcnt lgkmcnt(8)
	s_waitcnt vmcnt(10)
	s_barrier
	s_waitcnt lgkmcnt(0)
	s_setprio 1
	s_waitcnt lgkmcnt(0)
	v_mfma_f32_16x16x32_bf16 v[126:129], v[156:159], v[172:175], v[126:129]
	v_mfma_f32_16x16x32_bf16 v[122:125], v[164:167], v[172:175], v[122:125]
	v_mfma_f32_16x16x32_bf16 v[118:121], v[156:159], v[180:183], v[118:121]
	v_mfma_f32_16x16x32_bf16 v[110:113], v[164:167], v[180:183], v[110:113]
	v_mfma_f32_16x16x32_bf16 v[102:105], v[156:159], v[188:191], v[102:105]
	v_mfma_f32_16x16x32_bf16 v[94:97], v[164:167], v[188:191], v[94:97]
	v_mfma_f32_16x16x32_bf16 v[86:89], v[156:159], v[196:199], v[86:89]
	v_mfma_f32_16x16x32_bf16 v[78:81], v[164:167], v[196:199], v[78:81]
	v_mfma_f32_16x16x32_bf16 v[126:129], v[160:163], v[176:179], v[126:129]
	v_mfma_f32_16x16x32_bf16 v[122:125], v[168:171], v[176:179], v[122:125]
	v_mfma_f32_16x16x32_bf16 v[118:121], v[160:163], v[184:187], v[118:121]
	v_mfma_f32_16x16x32_bf16 v[110:113], v[168:171], v[184:187], v[110:113]
	v_mfma_f32_16x16x32_bf16 v[102:105], v[160:163], v[192:195], v[102:105]
	v_mfma_f32_16x16x32_bf16 v[94:97], v[168:171], v[192:195], v[94:97]
	v_mfma_f32_16x16x32_bf16 v[86:89], v[160:163], v[200:203], v[86:89]
	v_mfma_f32_16x16x32_bf16 v[78:81], v[168:171], v[200:203], v[78:81]
	s_setprio 0
	s_barrier
	s_add_i32 s0, s47, s11
	v_lshl_add_u64 v[148:149], s[34:35], 0, v[134:135]
	s_mov_b32 m0, s0
	ds_read_b128 v[204:207], v154
	ds_read_b128 v[208:211], v154 offset:1024
	ds_read_b128 v[212:215], v154 offset:2048
	ds_read_b128 v[216:219], v154 offset:3072
	global_load_lds_dwordx4 v[148:149], off
	v_lshl_add_u64 v[220:221], s[34:35], 0, v[130:131]
	s_add_i32 m0, s0, 0x2000
	s_nop 0
	global_load_lds_dwordx4 v[220:221], off
	s_waitcnt vmcnt(10)
	s_barrier
	s_waitcnt lgkmcnt(0)
	s_setprio 1
	s_waitcnt lgkmcnt(0)
	v_mfma_f32_16x16x32_bf16 v[114:117], v[204:207], v[172:175], v[114:117]
	v_mfma_f32_16x16x32_bf16 v[106:109], v[212:215], v[172:175], v[106:109]
	v_mfma_f32_16x16x32_bf16 v[98:101], v[204:207], v[180:183], v[98:101]
	v_mfma_f32_16x16x32_bf16 v[90:93], v[212:215], v[180:183], v[90:93]
	v_mfma_f32_16x16x32_bf16 v[82:85], v[204:207], v[188:191], v[82:85]
	v_mfma_f32_16x16x32_bf16 v[74:77], v[212:215], v[188:191], v[74:77]
	v_mfma_f32_16x16x32_bf16 v[70:73], v[204:207], v[196:199], v[70:73]
	v_mfma_f32_16x16x32_bf16 v[66:69], v[212:215], v[196:199], v[66:69]
	v_mfma_f32_16x16x32_bf16 v[114:117], v[208:211], v[176:179], v[114:117]
	v_mfma_f32_16x16x32_bf16 v[106:109], v[216:219], v[176:179], v[106:109]
	v_mfma_f32_16x16x32_bf16 v[98:101], v[208:211], v[184:187], v[98:101]
	v_mfma_f32_16x16x32_bf16 v[90:93], v[216:219], v[184:187], v[90:93]
	v_mfma_f32_16x16x32_bf16 v[82:85], v[208:211], v[192:195], v[82:85]
	v_mfma_f32_16x16x32_bf16 v[74:77], v[216:219], v[192:195], v[74:77]
	v_mfma_f32_16x16x32_bf16 v[70:73], v[208:211], v[200:203], v[70:73]
	v_mfma_f32_16x16x32_bf16 v[66:69], v[216:219], v[200:203], v[66:69]
	s_setprio 0
	s_mov_b32 m0, s25
	v_lshl_add_u64 v[222:223], s[36:37], 0, v[136:137]
	s_barrier
	ds_read_b128 v[172:175], v153 offset:16384
	ds_read_b128 v[176:179], v153 offset:17408
	ds_read_b128 v[180:183], v153 offset:18432
	ds_read_b128 v[184:187], v153 offset:19456
	ds_read_b128 v[188:191], v153 offset:20480
	ds_read_b128 v[192:195], v153 offset:21504
	ds_read_b128 v[196:199], v153 offset:22528
	ds_read_b128 v[200:203], v153 offset:23552
	global_load_lds_dwordx4 v[222:223], off
	v_lshl_add_u64 v[224:225], s[36:37], 0, v[132:133]
	s_mov_b32 m0, s39
	s_nop 0
	global_load_lds_dwordx4 v[224:225], off
	s_waitcnt vmcnt(10)
	s_barrier
	s_waitcnt lgkmcnt(0)
	s_setprio 1
	s_waitcnt lgkmcnt(0)
	v_mfma_f32_16x16x32_bf16 v[62:65], v[156:159], v[172:175], v[62:65]
	v_mfma_f32_16x16x32_bf16 v[58:61], v[164:167], v[172:175], v[58:61]
	v_mfma_f32_16x16x32_bf16 v[54:57], v[156:159], v[180:183], v[54:57]
	v_mfma_f32_16x16x32_bf16 v[46:49], v[164:167], v[180:183], v[46:49]
	v_mfma_f32_16x16x32_bf16 v[38:41], v[156:159], v[188:191], v[38:41]
	v_mfma_f32_16x16x32_bf16 v[30:33], v[164:167], v[188:191], v[30:33]
	v_mfma_f32_16x16x32_bf16 v[22:25], v[156:159], v[196:199], v[22:25]
	v_mfma_f32_16x16x32_bf16 v[14:17], v[164:167], v[196:199], v[14:17]
	v_mfma_f32_16x16x32_bf16 v[62:65], v[160:163], v[176:179], v[62:65]
	v_mfma_f32_16x16x32_bf16 v[58:61], v[168:171], v[176:179], v[58:61]
	v_mfma_f32_16x16x32_bf16 v[54:57], v[160:163], v[184:187], v[54:57]
	v_mfma_f32_16x16x32_bf16 v[46:49], v[168:171], v[184:187], v[46:49]
	v_mfma_f32_16x16x32_bf16 v[38:41], v[160:163], v[192:195], v[38:41]
	v_mfma_f32_16x16x32_bf16 v[30:33], v[168:171], v[192:195], v[30:33]
	v_mfma_f32_16x16x32_bf16 v[22:25], v[160:163], v[200:203], v[22:25]
	v_mfma_f32_16x16x32_bf16 v[14:17], v[168:171], v[200:203], v[14:17]
	s_setprio 0
	s_barrier
	s_add_u32 s0, s34, 0x40000
	s_addc_u32 s1, s35, 0
	s_add_i32 s56, s48, s11
	v_lshl_add_u64 v[156:157], s[0:1], 0, v[134:135]
	s_mov_b32 m0, s56
	s_nop 0
	global_load_lds_dwordx4 v[156:157], off
	v_lshl_add_u64 v[156:157], s[0:1], 0, v[130:131]
	s_add_i32 m0, s56, 0x2000
	s_nop 0
	global_load_lds_dwordx4 v[156:157], off
	s_waitcnt vmcnt(10)
	s_barrier
	s_setprio 1
	v_mfma_f32_16x16x32_bf16 v[50:53], v[204:207], v[172:175], v[50:53]
	v_mfma_f32_16x16x32_bf16 v[42:45], v[212:215], v[172:175], v[42:45]
	v_mfma_f32_16x16x32_bf16 v[34:37], v[204:207], v[180:183], v[34:37]
	v_mfma_f32_16x16x32_bf16 v[26:29], v[212:215], v[180:183], v[26:29]
	v_mfma_f32_16x16x32_bf16 v[18:21], v[204:207], v[188:191], v[18:21]
	v_mfma_f32_16x16x32_bf16 v[10:13], v[212:215], v[188:191], v[10:13]
	v_mfma_f32_16x16x32_bf16 v[6:9], v[204:207], v[196:199], v[6:9]
	v_mfma_f32_16x16x32_bf16 v[2:5], v[212:215], v[196:199], v[2:5]
	v_mfma_f32_16x16x32_bf16 v[50:53], v[208:211], v[176:179], v[50:53]
	v_mfma_f32_16x16x32_bf16 v[42:45], v[216:219], v[176:179], v[42:45]
	v_mfma_f32_16x16x32_bf16 v[34:37], v[208:211], v[184:187], v[34:37]
	v_mfma_f32_16x16x32_bf16 v[26:29], v[216:219], v[184:187], v[26:29]
	v_mfma_f32_16x16x32_bf16 v[18:21], v[208:211], v[192:195], v[18:21]
	v_mfma_f32_16x16x32_bf16 v[10:13], v[216:219], v[192:195], v[10:13]
	v_mfma_f32_16x16x32_bf16 v[6:9], v[208:211], v[200:203], v[6:9]
	v_mfma_f32_16x16x32_bf16 v[2:5], v[216:219], v[200:203], v[2:5]
	s_setprio 0
	s_add_i32 s56, 0, 0x18000
	v_add_u32_e32 v146, s56, v151
	s_barrier
	ds_read_b128 v[156:159], v146
	ds_read_b128 v[160:163], v146 offset:1024
	ds_read_b128 v[164:167], v146 offset:2048
	ds_read_b128 v[168:171], v146 offset:3072
	s_add_u32 s0, s36, 0x40000
	s_addc_u32 s1, s37, 0
	s_mov_b32 m0, s40
	v_lshl_add_u64 v[204:205], s[0:1], 0, v[136:137]
	ds_read_b128 v[172:175], v153 offset:32768
	ds_read_b128 v[176:179], v153 offset:33792
	ds_read_b128 v[180:183], v153 offset:34816
	ds_read_b128 v[184:187], v153 offset:35840
	ds_read_b128 v[188:191], v153 offset:36864
	ds_read_b128 v[192:195], v153 offset:37888
	ds_read_b128 v[196:199], v153 offset:38912
	ds_read_b128 v[200:203], v153 offset:39936
	global_load_lds_dwordx4 v[204:205], off
	v_lshl_add_u64 v[204:205], s[0:1], 0, v[132:133]
	s_mov_b32 m0, s41
	s_nop 0
	global_load_lds_dwordx4 v[204:205], off
	s_waitcnt lgkmcnt(8)
	s_waitcnt vmcnt(10)
	s_barrier
	s_waitcnt lgkmcnt(0)
	s_setprio 1
	s_waitcnt lgkmcnt(0)
	v_mfma_f32_16x16x32_bf16 v[126:129], v[156:159], v[172:175], v[126:129]
	v_mfma_f32_16x16x32_bf16 v[122:125], v[164:167], v[172:175], v[122:125]
	v_mfma_f32_16x16x32_bf16 v[118:121], v[156:159], v[180:183], v[118:121]
	v_mfma_f32_16x16x32_bf16 v[110:113], v[164:167], v[180:183], v[110:113]
	v_mfma_f32_16x16x32_bf16 v[102:105], v[156:159], v[188:191], v[102:105]
	v_mfma_f32_16x16x32_bf16 v[94:97], v[164:167], v[188:191], v[94:97]
	v_mfma_f32_16x16x32_bf16 v[86:89], v[156:159], v[196:199], v[86:89]
	v_mfma_f32_16x16x32_bf16 v[78:81], v[164:167], v[196:199], v[78:81]
	v_mfma_f32_16x16x32_bf16 v[126:129], v[160:163], v[176:179], v[126:129]
	v_mfma_f32_16x16x32_bf16 v[122:125], v[168:171], v[176:179], v[122:125]
	v_mfma_f32_16x16x32_bf16 v[118:121], v[160:163], v[184:187], v[118:121]
	v_mfma_f32_16x16x32_bf16 v[110:113], v[168:171], v[184:187], v[110:113]
	v_mfma_f32_16x16x32_bf16 v[102:105], v[160:163], v[192:195], v[102:105]
	v_mfma_f32_16x16x32_bf16 v[94:97], v[168:171], v[192:195], v[94:97]
	v_mfma_f32_16x16x32_bf16 v[86:89], v[160:163], v[200:203], v[86:89]
	v_mfma_f32_16x16x32_bf16 v[78:81], v[168:171], v[200:203], v[78:81]
	s_setprio 0
	s_barrier
	s_add_i32 s36, 0, 0x1c000
	s_add_i32 s0, s56, s11
	v_add_u32_e32 v146, s36, v151
	v_lshl_add_u64 v[148:149], v[148:149], 0, s[16:17]
	s_mov_b32 m0, s0
	ds_read_b128 v[204:207], v146
	ds_read_b128 v[208:211], v146 offset:1024
	ds_read_b128 v[212:215], v146 offset:2048
	ds_read_b128 v[216:219], v146 offset:3072
	global_load_lds_dwordx4 v[148:149], off
	v_lshl_add_u64 v[148:149], v[220:221], 0, s[16:17]
	s_add_i32 m0, s0, 0x2000
	s_nop 0
	global_load_lds_dwordx4 v[148:149], off
	s_waitcnt vmcnt(10)
	s_barrier
	s_waitcnt lgkmcnt(0)
	s_setprio 1
	s_waitcnt lgkmcnt(0)
	v_mfma_f32_16x16x32_bf16 v[114:117], v[204:207], v[172:175], v[114:117]
	v_mfma_f32_16x16x32_bf16 v[106:109], v[212:215], v[172:175], v[106:109]
	v_mfma_f32_16x16x32_bf16 v[98:101], v[204:207], v[180:183], v[98:101]
	v_mfma_f32_16x16x32_bf16 v[90:93], v[212:215], v[180:183], v[90:93]
	v_mfma_f32_16x16x32_bf16 v[82:85], v[204:207], v[188:191], v[82:85]
	v_mfma_f32_16x16x32_bf16 v[74:77], v[212:215], v[188:191], v[74:77]
	v_mfma_f32_16x16x32_bf16 v[70:73], v[204:207], v[196:199], v[70:73]
	v_mfma_f32_16x16x32_bf16 v[66:69], v[212:215], v[196:199], v[66:69]
	v_mfma_f32_16x16x32_bf16 v[114:117], v[208:211], v[176:179], v[114:117]
	v_mfma_f32_16x16x32_bf16 v[106:109], v[216:219], v[176:179], v[106:109]
	v_mfma_f32_16x16x32_bf16 v[98:101], v[208:211], v[184:187], v[98:101]
	v_mfma_f32_16x16x32_bf16 v[90:93], v[216:219], v[184:187], v[90:93]
	v_mfma_f32_16x16x32_bf16 v[82:85], v[208:211], v[192:195], v[82:85]
	v_mfma_f32_16x16x32_bf16 v[74:77], v[216:219], v[192:195], v[74:77]
	v_mfma_f32_16x16x32_bf16 v[70:73], v[208:211], v[200:203], v[70:73]
	v_mfma_f32_16x16x32_bf16 v[66:69], v[216:219], v[200:203], v[66:69]
	s_setprio 0
	s_mov_b32 m0, s45
	v_lshl_add_u64 v[148:149], v[222:223], 0, s[16:17]
	s_barrier
	ds_read_b128 v[172:175], v153 offset:49152
	ds_read_b128 v[176:179], v153 offset:50176
	ds_read_b128 v[180:183], v153 offset:51200
	ds_read_b128 v[184:187], v153 offset:52224
	ds_read_b128 v[188:191], v153 offset:53248
	ds_read_b128 v[192:195], v153 offset:54272
	ds_read_b128 v[196:199], v153 offset:55296
	ds_read_b128 v[200:203], v153 offset:56320
	global_load_lds_dwordx4 v[148:149], off
	v_lshl_add_u64 v[148:149], v[224:225], 0, s[16:17]
	s_mov_b32 m0, s46
	s_nop 0
	global_load_lds_dwordx4 v[148:149], off
	s_waitcnt vmcnt(10)
	s_barrier
	s_waitcnt lgkmcnt(0)
	s_setprio 1
	s_waitcnt lgkmcnt(0)
	v_mfma_f32_16x16x32_bf16 v[62:65], v[156:159], v[172:175], v[62:65]
	v_mfma_f32_16x16x32_bf16 v[58:61], v[164:167], v[172:175], v[58:61]
	v_mfma_f32_16x16x32_bf16 v[54:57], v[156:159], v[180:183], v[54:57]
	v_mfma_f32_16x16x32_bf16 v[46:49], v[164:167], v[180:183], v[46:49]
	v_mfma_f32_16x16x32_bf16 v[38:41], v[156:159], v[188:191], v[38:41]
	v_mfma_f32_16x16x32_bf16 v[30:33], v[164:167], v[188:191], v[30:33]
	v_mfma_f32_16x16x32_bf16 v[22:25], v[156:159], v[196:199], v[22:25]
	v_mfma_f32_16x16x32_bf16 v[14:17], v[164:167], v[196:199], v[14:17]
	v_mfma_f32_16x16x32_bf16 v[62:65], v[160:163], v[176:179], v[62:65]
	v_mfma_f32_16x16x32_bf16 v[58:61], v[168:171], v[176:179], v[58:61]
	v_mfma_f32_16x16x32_bf16 v[54:57], v[160:163], v[184:187], v[54:57]
	v_mfma_f32_16x16x32_bf16 v[46:49], v[168:171], v[184:187], v[46:49]
	v_mfma_f32_16x16x32_bf16 v[38:41], v[160:163], v[192:195], v[38:41]
	v_mfma_f32_16x16x32_bf16 v[30:33], v[168:171], v[192:195], v[30:33]
	v_mfma_f32_16x16x32_bf16 v[22:25], v[160:163], v[200:203], v[22:25]
	v_mfma_f32_16x16x32_bf16 v[14:17], v[168:171], v[200:203], v[14:17]
	s_setprio 0
	s_barrier
	s_add_u32 s0, s34, 0x40080
	s_addc_u32 s1, s35, 0
	s_add_i32 s34, s36, s11
	v_lshl_add_u64 v[148:149], s[0:1], 0, v[134:135]
	s_mov_b32 m0, s34
	s_nop 0
	global_load_lds_dwordx4 v[148:149], off
	v_lshl_add_u64 v[148:149], s[0:1], 0, v[130:131]
	s_add_i32 m0, s34, 0x2000
	s_nop 0
	global_load_lds_dwordx4 v[148:149], off
	s_waitcnt vmcnt(10)
	s_barrier
	s_setprio 1
	v_mfma_f32_16x16x32_bf16 v[50:53], v[204:207], v[172:175], v[50:53]
	v_mfma_f32_16x16x32_bf16 v[42:45], v[212:215], v[172:175], v[42:45]
	v_mfma_f32_16x16x32_bf16 v[34:37], v[204:207], v[180:183], v[34:37]
	v_mfma_f32_16x16x32_bf16 v[26:29], v[212:215], v[180:183], v[26:29]
	v_mfma_f32_16x16x32_bf16 v[18:21], v[204:207], v[188:191], v[18:21]
	v_mfma_f32_16x16x32_bf16 v[10:13], v[212:215], v[188:191], v[10:13]
	v_mfma_f32_16x16x32_bf16 v[6:9], v[204:207], v[196:199], v[6:9]
	v_mfma_f32_16x16x32_bf16 v[2:5], v[212:215], v[196:199], v[2:5]
	v_mfma_f32_16x16x32_bf16 v[50:53], v[208:211], v[176:179], v[50:53]
	v_mfma_f32_16x16x32_bf16 v[42:45], v[216:219], v[176:179], v[42:45]
	v_mfma_f32_16x16x32_bf16 v[34:37], v[208:211], v[184:187], v[34:37]
	v_mfma_f32_16x16x32_bf16 v[26:29], v[216:219], v[184:187], v[26:29]
	v_mfma_f32_16x16x32_bf16 v[18:21], v[208:211], v[192:195], v[18:21]
	v_mfma_f32_16x16x32_bf16 v[10:13], v[216:219], v[192:195], v[10:13]
	v_mfma_f32_16x16x32_bf16 v[6:9], v[208:211], v[200:203], v[6:9]
	v_mfma_f32_16x16x32_bf16 v[2:5], v[216:219], v[200:203], v[2:5]
	s_setprio 0
	s_add_i32 s55, s55, 2
	s_add_u32 s53, s53, 0x100
	s_addc_u32 s54, s54, 0
	s_add_u32 s30, s30, 0x100
	s_addc_u32 s31, s31, 0
	s_cmp_gt_u32 s55, 13
	s_barrier
	s_cbranch_scc0 .LBB0_895
	v_mov_b32_e32 v156, v147
	v_mov_b32_e32 v146, v150
	s_cmp_gt_i32 s50, 11
	s_mov_b64 s[30:31], -1
	s_cbranch_scc0 .LBB0_900
	s_cmp_eq_u32 s50, 12
	s_cselect_b64 s[0:1], -1, 0
	s_and_b64 s[0:1], s[0:1], s[18:19]
	v_cmp_gt_i32_e32 vcc, 4, v146
	s_and_b64 s[0:1], s[0:1], vcc
	s_and_saveexec_b64 s[30:31], s[0:1]
	s_cbranch_execz .LBB0_899
	s_lshl_b32 s0, s24, 8
	s_add_i32 s0, s0, s43
	v_add_u32_e32 v157, s0, v156
	v_mov_b32_e32 v158, v157
	v_lshlrev_b32_e32 v148, 3, v146
	v_ashrrev_i32_e32 v149, 31, v148
	v_ashrrev_i32_e32 v159, 31, v158
	v_lshlrev_b64 v[158:159], 7, v[158:159]
	v_lshl_add_u64 v[158:159], s[14:15], 0, v[158:159]
	v_lshlrev_b64 v[148:149], 2, v[148:149]
	v_lshl_add_u64 v[162:163], v[158:159], 0, v[148:149]
	v_pk_add_f32 v[160:161], v[128:129], 0 op_sel_hi:[1,0]
	v_pk_add_f32 v[158:159], v[126:127], 0 op_sel_hi:[1,0]
	flat_store_dwordx4 v[162:163], v[158:161] nt
	s_nop 1
	v_pk_add_f32 v[160:161], v[124:125], 0 op_sel_hi:[1,0]
	v_pk_add_f32 v[158:159], v[122:123], 0 op_sel_hi:[1,0]
	flat_store_dwordx4 v[162:163], v[158:161] offset:16 nt
	s_nop 1
	v_add_u32_e32 v158, 16, v157
	v_pk_add_f32 v[160:161], v[120:121], 0 op_sel_hi:[1,0]
	v_ashrrev_i32_e32 v159, 31, v158
	v_lshlrev_b64 v[158:159], 7, v[158:159]
	v_lshl_add_u64 v[158:159], s[14:15], 0, v[158:159]
	v_lshl_add_u64 v[162:163], v[158:159], 0, v[148:149]
	v_pk_add_f32 v[158:159], v[118:119], 0 op_sel_hi:[1,0]
	flat_store_dwordx4 v[162:163], v[158:161] nt
	s_nop 1
	v_pk_add_f32 v[160:161], v[112:113], 0 op_sel_hi:[1,0]
	v_pk_add_f32 v[158:159], v[110:111], 0 op_sel_hi:[1,0]
	flat_store_dwordx4 v[162:163], v[158:161] offset:16 nt
	s_nop 1
	v_add_u32_e32 v158, 32, v157
	v_pk_add_f32 v[160:161], v[104:105], 0 op_sel_hi:[1,0]
	v_ashrrev_i32_e32 v159, 31, v158
	v_lshlrev_b64 v[158:159], 7, v[158:159]
	v_lshl_add_u64 v[158:159], s[14:15], 0, v[158:159]
	v_lshl_add_u64 v[162:163], v[158:159], 0, v[148:149]
	v_pk_add_f32 v[158:159], v[102:103], 0 op_sel_hi:[1,0]
	flat_store_dwordx4 v[162:163], v[158:161] nt
	s_nop 1
	v_pk_add_f32 v[160:161], v[96:97], 0 op_sel_hi:[1,0]
	v_pk_add_f32 v[158:159], v[94:95], 0 op_sel_hi:[1,0]
	flat_store_dwordx4 v[162:163], v[158:161] offset:16 nt
	s_nop 1
	v_add_u32_e32 v158, 48, v157
	v_pk_add_f32 v[160:161], v[88:89], 0 op_sel_hi:[1,0]
	v_ashrrev_i32_e32 v159, 31, v158
	v_lshlrev_b64 v[158:159], 7, v[158:159]
	v_lshl_add_u64 v[158:159], s[14:15], 0, v[158:159]
	v_lshl_add_u64 v[162:163], v[158:159], 0, v[148:149]
	v_pk_add_f32 v[158:159], v[86:87], 0 op_sel_hi:[1,0]
	flat_store_dwordx4 v[162:163], v[158:161] nt
	s_nop 1
	v_pk_add_f32 v[160:161], v[80:81], 0 op_sel_hi:[1,0]
	v_pk_add_f32 v[158:159], v[78:79], 0 op_sel_hi:[1,0]
	flat_store_dwordx4 v[162:163], v[158:161] offset:16 nt
	s_nop 1
	v_add_u32_e32 v158, 0x80, v157
	v_pk_add_f32 v[160:161], v[64:65], 0 op_sel_hi:[1,0]
	v_ashrrev_i32_e32 v159, 31, v158
	v_lshlrev_b64 v[158:159], 7, v[158:159]
	v_lshl_add_u64 v[158:159], s[14:15], 0, v[158:159]
	v_lshl_add_u64 v[162:163], v[158:159], 0, v[148:149]
	v_pk_add_f32 v[158:159], v[62:63], 0 op_sel_hi:[1,0]
	flat_store_dwordx4 v[162:163], v[158:161] nt
	s_nop 1
	v_pk_add_f32 v[160:161], v[60:61], 0 op_sel_hi:[1,0]
	v_pk_add_f32 v[158:159], v[58:59], 0 op_sel_hi:[1,0]
	flat_store_dwordx4 v[162:163], v[158:161] offset:16 nt
	s_nop 1
	v_add_u32_e32 v158, 0x90, v157
	v_pk_add_f32 v[160:161], v[56:57], 0 op_sel_hi:[1,0]
	v_ashrrev_i32_e32 v159, 31, v158
	v_lshlrev_b64 v[158:159], 7, v[158:159]
	v_lshl_add_u64 v[158:159], s[14:15], 0, v[158:159]
	v_lshl_add_u64 v[162:163], v[158:159], 0, v[148:149]
	v_pk_add_f32 v[158:159], v[54:55], 0 op_sel_hi:[1,0]
	flat_store_dwordx4 v[162:163], v[158:161] nt
	s_nop 1
	v_pk_add_f32 v[160:161], v[48:49], 0 op_sel_hi:[1,0]
	v_pk_add_f32 v[158:159], v[46:47], 0 op_sel_hi:[1,0]
	flat_store_dwordx4 v[162:163], v[158:161] offset:16 nt
	s_nop 1
	v_add_u32_e32 v158, 0xa0, v157
	v_pk_add_f32 v[160:161], v[40:41], 0 op_sel_hi:[1,0]
	v_ashrrev_i32_e32 v159, 31, v158
	v_lshlrev_b64 v[158:159], 7, v[158:159]
	v_lshl_add_u64 v[158:159], s[14:15], 0, v[158:159]
	v_lshl_add_u64 v[162:163], v[158:159], 0, v[148:149]
	v_pk_add_f32 v[158:159], v[38:39], 0 op_sel_hi:[1,0]
	flat_store_dwordx4 v[162:163], v[158:161] nt
	s_nop 1
	v_pk_add_f32 v[160:161], v[32:33], 0 op_sel_hi:[1,0]
	v_pk_add_f32 v[158:159], v[30:31], 0 op_sel_hi:[1,0]
	flat_store_dwordx4 v[162:163], v[158:161] offset:16 nt
	s_nop 1
	v_add_u32_e32 v158, 0xb0, v157
	v_pk_add_f32 v[160:161], v[24:25], 0 op_sel_hi:[1,0]
	v_ashrrev_i32_e32 v159, 31, v158
	v_lshlrev_b64 v[158:159], 7, v[158:159]
	v_lshl_add_u64 v[158:159], s[14:15], 0, v[158:159]
	v_lshl_add_u64 v[148:149], v[158:159], 0, v[148:149]
	v_pk_add_f32 v[158:159], v[22:23], 0 op_sel_hi:[1,0]
	flat_store_dwordx4 v[148:149], v[158:161] nt
	s_nop 1
	v_pk_add_f32 v[160:161], v[16:17], 0 op_sel_hi:[1,0]
	v_pk_add_f32 v[158:159], v[14:15], 0 op_sel_hi:[1,0]
	flat_store_dwordx4 v[148:149], v[158:161] offset:16 nt

.LBB0_900:
	s_andn2_b64 vcc, exec, s[30:31]
	s_cbranch_vccnz .LBB0_891
	s_lshl_b32 s0, s50, 8
	s_or_b32 s0, s0, s44
	s_cmp_lt_i32 s50, 2
	v_lshl_add_u32 v148, v146, 3, s0
	s_cselect_b64 vcc, -1, 0
	s_lshl_b32 s0, s24, 8
	s_add_i32 s0, s0, s43
	v_add_u32_e32 v160, s0, v156
	v_cndmask_b32_e32 v146, 1.0, v155, vcc
	v_ashrrev_i32_e32 v149, 31, v148
	v_mov_b32_e32 v156, v160
	v_lshl_add_u64 v[148:149], v[148:149], 1, s[12:13]
	v_pk_mul_f32 v[128:129], v[146:147], v[128:129] op_sel_hi:[0,1]
	v_pk_mul_f32 v[126:127], v[146:147], v[126:127] op_sel_hi:[0,1]
	v_pk_mul_f32 v[158:159], v[146:147], v[124:125] op_sel_hi:[0,1]
	v_pk_mul_f32 v[124:125], v[146:147], v[122:123] op_sel_hi:[0,1]
	v_mad_i64_i32 v[156:157], s[0:1], v156, s49, v[148:149]
	v_cvt_pk_bf16_f32 v122, v126, v127
	v_cvt_pk_bf16_f32 v123, v128, v129
	v_cvt_pk_bf16_f32 v124, v124, v125
	v_cvt_pk_bf16_f32 v125, v158, v159
	flat_store_dwordx4 v[156:157], v[122:125] nt
	v_pk_mul_f32 v[116:117], v[146:147], v[116:117] op_sel_hi:[0,1]
	v_pk_mul_f32 v[114:115], v[146:147], v[114:115] op_sel_hi:[0,1]
	v_pk_mul_f32 v[122:123], v[146:147], v[108:109] op_sel_hi:[0,1]
	v_pk_mul_f32 v[108:109], v[146:147], v[106:107] op_sel_hi:[0,1]
	v_cvt_pk_bf16_f32 v106, v114, v115
	v_cvt_pk_bf16_f32 v107, v116, v117
	v_cvt_pk_bf16_f32 v108, v108, v109
	v_cvt_pk_bf16_f32 v109, v122, v123
	flat_store_dwordx4 v[156:157], v[106:109] offset:256 nt
	v_pk_mul_f32 v[112:113], v[146:147], v[112:113] op_sel_hi:[0,1]
	v_pk_mul_f32 v[110:111], v[146:147], v[110:111] op_sel_hi:[0,1]
	v_add_u32_e32 v106, 16, v160
	v_pk_mul_f32 v[108:109], v[146:147], v[120:121] op_sel_hi:[0,1]
	v_mad_i64_i32 v[114:115], s[0:1], v106, s49, v[148:149]
	v_pk_mul_f32 v[106:107], v[146:147], v[118:119] op_sel_hi:[0,1]
	v_cvt_pk_bf16_f32 v106, v106, v107
	v_cvt_pk_bf16_f32 v107, v108, v109
	v_cvt_pk_bf16_f32 v108, v110, v111
	v_cvt_pk_bf16_f32 v109, v112, v113
	flat_store_dwordx4 v[114:115], v[106:109] nt
	v_pk_mul_f32 v[100:101], v[146:147], v[100:101] op_sel_hi:[0,1]
	v_pk_mul_f32 v[98:99], v[146:147], v[98:99] op_sel_hi:[0,1]
	v_pk_mul_f32 v[106:107], v[146:147], v[92:93] op_sel_hi:[0,1]
	v_pk_mul_f32 v[92:93], v[146:147], v[90:91] op_sel_hi:[0,1]
	v_cvt_pk_bf16_f32 v90, v98, v99
	v_cvt_pk_bf16_f32 v91, v100, v101
	v_cvt_pk_bf16_f32 v92, v92, v93
	v_cvt_pk_bf16_f32 v93, v106, v107
	flat_store_dwordx4 v[114:115], v[90:93] offset:256 nt
	v_pk_mul_f32 v[96:97], v[146:147], v[96:97] op_sel_hi:[0,1]
	v_pk_mul_f32 v[94:95], v[146:147], v[94:95] op_sel_hi:[0,1]
	v_add_u32_e32 v90, 32, v160
	v_pk_mul_f32 v[92:93], v[146:147], v[104:105] op_sel_hi:[0,1]
	v_mad_i64_i32 v[98:99], s[0:1], v90, s49, v[148:149]
	v_pk_mul_f32 v[90:91], v[146:147], v[102:103] op_sel_hi:[0,1]
	v_cvt_pk_bf16_f32 v90, v90, v91
	v_cvt_pk_bf16_f32 v91, v92, v93
	v_cvt_pk_bf16_f32 v92, v94, v95
	v_cvt_pk_bf16_f32 v93, v96, v97
	flat_store_dwordx4 v[98:99], v[90:93] nt
	v_pk_mul_f32 v[84:85], v[146:147], v[84:85] op_sel_hi:[0,1]
	v_pk_mul_f32 v[82:83], v[146:147], v[82:83] op_sel_hi:[0,1]
	v_pk_mul_f32 v[90:91], v[146:147], v[76:77] op_sel_hi:[0,1]
	v_pk_mul_f32 v[76:77], v[146:147], v[74:75] op_sel_hi:[0,1]
	v_cvt_pk_bf16_f32 v74, v82, v83
	v_cvt_pk_bf16_f32 v75, v84, v85
	v_cvt_pk_bf16_f32 v76, v76, v77
	v_cvt_pk_bf16_f32 v77, v90, v91
	flat_store_dwordx4 v[98:99], v[74:77] offset:256 nt
	v_pk_mul_f32 v[80:81], v[146:147], v[80:81] op_sel_hi:[0,1]
	v_pk_mul_f32 v[78:79], v[146:147], v[78:79] op_sel_hi:[0,1]
	v_add_u32_e32 v74, 48, v160
	v_pk_mul_f32 v[76:77], v[146:147], v[88:89] op_sel_hi:[0,1]
	v_mad_i64_i32 v[82:83], s[0:1], v74, s49, v[148:149]
	v_pk_mul_f32 v[74:75], v[146:147], v[86:87] op_sel_hi:[0,1]
	v_cvt_pk_bf16_f32 v74, v74, v75
	v_cvt_pk_bf16_f32 v75, v76, v77
	v_cvt_pk_bf16_f32 v76, v78, v79
	v_cvt_pk_bf16_f32 v77, v80, v81
	flat_store_dwordx4 v[82:83], v[74:77] nt
	v_pk_mul_f32 v[72:73], v[146:147], v[72:73] op_sel_hi:[0,1]
	v_pk_mul_f32 v[70:71], v[146:147], v[70:71] op_sel_hi:[0,1]
	v_pk_mul_f32 v[74:75], v[146:147], v[68:69] op_sel_hi:[0,1]
	v_pk_mul_f32 v[68:69], v[146:147], v[66:67] op_sel_hi:[0,1]
	v_cvt_pk_bf16_f32 v66, v70, v71
	v_cvt_pk_bf16_f32 v67, v72, v73
	v_cvt_pk_bf16_f32 v68, v68, v69
	v_cvt_pk_bf16_f32 v69, v74, v75
	flat_store_dwordx4 v[82:83], v[66:69] offset:256 nt
	v_pk_mul_f32 v[64:65], v[146:147], v[64:65] op_sel_hi:[0,1]
	v_pk_mul_f32 v[62:63], v[146:147], v[62:63] op_sel_hi:[0,1]
	v_add_u32_e32 v66, 0x80, v160
	v_pk_mul_f32 v[68:69], v[146:147], v[60:61] op_sel_hi:[0,1]
	v_pk_mul_f32 v[60:61], v[146:147], v[58:59] op_sel_hi:[0,1]
	v_mad_i64_i32 v[66:67], s[0:1], v66, s49, v[148:149]
	v_cvt_pk_bf16_f32 v58, v62, v63
	v_cvt_pk_bf16_f32 v59, v64, v65
	v_cvt_pk_bf16_f32 v60, v60, v61
	v_cvt_pk_bf16_f32 v61, v68, v69
	flat_store_dwordx4 v[66:67], v[58:61] nt
	v_pk_mul_f32 v[52:53], v[146:147], v[52:53] op_sel_hi:[0,1]
	v_pk_mul_f32 v[50:51], v[146:147], v[50:51] op_sel_hi:[0,1]
	v_pk_mul_f32 v[58:59], v[146:147], v[44:45] op_sel_hi:[0,1]
	v_pk_mul_f32 v[44:45], v[146:147], v[42:43] op_sel_hi:[0,1]
	v_cvt_pk_bf16_f32 v42, v50, v51
	v_cvt_pk_bf16_f32 v43, v52, v53
	v_cvt_pk_bf16_f32 v44, v44, v45
	v_cvt_pk_bf16_f32 v45, v58, v59
	flat_store_dwordx4 v[66:67], v[42:45] offset:256 nt
	v_pk_mul_f32 v[48:49], v[146:147], v[48:49] op_sel_hi:[0,1]
	v_pk_mul_f32 v[46:47], v[146:147], v[46:47] op_sel_hi:[0,1]
	v_add_u32_e32 v42, 0x90, v160
	v_pk_mul_f32 v[44:45], v[146:147], v[56:57] op_sel_hi:[0,1]
	v_mad_i64_i32 v[50:51], s[0:1], v42, s49, v[148:149]
	v_pk_mul_f32 v[42:43], v[146:147], v[54:55] op_sel_hi:[0,1]
	v_cvt_pk_bf16_f32 v42, v42, v43
	v_cvt_pk_bf16_f32 v43, v44, v45
	v_cvt_pk_bf16_f32 v44, v46, v47
	v_cvt_pk_bf16_f32 v45, v48, v49
	flat_store_dwordx4 v[50:51], v[42:45] nt
	v_pk_mul_f32 v[36:37], v[146:147], v[36:37] op_sel_hi:[0,1]
	v_pk_mul_f32 v[34:35], v[146:147], v[34:35] op_sel_hi:[0,1]
	v_pk_mul_f32 v[42:43], v[146:147], v[28:29] op_sel_hi:[0,1]
	v_pk_mul_f32 v[28:29], v[146:147], v[26:27] op_sel_hi:[0,1]
	v_cvt_pk_bf16_f32 v26, v34, v35
	v_cvt_pk_bf16_f32 v27, v36, v37
	v_cvt_pk_bf16_f32 v28, v28, v29
	v_cvt_pk_bf16_f32 v29, v42, v43
	flat_store_dwordx4 v[50:51], v[26:29] offset:256 nt
	v_pk_mul_f32 v[32:33], v[146:147], v[32:33] op_sel_hi:[0,1]
	v_pk_mul_f32 v[30:31], v[146:147], v[30:31] op_sel_hi:[0,1]
	v_add_u32_e32 v26, 0xa0, v160
	v_pk_mul_f32 v[28:29], v[146:147], v[40:41] op_sel_hi:[0,1]
	v_mad_i64_i32 v[34:35], s[0:1], v26, s49, v[148:149]
	v_pk_mul_f32 v[26:27], v[146:147], v[38:39] op_sel_hi:[0,1]
	v_cvt_pk_bf16_f32 v26, v26, v27
	v_cvt_pk_bf16_f32 v27, v28, v29
	v_cvt_pk_bf16_f32 v28, v30, v31
	v_cvt_pk_bf16_f32 v29, v32, v33
	flat_store_dwordx4 v[34:35], v[26:29] nt
	v_pk_mul_f32 v[20:21], v[146:147], v[20:21] op_sel_hi:[0,1]
	v_pk_mul_f32 v[18:19], v[146:147], v[18:19] op_sel_hi:[0,1]
	v_pk_mul_f32 v[26:27], v[146:147], v[12:13] op_sel_hi:[0,1]
	v_pk_mul_f32 v[12:13], v[146:147], v[10:11] op_sel_hi:[0,1]
	v_cvt_pk_bf16_f32 v10, v18, v19
	v_cvt_pk_bf16_f32 v11, v20, v21
	v_cvt_pk_bf16_f32 v12, v12, v13
	v_cvt_pk_bf16_f32 v13, v26, v27
	flat_store_dwordx4 v[34:35], v[10:13] offset:256 nt
	v_pk_mul_f32 v[16:17], v[146:147], v[16:17] op_sel_hi:[0,1]
	v_pk_mul_f32 v[14:15], v[146:147], v[14:15] op_sel_hi:[0,1]
	v_add_u32_e32 v10, 0xb0, v160
	v_pk_mul_f32 v[12:13], v[146:147], v[24:25] op_sel_hi:[0,1]
	v_mad_i64_i32 v[18:19], s[0:1], v10, s49, v[148:149]
	v_pk_mul_f32 v[10:11], v[146:147], v[22:23] op_sel_hi:[0,1]
	v_cvt_pk_bf16_f32 v10, v10, v11
	v_cvt_pk_bf16_f32 v11, v12, v13
	v_cvt_pk_bf16_f32 v12, v14, v15
	v_cvt_pk_bf16_f32 v13, v16, v17
	flat_store_dwordx4 v[18:19], v[10:13] nt
	v_pk_mul_f32 v[8:9], v[146:147], v[8:9] op_sel_hi:[0,1]
	v_pk_mul_f32 v[6:7], v[146:147], v[6:7] op_sel_hi:[0,1]
	v_pk_mul_f32 v[10:11], v[146:147], v[4:5] op_sel_hi:[0,1]
	v_pk_mul_f32 v[4:5], v[146:147], v[2:3] op_sel_hi:[0,1]
	v_cvt_pk_bf16_f32 v2, v6, v7
	v_cvt_pk_bf16_f32 v3, v8, v9
	v_cvt_pk_bf16_f32 v4, v4, v5
	v_cvt_pk_bf16_f32 v5, v10, v11
	flat_store_dwordx4 v[18:19], v[2:5] offset:256 nt
	s_branch .LBB0_891

.LBB0_1302:
	s_add_u32 s12, s36, 0x100
	s_addc_u32 s13, s37, 0
	s_add_u32 s34, s31, s36
	s_addc_u32 s35, s55, s37
	s_cmpk_eq_i32 s36, 0x300
	s_cselect_b64 vcc, -1, 0
	s_and_b64 s[0:1], vcc, exec
	s_cselect_b32 s1, 0, s12
	s_cselect_b32 s0, 0, s13
	s_cselect_b32 s34, s29, s34
	s_cselect_b32 s35, s27, s35
	s_add_u32 s38, s16, s1
	s_addc_u32 s39, s17, s0
	s_add_i32 s1, 0, 0x10000
	v_add_u32_e32 v14, s1, v197
	ds_read_b128 v[2:5], v14
	ds_read_b128 v[6:9], v14 offset:1024
	ds_read_b128 v[10:13], v14 offset:2048
	ds_read_b128 v[14:17], v14 offset:3072
	v_cndmask_b32_e32 v162, v168, v171, vcc
	v_cndmask_b32_e32 v184, v170, v198, vcc
	v_cndmask_b32_e32 v175, v172, v199, vcc
	v_cndmask_b32_e32 v173, v174, v200, vcc
	v_lshl_add_u64 v[18:19], v[178:179], 0, s[36:37]
	s_add_i32 m0, s45, 0xc000
	ds_read_b128 v[202:205], v169
	ds_read_b128 v[206:209], v169 offset:1024
	ds_read_b128 v[210:213], v169 offset:2048
	ds_read_b128 v[214:217], v169 offset:3072
	ds_read_b128 v[218:221], v169 offset:4096
	ds_read_b128 v[222:225], v169 offset:5120
	ds_read_b128 v[226:229], v169 offset:6144
	ds_read_b128 v[230:233], v169 offset:7168
	global_load_lds_dwordx4 v[18:19], off
	v_lshl_add_u64 v[18:19], v[176:177], 0, s[36:37]
	s_add_i32 m0, s45, 0xe000
	s_nop 0
	global_load_lds_dwordx4 v[18:19], off
	s_waitcnt lgkmcnt(8)
	s_waitcnt vmcnt(10)
	s_barrier
	s_waitcnt lgkmcnt(0)
	s_setprio 1
	s_waitcnt lgkmcnt(0)
	v_mfma_scale_f32_16x16x128_f8f6f4 v[158:161], v[2:9], v[202:209], v[158:161], v188, v188 op_sel_hi:[0,0,0]
	v_mfma_scale_f32_16x16x128_f8f6f4 v[150:153], v[10:17], v[202:209], v[150:153], v188, v188 op_sel_hi:[0,0,0]
	v_mfma_scale_f32_16x16x128_f8f6f4 v[142:145], v[2:9], v[210:217], v[142:145], v188, v188 op_sel_hi:[0,0,0]
	v_mfma_scale_f32_16x16x128_f8f6f4 v[134:137], v[10:17], v[210:217], v[134:137], v188, v188 op_sel_hi:[0,0,0]
	v_mfma_scale_f32_16x16x128_f8f6f4 v[126:129], v[2:9], v[218:225], v[126:129], v188, v188 op_sel_hi:[0,0,0]
	v_mfma_scale_f32_16x16x128_f8f6f4 v[118:121], v[10:17], v[218:225], v[118:121], v188, v188 op_sel_hi:[0,0,0]
	v_mfma_scale_f32_16x16x128_f8f6f4 v[110:113], v[2:9], v[226:233], v[110:113], v188, v188 op_sel_hi:[0,0,0]
	v_mfma_scale_f32_16x16x128_f8f6f4 v[102:105], v[10:17], v[226:233], v[102:105], v188, v188 op_sel_hi:[0,0,0]
	s_setprio 0
	s_barrier
	s_add_i32 s0, 0, 0x14000
	s_add_i32 s1, s1, s43
	v_add_u32_e32 v30, s0, v197
	v_lshl_add_u64 v[180:181], s[34:35], 0, v[164:165]
	s_mov_b32 m0, s1
	ds_read_b128 v[18:21], v30
	ds_read_b128 v[22:25], v30 offset:1024
	ds_read_b128 v[26:29], v30 offset:2048
	ds_read_b128 v[30:33], v30 offset:3072
	global_load_lds_dwordx4 v[180:181], off
	v_lshl_add_u64 v[182:183], s[34:35], 0, v[166:167]
	s_add_i32 m0, s1, 0x2000
	s_nop 0
	global_load_lds_dwordx4 v[182:183], off
	s_waitcnt vmcnt(10)
	s_barrier
	s_waitcnt lgkmcnt(0)
	s_setprio 1
	s_waitcnt lgkmcnt(0)
	v_mfma_scale_f32_16x16x128_f8f6f4 v[154:157], v[18:25], v[202:209], v[154:157], v188, v188 op_sel_hi:[0,0,0]
	v_mfma_scale_f32_16x16x128_f8f6f4 v[146:149], v[26:33], v[202:209], v[146:149], v188, v188 op_sel_hi:[0,0,0]
	v_mfma_scale_f32_16x16x128_f8f6f4 v[138:141], v[18:25], v[210:217], v[138:141], v188, v188 op_sel_hi:[0,0,0]
	v_mfma_scale_f32_16x16x128_f8f6f4 v[130:133], v[26:33], v[210:217], v[130:133], v188, v188 op_sel_hi:[0,0,0]
	v_mfma_scale_f32_16x16x128_f8f6f4 v[122:125], v[18:25], v[218:225], v[122:125], v188, v188 op_sel_hi:[0,0,0]
	v_mfma_scale_f32_16x16x128_f8f6f4 v[114:117], v[26:33], v[218:225], v[114:117], v188, v188 op_sel_hi:[0,0,0]
	v_mfma_scale_f32_16x16x128_f8f6f4 v[106:109], v[18:25], v[226:233], v[106:109], v188, v188 op_sel_hi:[0,0,0]
	v_mfma_scale_f32_16x16x128_f8f6f4 v[98:101], v[26:33], v[226:233], v[98:101], v188, v188 op_sel_hi:[0,0,0]
	s_setprio 0
	s_mov_b32 m0, s45
	s_barrier
	ds_read_b128 v[202:205], v169 offset:16384
	ds_read_b128 v[206:209], v169 offset:17408
	ds_read_b128 v[210:213], v169 offset:18432
	ds_read_b128 v[214:217], v169 offset:19456
	ds_read_b128 v[218:221], v169 offset:20480
	ds_read_b128 v[222:225], v169 offset:21504
	ds_read_b128 v[226:229], v169 offset:22528
	ds_read_b128 v[230:233], v169 offset:23552
	global_load_lds_dwordx4 v162, s[38:39]
	s_mov_b32 m0, s46
	v_mov_b32_e32 v185, v163
	global_load_lds_dwordx4 v184, s[38:39]
	s_waitcnt vmcnt(10)
	s_barrier
	s_waitcnt lgkmcnt(0)
	v_lshl_add_u64 v[186:187], s[38:39], 0, v[162:163]
	v_lshl_add_u64 v[184:185], s[38:39], 0, v[184:185]
	s_setprio 1
	s_waitcnt lgkmcnt(0)
	v_mfma_scale_f32_16x16x128_f8f6f4 v[94:97], v[2:9], v[202:209], v[94:97], v188, v188 op_sel_hi:[0,0,0]
	v_mfma_scale_f32_16x16x128_f8f6f4 v[86:89], v[10:17], v[202:209], v[86:89], v188, v188 op_sel_hi:[0,0,0]
	v_mfma_scale_f32_16x16x128_f8f6f4 v[78:81], v[2:9], v[210:217], v[78:81], v188, v188 op_sel_hi:[0,0,0]
	v_mfma_scale_f32_16x16x128_f8f6f4 v[70:73], v[10:17], v[210:217], v[70:73], v188, v188 op_sel_hi:[0,0,0]
	v_mfma_scale_f32_16x16x128_f8f6f4 v[62:65], v[2:9], v[218:225], v[62:65], v188, v188 op_sel_hi:[0,0,0]
	v_mfma_scale_f32_16x16x128_f8f6f4 v[54:57], v[10:17], v[218:225], v[54:57], v188, v188 op_sel_hi:[0,0,0]
	v_mfma_scale_f32_16x16x128_f8f6f4 v[46:49], v[2:9], v[226:233], v[46:49], v188, v188 op_sel_hi:[0,0,0]
	v_mfma_scale_f32_16x16x128_f8f6f4 v[38:41], v[10:17], v[226:233], v[38:41], v188, v188 op_sel_hi:[0,0,0]
	s_setprio 0
	s_barrier
	s_add_u32 s36, s34, 0x20000
	s_addc_u32 s37, s35, 0
	s_add_i32 s0, s0, s43
	v_lshl_add_u64 v[2:3], s[36:37], 0, v[164:165]
	s_mov_b32 m0, s0
	s_nop 0
	global_load_lds_dwordx4 v[2:3], off
	v_lshl_add_u64 v[2:3], s[36:37], 0, v[166:167]
	s_add_i32 m0, s0, 0x2000
	s_nop 0
	global_load_lds_dwordx4 v[2:3], off
	s_waitcnt vmcnt(10)
	s_barrier
	s_setprio 1
	v_mfma_scale_f32_16x16x128_f8f6f4 v[90:93], v[18:25], v[202:209], v[90:93], v188, v188 op_sel_hi:[0,0,0]
	v_mfma_scale_f32_16x16x128_f8f6f4 v[82:85], v[26:33], v[202:209], v[82:85], v188, v188 op_sel_hi:[0,0,0]
	v_mfma_scale_f32_16x16x128_f8f6f4 v[74:77], v[18:25], v[210:217], v[74:77], v188, v188 op_sel_hi:[0,0,0]
	v_mfma_scale_f32_16x16x128_f8f6f4 v[66:69], v[26:33], v[210:217], v[66:69], v188, v188 op_sel_hi:[0,0,0]
	v_mfma_scale_f32_16x16x128_f8f6f4 v[58:61], v[18:25], v[218:225], v[58:61], v188, v188 op_sel_hi:[0,0,0]
	v_mfma_scale_f32_16x16x128_f8f6f4 v[50:53], v[26:33], v[218:225], v[50:53], v188, v188 op_sel_hi:[0,0,0]
	v_mfma_scale_f32_16x16x128_f8f6f4 v[42:45], v[18:25], v[226:233], v[42:45], v188, v188 op_sel_hi:[0,0,0]
	v_mfma_scale_f32_16x16x128_f8f6f4 v[34:37], v[26:33], v[226:233], v[34:37], v188, v188 op_sel_hi:[0,0,0]
	s_setprio 0
	s_add_i32 s0, 0, 0x18000
	v_add_u32_e32 v14, s0, v197
	s_barrier
	ds_read_b128 v[2:5], v14
	ds_read_b128 v[6:9], v14 offset:1024
	ds_read_b128 v[10:13], v14 offset:2048
	ds_read_b128 v[14:17], v14 offset:3072
	s_mov_b32 m0, s47
	ds_read_b128 v[18:21], v169 offset:32768
	ds_read_b128 v[22:25], v169 offset:33792
	ds_read_b128 v[26:29], v169 offset:34816
	ds_read_b128 v[30:33], v169 offset:35840
	ds_read_b128 v[202:205], v169 offset:36864
	ds_read_b128 v[206:209], v169 offset:37888
	ds_read_b128 v[210:213], v169 offset:38912
	ds_read_b128 v[214:217], v169 offset:39936
	global_load_lds_dwordx4 v175, s[38:39]
	s_mov_b32 m0, s48
	s_nop 0
	global_load_lds_dwordx4 v173, s[38:39]
	s_waitcnt lgkmcnt(8)
	s_waitcnt vmcnt(10)
	s_barrier
	s_waitcnt lgkmcnt(0)
	s_setprio 1
	s_waitcnt lgkmcnt(0)
	v_mfma_scale_f32_16x16x128_f8f6f4 v[158:161], v[2:9], v[18:25], v[158:161], v188, v188 op_sel_hi:[0,0,0]
	v_mfma_scale_f32_16x16x128_f8f6f4 v[150:153], v[10:17], v[18:25], v[150:153], v188, v188 op_sel_hi:[0,0,0]
	v_mfma_scale_f32_16x16x128_f8f6f4 v[142:145], v[2:9], v[26:33], v[142:145], v188, v188 op_sel_hi:[0,0,0]
	v_mfma_scale_f32_16x16x128_f8f6f4 v[134:137], v[10:17], v[26:33], v[134:137], v188, v188 op_sel_hi:[0,0,0]
	v_mfma_scale_f32_16x16x128_f8f6f4 v[126:129], v[2:9], v[202:209], v[126:129], v188, v188 op_sel_hi:[0,0,0]
	v_mfma_scale_f32_16x16x128_f8f6f4 v[118:121], v[10:17], v[202:209], v[118:121], v188, v188 op_sel_hi:[0,0,0]
	v_mfma_scale_f32_16x16x128_f8f6f4 v[110:113], v[2:9], v[210:217], v[110:113], v188, v188 op_sel_hi:[0,0,0]
	v_mfma_scale_f32_16x16x128_f8f6f4 v[102:105], v[10:17], v[210:217], v[102:105], v188, v188 op_sel_hi:[0,0,0]
	s_setprio 0
	s_barrier
	s_add_i32 s36, 0, 0x1c000
	s_add_i32 s0, s0, s43
	v_add_u32_e32 v162, s36, v197
	v_lshl_add_u64 v[180:181], v[180:181], 0, s[22:23]
	s_mov_b32 m0, s0
	ds_read_b128 v[218:221], v162
	ds_read_b128 v[222:225], v162 offset:1024
	ds_read_b128 v[226:229], v162 offset:2048
	ds_read_b128 v[230:233], v162 offset:3072
	global_load_lds_dwordx4 v[180:181], off
	v_lshl_add_u64 v[180:181], v[182:183], 0, s[22:23]
	s_add_i32 m0, s0, 0x2000
	s_nop 0
	global_load_lds_dwordx4 v[180:181], off
	s_waitcnt vmcnt(10)
	s_barrier
	s_waitcnt lgkmcnt(0)
	s_setprio 1
	s_waitcnt lgkmcnt(0)
	v_mfma_scale_f32_16x16x128_f8f6f4 v[154:157], v[218:225], v[18:25], v[154:157], v188, v188 op_sel_hi:[0,0,0]
	v_mfma_scale_f32_16x16x128_f8f6f4 v[146:149], v[226:233], v[18:25], v[146:149], v188, v188 op_sel_hi:[0,0,0]
	v_mfma_scale_f32_16x16x128_f8f6f4 v[138:141], v[218:225], v[26:33], v[138:141], v188, v188 op_sel_hi:[0,0,0]
	v_mfma_scale_f32_16x16x128_f8f6f4 v[130:133], v[226:233], v[26:33], v[130:133], v188, v188 op_sel_hi:[0,0,0]
	v_mfma_scale_f32_16x16x128_f8f6f4 v[122:125], v[218:225], v[202:209], v[122:125], v188, v188 op_sel_hi:[0,0,0]
	v_mfma_scale_f32_16x16x128_f8f6f4 v[114:117], v[226:233], v[202:209], v[114:117], v188, v188 op_sel_hi:[0,0,0]
	v_mfma_scale_f32_16x16x128_f8f6f4 v[106:109], v[218:225], v[210:217], v[106:109], v188, v188 op_sel_hi:[0,0,0]
	v_mfma_scale_f32_16x16x128_f8f6f4 v[98:101], v[226:233], v[210:217], v[98:101], v188, v188 op_sel_hi:[0,0,0]
	s_setprio 0
	s_mov_b32 m0, s51
	v_lshl_add_u64 v[180:181], v[186:187], 0, s[22:23]
	s_barrier
	ds_read_b128 v[18:21], v169 offset:49152
	ds_read_b128 v[22:25], v169 offset:50176
	ds_read_b128 v[26:29], v169 offset:51200
	ds_read_b128 v[30:33], v169 offset:52224
	ds_read_b128 v[202:205], v169 offset:53248
	ds_read_b128 v[206:209], v169 offset:54272
	ds_read_b128 v[210:213], v169 offset:55296
	ds_read_b128 v[214:217], v169 offset:56320
	global_load_lds_dwordx4 v[180:181], off
	v_lshl_add_u64 v[180:181], v[184:185], 0, s[22:23]
	s_mov_b32 m0, s52
	s_nop 0
	global_load_lds_dwordx4 v[180:181], off
	s_waitcnt vmcnt(10)
	s_barrier
	s_waitcnt lgkmcnt(0)
	s_setprio 1
	s_waitcnt lgkmcnt(0)
	v_mfma_scale_f32_16x16x128_f8f6f4 v[94:97], v[2:9], v[18:25], v[94:97], v188, v188 op_sel_hi:[0,0,0]
	v_mfma_scale_f32_16x16x128_f8f6f4 v[86:89], v[10:17], v[18:25], v[86:89], v188, v188 op_sel_hi:[0,0,0]
	v_mfma_scale_f32_16x16x128_f8f6f4 v[78:81], v[2:9], v[26:33], v[78:81], v188, v188 op_sel_hi:[0,0,0]
	v_mfma_scale_f32_16x16x128_f8f6f4 v[70:73], v[10:17], v[26:33], v[70:73], v188, v188 op_sel_hi:[0,0,0]
	v_mfma_scale_f32_16x16x128_f8f6f4 v[62:65], v[2:9], v[202:209], v[62:65], v188, v188 op_sel_hi:[0,0,0]
	v_mfma_scale_f32_16x16x128_f8f6f4 v[54:57], v[10:17], v[202:209], v[54:57], v188, v188 op_sel_hi:[0,0,0]
	v_mfma_scale_f32_16x16x128_f8f6f4 v[46:49], v[2:9], v[210:217], v[46:49], v188, v188 op_sel_hi:[0,0,0]
	v_mfma_scale_f32_16x16x128_f8f6f4 v[38:41], v[10:17], v[210:217], v[38:41], v188, v188 op_sel_hi:[0,0,0]
	s_setprio 0
	s_barrier
	s_add_u32 s0, s34, 0x20080
	s_addc_u32 s1, s35, 0
	s_add_i32 s34, s36, s43
	v_lshl_add_u64 v[2:3], s[0:1], 0, v[164:165]
	s_mov_b32 m0, s34
	s_nop 0
	global_load_lds_dwordx4 v[2:3], off
	v_lshl_add_u64 v[2:3], s[0:1], 0, v[166:167]
	s_add_i32 m0, s34, 0x2000
	s_nop 0
	global_load_lds_dwordx4 v[2:3], off
	s_waitcnt vmcnt(10)
	s_barrier
	s_setprio 1
	v_mfma_scale_f32_16x16x128_f8f6f4 v[90:93], v[218:225], v[18:25], v[90:93], v188, v188 op_sel_hi:[0,0,0]
	v_mfma_scale_f32_16x16x128_f8f6f4 v[82:85], v[226:233], v[18:25], v[82:85], v188, v188 op_sel_hi:[0,0,0]
	v_mfma_scale_f32_16x16x128_f8f6f4 v[74:77], v[218:225], v[26:33], v[74:77], v188, v188 op_sel_hi:[0,0,0]
	v_mfma_scale_f32_16x16x128_f8f6f4 v[66:69], v[226:233], v[26:33], v[66:69], v188, v188 op_sel_hi:[0,0,0]
	v_mfma_scale_f32_16x16x128_f8f6f4 v[58:61], v[218:225], v[202:209], v[58:61], v188, v188 op_sel_hi:[0,0,0]
	v_mfma_scale_f32_16x16x128_f8f6f4 v[50:53], v[226:233], v[202:209], v[50:53], v188, v188 op_sel_hi:[0,0,0]
	v_mfma_scale_f32_16x16x128_f8f6f4 v[42:45], v[218:225], v[210:217], v[42:45], v188, v188 op_sel_hi:[0,0,0]
	v_mfma_scale_f32_16x16x128_f8f6f4 v[34:37], v[226:233], v[210:217], v[34:37], v188, v188 op_sel_hi:[0,0,0]
	s_setprio 0
	s_add_i32 s56, s56, 2
	s_cmp_gt_u32 s56, 5
	s_mov_b64 s[36:37], s[12:13]
	s_barrier
	s_cbranch_scc0 .LBB0_1302
	v_mul_f32_e32 v5, 0x3c800000, v158
	v_mul_f32_e32 v6, 0xbfb8aa3b, v5
	v_exp_f32_e32 v6, v6
	s_ashr_i32 s31, s30, 31
	s_ashr_i32 s29, s28, 31
	s_lshl_b64 s[12:13], s[30:31], 18
	v_add_f32_e32 v6, 1.0, v6
	v_rcp_f32_e32 v6, v6
	s_lshl_b64 s[28:29], s[28:29], 15
	v_mov_b32_e32 v3, v195
	s_add_u32 s0, s6, s12
	v_mul_f32_e32 v5, v5, v6
	v_mul_f32_e32 v6, 0x3c800000, v159
	v_mul_f32_e32 v7, 0xbfb8aa3b, v6
	v_exp_f32_e32 v7, v7
	v_mul_f32_e32 v5, v5, v154
	v_mul_f32_e32 v5, 0x3e000000, v5
	v_med3_f32 v5, v5, s40, v190
	v_add_f32_e32 v7, 1.0, v7
	v_rcp_f32_e32 v7, v7
	s_nop 15
	s_nop 15
	v_mov_b32_e32 v2, v196
	v_mul_f32_e32 v6, v6, v7
	v_mul_f32_e32 v7, 0x3c800000, v160
	v_mul_f32_e32 v8, 0xbfb8aa3b, v7
	v_exp_f32_e32 v8, v8
	v_mul_f32_e32 v6, v6, v155
	v_mul_f32_e32 v6, 0x3e000000, v6
	v_add_u32_e32 v4, s49, v3
	v_add_f32_e32 v8, 1.0, v8
	v_rcp_f32_e32 v8, v8
	s_addc_u32 s1, s7, s13
	s_add_u32 s12, s0, s28
	v_mul_f32_e32 v7, v7, v8
	v_mul_f32_e32 v8, 0x3c800000, v161
	v_mul_f32_e32 v9, 0xbfb8aa3b, v8
	v_exp_f32_e32 v9, v9
	v_mul_f32_e32 v7, v7, v156
	v_mul_f32_e32 v7, 0x3e000000, v7
	v_lshl_add_u32 v2, v2, 3, s50
	v_add_f32_e32 v9, 1.0, v9
	v_rcp_f32_e32 v9, v9
	s_addc_u32 s13, s1, s29
	v_ashrrev_i32_e32 v3, 31, v2
	s_and_b64 vcc, exec, s[8:9]
	v_mul_f32_e32 v8, v8, v9
	v_mul_f32_e32 v9, 0x3c800000, v150
	v_mul_f32_e32 v10, 0xbfb8aa3b, v9
	v_exp_f32_e32 v10, v10
	v_mul_f32_e32 v8, v8, v157
	v_mul_f32_e32 v8, 0x3e000000, v8
	v_mov_b32_e32 v174, v200
	v_add_f32_e32 v10, 1.0, v10
	v_rcp_f32_e32 v10, v10
	v_mov_b32_e32 v172, v199
	v_mov_b32_e32 v170, v198
	v_mov_b32_e32 v168, v171
	v_mul_f32_e32 v9, v9, v10
	v_mul_f32_e32 v10, 0x3c800000, v151
	v_mul_f32_e32 v11, 0xbfb8aa3b, v10
	v_exp_f32_e32 v11, v11
	v_mul_f32_e32 v9, v9, v146
	v_mul_f32_e32 v9, 0x3e000000, v9
	s_mov_b32 s28, s26
	v_add_f32_e32 v11, 1.0, v11
	v_rcp_f32_e32 v11, v11
	s_mov_b32 s30, s54
	s_mov_b64 s[34:35], s[14:15]
	v_mul_f32_e32 v10, v10, v11
	v_mul_f32_e32 v11, 0x3c800000, v152
	v_mul_f32_e32 v12, 0xbfb8aa3b, v11
	v_exp_f32_e32 v12, v12
	v_mul_f32_e32 v10, v10, v147
	v_mul_f32_e32 v10, 0x3e000000, v10
	v_add_f32_e32 v12, 1.0, v12
	v_rcp_f32_e32 v12, v12
	s_nop 0
	v_mul_f32_e32 v11, v11, v12
	v_mul_f32_e32 v12, 0x3c800000, v153
	v_mul_f32_e32 v13, 0xbfb8aa3b, v12
	v_exp_f32_e32 v13, v13
	v_mul_f32_e32 v11, v11, v148
	v_mul_f32_e32 v11, 0x3e000000, v11
	v_add_f32_e32 v13, 1.0, v13
	v_rcp_f32_e32 v13, v13
	s_nop 0
	v_mul_f32_e32 v12, v12, v13
	v_med3_f32 v13, v6, s40, v190
	v_mov_b32_e32 v6, v163
	v_cvt_pk_fp8_f32 v6, v5, v13
	v_med3_f32 v5, v7, s40, v190
	v_med3_f32 v7, v8, s40, v190
	v_med3_f32 v8, v10, s40, v190
	v_cvt_pk_fp8_f32 v6, v5, v7 op_sel:[0,0,1]
	v_med3_f32 v5, v9, s40, v190
	v_mov_b32_e32 v7, v163
	v_cvt_pk_fp8_f32 v7, v5, v8
	v_mul_f32_e32 v12, v12, v149
	v_mul_f32_e32 v12, 0x3e000000, v12
	v_med3_f32 v5, v11, s40, v190
	v_med3_f32 v8, v12, s40, v190
	v_cvt_pk_fp8_f32 v7, v5, v8 op_sel:[0,0,1]
	v_ashrrev_i32_e32 v5, 31, v4
	v_lshlrev_b64 v[8:9], 7, v[4:5]
	v_lshl_add_u64 v[8:9], s[12:13], 0, v[8:9]
	v_lshl_add_u64 v[8:9], v[8:9], 0, v[2:3]
	v_mul_f32_e32 v5, 0x3c800000, v142
	flat_store_dwordx2 v[8:9], v[6:7] nt
	v_mul_f32_e32 v6, 0xbfb8aa3b, v5
	v_exp_f32_e32 v6, v6
	s_nop 0
	v_add_f32_e32 v6, 1.0, v6
	v_rcp_f32_e32 v6, v6
	s_nop 0
	v_mul_f32_e32 v5, v5, v6
	v_mul_f32_e32 v6, 0x3c800000, v143
	v_mul_f32_e32 v7, 0xbfb8aa3b, v6
	v_exp_f32_e32 v7, v7
	v_mul_f32_e32 v5, v5, v138
	v_mul_f32_e32 v5, 0x3e000000, v5
	v_med3_f32 v5, v5, s40, v190
	v_add_f32_e32 v7, 1.0, v7
	v_rcp_f32_e32 v7, v7
	s_nop 0
	v_mul_f32_e32 v6, v6, v7
	v_mul_f32_e32 v6, v6, v139
	v_mul_f32_e32 v7, 0x3e000000, v6
	v_mul_f32_e32 v6, 0x3c800000, v144
	v_mul_f32_e32 v8, 0xbfb8aa3b, v6
	v_exp_f32_e32 v8, v8
	v_med3_f32 v7, v7, s40, v190
	v_add_f32_e32 v8, 1.0, v8
	v_rcp_f32_e32 v8, v8
	s_nop 0
	v_mul_f32_e32 v6, v6, v8
	v_mul_f32_e32 v6, v6, v140
	v_mul_f32_e32 v9, 0x3e000000, v6
	v_mul_f32_e32 v6, 0x3c800000, v145
	v_mul_f32_e32 v8, 0xbfb8aa3b, v6
	v_exp_f32_e32 v8, v8
	s_nop 0
	v_add_f32_e32 v8, 1.0, v8
	v_rcp_f32_e32 v8, v8
	s_nop 0
	v_mul_f32_e32 v6, v6, v8
	v_mul_f32_e32 v6, v6, v141
	v_mul_f32_e32 v10, 0x3e000000, v6
	v_mul_f32_e32 v6, 0x3c800000, v134
	v_mul_f32_e32 v8, 0xbfb8aa3b, v6
	v_exp_f32_e32 v8, v8
	s_nop 0
	v_add_f32_e32 v8, 1.0, v8
	v_rcp_f32_e32 v8, v8
	s_nop 0
	v_mul_f32_e32 v6, v6, v8
	v_mul_f32_e32 v6, v6, v130
	v_mul_f32_e32 v11, 0x3e000000, v6
	v_mul_f32_e32 v6, 0x3c800000, v135
	v_mul_f32_e32 v8, 0xbfb8aa3b, v6
	v_exp_f32_e32 v8, v8
	s_nop 0
	v_add_f32_e32 v8, 1.0, v8
	v_rcp_f32_e32 v8, v8
	s_nop 0
	v_mul_f32_e32 v6, v6, v8
	v_mul_f32_e32 v6, v6, v131
	v_mul_f32_e32 v12, 0x3e000000, v6
	v_mul_f32_e32 v6, 0x3c800000, v136
	v_mul_f32_e32 v8, 0xbfb8aa3b, v6
	v_exp_f32_e32 v8, v8
	s_nop 0
	v_add_f32_e32 v8, 1.0, v8
	v_rcp_f32_e32 v8, v8
	s_nop 0
	v_mul_f32_e32 v6, v6, v8
	v_mul_f32_e32 v6, v6, v132
	v_mul_f32_e32 v13, 0x3e000000, v6
	v_mul_f32_e32 v6, 0x3c800000, v137
	v_mul_f32_e32 v8, 0xbfb8aa3b, v6
	v_exp_f32_e32 v8, v8
	s_nop 0
	v_add_f32_e32 v8, 1.0, v8
	v_rcp_f32_e32 v8, v8
	s_nop 0
	v_mul_f32_e32 v6, v6, v8
	v_mov_b32_e32 v8, v163
	v_cvt_pk_fp8_f32 v8, v5, v7
	v_med3_f32 v5, v9, s40, v190
	v_med3_f32 v7, v10, s40, v190
	v_mov_b32_e32 v9, v163
	v_cvt_pk_fp8_f32 v8, v5, v7 op_sel:[0,0,1]
	v_med3_f32 v5, v11, s40, v190
	v_med3_f32 v7, v12, s40, v190
	v_cvt_pk_fp8_f32 v9, v5, v7
	v_mul_f32_e32 v6, v6, v133
	v_mul_f32_e32 v14, 0x3e000000, v6
	v_add_u32_e32 v6, 16, v4
	v_med3_f32 v5, v13, s40, v190
	v_med3_f32 v7, v14, s40, v190
	v_cvt_pk_fp8_f32 v9, v5, v7 op_sel:[0,0,1]
	v_ashrrev_i32_e32 v7, 31, v6
	v_lshlrev_b64 v[6:7], 7, v[6:7]
	v_lshl_add_u64 v[6:7], s[12:13], 0, v[6:7]
	v_lshl_add_u64 v[6:7], v[6:7], 0, v[2:3]
	v_mul_f32_e32 v5, 0x3c800000, v126
	flat_store_dwordx2 v[6:7], v[8:9] nt
	v_mul_f32_e32 v6, 0xbfb8aa3b, v5
	v_exp_f32_e32 v6, v6
	s_nop 0
	v_add_f32_e32 v6, 1.0, v6
	v_rcp_f32_e32 v6, v6
	s_nop 0
	v_mul_f32_e32 v5, v5, v6
	v_mul_f32_e32 v6, 0x3c800000, v127
	v_mul_f32_e32 v7, 0xbfb8aa3b, v6
	v_exp_f32_e32 v7, v7
	v_mul_f32_e32 v5, v5, v122
	v_mul_f32_e32 v5, 0x3e000000, v5
	v_med3_f32 v5, v5, s40, v190
	v_add_f32_e32 v7, 1.0, v7
	v_rcp_f32_e32 v7, v7
	s_nop 0
	v_mul_f32_e32 v6, v6, v7
	v_mul_f32_e32 v6, v6, v123
	v_mul_f32_e32 v7, 0x3e000000, v6
	v_mul_f32_e32 v6, 0x3c800000, v128
	v_mul_f32_e32 v8, 0xbfb8aa3b, v6
	v_exp_f32_e32 v8, v8
	v_med3_f32 v7, v7, s40, v190
	v_add_f32_e32 v8, 1.0, v8
	v_rcp_f32_e32 v8, v8
	s_nop 0
	v_mul_f32_e32 v6, v6, v8
	v_mul_f32_e32 v6, v6, v124
	v_mul_f32_e32 v9, 0x3e000000, v6
	v_mul_f32_e32 v6, 0x3c800000, v129
	v_mul_f32_e32 v8, 0xbfb8aa3b, v6
	v_exp_f32_e32 v8, v8
	s_nop 0
	v_add_f32_e32 v8, 1.0, v8
	v_rcp_f32_e32 v8, v8
	s_nop 0
	v_mul_f32_e32 v6, v6, v8
	v_mul_f32_e32 v6, v6, v125
	v_mul_f32_e32 v10, 0x3e000000, v6
	v_mul_f32_e32 v6, 0x3c800000, v118
	v_mul_f32_e32 v8, 0xbfb8aa3b, v6
	v_exp_f32_e32 v8, v8
	s_nop 0
	v_add_f32_e32 v8, 1.0, v8
	v_rcp_f32_e32 v8, v8
	s_nop 0
	v_mul_f32_e32 v6, v6, v8
	v_mul_f32_e32 v6, v6, v114
	v_mul_f32_e32 v11, 0x3e000000, v6
	v_mul_f32_e32 v6, 0x3c800000, v119
	v_mul_f32_e32 v8, 0xbfb8aa3b, v6
	v_exp_f32_e32 v8, v8
	s_nop 0
	v_add_f32_e32 v8, 1.0, v8
	v_rcp_f32_e32 v8, v8
	s_nop 0
	v_mul_f32_e32 v6, v6, v8
	v_mul_f32_e32 v6, v6, v115
	v_mul_f32_e32 v12, 0x3e000000, v6
	v_mul_f32_e32 v6, 0x3c800000, v120
	v_mul_f32_e32 v8, 0xbfb8aa3b, v6
	v_exp_f32_e32 v8, v8
	s_nop 0
	v_add_f32_e32 v8, 1.0, v8
	v_rcp_f32_e32 v8, v8
	s_nop 0
	v_mul_f32_e32 v6, v6, v8
	v_mul_f32_e32 v6, v6, v116
	v_mul_f32_e32 v13, 0x3e000000, v6
	v_mul_f32_e32 v6, 0x3c800000, v121
	v_mul_f32_e32 v8, 0xbfb8aa3b, v6
	v_exp_f32_e32 v8, v8
	s_nop 0
	v_add_f32_e32 v8, 1.0, v8
	v_rcp_f32_e32 v8, v8
	s_nop 0
	v_mul_f32_e32 v6, v6, v8
	v_mov_b32_e32 v8, v163
	v_cvt_pk_fp8_f32 v8, v5, v7
	v_med3_f32 v5, v9, s40, v190
	v_med3_f32 v7, v10, s40, v190
	v_mov_b32_e32 v9, v163
	v_cvt_pk_fp8_f32 v8, v5, v7 op_sel:[0,0,1]
	v_med3_f32 v5, v11, s40, v190
	v_med3_f32 v7, v12, s40, v190
	v_cvt_pk_fp8_f32 v9, v5, v7
	v_mul_f32_e32 v6, v6, v117
	v_mul_f32_e32 v14, 0x3e000000, v6
	v_add_u32_e32 v6, 32, v4
	v_med3_f32 v5, v13, s40, v190
	v_med3_f32 v7, v14, s40, v190
	v_cvt_pk_fp8_f32 v9, v5, v7 op_sel:[0,0,1]
	v_ashrrev_i32_e32 v7, 31, v6
	v_lshlrev_b64 v[6:7], 7, v[6:7]
	v_lshl_add_u64 v[6:7], s[12:13], 0, v[6:7]
	v_lshl_add_u64 v[6:7], v[6:7], 0, v[2:3]
	v_mul_f32_e32 v5, 0x3c800000, v110
	flat_store_dwordx2 v[6:7], v[8:9] nt
	v_mul_f32_e32 v6, 0xbfb8aa3b, v5
	v_exp_f32_e32 v6, v6
	s_nop 0
	v_add_f32_e32 v6, 1.0, v6
	v_rcp_f32_e32 v6, v6
	s_nop 0
	v_mul_f32_e32 v5, v5, v6
	v_mul_f32_e32 v6, 0x3c800000, v111
	v_mul_f32_e32 v7, 0xbfb8aa3b, v6
	v_exp_f32_e32 v7, v7
	v_mul_f32_e32 v5, v5, v106
	v_mul_f32_e32 v5, 0x3e000000, v5
	v_med3_f32 v5, v5, s40, v190
	v_add_f32_e32 v7, 1.0, v7
	v_rcp_f32_e32 v7, v7
	s_nop 0
	v_mul_f32_e32 v6, v6, v7
	v_mul_f32_e32 v6, v6, v107
	v_mul_f32_e32 v7, 0x3e000000, v6
	v_mul_f32_e32 v6, 0x3c800000, v112
	v_mul_f32_e32 v8, 0xbfb8aa3b, v6
	v_exp_f32_e32 v8, v8
	v_med3_f32 v7, v7, s40, v190
	v_add_f32_e32 v8, 1.0, v8
	v_rcp_f32_e32 v8, v8
	s_nop 0
	v_mul_f32_e32 v6, v6, v8
	v_mul_f32_e32 v6, v6, v108
	v_mul_f32_e32 v9, 0x3e000000, v6
	v_mul_f32_e32 v6, 0x3c800000, v113
	v_mul_f32_e32 v8, 0xbfb8aa3b, v6
	v_exp_f32_e32 v8, v8
	s_nop 0
	v_add_f32_e32 v8, 1.0, v8
	v_rcp_f32_e32 v8, v8
	s_nop 0
	v_mul_f32_e32 v6, v6, v8
	v_mul_f32_e32 v6, v6, v109
	v_mul_f32_e32 v10, 0x3e000000, v6
	v_mul_f32_e32 v6, 0x3c800000, v102
	v_mul_f32_e32 v8, 0xbfb8aa3b, v6
	v_exp_f32_e32 v8, v8
	s_nop 0
	v_add_f32_e32 v8, 1.0, v8
	v_rcp_f32_e32 v8, v8
	s_nop 0
	v_mul_f32_e32 v6, v6, v8
	v_mul_f32_e32 v6, v6, v98
	v_mul_f32_e32 v11, 0x3e000000, v6
	v_mul_f32_e32 v6, 0x3c800000, v103
	v_mul_f32_e32 v8, 0xbfb8aa3b, v6
	v_exp_f32_e32 v8, v8
	s_nop 0
	v_add_f32_e32 v8, 1.0, v8
	v_rcp_f32_e32 v8, v8
	s_nop 0
	v_mul_f32_e32 v6, v6, v8
	v_mul_f32_e32 v6, v6, v99
	v_mul_f32_e32 v12, 0x3e000000, v6
	v_mul_f32_e32 v6, 0x3c800000, v104
	v_mul_f32_e32 v8, 0xbfb8aa3b, v6
	v_exp_f32_e32 v8, v8
	s_nop 0
	v_add_f32_e32 v8, 1.0, v8
	v_rcp_f32_e32 v8, v8
	s_nop 0
	v_mul_f32_e32 v6, v6, v8
	v_mul_f32_e32 v6, v6, v100
	v_mul_f32_e32 v13, 0x3e000000, v6
	v_mul_f32_e32 v6, 0x3c800000, v105
	v_mul_f32_e32 v8, 0xbfb8aa3b, v6
	v_exp_f32_e32 v8, v8
	s_nop 0
	v_add_f32_e32 v8, 1.0, v8
	v_rcp_f32_e32 v8, v8
	s_nop 0
	v_mul_f32_e32 v6, v6, v8
	v_mov_b32_e32 v8, v163
	v_cvt_pk_fp8_f32 v8, v5, v7
	v_med3_f32 v5, v9, s40, v190
	v_med3_f32 v7, v10, s40, v190
	v_mov_b32_e32 v9, v163
	v_cvt_pk_fp8_f32 v8, v5, v7 op_sel:[0,0,1]
	v_med3_f32 v5, v11, s40, v190
	v_med3_f32 v7, v12, s40, v190
	v_cvt_pk_fp8_f32 v9, v5, v7
	v_mul_f32_e32 v6, v6, v101
	v_mul_f32_e32 v14, 0x3e000000, v6
	v_add_u32_e32 v6, 48, v4
	v_med3_f32 v5, v13, s40, v190
	v_med3_f32 v7, v14, s40, v190
	v_cvt_pk_fp8_f32 v9, v5, v7 op_sel:[0,0,1]
	v_ashrrev_i32_e32 v7, 31, v6
	v_lshlrev_b64 v[6:7], 7, v[6:7]
	v_lshl_add_u64 v[6:7], s[12:13], 0, v[6:7]
	v_lshl_add_u64 v[6:7], v[6:7], 0, v[2:3]
	v_mul_f32_e32 v5, 0x3c800000, v94
	flat_store_dwordx2 v[6:7], v[8:9] nt
	v_mul_f32_e32 v7, 0xbfb8aa3b, v5
	v_exp_f32_e32 v7, v7
	v_add_u32_e32 v6, 0x80, v4
	v_add_f32_e32 v7, 1.0, v7
	v_rcp_f32_e32 v7, v7
	s_nop 0
	v_mul_f32_e32 v5, v5, v7
	v_mul_f32_e32 v7, 0x3c800000, v95
	v_mul_f32_e32 v8, 0xbfb8aa3b, v7
	v_exp_f32_e32 v8, v8
	v_mul_f32_e32 v5, v5, v90
	v_mul_f32_e32 v5, 0x3e000000, v5
	v_med3_f32 v5, v5, s40, v190
	v_add_f32_e32 v8, 1.0, v8
	v_rcp_f32_e32 v8, v8
	s_nop 0
	v_mul_f32_e32 v7, v7, v8
	v_mul_f32_e32 v8, 0x3c800000, v96
	v_mul_f32_e32 v9, 0xbfb8aa3b, v8
	v_exp_f32_e32 v9, v9
	v_mul_f32_e32 v7, v7, v91
	v_mul_f32_e32 v7, 0x3e000000, v7
	v_med3_f32 v7, v7, s40, v190
	v_add_f32_e32 v9, 1.0, v9
	v_rcp_f32_e32 v9, v9
	s_nop 0
	v_mul_f32_e32 v8, v8, v9
	v_mul_f32_e32 v8, v8, v92
	v_mul_f32_e32 v9, 0x3e000000, v8
	v_mul_f32_e32 v8, 0x3c800000, v97
	v_mul_f32_e32 v10, 0xbfb8aa3b, v8
	v_exp_f32_e32 v10, v10
	s_nop 0
	v_add_f32_e32 v10, 1.0, v10
	v_rcp_f32_e32 v10, v10
	s_nop 0
	v_mul_f32_e32 v8, v8, v10
	v_mul_f32_e32 v8, v8, v93
	v_mul_f32_e32 v10, 0x3e000000, v8
	v_mul_f32_e32 v8, 0x3c800000, v86
	v_mul_f32_e32 v11, 0xbfb8aa3b, v8
	v_exp_f32_e32 v11, v11
	s_nop 0
	v_add_f32_e32 v11, 1.0, v11
	v_rcp_f32_e32 v11, v11
	s_nop 0
	v_mul_f32_e32 v8, v8, v11
	v_mul_f32_e32 v8, v8, v82
	v_mul_f32_e32 v11, 0x3e000000, v8
	v_mul_f32_e32 v8, 0x3c800000, v87
	v_mul_f32_e32 v12, 0xbfb8aa3b, v8
	v_exp_f32_e32 v12, v12
	s_nop 0
	v_add_f32_e32 v12, 1.0, v12
	v_rcp_f32_e32 v12, v12
	s_nop 0
	v_mul_f32_e32 v8, v8, v12
	v_mul_f32_e32 v8, v8, v83
	v_mul_f32_e32 v12, 0x3e000000, v8
	v_mul_f32_e32 v8, 0x3c800000, v88
	v_mul_f32_e32 v13, 0xbfb8aa3b, v8
	v_exp_f32_e32 v13, v13
	s_nop 0
	v_add_f32_e32 v13, 1.0, v13
	v_rcp_f32_e32 v13, v13
	s_nop 0
	v_mul_f32_e32 v8, v8, v13
	v_mul_f32_e32 v8, v8, v84
	v_mul_f32_e32 v13, 0x3e000000, v8
	v_mul_f32_e32 v8, 0x3c800000, v89
	v_mul_f32_e32 v14, 0xbfb8aa3b, v8
	v_exp_f32_e32 v14, v14
	s_nop 0
	v_add_f32_e32 v14, 1.0, v14
	v_rcp_f32_e32 v14, v14
	s_nop 0
	v_mul_f32_e32 v8, v8, v14
	v_mul_f32_e32 v8, v8, v85
	v_mul_f32_e32 v14, 0x3e000000, v8
	v_mov_b32_e32 v8, v163
	v_cvt_pk_fp8_f32 v8, v5, v7
	v_med3_f32 v5, v9, s40, v190
	v_med3_f32 v7, v10, s40, v190
	v_mov_b32_e32 v9, v163
	v_cvt_pk_fp8_f32 v8, v5, v7 op_sel:[0,0,1]
	v_med3_f32 v5, v11, s40, v190
	v_med3_f32 v7, v12, s40, v190
	v_cvt_pk_fp8_f32 v9, v5, v7
	v_med3_f32 v5, v13, s40, v190
	v_med3_f32 v7, v14, s40, v190
	v_cvt_pk_fp8_f32 v9, v5, v7 op_sel:[0,0,1]
	v_ashrrev_i32_e32 v7, 31, v6
	v_lshlrev_b64 v[6:7], 7, v[6:7]
	v_lshl_add_u64 v[6:7], s[12:13], 0, v[6:7]
	v_lshl_add_u64 v[6:7], v[6:7], 0, v[2:3]
	v_mul_f32_e32 v5, 0x3c800000, v78
	flat_store_dwordx2 v[6:7], v[8:9] nt
	v_mul_f32_e32 v6, 0xbfb8aa3b, v5
	v_exp_f32_e32 v6, v6
	s_nop 0
	v_add_f32_e32 v6, 1.0, v6
	v_rcp_f32_e32 v6, v6
	s_nop 0
	v_mul_f32_e32 v5, v5, v6
	v_mul_f32_e32 v6, 0x3c800000, v79
	v_mul_f32_e32 v7, 0xbfb8aa3b, v6
	v_exp_f32_e32 v7, v7
	v_mul_f32_e32 v5, v5, v74
	v_mul_f32_e32 v5, 0x3e000000, v5
	v_med3_f32 v5, v5, s40, v190
	v_add_f32_e32 v7, 1.0, v7
	v_rcp_f32_e32 v7, v7
	s_nop 0
	v_mul_f32_e32 v6, v6, v7
	v_mul_f32_e32 v6, v6, v75
	v_mul_f32_e32 v7, 0x3e000000, v6
	v_mul_f32_e32 v6, 0x3c800000, v80
	v_mul_f32_e32 v8, 0xbfb8aa3b, v6
	v_exp_f32_e32 v8, v8
	v_med3_f32 v7, v7, s40, v190
	v_add_f32_e32 v8, 1.0, v8
	v_rcp_f32_e32 v8, v8
	s_nop 0
	v_mul_f32_e32 v6, v6, v8
	v_mul_f32_e32 v6, v6, v76
	v_mul_f32_e32 v9, 0x3e000000, v6
	v_mul_f32_e32 v6, 0x3c800000, v81
	v_mul_f32_e32 v8, 0xbfb8aa3b, v6
	v_exp_f32_e32 v8, v8
	s_nop 0
	v_add_f32_e32 v8, 1.0, v8
	v_rcp_f32_e32 v8, v8
	s_nop 0
	v_mul_f32_e32 v6, v6, v8
	v_mul_f32_e32 v6, v6, v77
	v_mul_f32_e32 v10, 0x3e000000, v6
	v_mul_f32_e32 v6, 0x3c800000, v70
	v_mul_f32_e32 v8, 0xbfb8aa3b, v6
	v_exp_f32_e32 v8, v8
	s_nop 0
	v_add_f32_e32 v8, 1.0, v8
	v_rcp_f32_e32 v8, v8
	s_nop 0
	v_mul_f32_e32 v6, v6, v8
	v_mul_f32_e32 v6, v6, v66
	v_mul_f32_e32 v11, 0x3e000000, v6
	v_mul_f32_e32 v6, 0x3c800000, v71
	v_mul_f32_e32 v8, 0xbfb8aa3b, v6
	v_exp_f32_e32 v8, v8
	s_nop 0
	v_add_f32_e32 v8, 1.0, v8
	v_rcp_f32_e32 v8, v8
	s_nop 0
	v_mul_f32_e32 v6, v6, v8
	v_mul_f32_e32 v6, v6, v67
	v_mul_f32_e32 v12, 0x3e000000, v6
	v_mul_f32_e32 v6, 0x3c800000, v72
	v_mul_f32_e32 v8, 0xbfb8aa3b, v6
	v_exp_f32_e32 v8, v8
	s_nop 0
	v_add_f32_e32 v8, 1.0, v8
	v_rcp_f32_e32 v8, v8
	s_nop 0
	v_mul_f32_e32 v6, v6, v8
	v_mul_f32_e32 v6, v6, v68
	v_mul_f32_e32 v13, 0x3e000000, v6
	v_mul_f32_e32 v6, 0x3c800000, v73
	v_mul_f32_e32 v8, 0xbfb8aa3b, v6
	v_exp_f32_e32 v8, v8
	s_nop 0
	v_add_f32_e32 v8, 1.0, v8
	v_rcp_f32_e32 v8, v8
	s_nop 0
	v_mul_f32_e32 v6, v6, v8
	v_mov_b32_e32 v8, v163
	v_cvt_pk_fp8_f32 v8, v5, v7
	v_med3_f32 v5, v9, s40, v190
	v_med3_f32 v7, v10, s40, v190
	v_mov_b32_e32 v9, v163
	v_cvt_pk_fp8_f32 v8, v5, v7 op_sel:[0,0,1]
	v_med3_f32 v5, v11, s40, v190
	v_med3_f32 v7, v12, s40, v190
	v_cvt_pk_fp8_f32 v9, v5, v7
	v_mul_f32_e32 v6, v6, v69
	v_mul_f32_e32 v14, 0x3e000000, v6
	v_add_u32_e32 v6, 0x90, v4
	v_med3_f32 v5, v13, s40, v190
	v_med3_f32 v7, v14, s40, v190
	v_cvt_pk_fp8_f32 v9, v5, v7 op_sel:[0,0,1]
	v_ashrrev_i32_e32 v7, 31, v6
	v_lshlrev_b64 v[6:7], 7, v[6:7]
	v_lshl_add_u64 v[6:7], s[12:13], 0, v[6:7]
	v_lshl_add_u64 v[6:7], v[6:7], 0, v[2:3]
	v_mul_f32_e32 v5, 0x3c800000, v62
	flat_store_dwordx2 v[6:7], v[8:9] nt
	v_mul_f32_e32 v6, 0xbfb8aa3b, v5
	v_exp_f32_e32 v6, v6
	s_nop 0
	v_add_f32_e32 v6, 1.0, v6
	v_rcp_f32_e32 v6, v6
	s_nop 0
	v_mul_f32_e32 v5, v5, v6
	v_mul_f32_e32 v6, 0x3c800000, v63
	v_mul_f32_e32 v7, 0xbfb8aa3b, v6
	v_exp_f32_e32 v7, v7
	v_mul_f32_e32 v5, v5, v58
	v_mul_f32_e32 v5, 0x3e000000, v5
	v_med3_f32 v5, v5, s40, v190
	v_add_f32_e32 v7, 1.0, v7
	v_rcp_f32_e32 v7, v7
	s_nop 0
	v_mul_f32_e32 v6, v6, v7
	v_mul_f32_e32 v6, v6, v59
	v_mul_f32_e32 v7, 0x3e000000, v6
	v_mul_f32_e32 v6, 0x3c800000, v64
	v_mul_f32_e32 v8, 0xbfb8aa3b, v6
	v_exp_f32_e32 v8, v8
	v_med3_f32 v7, v7, s40, v190
	v_add_f32_e32 v8, 1.0, v8
	v_rcp_f32_e32 v8, v8
	s_nop 0
	v_mul_f32_e32 v6, v6, v8
	v_mul_f32_e32 v6, v6, v60
	v_mul_f32_e32 v9, 0x3e000000, v6
	v_mul_f32_e32 v6, 0x3c800000, v65
	v_mul_f32_e32 v8, 0xbfb8aa3b, v6
	v_exp_f32_e32 v8, v8
	s_nop 0
	v_add_f32_e32 v8, 1.0, v8
	v_rcp_f32_e32 v8, v8
	s_nop 0
	v_mul_f32_e32 v6, v6, v8
	v_mul_f32_e32 v6, v6, v61
	v_mul_f32_e32 v10, 0x3e000000, v6
	v_mul_f32_e32 v6, 0x3c800000, v54
	v_mul_f32_e32 v8, 0xbfb8aa3b, v6
	v_exp_f32_e32 v8, v8
	s_nop 0
	v_add_f32_e32 v8, 1.0, v8
	v_rcp_f32_e32 v8, v8
	s_nop 0
	v_mul_f32_e32 v6, v6, v8
	v_mul_f32_e32 v6, v6, v50
	v_mul_f32_e32 v11, 0x3e000000, v6
	v_mul_f32_e32 v6, 0x3c800000, v55
	v_mul_f32_e32 v8, 0xbfb8aa3b, v6
	v_exp_f32_e32 v8, v8
	s_nop 0
	v_add_f32_e32 v8, 1.0, v8
	v_rcp_f32_e32 v8, v8
	s_nop 0
	v_mul_f32_e32 v6, v6, v8
	v_mul_f32_e32 v6, v6, v51
	v_mul_f32_e32 v12, 0x3e000000, v6
	v_mul_f32_e32 v6, 0x3c800000, v56
	v_mul_f32_e32 v8, 0xbfb8aa3b, v6
	v_exp_f32_e32 v8, v8
	s_nop 0
	v_add_f32_e32 v8, 1.0, v8
	v_rcp_f32_e32 v8, v8
	s_nop 0
	v_mul_f32_e32 v6, v6, v8
	v_mul_f32_e32 v6, v6, v52
	v_mul_f32_e32 v13, 0x3e000000, v6
	v_mul_f32_e32 v6, 0x3c800000, v57
	v_mul_f32_e32 v8, 0xbfb8aa3b, v6
	v_exp_f32_e32 v8, v8
	s_nop 0
	v_add_f32_e32 v8, 1.0, v8
	v_rcp_f32_e32 v8, v8
	s_nop 0
	v_mul_f32_e32 v6, v6, v8
	v_mov_b32_e32 v8, v163
	v_cvt_pk_fp8_f32 v8, v5, v7
	v_med3_f32 v5, v9, s40, v190
	v_med3_f32 v7, v10, s40, v190
	v_mov_b32_e32 v9, v163
	v_cvt_pk_fp8_f32 v8, v5, v7 op_sel:[0,0,1]
	v_med3_f32 v5, v11, s40, v190
	v_med3_f32 v7, v12, s40, v190
	v_cvt_pk_fp8_f32 v9, v5, v7
	v_mul_f32_e32 v6, v6, v53
	v_mul_f32_e32 v14, 0x3e000000, v6
	v_add_u32_e32 v6, 0xa0, v4
	v_med3_f32 v5, v13, s40, v190
	v_med3_f32 v7, v14, s40, v190
	v_cvt_pk_fp8_f32 v9, v5, v7 op_sel:[0,0,1]
	v_ashrrev_i32_e32 v7, 31, v6
	v_lshlrev_b64 v[6:7], 7, v[6:7]
	v_lshl_add_u64 v[6:7], s[12:13], 0, v[6:7]
	v_lshl_add_u64 v[6:7], v[6:7], 0, v[2:3]
	v_mul_f32_e32 v5, 0x3c800000, v46
	flat_store_dwordx2 v[6:7], v[8:9] nt
	v_mul_f32_e32 v6, 0xbfb8aa3b, v5
	v_exp_f32_e32 v6, v6
	v_add_u32_e32 v4, 0xb0, v4
	v_add_f32_e32 v6, 1.0, v6
	v_rcp_f32_e32 v6, v6
	s_nop 0
	v_mul_f32_e32 v5, v5, v6
	v_mul_f32_e32 v6, 0x3c800000, v47
	v_mul_f32_e32 v7, 0xbfb8aa3b, v6
	v_exp_f32_e32 v7, v7
	v_mul_f32_e32 v5, v5, v42
	v_mul_f32_e32 v5, 0x3e000000, v5
	v_med3_f32 v5, v5, s40, v190
	v_add_f32_e32 v7, 1.0, v7
	v_rcp_f32_e32 v7, v7
	s_nop 0
	v_mul_f32_e32 v6, v6, v7
	v_mul_f32_e32 v7, 0x3c800000, v48
	v_mul_f32_e32 v8, 0xbfb8aa3b, v7
	v_exp_f32_e32 v8, v8
	v_mul_f32_e32 v6, v6, v43
	v_mul_f32_e32 v6, 0x3e000000, v6
	v_add_f32_e32 v8, 1.0, v8
	v_rcp_f32_e32 v8, v8
	s_nop 0
	v_mul_f32_e32 v7, v7, v8
	v_mul_f32_e32 v8, 0x3c800000, v49
	v_mul_f32_e32 v9, 0xbfb8aa3b, v8
	v_exp_f32_e32 v9, v9
	v_mul_f32_e32 v7, v7, v44
	v_mul_f32_e32 v7, 0x3e000000, v7
	v_add_f32_e32 v9, 1.0, v9
	v_rcp_f32_e32 v9, v9
	s_nop 0
	v_mul_f32_e32 v8, v8, v9
	v_mul_f32_e32 v9, 0x3c800000, v38
	v_mul_f32_e32 v10, 0xbfb8aa3b, v9
	v_exp_f32_e32 v10, v10
	v_mul_f32_e32 v8, v8, v45
	v_mul_f32_e32 v8, 0x3e000000, v8
	v_add_f32_e32 v10, 1.0, v10
	v_rcp_f32_e32 v10, v10
	s_nop 0
	v_mul_f32_e32 v9, v9, v10
	v_mul_f32_e32 v10, 0x3c800000, v39
	v_mul_f32_e32 v11, 0xbfb8aa3b, v10
	v_exp_f32_e32 v11, v11
	v_mul_f32_e32 v9, v9, v34
	v_mul_f32_e32 v9, 0x3e000000, v9
	v_add_f32_e32 v11, 1.0, v11
	v_rcp_f32_e32 v11, v11
	s_nop 0
	v_mul_f32_e32 v10, v10, v11
	v_mul_f32_e32 v11, 0x3c800000, v40
	v_mul_f32_e32 v12, 0xbfb8aa3b, v11
	v_exp_f32_e32 v12, v12
	v_mul_f32_e32 v10, v10, v35
	v_mul_f32_e32 v10, 0x3e000000, v10
	v_add_f32_e32 v12, 1.0, v12
	v_rcp_f32_e32 v12, v12
	s_nop 0
	v_mul_f32_e32 v11, v11, v12
	v_mul_f32_e32 v12, 0x3c800000, v41
	v_mul_f32_e32 v13, 0xbfb8aa3b, v12
	v_exp_f32_e32 v13, v13
	v_mul_f32_e32 v11, v11, v36
	v_mul_f32_e32 v11, 0x3e000000, v11
	v_add_f32_e32 v13, 1.0, v13
	v_rcp_f32_e32 v13, v13
	s_nop 0
	v_mul_f32_e32 v12, v12, v13
	v_med3_f32 v13, v6, s40, v190
	v_mov_b32_e32 v6, v163
	v_cvt_pk_fp8_f32 v6, v5, v13
	v_med3_f32 v5, v7, s40, v190
	v_med3_f32 v7, v8, s40, v190
	v_med3_f32 v8, v10, s40, v190
	v_cvt_pk_fp8_f32 v6, v5, v7 op_sel:[0,0,1]
	v_med3_f32 v5, v9, s40, v190
	v_mov_b32_e32 v7, v163
	v_cvt_pk_fp8_f32 v7, v5, v8
	v_mul_f32_e32 v12, v12, v37
	v_mul_f32_e32 v12, 0x3e000000, v12
	v_med3_f32 v5, v11, s40, v190
	v_med3_f32 v8, v12, s40, v190
	v_cvt_pk_fp8_f32 v7, v5, v8 op_sel:[0,0,1]
	v_ashrrev_i32_e32 v5, 31, v4
	v_lshlrev_b64 v[4:5], 7, v[4:5]
	v_lshl_add_u64 v[4:5], s[12:13], 0, v[4:5]
	v_lshl_add_u64 v[2:3], v[4:5], 0, v[2:3]
	flat_store_dwordx2 v[2:3], v[6:7] nt
	s_cbranch_vccz .LBB0_1291
	s_waitcnt vmcnt(0)
	s_cmpk_gt_u32 s42, 0xff
	s_cbranch_scc1 .LBB0_1237
	s_barrier
	s_branch .LBB0_1237

.LBB0_1369:
	ds_read_b128 v[2:5], v169
	ds_read_b128 v[6:9], v169 offset:1024
	ds_read_b128 v[10:13], v169 offset:2048
	ds_read_b128 v[14:17], v169 offset:3072
	s_add_u32 s0, s28, 0x4000
	s_addc_u32 s1, s29, 0
	s_cmp_eq_u32 s53, 4
	s_cselect_b32 s36, s49, s0
	s_cselect_b32 s37, s21, s1
	s_cselect_b32 s30, s50, s51
	s_cselect_b32 s31, s19, s52
	s_add_u32 s34, s36, 0x8000
	s_addc_u32 s35, s37, 0
	v_lshl_add_u64 v[162:163], s[28:29], 0, v[156:157]
	s_add_i32 m0, s17, 0xc000
	ds_read_b128 v[174:177], v170
	ds_read_b128 v[178:181], v170 offset:1024
	ds_read_b128 v[182:185], v170 offset:2048
	ds_read_b128 v[186:189], v170 offset:3072
	ds_read_b128 v[190:193], v170 offset:4096
	ds_read_b128 v[194:197], v170 offset:5120
	ds_read_b128 v[198:201], v170 offset:6144
	ds_read_b128 v[202:205], v170 offset:7168
	global_load_lds_dwordx4 v[162:163], off
	v_lshl_add_u64 v[162:163], s[28:29], 0, v[154:155]
	s_add_i32 m0, s17, 0xe000
	s_nop 0
	global_load_lds_dwordx4 v[162:163], off
	s_waitcnt lgkmcnt(8)
	s_waitcnt vmcnt(10)
	s_barrier
	s_waitcnt lgkmcnt(0)
	s_setprio 1
	s_waitcnt lgkmcnt(0)
	v_mfma_scale_f32_16x16x128_f8f6f4 v[142:145], v[2:9], v[174:181], v[142:145], v171, v171 op_sel_hi:[0,0,0]
	v_mfma_scale_f32_16x16x128_f8f6f4 v[138:141], v[10:17], v[174:181], v[138:141], v171, v171 op_sel_hi:[0,0,0]
	v_mfma_scale_f32_16x16x128_f8f6f4 v[126:129], v[2:9], v[182:189], v[126:129], v171, v171 op_sel_hi:[0,0,0]
	v_mfma_scale_f32_16x16x128_f8f6f4 v[122:125], v[10:17], v[182:189], v[122:125], v171, v171 op_sel_hi:[0,0,0]
	v_mfma_scale_f32_16x16x128_f8f6f4 v[110:113], v[2:9], v[190:197], v[110:113], v171, v171 op_sel_hi:[0,0,0]
	v_mfma_scale_f32_16x16x128_f8f6f4 v[106:109], v[10:17], v[190:197], v[106:109], v171, v171 op_sel_hi:[0,0,0]
	v_mfma_scale_f32_16x16x128_f8f6f4 v[94:97], v[2:9], v[198:205], v[94:97], v171, v171 op_sel_hi:[0,0,0]
	v_mfma_scale_f32_16x16x128_f8f6f4 v[90:93], v[10:17], v[198:205], v[90:93], v171, v171 op_sel_hi:[0,0,0]
	s_setprio 0
	s_barrier
	s_add_i32 s0, s45, s11
	v_lshl_add_u64 v[162:163], s[30:31], 0, v[150:151]
	s_mov_b32 m0, s0
	ds_read_b128 v[206:209], v172
	ds_read_b128 v[210:213], v172 offset:1024
	ds_read_b128 v[214:217], v172 offset:2048
	ds_read_b128 v[218:221], v172 offset:3072
	global_load_lds_dwordx4 v[162:163], off
	v_lshl_add_u64 v[164:165], s[30:31], 0, v[146:147]
	s_add_i32 m0, s0, 0x2000
	s_nop 0
	global_load_lds_dwordx4 v[164:165], off
	s_waitcnt vmcnt(10)
	s_barrier
	s_waitcnt lgkmcnt(0)
	s_setprio 1
	s_waitcnt lgkmcnt(0)
	v_mfma_scale_f32_16x16x128_f8f6f4 v[134:137], v[206:213], v[174:181], v[134:137], v171, v171 op_sel_hi:[0,0,0]
	v_mfma_scale_f32_16x16x128_f8f6f4 v[130:133], v[214:221], v[174:181], v[130:133], v171, v171 op_sel_hi:[0,0,0]
	v_mfma_scale_f32_16x16x128_f8f6f4 v[118:121], v[206:213], v[182:189], v[118:121], v171, v171 op_sel_hi:[0,0,0]
	v_mfma_scale_f32_16x16x128_f8f6f4 v[114:117], v[214:221], v[182:189], v[114:117], v171, v171 op_sel_hi:[0,0,0]
	v_mfma_scale_f32_16x16x128_f8f6f4 v[102:105], v[206:213], v[190:197], v[102:105], v171, v171 op_sel_hi:[0,0,0]
	v_mfma_scale_f32_16x16x128_f8f6f4 v[98:101], v[214:221], v[190:197], v[98:101], v171, v171 op_sel_hi:[0,0,0]
	v_mfma_scale_f32_16x16x128_f8f6f4 v[86:89], v[206:213], v[198:205], v[86:89], v171, v171 op_sel_hi:[0,0,0]
	v_mfma_scale_f32_16x16x128_f8f6f4 v[82:85], v[214:221], v[198:205], v[82:85], v171, v171 op_sel_hi:[0,0,0]
	s_setprio 0
	s_mov_b32 m0, s17
	v_lshl_add_u64 v[222:223], s[36:37], 0, v[152:153]
	s_barrier
	ds_read_b128 v[174:177], v170 offset:16384
	ds_read_b128 v[178:181], v170 offset:17408
	ds_read_b128 v[182:185], v170 offset:18432
	ds_read_b128 v[186:189], v170 offset:19456
	ds_read_b128 v[190:193], v170 offset:20480
	ds_read_b128 v[194:197], v170 offset:21504
	ds_read_b128 v[198:201], v170 offset:22528
	ds_read_b128 v[202:205], v170 offset:23552
	global_load_lds_dwordx4 v[222:223], off
	v_lshl_add_u64 v[222:223], s[36:37], 0, v[148:149]
	s_mov_b32 m0, s27
	s_nop 0
	global_load_lds_dwordx4 v[222:223], off
	s_waitcnt vmcnt(10)
	s_barrier
	s_waitcnt lgkmcnt(0)
	s_setprio 1
	s_waitcnt lgkmcnt(0)
	v_mfma_scale_f32_16x16x128_f8f6f4 v[78:81], v[2:9], v[174:181], v[78:81], v171, v171 op_sel_hi:[0,0,0]
	v_mfma_scale_f32_16x16x128_f8f6f4 v[74:77], v[10:17], v[174:181], v[74:77], v171, v171 op_sel_hi:[0,0,0]
	v_mfma_scale_f32_16x16x128_f8f6f4 v[62:65], v[2:9], v[182:189], v[62:65], v171, v171 op_sel_hi:[0,0,0]
	v_mfma_scale_f32_16x16x128_f8f6f4 v[58:61], v[10:17], v[182:189], v[58:61], v171, v171 op_sel_hi:[0,0,0]
	v_mfma_scale_f32_16x16x128_f8f6f4 v[46:49], v[2:9], v[190:197], v[46:49], v171, v171 op_sel_hi:[0,0,0]
	v_mfma_scale_f32_16x16x128_f8f6f4 v[42:45], v[10:17], v[190:197], v[42:45], v171, v171 op_sel_hi:[0,0,0]
	v_mfma_scale_f32_16x16x128_f8f6f4 v[30:33], v[2:9], v[198:205], v[30:33], v171, v171 op_sel_hi:[0,0,0]
	v_mfma_scale_f32_16x16x128_f8f6f4 v[26:29], v[10:17], v[198:205], v[26:29], v171, v171 op_sel_hi:[0,0,0]
	s_setprio 0
	s_barrier
	s_add_u32 s0, s30, 0x20000
	s_addc_u32 s1, s31, 0
	s_add_i32 s54, s46, s11
	v_lshl_add_u64 v[2:3], s[0:1], 0, v[150:151]
	s_mov_b32 m0, s54
	s_nop 0
	global_load_lds_dwordx4 v[2:3], off
	v_lshl_add_u64 v[2:3], s[0:1], 0, v[146:147]
	s_add_i32 m0, s54, 0x2000
	s_nop 0
	global_load_lds_dwordx4 v[2:3], off
	s_waitcnt vmcnt(10)
	s_barrier
	s_setprio 1
	v_mfma_scale_f32_16x16x128_f8f6f4 v[70:73], v[206:213], v[174:181], v[70:73], v171, v171 op_sel_hi:[0,0,0]
	v_mfma_scale_f32_16x16x128_f8f6f4 v[66:69], v[214:221], v[174:181], v[66:69], v171, v171 op_sel_hi:[0,0,0]
	v_mfma_scale_f32_16x16x128_f8f6f4 v[54:57], v[206:213], v[182:189], v[54:57], v171, v171 op_sel_hi:[0,0,0]
	v_mfma_scale_f32_16x16x128_f8f6f4 v[50:53], v[214:221], v[182:189], v[50:53], v171, v171 op_sel_hi:[0,0,0]
	v_mfma_scale_f32_16x16x128_f8f6f4 v[38:41], v[206:213], v[190:197], v[38:41], v171, v171 op_sel_hi:[0,0,0]
	v_mfma_scale_f32_16x16x128_f8f6f4 v[34:37], v[214:221], v[190:197], v[34:37], v171, v171 op_sel_hi:[0,0,0]
	v_mfma_scale_f32_16x16x128_f8f6f4 v[22:25], v[206:213], v[198:205], v[22:25], v171, v171 op_sel_hi:[0,0,0]
	v_mfma_scale_f32_16x16x128_f8f6f4 v[18:21], v[214:221], v[198:205], v[18:21], v171, v171 op_sel_hi:[0,0,0]
	s_setprio 0
	s_add_i32 s54, 0, 0x18000
	v_add_u32_e32 v14, s54, v168
	s_barrier
	ds_read_b128 v[2:5], v14
	ds_read_b128 v[6:9], v14 offset:1024
	ds_read_b128 v[10:13], v14 offset:2048
	ds_read_b128 v[14:17], v14 offset:3072
	s_add_u32 s0, s36, 0x4000
	s_addc_u32 s1, s37, 0
	s_mov_b32 m0, s38
	v_lshl_add_u64 v[206:207], s[0:1], 0, v[152:153]
	ds_read_b128 v[174:177], v170 offset:32768
	ds_read_b128 v[178:181], v170 offset:33792
	ds_read_b128 v[182:185], v170 offset:34816
	ds_read_b128 v[186:189], v170 offset:35840
	ds_read_b128 v[190:193], v170 offset:36864
	ds_read_b128 v[194:197], v170 offset:37888
	ds_read_b128 v[198:201], v170 offset:38912
	ds_read_b128 v[202:205], v170 offset:39936
	global_load_lds_dwordx4 v[206:207], off
	v_lshl_add_u64 v[206:207], s[0:1], 0, v[148:149]
	s_mov_b32 m0, s39
	s_nop 0
	global_load_lds_dwordx4 v[206:207], off
	s_waitcnt lgkmcnt(8)
	s_waitcnt vmcnt(10)
	s_barrier
	s_waitcnt lgkmcnt(0)
	s_setprio 1
	s_waitcnt lgkmcnt(0)
	v_mfma_scale_f32_16x16x128_f8f6f4 v[142:145], v[2:9], v[174:181], v[142:145], v171, v171 op_sel_hi:[0,0,0]
	v_mfma_scale_f32_16x16x128_f8f6f4 v[138:141], v[10:17], v[174:181], v[138:141], v171, v171 op_sel_hi:[0,0,0]
	v_mfma_scale_f32_16x16x128_f8f6f4 v[126:129], v[2:9], v[182:189], v[126:129], v171, v171 op_sel_hi:[0,0,0]
	v_mfma_scale_f32_16x16x128_f8f6f4 v[122:125], v[10:17], v[182:189], v[122:125], v171, v171 op_sel_hi:[0,0,0]
	v_mfma_scale_f32_16x16x128_f8f6f4 v[110:113], v[2:9], v[190:197], v[110:113], v171, v171 op_sel_hi:[0,0,0]
	v_mfma_scale_f32_16x16x128_f8f6f4 v[106:109], v[10:17], v[190:197], v[106:109], v171, v171 op_sel_hi:[0,0,0]
	v_mfma_scale_f32_16x16x128_f8f6f4 v[94:97], v[2:9], v[198:205], v[94:97], v171, v171 op_sel_hi:[0,0,0]
	v_mfma_scale_f32_16x16x128_f8f6f4 v[90:93], v[10:17], v[198:205], v[90:93], v171, v171 op_sel_hi:[0,0,0]
	s_setprio 0
	s_barrier
	s_add_i32 s36, 0, 0x1c000
	s_add_i32 s0, s54, s11
	v_add_u32_e32 v218, s36, v168
	v_lshl_add_u64 v[162:163], v[162:163], 0, s[14:15]
	s_mov_b32 m0, s0
	ds_read_b128 v[206:209], v218
	ds_read_b128 v[210:213], v218 offset:1024
	ds_read_b128 v[214:217], v218 offset:2048
	ds_read_b128 v[218:221], v218 offset:3072
	global_load_lds_dwordx4 v[162:163], off
	v_lshl_add_u64 v[162:163], v[164:165], 0, s[14:15]
	s_add_i32 m0, s0, 0x2000
	s_nop 0
	global_load_lds_dwordx4 v[162:163], off
	s_waitcnt vmcnt(10)
	s_barrier
	s_waitcnt lgkmcnt(0)
	s_setprio 1
	s_waitcnt lgkmcnt(0)
	v_mfma_scale_f32_16x16x128_f8f6f4 v[134:137], v[206:213], v[174:181], v[134:137], v171, v171 op_sel_hi:[0,0,0]
	v_mfma_scale_f32_16x16x128_f8f6f4 v[130:133], v[214:221], v[174:181], v[130:133], v171, v171 op_sel_hi:[0,0,0]
	v_mfma_scale_f32_16x16x128_f8f6f4 v[118:121], v[206:213], v[182:189], v[118:121], v171, v171 op_sel_hi:[0,0,0]
	v_mfma_scale_f32_16x16x128_f8f6f4 v[114:117], v[214:221], v[182:189], v[114:117], v171, v171 op_sel_hi:[0,0,0]
	v_mfma_scale_f32_16x16x128_f8f6f4 v[102:105], v[206:213], v[190:197], v[102:105], v171, v171 op_sel_hi:[0,0,0]
	v_mfma_scale_f32_16x16x128_f8f6f4 v[98:101], v[214:221], v[190:197], v[98:101], v171, v171 op_sel_hi:[0,0,0]
	v_mfma_scale_f32_16x16x128_f8f6f4 v[86:89], v[206:213], v[198:205], v[86:89], v171, v171 op_sel_hi:[0,0,0]
	v_mfma_scale_f32_16x16x128_f8f6f4 v[82:85], v[214:221], v[198:205], v[82:85], v171, v171 op_sel_hi:[0,0,0]
	s_setprio 0
	s_mov_b32 m0, s43
	v_lshl_add_u64 v[162:163], s[34:35], 0, v[152:153]
	s_barrier
	ds_read_b128 v[174:177], v170 offset:49152
	ds_read_b128 v[178:181], v170 offset:50176
	ds_read_b128 v[182:185], v170 offset:51200
	ds_read_b128 v[186:189], v170 offset:52224
	ds_read_b128 v[190:193], v170 offset:53248
	ds_read_b128 v[194:197], v170 offset:54272
	ds_read_b128 v[198:201], v170 offset:55296
	ds_read_b128 v[202:205], v170 offset:56320
	global_load_lds_dwordx4 v[162:163], off
	v_lshl_add_u64 v[162:163], s[34:35], 0, v[148:149]
	s_mov_b32 m0, s44
	s_nop 0
	global_load_lds_dwordx4 v[162:163], off
	s_waitcnt vmcnt(10)
	s_barrier
	s_waitcnt lgkmcnt(0)
	s_setprio 1
	s_waitcnt lgkmcnt(0)
	v_mfma_scale_f32_16x16x128_f8f6f4 v[78:81], v[2:9], v[174:181], v[78:81], v171, v171 op_sel_hi:[0,0,0]
	v_mfma_scale_f32_16x16x128_f8f6f4 v[74:77], v[10:17], v[174:181], v[74:77], v171, v171 op_sel_hi:[0,0,0]
	v_mfma_scale_f32_16x16x128_f8f6f4 v[62:65], v[2:9], v[182:189], v[62:65], v171, v171 op_sel_hi:[0,0,0]
	v_mfma_scale_f32_16x16x128_f8f6f4 v[58:61], v[10:17], v[182:189], v[58:61], v171, v171 op_sel_hi:[0,0,0]
	v_mfma_scale_f32_16x16x128_f8f6f4 v[46:49], v[2:9], v[190:197], v[46:49], v171, v171 op_sel_hi:[0,0,0]
	v_mfma_scale_f32_16x16x128_f8f6f4 v[42:45], v[10:17], v[190:197], v[42:45], v171, v171 op_sel_hi:[0,0,0]
	v_mfma_scale_f32_16x16x128_f8f6f4 v[30:33], v[2:9], v[198:205], v[30:33], v171, v171 op_sel_hi:[0,0,0]
	v_mfma_scale_f32_16x16x128_f8f6f4 v[26:29], v[10:17], v[198:205], v[26:29], v171, v171 op_sel_hi:[0,0,0]
	s_setprio 0
	s_barrier
	s_add_u32 s0, s30, 0x20080
	s_addc_u32 s1, s31, 0
	s_add_i32 s30, s36, s11
	v_lshl_add_u64 v[2:3], s[0:1], 0, v[150:151]
	s_mov_b32 m0, s30
	s_nop 0
	global_load_lds_dwordx4 v[2:3], off
	v_lshl_add_u64 v[2:3], s[0:1], 0, v[146:147]
	s_add_i32 m0, s30, 0x2000
	s_nop 0
	global_load_lds_dwordx4 v[2:3], off
	s_waitcnt vmcnt(10)
	s_barrier
	s_setprio 1
	v_mfma_scale_f32_16x16x128_f8f6f4 v[70:73], v[206:213], v[174:181], v[70:73], v171, v171 op_sel_hi:[0,0,0]
	v_mfma_scale_f32_16x16x128_f8f6f4 v[66:69], v[214:221], v[174:181], v[66:69], v171, v171 op_sel_hi:[0,0,0]
	v_mfma_scale_f32_16x16x128_f8f6f4 v[54:57], v[206:213], v[182:189], v[54:57], v171, v171 op_sel_hi:[0,0,0]
	v_mfma_scale_f32_16x16x128_f8f6f4 v[50:53], v[214:221], v[182:189], v[50:53], v171, v171 op_sel_hi:[0,0,0]
	v_mfma_scale_f32_16x16x128_f8f6f4 v[38:41], v[206:213], v[190:197], v[38:41], v171, v171 op_sel_hi:[0,0,0]
	v_mfma_scale_f32_16x16x128_f8f6f4 v[34:37], v[214:221], v[190:197], v[34:37], v171, v171 op_sel_hi:[0,0,0]
	v_mfma_scale_f32_16x16x128_f8f6f4 v[22:25], v[206:213], v[198:205], v[22:25], v171, v171 op_sel_hi:[0,0,0]
	v_mfma_scale_f32_16x16x128_f8f6f4 v[18:21], v[214:221], v[198:205], v[18:21], v171, v171 op_sel_hi:[0,0,0]
	s_setprio 0
	s_add_i32 s53, s53, 2
	s_add_u32 s51, s51, 0x100
	s_addc_u32 s52, s52, 0
	s_add_u32 s28, s28, 0x10000
	s_addc_u32 s29, s29, 0
	s_cmp_gt_u32 s53, 5
	s_barrier
	s_cbranch_scc0 .LBB0_1369
	v_pk_mul_f32 v[10:11], v[142:143], s[16:17] op_sel_hi:[1,0]
	v_pk_mul_f32 v[8:9], v[144:145], s[16:17] op_sel_hi:[1,0]
	v_med3_f32 v5, v10, s47, v173
	v_med3_f32 v11, v11, s47, v173
	v_mov_b32_e32 v10, 0
	v_cvt_pk_fp8_f32 v10, v5, v11
	v_mov_b32_e32 v3, v166
	v_mov_b32_e32 v2, v167
	s_lshl_b32 s0, s48, 8
	v_pk_mul_f32 v[14:15], v[138:139], s[16:17] op_sel_hi:[1,0]
	v_med3_f32 v5, v8, s47, v173
	v_med3_f32 v8, v9, s47, v173
	s_nop 15
	s_nop 15
	s_or_b32 s0, s0, s42
	v_cvt_pk_fp8_f32 v10, v5, v8 op_sel:[0,0,1]
	v_med3_f32 v5, v14, s47, v173
	v_med3_f32 v8, v15, s47, v173
	v_mov_b32_e32 v11, 0
	v_lshl_add_u32 v2, v2, 3, s0
	s_lshl_b32 s0, s26, 8
	v_cvt_pk_fp8_f32 v11, v5, v8
	s_add_i32 s0, s0, s41
	v_add_u32_e32 v4, s0, v3
	v_pk_mul_f32 v[12:13], v[140:141], s[16:17] op_sel_hi:[1,0]
	v_mov_b32_e32 v6, v4
	v_med3_f32 v5, v12, s47, v173
	v_med3_f32 v8, v13, s47, v173
	v_cvt_pk_fp8_f32 v11, v5, v8 op_sel:[0,0,1]
	v_ashrrev_i32_e32 v7, 31, v6
	v_lshlrev_b64 v[6:7], 10, v[6:7]
	v_ashrrev_i32_e32 v3, 31, v2
	v_lshl_add_u64 v[6:7], s[12:13], 0, v[6:7]
	v_lshl_add_u64 v[6:7], v[6:7], 0, v[2:3]
	flat_store_dwordx2 v[6:7], v[10:11] nt
	v_pk_mul_f32 v[10:11], v[134:135], s[16:17] op_sel_hi:[1,0]
	v_pk_mul_f32 v[8:9], v[136:137], s[16:17] op_sel_hi:[1,0]
	v_med3_f32 v5, v10, s47, v173
	v_med3_f32 v11, v11, s47, v173
	v_mov_b32_e32 v10, 0
	v_cvt_pk_fp8_f32 v10, v5, v11
	v_pk_mul_f32 v[14:15], v[130:131], s[16:17] op_sel_hi:[1,0]
	v_med3_f32 v5, v8, s47, v173
	v_med3_f32 v8, v9, s47, v173
	v_cvt_pk_fp8_f32 v10, v5, v8 op_sel:[0,0,1]
	v_med3_f32 v5, v14, s47, v173
	v_med3_f32 v8, v15, s47, v173
	v_mov_b32_e32 v11, 0
	v_cvt_pk_fp8_f32 v11, v5, v8
	v_pk_mul_f32 v[12:13], v[132:133], s[16:17] op_sel_hi:[1,0]
	v_pk_mul_f32 v[14:15], v[122:123], s[16:17] op_sel_hi:[1,0]
	v_med3_f32 v5, v12, s47, v173
	v_med3_f32 v8, v13, s47, v173
	v_cvt_pk_fp8_f32 v11, v5, v8 op_sel:[0,0,1]
	v_pk_mul_f32 v[8:9], v[128:129], s[16:17] op_sel_hi:[1,0]
	v_pk_mul_f32 v[12:13], v[124:125], s[16:17] op_sel_hi:[1,0]
	s_and_b64 vcc, exec, s[8:9]
	flat_store_dwordx2 v[6:7], v[10:11] offset:128 nt
	v_pk_mul_f32 v[10:11], v[126:127], s[16:17] op_sel_hi:[1,0]
	v_add_u32_e32 v6, 16, v4
	v_med3_f32 v5, v10, s47, v173
	v_med3_f32 v11, v11, s47, v173
	v_mov_b32_e32 v10, 0
	v_cvt_pk_fp8_f32 v10, v5, v11
	v_med3_f32 v5, v8, s47, v173
	v_med3_f32 v8, v9, s47, v173
	v_mov_b32_e32 v11, 0
	v_cvt_pk_fp8_f32 v10, v5, v8 op_sel:[0,0,1]
	v_med3_f32 v5, v14, s47, v173
	v_med3_f32 v8, v15, s47, v173
	v_cvt_pk_fp8_f32 v11, v5, v8
	v_med3_f32 v5, v12, s47, v173
	v_med3_f32 v8, v13, s47, v173
	v_cvt_pk_fp8_f32 v11, v5, v8 op_sel:[0,0,1]
	v_ashrrev_i32_e32 v7, 31, v6
	v_lshlrev_b64 v[6:7], 10, v[6:7]
	v_lshl_add_u64 v[6:7], s[12:13], 0, v[6:7]
	v_lshl_add_u64 v[6:7], v[6:7], 0, v[2:3]
	flat_store_dwordx2 v[6:7], v[10:11] nt
	v_pk_mul_f32 v[10:11], v[118:119], s[16:17] op_sel_hi:[1,0]
	v_pk_mul_f32 v[8:9], v[120:121], s[16:17] op_sel_hi:[1,0]
	v_med3_f32 v5, v10, s47, v173
	v_med3_f32 v11, v11, s47, v173
	v_mov_b32_e32 v10, 0
	v_cvt_pk_fp8_f32 v10, v5, v11
	v_pk_mul_f32 v[14:15], v[114:115], s[16:17] op_sel_hi:[1,0]
	v_med3_f32 v5, v8, s47, v173
	v_med3_f32 v8, v9, s47, v173
	v_cvt_pk_fp8_f32 v10, v5, v8 op_sel:[0,0,1]
	v_med3_f32 v5, v14, s47, v173
	v_med3_f32 v8, v15, s47, v173
	v_mov_b32_e32 v11, 0
	v_cvt_pk_fp8_f32 v11, v5, v8
	v_pk_mul_f32 v[12:13], v[116:117], s[16:17] op_sel_hi:[1,0]
	v_pk_mul_f32 v[14:15], v[106:107], s[16:17] op_sel_hi:[1,0]
	v_med3_f32 v5, v12, s47, v173
	v_med3_f32 v8, v13, s47, v173
	v_cvt_pk_fp8_f32 v11, v5, v8 op_sel:[0,0,1]
	v_pk_mul_f32 v[8:9], v[112:113], s[16:17] op_sel_hi:[1,0]
	v_pk_mul_f32 v[12:13], v[108:109], s[16:17] op_sel_hi:[1,0]
	s_mov_b32 s48, s18
	flat_store_dwordx2 v[6:7], v[10:11] offset:128 nt
	v_pk_mul_f32 v[10:11], v[110:111], s[16:17] op_sel_hi:[1,0]
	v_add_u32_e32 v6, 32, v4
	v_med3_f32 v5, v10, s47, v173
	v_med3_f32 v11, v11, s47, v173
	v_mov_b32_e32 v10, 0
	v_cvt_pk_fp8_f32 v10, v5, v11
	v_med3_f32 v5, v8, s47, v173
	v_med3_f32 v8, v9, s47, v173
	v_mov_b32_e32 v11, 0
	v_cvt_pk_fp8_f32 v10, v5, v8 op_sel:[0,0,1]
	v_med3_f32 v5, v14, s47, v173
	v_med3_f32 v8, v15, s47, v173
	v_cvt_pk_fp8_f32 v11, v5, v8
	v_med3_f32 v5, v12, s47, v173
	v_med3_f32 v8, v13, s47, v173
	v_cvt_pk_fp8_f32 v11, v5, v8 op_sel:[0,0,1]
	v_ashrrev_i32_e32 v7, 31, v6
	v_lshlrev_b64 v[6:7], 10, v[6:7]
	v_lshl_add_u64 v[6:7], s[12:13], 0, v[6:7]
	v_lshl_add_u64 v[6:7], v[6:7], 0, v[2:3]
	flat_store_dwordx2 v[6:7], v[10:11] nt
	v_pk_mul_f32 v[10:11], v[102:103], s[16:17] op_sel_hi:[1,0]
	v_pk_mul_f32 v[8:9], v[104:105], s[16:17] op_sel_hi:[1,0]
	v_med3_f32 v5, v10, s47, v173
	v_med3_f32 v11, v11, s47, v173
	v_mov_b32_e32 v10, 0
	v_cvt_pk_fp8_f32 v10, v5, v11
	v_pk_mul_f32 v[14:15], v[98:99], s[16:17] op_sel_hi:[1,0]
	v_med3_f32 v5, v8, s47, v173
	v_med3_f32 v8, v9, s47, v173
	v_cvt_pk_fp8_f32 v10, v5, v8 op_sel:[0,0,1]
	v_med3_f32 v5, v14, s47, v173
	v_med3_f32 v8, v15, s47, v173
	v_mov_b32_e32 v11, 0
	v_cvt_pk_fp8_f32 v11, v5, v8
	v_pk_mul_f32 v[12:13], v[100:101], s[16:17] op_sel_hi:[1,0]
	v_pk_mul_f32 v[14:15], v[90:91], s[16:17] op_sel_hi:[1,0]
	v_med3_f32 v5, v12, s47, v173
	v_med3_f32 v8, v13, s47, v173
	v_cvt_pk_fp8_f32 v11, v5, v8 op_sel:[0,0,1]
	v_pk_mul_f32 v[8:9], v[96:97], s[16:17] op_sel_hi:[1,0]
	v_pk_mul_f32 v[12:13], v[92:93], s[16:17] op_sel_hi:[1,0]
	s_mov_b32 s26, s20
	flat_store_dwordx2 v[6:7], v[10:11] offset:128 nt
	v_pk_mul_f32 v[10:11], v[94:95], s[16:17] op_sel_hi:[1,0]
	v_add_u32_e32 v6, 48, v4
	v_med3_f32 v5, v10, s47, v173
	v_med3_f32 v11, v11, s47, v173
	v_mov_b32_e32 v10, 0
	v_cvt_pk_fp8_f32 v10, v5, v11
	v_med3_f32 v5, v8, s47, v173
	v_med3_f32 v8, v9, s47, v173
	v_mov_b32_e32 v11, 0
	v_cvt_pk_fp8_f32 v10, v5, v8 op_sel:[0,0,1]
	v_med3_f32 v5, v14, s47, v173
	v_med3_f32 v8, v15, s47, v173
	v_cvt_pk_fp8_f32 v11, v5, v8
	v_med3_f32 v5, v12, s47, v173
	v_med3_f32 v8, v13, s47, v173
	v_cvt_pk_fp8_f32 v11, v5, v8 op_sel:[0,0,1]
	v_ashrrev_i32_e32 v7, 31, v6
	v_lshlrev_b64 v[6:7], 10, v[6:7]
	v_lshl_add_u64 v[6:7], s[12:13], 0, v[6:7]
	v_lshl_add_u64 v[6:7], v[6:7], 0, v[2:3]
	flat_store_dwordx2 v[6:7], v[10:11] nt
	v_pk_mul_f32 v[10:11], v[86:87], s[16:17] op_sel_hi:[1,0]
	v_pk_mul_f32 v[8:9], v[88:89], s[16:17] op_sel_hi:[1,0]
	v_med3_f32 v5, v10, s47, v173
	v_med3_f32 v11, v11, s47, v173
	v_mov_b32_e32 v10, 0
	v_cvt_pk_fp8_f32 v10, v5, v11
	v_pk_mul_f32 v[14:15], v[82:83], s[16:17] op_sel_hi:[1,0]
	v_med3_f32 v5, v8, s47, v173
	v_med3_f32 v8, v9, s47, v173
	v_cvt_pk_fp8_f32 v10, v5, v8 op_sel:[0,0,1]
	v_med3_f32 v5, v14, s47, v173
	v_med3_f32 v8, v15, s47, v173
	v_mov_b32_e32 v11, 0
	v_cvt_pk_fp8_f32 v11, v5, v8
	v_pk_mul_f32 v[12:13], v[84:85], s[16:17] op_sel_hi:[1,0]
	v_pk_mul_f32 v[14:15], v[74:75], s[16:17] op_sel_hi:[1,0]
	v_med3_f32 v5, v12, s47, v173
	v_med3_f32 v8, v13, s47, v173
	v_cvt_pk_fp8_f32 v11, v5, v8 op_sel:[0,0,1]
	v_pk_mul_f32 v[8:9], v[80:81], s[16:17] op_sel_hi:[1,0]
	v_pk_mul_f32 v[12:13], v[76:77], s[16:17] op_sel_hi:[1,0]
	s_mov_b64 s[28:29], s[24:25]
	flat_store_dwordx2 v[6:7], v[10:11] offset:128 nt
	v_pk_mul_f32 v[10:11], v[78:79], s[16:17] op_sel_hi:[1,0]
	v_add_u32_e32 v6, 0x80, v4
	v_med3_f32 v5, v10, s47, v173
	v_med3_f32 v11, v11, s47, v173
	v_mov_b32_e32 v10, 0
	v_cvt_pk_fp8_f32 v10, v5, v11
	v_med3_f32 v5, v8, s47, v173
	v_med3_f32 v8, v9, s47, v173
	v_mov_b32_e32 v11, 0
	v_cvt_pk_fp8_f32 v10, v5, v8 op_sel:[0,0,1]
	v_med3_f32 v5, v14, s47, v173
	v_med3_f32 v8, v15, s47, v173
	v_cvt_pk_fp8_f32 v11, v5, v8
	v_med3_f32 v5, v12, s47, v173
	v_med3_f32 v8, v13, s47, v173
	v_cvt_pk_fp8_f32 v11, v5, v8 op_sel:[0,0,1]
	v_ashrrev_i32_e32 v7, 31, v6
	v_lshlrev_b64 v[6:7], 10, v[6:7]
	v_lshl_add_u64 v[6:7], s[12:13], 0, v[6:7]
	v_lshl_add_u64 v[6:7], v[6:7], 0, v[2:3]
	flat_store_dwordx2 v[6:7], v[10:11] nt
	v_pk_mul_f32 v[10:11], v[70:71], s[16:17] op_sel_hi:[1,0]
	v_pk_mul_f32 v[8:9], v[72:73], s[16:17] op_sel_hi:[1,0]
	v_med3_f32 v5, v10, s47, v173
	v_med3_f32 v11, v11, s47, v173
	v_mov_b32_e32 v10, 0
	v_cvt_pk_fp8_f32 v10, v5, v11
	v_pk_mul_f32 v[14:15], v[66:67], s[16:17] op_sel_hi:[1,0]
	v_med3_f32 v5, v8, s47, v173
	v_med3_f32 v8, v9, s47, v173
	v_cvt_pk_fp8_f32 v10, v5, v8 op_sel:[0,0,1]
	v_med3_f32 v5, v14, s47, v173
	v_med3_f32 v8, v15, s47, v173
	v_mov_b32_e32 v11, 0
	v_cvt_pk_fp8_f32 v11, v5, v8
	v_pk_mul_f32 v[12:13], v[68:69], s[16:17] op_sel_hi:[1,0]
	v_pk_mul_f32 v[14:15], v[58:59], s[16:17] op_sel_hi:[1,0]
	v_med3_f32 v5, v12, s47, v173
	v_med3_f32 v8, v13, s47, v173
	v_cvt_pk_fp8_f32 v11, v5, v8 op_sel:[0,0,1]
	v_pk_mul_f32 v[8:9], v[64:65], s[16:17] op_sel_hi:[1,0]
	v_pk_mul_f32 v[12:13], v[60:61], s[16:17] op_sel_hi:[1,0]
	s_mov_b64 s[30:31], s[22:23]
	flat_store_dwordx2 v[6:7], v[10:11] offset:128 nt
	v_pk_mul_f32 v[10:11], v[62:63], s[16:17] op_sel_hi:[1,0]
	v_add_u32_e32 v6, 0x90, v4
	v_med3_f32 v5, v10, s47, v173
	v_med3_f32 v11, v11, s47, v173
	v_mov_b32_e32 v10, 0
	v_cvt_pk_fp8_f32 v10, v5, v11
	v_med3_f32 v5, v8, s47, v173
	v_med3_f32 v8, v9, s47, v173
	v_mov_b32_e32 v11, 0
	v_cvt_pk_fp8_f32 v10, v5, v8 op_sel:[0,0,1]
	v_med3_f32 v5, v14, s47, v173
	v_med3_f32 v8, v15, s47, v173
	v_cvt_pk_fp8_f32 v11, v5, v8
	v_med3_f32 v5, v12, s47, v173
	v_med3_f32 v8, v13, s47, v173
	v_cvt_pk_fp8_f32 v11, v5, v8 op_sel:[0,0,1]
	v_ashrrev_i32_e32 v7, 31, v6
	v_lshlrev_b64 v[6:7], 10, v[6:7]
	v_lshl_add_u64 v[6:7], s[12:13], 0, v[6:7]
	v_lshl_add_u64 v[6:7], v[6:7], 0, v[2:3]
	flat_store_dwordx2 v[6:7], v[10:11] nt
	v_pk_mul_f32 v[10:11], v[54:55], s[16:17] op_sel_hi:[1,0]
	v_pk_mul_f32 v[8:9], v[56:57], s[16:17] op_sel_hi:[1,0]
	v_med3_f32 v5, v10, s47, v173
	v_med3_f32 v11, v11, s47, v173
	v_mov_b32_e32 v10, 0
	v_cvt_pk_fp8_f32 v10, v5, v11
	v_pk_mul_f32 v[14:15], v[50:51], s[16:17] op_sel_hi:[1,0]
	v_med3_f32 v5, v8, s47, v173
	v_med3_f32 v8, v9, s47, v173
	v_cvt_pk_fp8_f32 v10, v5, v8 op_sel:[0,0,1]
	v_med3_f32 v5, v14, s47, v173
	v_med3_f32 v8, v15, s47, v173
	v_mov_b32_e32 v11, 0
	v_cvt_pk_fp8_f32 v11, v5, v8
	v_pk_mul_f32 v[12:13], v[52:53], s[16:17] op_sel_hi:[1,0]
	v_pk_mul_f32 v[14:15], v[42:43], s[16:17] op_sel_hi:[1,0]
	v_med3_f32 v5, v12, s47, v173
	v_med3_f32 v8, v13, s47, v173
	v_cvt_pk_fp8_f32 v11, v5, v8 op_sel:[0,0,1]
	v_pk_mul_f32 v[8:9], v[48:49], s[16:17] op_sel_hi:[1,0]
	v_pk_mul_f32 v[12:13], v[44:45], s[16:17] op_sel_hi:[1,0]
	flat_store_dwordx2 v[6:7], v[10:11] offset:128 nt
	v_pk_mul_f32 v[10:11], v[46:47], s[16:17] op_sel_hi:[1,0]
	v_add_u32_e32 v6, 0xa0, v4
	v_med3_f32 v5, v10, s47, v173
	v_med3_f32 v11, v11, s47, v173
	v_mov_b32_e32 v10, 0
	v_cvt_pk_fp8_f32 v10, v5, v11
	v_med3_f32 v5, v8, s47, v173
	v_med3_f32 v8, v9, s47, v173
	v_mov_b32_e32 v11, 0
	v_cvt_pk_fp8_f32 v10, v5, v8 op_sel:[0,0,1]
	v_med3_f32 v5, v14, s47, v173
	v_med3_f32 v8, v15, s47, v173
	v_cvt_pk_fp8_f32 v11, v5, v8
	v_med3_f32 v5, v12, s47, v173
	v_med3_f32 v8, v13, s47, v173
	v_cvt_pk_fp8_f32 v11, v5, v8 op_sel:[0,0,1]
	v_ashrrev_i32_e32 v7, 31, v6
	v_lshlrev_b64 v[6:7], 10, v[6:7]
	v_lshl_add_u64 v[6:7], s[12:13], 0, v[6:7]
	v_lshl_add_u64 v[6:7], v[6:7], 0, v[2:3]
	flat_store_dwordx2 v[6:7], v[10:11] nt
	v_pk_mul_f32 v[10:11], v[38:39], s[16:17] op_sel_hi:[1,0]
	v_pk_mul_f32 v[8:9], v[40:41], s[16:17] op_sel_hi:[1,0]
	v_med3_f32 v5, v10, s47, v173
	v_med3_f32 v11, v11, s47, v173
	v_mov_b32_e32 v10, 0
	v_cvt_pk_fp8_f32 v10, v5, v11
	v_pk_mul_f32 v[14:15], v[34:35], s[16:17] op_sel_hi:[1,0]
	v_med3_f32 v5, v8, s47, v173
	v_med3_f32 v8, v9, s47, v173
	v_cvt_pk_fp8_f32 v10, v5, v8 op_sel:[0,0,1]
	v_med3_f32 v5, v14, s47, v173
	v_med3_f32 v8, v15, s47, v173
	v_mov_b32_e32 v11, 0
	v_cvt_pk_fp8_f32 v11, v5, v8
	v_pk_mul_f32 v[12:13], v[36:37], s[16:17] op_sel_hi:[1,0]
	v_add_u32_e32 v4, 0xb0, v4
	v_med3_f32 v5, v12, s47, v173
	v_med3_f32 v8, v13, s47, v173
	v_cvt_pk_fp8_f32 v11, v5, v8 op_sel:[0,0,1]
	v_pk_mul_f32 v[8:9], v[28:29], s[16:17] op_sel_hi:[1,0]
	flat_store_dwordx2 v[6:7], v[10:11] offset:128 nt
	v_pk_mul_f32 v[6:7], v[30:31], s[16:17] op_sel_hi:[1,0]
	v_pk_mul_f32 v[10:11], v[26:27], s[16:17] op_sel_hi:[1,0]
	v_ashrrev_i32_e32 v5, 31, v4
	v_med3_f32 v12, v6, s47, v173
	v_med3_f32 v7, v7, s47, v173
	v_mov_b32_e32 v6, 0
	v_lshlrev_b64 v[4:5], 10, v[4:5]
	v_cvt_pk_fp8_f32 v6, v12, v7
	v_lshl_add_u64 v[4:5], s[12:13], 0, v[4:5]
	v_lshl_add_u64 v[2:3], v[4:5], 0, v[2:3]
	v_pk_mul_f32 v[4:5], v[32:33], s[16:17] op_sel_hi:[1,0]
	v_mov_b32_e32 v7, 0
	v_med3_f32 v4, v4, s47, v173
	v_med3_f32 v5, v5, s47, v173
	v_cvt_pk_fp8_f32 v6, v4, v5 op_sel:[0,0,1]
	v_med3_f32 v4, v10, s47, v173
	v_med3_f32 v5, v11, s47, v173
	v_cvt_pk_fp8_f32 v7, v4, v5
	v_med3_f32 v4, v8, s47, v173
	v_med3_f32 v5, v9, s47, v173
	v_pk_mul_f32 v[10:11], v[18:19], s[16:17] op_sel_hi:[1,0]
	v_cvt_pk_fp8_f32 v7, v4, v5 op_sel:[0,0,1]
	v_pk_mul_f32 v[4:5], v[24:25], s[16:17] op_sel_hi:[1,0]
	v_pk_mul_f32 v[8:9], v[20:21], s[16:17] op_sel_hi:[1,0]
	v_med3_f32 v4, v4, s47, v173
	flat_store_dwordx2 v[2:3], v[6:7] nt
	v_pk_mul_f32 v[6:7], v[22:23], s[16:17] op_sel_hi:[1,0]
	v_med3_f32 v5, v5, s47, v173
	v_med3_f32 v12, v6, s47, v173
	v_med3_f32 v7, v7, s47, v173
	v_mov_b32_e32 v6, 0
	v_cvt_pk_fp8_f32 v6, v12, v7
	v_mov_b32_e32 v7, 0
	v_cvt_pk_fp8_f32 v6, v4, v5 op_sel:[0,0,1]
	v_med3_f32 v4, v10, s47, v173
	v_med3_f32 v5, v11, s47, v173
	v_cvt_pk_fp8_f32 v7, v4, v5
	v_med3_f32 v4, v8, s47, v173
	v_med3_f32 v5, v9, s47, v173
	v_cvt_pk_fp8_f32 v7, v4, v5 op_sel:[0,0,1]
	flat_store_dwordx2 v[2:3], v[6:7] offset:128 nt
	s_cbranch_vccz .LBB0_1362
	s_waitcnt vmcnt(0)
	s_cmpk_gt_u32 s4, 0xff
	s_cbranch_scc1 .LBB0_1373
	s_barrier

.LBB0_1513:
	ds_read_b128 v[152:155], v149
	ds_read_b128 v[156:159], v149 offset:1024
	ds_read_b128 v[160:163], v149 offset:2048
	ds_read_b128 v[164:167], v149 offset:3072
	s_add_u32 s0, s26, 0xfffc0080
	s_addc_u32 s1, s27, -1
	s_cmp_eq_u32 s49, 12
	s_cselect_b32 s31, s21, s1
	s_cselect_b32 s30, s45, s0
	s_cselect_b32 s29, s19, s48
	s_cselect_b32 s28, s46, s47
	v_lshl_add_u64 v[200:201], s[26:27], 0, v[140:141]
	s_add_i32 m0, s10, 0xc000
	ds_read_b128 v[168:171], v150
	ds_read_b128 v[172:175], v150 offset:1024
	ds_read_b128 v[176:179], v150 offset:2048
	ds_read_b128 v[180:183], v150 offset:3072
	ds_read_b128 v[184:187], v150 offset:4096
	ds_read_b128 v[188:191], v150 offset:5120
	ds_read_b128 v[192:195], v150 offset:6144
	ds_read_b128 v[196:199], v150 offset:7168
	global_load_lds_dwordx4 v[200:201], off
	v_lshl_add_u64 v[200:201], s[26:27], 0, v[138:139]
	s_add_i32 m0, s10, 0xe000
	s_nop 0
	global_load_lds_dwordx4 v[200:201], off
	s_waitcnt lgkmcnt(8)
	s_waitcnt vmcnt(10)
	s_barrier
	s_waitcnt lgkmcnt(0)
	s_setprio 1
	s_waitcnt lgkmcnt(0)
	v_mfma_f32_16x16x32_bf16 v[126:129], v[152:155], v[168:171], v[126:129]
	v_mfma_f32_16x16x32_bf16 v[122:125], v[160:163], v[168:171], v[122:125]
	v_mfma_f32_16x16x32_bf16 v[118:121], v[152:155], v[176:179], v[118:121]
	v_mfma_f32_16x16x32_bf16 v[110:113], v[160:163], v[176:179], v[110:113]
	v_mfma_f32_16x16x32_bf16 v[102:105], v[152:155], v[184:187], v[102:105]
	v_mfma_f32_16x16x32_bf16 v[94:97], v[160:163], v[184:187], v[94:97]
	v_mfma_f32_16x16x32_bf16 v[86:89], v[152:155], v[192:195], v[86:89]
	v_mfma_f32_16x16x32_bf16 v[78:81], v[160:163], v[192:195], v[78:81]
	v_mfma_f32_16x16x32_bf16 v[126:129], v[156:159], v[172:175], v[126:129]
	v_mfma_f32_16x16x32_bf16 v[122:125], v[164:167], v[172:175], v[122:125]
	v_mfma_f32_16x16x32_bf16 v[118:121], v[156:159], v[180:183], v[118:121]
	v_mfma_f32_16x16x32_bf16 v[110:113], v[164:167], v[180:183], v[110:113]
	v_mfma_f32_16x16x32_bf16 v[102:105], v[156:159], v[188:191], v[102:105]
	v_mfma_f32_16x16x32_bf16 v[94:97], v[164:167], v[188:191], v[94:97]
	v_mfma_f32_16x16x32_bf16 v[86:89], v[156:159], v[196:199], v[86:89]
	v_mfma_f32_16x16x32_bf16 v[78:81], v[164:167], v[196:199], v[78:81]
	s_setprio 0
	s_barrier
	s_add_i32 s0, s42, s9
	v_lshl_add_u64 v[216:217], s[28:29], 0, v[134:135]
	s_mov_b32 m0, s0
	ds_read_b128 v[200:203], v151
	ds_read_b128 v[204:207], v151 offset:1024
	ds_read_b128 v[208:211], v151 offset:2048
	ds_read_b128 v[212:215], v151 offset:3072
	global_load_lds_dwordx4 v[216:217], off
	v_lshl_add_u64 v[218:219], s[28:29], 0, v[130:131]
	s_add_i32 m0, s0, 0x2000
	s_nop 0
	global_load_lds_dwordx4 v[218:219], off
	s_waitcnt vmcnt(10)
	s_barrier
	s_waitcnt lgkmcnt(0)
	s_setprio 1
	s_waitcnt lgkmcnt(0)
	v_mfma_f32_16x16x32_bf16 v[114:117], v[200:203], v[168:171], v[114:117]
	v_mfma_f32_16x16x32_bf16 v[106:109], v[208:211], v[168:171], v[106:109]
	v_mfma_f32_16x16x32_bf16 v[98:101], v[200:203], v[176:179], v[98:101]
	v_mfma_f32_16x16x32_bf16 v[90:93], v[208:211], v[176:179], v[90:93]
	v_mfma_f32_16x16x32_bf16 v[82:85], v[200:203], v[184:187], v[82:85]
	v_mfma_f32_16x16x32_bf16 v[74:77], v[208:211], v[184:187], v[74:77]
	v_mfma_f32_16x16x32_bf16 v[70:73], v[200:203], v[192:195], v[70:73]
	v_mfma_f32_16x16x32_bf16 v[66:69], v[208:211], v[192:195], v[66:69]
	v_mfma_f32_16x16x32_bf16 v[114:117], v[204:207], v[172:175], v[114:117]
	v_mfma_f32_16x16x32_bf16 v[106:109], v[212:215], v[172:175], v[106:109]
	v_mfma_f32_16x16x32_bf16 v[98:101], v[204:207], v[180:183], v[98:101]
	v_mfma_f32_16x16x32_bf16 v[90:93], v[212:215], v[180:183], v[90:93]
	v_mfma_f32_16x16x32_bf16 v[82:85], v[204:207], v[188:191], v[82:85]
	v_mfma_f32_16x16x32_bf16 v[74:77], v[212:215], v[188:191], v[74:77]
	v_mfma_f32_16x16x32_bf16 v[70:73], v[204:207], v[196:199], v[70:73]
	v_mfma_f32_16x16x32_bf16 v[66:69], v[212:215], v[196:199], v[66:69]
	s_setprio 0
	s_mov_b32 m0, s10
	v_lshl_add_u64 v[220:221], s[30:31], 0, v[136:137]
	s_barrier
	ds_read_b128 v[168:171], v150 offset:16384
	ds_read_b128 v[172:175], v150 offset:17408
	ds_read_b128 v[176:179], v150 offset:18432
	ds_read_b128 v[180:183], v150 offset:19456
	ds_read_b128 v[184:187], v150 offset:20480
	ds_read_b128 v[188:191], v150 offset:21504
	ds_read_b128 v[192:195], v150 offset:22528
	ds_read_b128 v[196:199], v150 offset:23552
	global_load_lds_dwordx4 v[220:221], off
	v_lshl_add_u64 v[222:223], s[30:31], 0, v[132:133]
	s_mov_b32 m0, s11
	s_nop 0
	global_load_lds_dwordx4 v[222:223], off
	s_waitcnt vmcnt(10)
	s_barrier
	s_waitcnt lgkmcnt(0)
	s_setprio 1
	s_waitcnt lgkmcnt(0)
	v_mfma_f32_16x16x32_bf16 v[62:65], v[152:155], v[168:171], v[62:65]
	v_mfma_f32_16x16x32_bf16 v[58:61], v[160:163], v[168:171], v[58:61]
	v_mfma_f32_16x16x32_bf16 v[54:57], v[152:155], v[176:179], v[54:57]
	v_mfma_f32_16x16x32_bf16 v[50:53], v[160:163], v[176:179], v[50:53]
	v_mfma_f32_16x16x32_bf16 v[38:41], v[152:155], v[184:187], v[38:41]
	v_mfma_f32_16x16x32_bf16 v[34:37], v[160:163], v[184:187], v[34:37]
	v_mfma_f32_16x16x32_bf16 v[22:25], v[152:155], v[192:195], v[22:25]
	v_mfma_f32_16x16x32_bf16 v[18:21], v[160:163], v[192:195], v[18:21]
	v_mfma_f32_16x16x32_bf16 v[62:65], v[156:159], v[172:175], v[62:65]
	v_mfma_f32_16x16x32_bf16 v[58:61], v[164:167], v[172:175], v[58:61]
	v_mfma_f32_16x16x32_bf16 v[54:57], v[156:159], v[180:183], v[54:57]
	v_mfma_f32_16x16x32_bf16 v[50:53], v[164:167], v[180:183], v[50:53]
	v_mfma_f32_16x16x32_bf16 v[38:41], v[156:159], v[188:191], v[38:41]
	v_mfma_f32_16x16x32_bf16 v[34:37], v[164:167], v[188:191], v[34:37]
	v_mfma_f32_16x16x32_bf16 v[22:25], v[156:159], v[196:199], v[22:25]
	v_mfma_f32_16x16x32_bf16 v[18:21], v[164:167], v[196:199], v[18:21]
	s_setprio 0
	s_barrier
	s_add_u32 s0, s28, 0x40000
	s_addc_u32 s1, s29, 0
	s_add_i32 s50, s43, s9
	v_lshl_add_u64 v[152:153], s[0:1], 0, v[134:135]
	s_mov_b32 m0, s50
	s_nop 0
	global_load_lds_dwordx4 v[152:153], off
	v_lshl_add_u64 v[152:153], s[0:1], 0, v[130:131]
	s_add_i32 m0, s50, 0x2000
	s_nop 0
	global_load_lds_dwordx4 v[152:153], off
	s_waitcnt vmcnt(10)
	s_barrier
	s_setprio 1
	v_mfma_f32_16x16x32_bf16 v[46:49], v[200:203], v[168:171], v[46:49]
	v_mfma_f32_16x16x32_bf16 v[42:45], v[208:211], v[168:171], v[42:45]
	v_mfma_f32_16x16x32_bf16 v[30:33], v[200:203], v[176:179], v[30:33]
	v_mfma_f32_16x16x32_bf16 v[26:29], v[208:211], v[176:179], v[26:29]
	v_mfma_f32_16x16x32_bf16 v[14:17], v[200:203], v[184:187], v[14:17]
	v_mfma_f32_16x16x32_bf16 v[10:13], v[208:211], v[184:187], v[10:13]
	v_mfma_f32_16x16x32_bf16 v[6:9], v[200:203], v[192:195], v[6:9]
	v_mfma_f32_16x16x32_bf16 v[2:5], v[208:211], v[192:195], v[2:5]
	v_mfma_f32_16x16x32_bf16 v[46:49], v[204:207], v[172:175], v[46:49]
	v_mfma_f32_16x16x32_bf16 v[42:45], v[212:215], v[172:175], v[42:45]
	v_mfma_f32_16x16x32_bf16 v[30:33], v[204:207], v[180:183], v[30:33]
	v_mfma_f32_16x16x32_bf16 v[26:29], v[212:215], v[180:183], v[26:29]
	v_mfma_f32_16x16x32_bf16 v[14:17], v[204:207], v[188:191], v[14:17]
	v_mfma_f32_16x16x32_bf16 v[10:13], v[212:215], v[188:191], v[10:13]
	v_mfma_f32_16x16x32_bf16 v[6:9], v[204:207], v[196:199], v[6:9]
	v_mfma_f32_16x16x32_bf16 v[2:5], v[212:215], v[196:199], v[2:5]
	s_setprio 0
	s_add_i32 s50, 0, 0x18000
	v_add_u32_e32 v164, s50, v148
	s_barrier
	ds_read_b128 v[152:155], v164
	ds_read_b128 v[156:159], v164 offset:1024
	ds_read_b128 v[160:163], v164 offset:2048
	ds_read_b128 v[164:167], v164 offset:3072
	s_add_u32 s0, s30, 0x40000
	s_addc_u32 s1, s31, 0
	s_mov_b32 m0, s17
	v_lshl_add_u64 v[200:201], s[0:1], 0, v[136:137]
	ds_read_b128 v[168:171], v150 offset:32768
	ds_read_b128 v[172:175], v150 offset:33792
	ds_read_b128 v[176:179], v150 offset:34816
	ds_read_b128 v[180:183], v150 offset:35840
	ds_read_b128 v[184:187], v150 offset:36864
	ds_read_b128 v[188:191], v150 offset:37888
	ds_read_b128 v[192:195], v150 offset:38912
	ds_read_b128 v[196:199], v150 offset:39936
	global_load_lds_dwordx4 v[200:201], off
	v_lshl_add_u64 v[200:201], s[0:1], 0, v[132:133]
	s_mov_b32 m0, s34
	s_nop 0
	global_load_lds_dwordx4 v[200:201], off
	s_waitcnt lgkmcnt(8)
	s_waitcnt vmcnt(10)
	s_barrier
	s_waitcnt lgkmcnt(0)
	s_setprio 1
	s_waitcnt lgkmcnt(0)
	v_mfma_f32_16x16x32_bf16 v[126:129], v[152:155], v[168:171], v[126:129]
	v_mfma_f32_16x16x32_bf16 v[122:125], v[160:163], v[168:171], v[122:125]
	v_mfma_f32_16x16x32_bf16 v[118:121], v[152:155], v[176:179], v[118:121]
	v_mfma_f32_16x16x32_bf16 v[110:113], v[160:163], v[176:179], v[110:113]
	v_mfma_f32_16x16x32_bf16 v[102:105], v[152:155], v[184:187], v[102:105]
	v_mfma_f32_16x16x32_bf16 v[94:97], v[160:163], v[184:187], v[94:97]
	v_mfma_f32_16x16x32_bf16 v[86:89], v[152:155], v[192:195], v[86:89]
	v_mfma_f32_16x16x32_bf16 v[78:81], v[160:163], v[192:195], v[78:81]
	v_mfma_f32_16x16x32_bf16 v[126:129], v[156:159], v[172:175], v[126:129]
	v_mfma_f32_16x16x32_bf16 v[122:125], v[164:167], v[172:175], v[122:125]
	v_mfma_f32_16x16x32_bf16 v[118:121], v[156:159], v[180:183], v[118:121]
	v_mfma_f32_16x16x32_bf16 v[110:113], v[164:167], v[180:183], v[110:113]
	v_mfma_f32_16x16x32_bf16 v[102:105], v[156:159], v[188:191], v[102:105]
	v_mfma_f32_16x16x32_bf16 v[94:97], v[164:167], v[188:191], v[94:97]
	v_mfma_f32_16x16x32_bf16 v[86:89], v[156:159], v[196:199], v[86:89]
	v_mfma_f32_16x16x32_bf16 v[78:81], v[164:167], v[196:199], v[78:81]
	s_setprio 0
	s_barrier
	s_add_i32 s30, 0, 0x1c000
	s_add_i32 s0, s50, s9
	v_add_u32_e32 v212, s30, v148
	v_lshl_add_u64 v[216:217], v[216:217], 0, s[14:15]
	s_mov_b32 m0, s0
	ds_read_b128 v[200:203], v212
	ds_read_b128 v[204:207], v212 offset:1024
	ds_read_b128 v[208:211], v212 offset:2048
	ds_read_b128 v[212:215], v212 offset:3072
	global_load_lds_dwordx4 v[216:217], off
	v_lshl_add_u64 v[216:217], v[218:219], 0, s[14:15]
	s_add_i32 m0, s0, 0x2000
	s_nop 0
	global_load_lds_dwordx4 v[216:217], off
	s_waitcnt vmcnt(10)
	s_barrier
	s_waitcnt lgkmcnt(0)
	s_setprio 1
	s_waitcnt lgkmcnt(0)
	v_mfma_f32_16x16x32_bf16 v[114:117], v[200:203], v[168:171], v[114:117]
	v_mfma_f32_16x16x32_bf16 v[106:109], v[208:211], v[168:171], v[106:109]
	v_mfma_f32_16x16x32_bf16 v[98:101], v[200:203], v[176:179], v[98:101]
	v_mfma_f32_16x16x32_bf16 v[90:93], v[208:211], v[176:179], v[90:93]
	v_mfma_f32_16x16x32_bf16 v[82:85], v[200:203], v[184:187], v[82:85]
	v_mfma_f32_16x16x32_bf16 v[74:77], v[208:211], v[184:187], v[74:77]
	v_mfma_f32_16x16x32_bf16 v[70:73], v[200:203], v[192:195], v[70:73]
	v_mfma_f32_16x16x32_bf16 v[66:69], v[208:211], v[192:195], v[66:69]
	v_mfma_f32_16x16x32_bf16 v[114:117], v[204:207], v[172:175], v[114:117]
	v_mfma_f32_16x16x32_bf16 v[106:109], v[212:215], v[172:175], v[106:109]
	v_mfma_f32_16x16x32_bf16 v[98:101], v[204:207], v[180:183], v[98:101]
	v_mfma_f32_16x16x32_bf16 v[90:93], v[212:215], v[180:183], v[90:93]
	v_mfma_f32_16x16x32_bf16 v[82:85], v[204:207], v[188:191], v[82:85]
	v_mfma_f32_16x16x32_bf16 v[74:77], v[212:215], v[188:191], v[74:77]
	v_mfma_f32_16x16x32_bf16 v[70:73], v[204:207], v[196:199], v[70:73]
	v_mfma_f32_16x16x32_bf16 v[66:69], v[212:215], v[196:199], v[66:69]
	s_setprio 0
	s_mov_b32 m0, s40
	v_lshl_add_u64 v[216:217], v[220:221], 0, s[14:15]
	s_barrier
	ds_read_b128 v[168:171], v150 offset:49152
	ds_read_b128 v[172:175], v150 offset:50176
	ds_read_b128 v[176:179], v150 offset:51200
	ds_read_b128 v[180:183], v150 offset:52224
	ds_read_b128 v[184:187], v150 offset:53248
	ds_read_b128 v[188:191], v150 offset:54272
	ds_read_b128 v[192:195], v150 offset:55296
	ds_read_b128 v[196:199], v150 offset:56320
	global_load_lds_dwordx4 v[216:217], off
	v_lshl_add_u64 v[216:217], v[222:223], 0, s[14:15]
	s_mov_b32 m0, s41
	s_nop 0
	global_load_lds_dwordx4 v[216:217], off
	s_waitcnt vmcnt(10)
	s_barrier
	s_waitcnt lgkmcnt(0)
	s_setprio 1
	s_waitcnt lgkmcnt(0)
	v_mfma_f32_16x16x32_bf16 v[62:65], v[152:155], v[168:171], v[62:65]
	v_mfma_f32_16x16x32_bf16 v[58:61], v[160:163], v[168:171], v[58:61]
	v_mfma_f32_16x16x32_bf16 v[54:57], v[152:155], v[176:179], v[54:57]
	v_mfma_f32_16x16x32_bf16 v[50:53], v[160:163], v[176:179], v[50:53]
	v_mfma_f32_16x16x32_bf16 v[38:41], v[152:155], v[184:187], v[38:41]
	v_mfma_f32_16x16x32_bf16 v[34:37], v[160:163], v[184:187], v[34:37]
	v_mfma_f32_16x16x32_bf16 v[22:25], v[152:155], v[192:195], v[22:25]
	v_mfma_f32_16x16x32_bf16 v[18:21], v[160:163], v[192:195], v[18:21]
	v_mfma_f32_16x16x32_bf16 v[62:65], v[156:159], v[172:175], v[62:65]
	v_mfma_f32_16x16x32_bf16 v[58:61], v[164:167], v[172:175], v[58:61]
	v_mfma_f32_16x16x32_bf16 v[54:57], v[156:159], v[180:183], v[54:57]
	v_mfma_f32_16x16x32_bf16 v[50:53], v[164:167], v[180:183], v[50:53]
	v_mfma_f32_16x16x32_bf16 v[38:41], v[156:159], v[188:191], v[38:41]
	v_mfma_f32_16x16x32_bf16 v[34:37], v[164:167], v[188:191], v[34:37]
	v_mfma_f32_16x16x32_bf16 v[22:25], v[156:159], v[196:199], v[22:25]
	v_mfma_f32_16x16x32_bf16 v[18:21], v[164:167], v[196:199], v[18:21]
	s_setprio 0
	s_barrier
	s_add_u32 s0, s28, 0x40080
	s_addc_u32 s1, s29, 0
	s_add_i32 s28, s30, s9
	v_lshl_add_u64 v[152:153], s[0:1], 0, v[134:135]
	s_mov_b32 m0, s28
	s_nop 0
	global_load_lds_dwordx4 v[152:153], off
	v_lshl_add_u64 v[152:153], s[0:1], 0, v[130:131]
	s_add_i32 m0, s28, 0x2000
	s_nop 0
	global_load_lds_dwordx4 v[152:153], off
	s_waitcnt vmcnt(10)
	s_barrier
	s_setprio 1
	v_mfma_f32_16x16x32_bf16 v[46:49], v[200:203], v[168:171], v[46:49]
	v_mfma_f32_16x16x32_bf16 v[42:45], v[208:211], v[168:171], v[42:45]
	v_mfma_f32_16x16x32_bf16 v[30:33], v[200:203], v[176:179], v[30:33]
	v_mfma_f32_16x16x32_bf16 v[26:29], v[208:211], v[176:179], v[26:29]
	v_mfma_f32_16x16x32_bf16 v[14:17], v[200:203], v[184:187], v[14:17]
	v_mfma_f32_16x16x32_bf16 v[10:13], v[208:211], v[184:187], v[10:13]
	v_mfma_f32_16x16x32_bf16 v[6:9], v[200:203], v[192:195], v[6:9]
	v_mfma_f32_16x16x32_bf16 v[2:5], v[208:211], v[192:195], v[2:5]
	v_mfma_f32_16x16x32_bf16 v[46:49], v[204:207], v[172:175], v[46:49]
	v_mfma_f32_16x16x32_bf16 v[42:45], v[212:215], v[172:175], v[42:45]
	v_mfma_f32_16x16x32_bf16 v[30:33], v[204:207], v[180:183], v[30:33]
	v_mfma_f32_16x16x32_bf16 v[26:29], v[212:215], v[180:183], v[26:29]
	v_mfma_f32_16x16x32_bf16 v[14:17], v[204:207], v[188:191], v[14:17]
	v_mfma_f32_16x16x32_bf16 v[10:13], v[212:215], v[188:191], v[10:13]
	v_mfma_f32_16x16x32_bf16 v[6:9], v[204:207], v[196:199], v[6:9]
	v_mfma_f32_16x16x32_bf16 v[2:5], v[212:215], v[196:199], v[2:5]
	s_setprio 0
	s_add_i32 s49, s49, 2
	s_add_u32 s47, s47, 0x100
	s_addc_u32 s48, s48, 0
	s_add_u32 s26, s26, 0x100
	s_addc_u32 s27, s27, 0
	s_cmp_gt_u32 s49, 13
	s_barrier
	s_cbranch_scc0 .LBB0_1513
	v_mov_b32_e32 v152, v146
	v_mov_b32_e32 v153, v147
	s_cmp_gt_i32 s44, 7
	s_cbranch_scc1 .LBB0_1505
	s_ashr_i32 s0, s44, 31
	s_lshr_b32 s0, s0, 30
	s_add_i32 s0, s44, s0
	s_ashr_i32 s0, s0, 2
	s_ashr_i32 s1, s0, 31
	s_lshl_b32 s19, s44, 8
	s_lshl_b64 s[26:27], s[0:1], 27
	s_add_u32 s26, s36, s26
	s_addc_u32 s27, s37, s27
	s_or_b32 s1, s19, s39
	s_lshl_b32 s0, s0, 10
	s_sub_i32 s0, s1, s0
	v_lshl_add_u32 v154, v153, 3, s0
	s_lshl_b32 s0, s16, 8
	s_add_i32 s0, s0, s38
	v_add_u32_e32 v156, s0, v152
	v_mov_b32_e32 v152, v156
	v_ashrrev_i32_e32 v155, 31, v154
	v_lshl_add_u64 v[154:155], v[154:155], 1, s[26:27]
	v_ashrrev_i32_e32 v153, 31, v152
	v_lshlrev_b64 v[152:153], 11, v[152:153]
	v_lshl_add_u64 v[152:153], v[154:155], 0, v[152:153]
	v_cvt_pk_bf16_f32 v126, v126, v127
	v_cvt_pk_bf16_f32 v127, v128, v129
	v_cvt_pk_bf16_f32 v128, v122, v123
	v_cvt_pk_bf16_f32 v129, v124, v125
	v_cvt_pk_bf16_f32 v114, v114, v115
	v_cvt_pk_bf16_f32 v115, v116, v117
	v_cvt_pk_bf16_f32 v116, v106, v107
	v_cvt_pk_bf16_f32 v117, v108, v109
	v_add_u32_e32 v106, 16, v156
	flat_store_dwordx4 v[152:153], v[126:129] nt
	flat_store_dwordx4 v[152:153], v[114:117] offset:256 nt
	v_cvt_pk_bf16_f32 v108, v110, v111
	v_ashrrev_i32_e32 v107, 31, v106
	v_lshlrev_b64 v[106:107], 11, v[106:107]
	v_lshl_add_u64 v[114:115], v[154:155], 0, v[106:107]
	v_cvt_pk_bf16_f32 v106, v118, v119
	v_cvt_pk_bf16_f32 v107, v120, v121
	v_cvt_pk_bf16_f32 v109, v112, v113
	v_cvt_pk_bf16_f32 v98, v98, v99
	v_cvt_pk_bf16_f32 v99, v100, v101
	v_cvt_pk_bf16_f32 v100, v90, v91
	v_cvt_pk_bf16_f32 v101, v92, v93
	v_add_u32_e32 v90, 32, v156
	flat_store_dwordx4 v[114:115], v[106:109] nt
	flat_store_dwordx4 v[114:115], v[98:101] offset:256 nt
	v_cvt_pk_bf16_f32 v92, v94, v95
	v_ashrrev_i32_e32 v91, 31, v90
	v_lshlrev_b64 v[90:91], 11, v[90:91]
	v_lshl_add_u64 v[98:99], v[154:155], 0, v[90:91]
	v_cvt_pk_bf16_f32 v90, v102, v103
	v_cvt_pk_bf16_f32 v91, v104, v105
	v_cvt_pk_bf16_f32 v93, v96, v97
	v_cvt_pk_bf16_f32 v82, v82, v83
	v_cvt_pk_bf16_f32 v83, v84, v85
	v_cvt_pk_bf16_f32 v84, v74, v75
	v_cvt_pk_bf16_f32 v85, v76, v77
	v_add_u32_e32 v74, 48, v156
	flat_store_dwordx4 v[98:99], v[90:93] nt
	flat_store_dwordx4 v[98:99], v[82:85] offset:256 nt
	v_cvt_pk_bf16_f32 v76, v78, v79
	v_ashrrev_i32_e32 v75, 31, v74
	v_lshlrev_b64 v[74:75], 11, v[74:75]
	v_lshl_add_u64 v[82:83], v[154:155], 0, v[74:75]
	v_cvt_pk_bf16_f32 v74, v86, v87
	v_cvt_pk_bf16_f32 v75, v88, v89
	v_cvt_pk_bf16_f32 v77, v80, v81
	v_cvt_pk_bf16_f32 v70, v70, v71
	v_cvt_pk_bf16_f32 v71, v72, v73
	v_cvt_pk_bf16_f32 v72, v66, v67
	v_cvt_pk_bf16_f32 v73, v68, v69
	v_add_u32_e32 v66, 0x80, v156
	flat_store_dwordx4 v[82:83], v[74:77] nt
	flat_store_dwordx4 v[82:83], v[70:73] offset:256 nt
	v_cvt_pk_bf16_f32 v62, v62, v63
	v_ashrrev_i32_e32 v67, 31, v66
	v_lshlrev_b64 v[66:67], 11, v[66:67]
	v_lshl_add_u64 v[66:67], v[154:155], 0, v[66:67]
	v_cvt_pk_bf16_f32 v63, v64, v65
	v_cvt_pk_bf16_f32 v64, v58, v59
	v_cvt_pk_bf16_f32 v65, v60, v61
	v_cvt_pk_bf16_f32 v46, v46, v47
	v_cvt_pk_bf16_f32 v47, v48, v49
	v_cvt_pk_bf16_f32 v48, v42, v43
	v_cvt_pk_bf16_f32 v49, v44, v45
	v_add_u32_e32 v42, 0x90, v156
	flat_store_dwordx4 v[66:67], v[62:65] nt
	flat_store_dwordx4 v[66:67], v[46:49] offset:256 nt
	v_cvt_pk_bf16_f32 v44, v50, v51
	v_ashrrev_i32_e32 v43, 31, v42
	v_lshlrev_b64 v[42:43], 11, v[42:43]
	v_lshl_add_u64 v[46:47], v[154:155], 0, v[42:43]
	v_cvt_pk_bf16_f32 v42, v54, v55
	v_cvt_pk_bf16_f32 v43, v56, v57
	v_cvt_pk_bf16_f32 v45, v52, v53
	v_cvt_pk_bf16_f32 v30, v30, v31
	v_cvt_pk_bf16_f32 v31, v32, v33
	v_cvt_pk_bf16_f32 v32, v26, v27
	v_cvt_pk_bf16_f32 v33, v28, v29
	v_add_u32_e32 v26, 0xa0, v156
	flat_store_dwordx4 v[46:47], v[42:45] nt
	flat_store_dwordx4 v[46:47], v[30:33] offset:256 nt
	v_cvt_pk_bf16_f32 v28, v34, v35
	v_ashrrev_i32_e32 v27, 31, v26
	v_lshlrev_b64 v[26:27], 11, v[26:27]
	v_lshl_add_u64 v[30:31], v[154:155], 0, v[26:27]
	v_cvt_pk_bf16_f32 v26, v38, v39
	v_cvt_pk_bf16_f32 v27, v40, v41
	v_cvt_pk_bf16_f32 v29, v36, v37
	v_cvt_pk_bf16_f32 v14, v14, v15
	v_cvt_pk_bf16_f32 v15, v16, v17
	v_cvt_pk_bf16_f32 v16, v10, v11
	v_cvt_pk_bf16_f32 v17, v12, v13
	v_add_u32_e32 v10, 0xb0, v156
	flat_store_dwordx4 v[30:31], v[26:29] nt
	flat_store_dwordx4 v[30:31], v[14:17] offset:256 nt
	v_cvt_pk_bf16_f32 v12, v18, v19
	v_ashrrev_i32_e32 v11, 31, v10
	v_lshlrev_b64 v[10:11], 11, v[10:11]
	v_lshl_add_u64 v[14:15], v[154:155], 0, v[10:11]
	v_cvt_pk_bf16_f32 v10, v22, v23
	v_cvt_pk_bf16_f32 v11, v24, v25
	v_cvt_pk_bf16_f32 v13, v20, v21
	v_cvt_pk_bf16_f32 v6, v6, v7
	v_cvt_pk_bf16_f32 v7, v8, v9
	v_cvt_pk_bf16_f32 v8, v2, v3
	v_cvt_pk_bf16_f32 v9, v4, v5
	flat_store_dwordx4 v[14:15], v[10:13] nt
	flat_store_dwordx4 v[14:15], v[6:9] offset:256 nt
	s_branch .LBB0_1505

.LBB0_1645:
	s_add_u32 s57, s48, s56
	s_addc_u32 s58, s49, 0
	s_add_u32 s59, s57, 0x100
	s_addc_u32 s60, s58, 0
	s_and_b64 s[0:1], s[54:55], exec
	s_cselect_b32 s61, s43, s60
	s_cselect_b32 s60, s83, s59
	s_add_u32 s0, s14, s56
	s_addc_u32 s1, s15, 0
	s_add_u32 s56, s0, 0x100
	s_addc_u32 s59, s1, 0
	s_and_b64 s[0:1], s[54:55], exec
	s_cselect_b32 s63, s41, s59
	s_cselect_b32 s62, s94, s56
	s_add_u32 s64, s57, 0x40080
	s_addc_u32 s65, s58, 0
	s_add_i32 s0, s85, s37
	s_add_i32 m0, s39, 0xc000
	s_add_i32 s71, s39, 0xe000
	s_add_i32 s70, s0, 0x2000
	s_add_u32 s58, s62, 0x10000
	s_addc_u32 s59, s63, 0
	s_add_i32 s1, s4, s37
	ds_read_b128 v[26:29], v225
	ds_read_b128 v[30:33], v225 offset:1024
	ds_read_b128 v[42:45], v225 offset:2048
	ds_read_b128 v[46:49], v225 offset:3072
	s_add_i32 s96, s1, 0x2000
	s_add_i32 s81, 0, 0x18000
	s_add_u32 s56, s60, 0x40000
	s_addc_u32 s57, s61, 0
	s_add_i32 s78, s81, s37
	s_add_i32 s79, 0, 0x1c000
	s_add_i32 s80, s78, 0x2000
	s_add_u32 s54, s62, 0x10080
	s_addc_u32 s55, s63, 0
	s_add_i32 vcc_hi, s79, s37
	s_add_i32 vcc_lo, vcc_hi, 0x2000
	v_lshl_add_u64 v[190:191], s[64:65], 0, v[160:161]
	ds_read_b128 v[146:149], v226
	ds_read_b128 v[150:153], v226 offset:1024
	ds_read_b128 v[166:169], v226 offset:2048
	ds_read_b128 v[170:173], v226 offset:3072
	ds_read_b128 v[174:177], v226 offset:4096
	ds_read_b128 v[178:181], v226 offset:5120
	ds_read_b128 v[182:185], v226 offset:6144
	ds_read_b128 v[186:189], v226 offset:7168
	global_load_lds_dwordx4 v[190:191], off
	v_lshl_add_u64 v[190:191], s[64:65], 0, v[156:157]
	s_mov_b32 m0, s71
	s_nop 0
	global_load_lds_dwordx4 v[190:191], off
	s_waitcnt lgkmcnt(8)
	s_waitcnt vmcnt(10)
	s_barrier
	s_waitcnt lgkmcnt(0)
	s_setprio 1
	s_waitcnt lgkmcnt(0)
	v_mfma_f32_16x16x32_bf16 v[142:145], v[26:29], v[146:149], v[142:145]
	v_mfma_f32_16x16x32_bf16 v[134:137], v[42:45], v[146:149], v[134:137]
	v_mfma_f32_16x16x32_bf16 v[126:129], v[26:29], v[166:169], v[126:129]
	v_mfma_f32_16x16x32_bf16 v[118:121], v[42:45], v[166:169], v[118:121]
	v_mfma_f32_16x16x32_bf16 v[110:113], v[26:29], v[174:177], v[110:113]
	v_mfma_f32_16x16x32_bf16 v[102:105], v[42:45], v[174:177], v[102:105]
	v_mfma_f32_16x16x32_bf16 v[94:97], v[26:29], v[182:185], v[94:97]
	v_mfma_f32_16x16x32_bf16 v[86:89], v[42:45], v[182:185], v[86:89]
	v_mfma_f32_16x16x32_bf16 v[142:145], v[30:33], v[150:153], v[142:145]
	v_mfma_f32_16x16x32_bf16 v[134:137], v[46:49], v[150:153], v[134:137]
	v_mfma_f32_16x16x32_bf16 v[126:129], v[30:33], v[170:173], v[126:129]
	v_mfma_f32_16x16x32_bf16 v[118:121], v[46:49], v[170:173], v[118:121]
	v_mfma_f32_16x16x32_bf16 v[110:113], v[30:33], v[178:181], v[110:113]
	v_mfma_f32_16x16x32_bf16 v[102:105], v[46:49], v[178:181], v[102:105]
	v_mfma_f32_16x16x32_bf16 v[94:97], v[30:33], v[186:189], v[94:97]
	v_mfma_f32_16x16x32_bf16 v[86:89], v[46:49], v[186:189], v[86:89]
	s_setprio 0
	s_barrier
	s_mov_b32 m0, s0
	v_lshl_add_u64 v[206:207], s[62:63], 0, v[158:159]
	ds_read_b128 v[190:193], v227
	ds_read_b128 v[194:197], v227 offset:1024
	ds_read_b128 v[198:201], v227 offset:2048
	ds_read_b128 v[202:205], v227 offset:3072
	global_load_lds_dwordx4 v[206:207], off
	v_lshl_add_u64 v[208:209], s[62:63], 0, v[154:155]
	s_mov_b32 m0, s70
	s_nop 0
	global_load_lds_dwordx4 v[208:209], off
	s_waitcnt vmcnt(10)
	s_barrier
	s_waitcnt lgkmcnt(0)
	s_setprio 1
	s_waitcnt lgkmcnt(0)
	v_mfma_f32_16x16x32_bf16 v[138:141], v[190:193], v[146:149], v[138:141]
	v_mfma_f32_16x16x32_bf16 v[130:133], v[198:201], v[146:149], v[130:133]
	v_mfma_f32_16x16x32_bf16 v[122:125], v[190:193], v[166:169], v[122:125]
	v_mfma_f32_16x16x32_bf16 v[114:117], v[198:201], v[166:169], v[114:117]
	v_mfma_f32_16x16x32_bf16 v[106:109], v[190:193], v[174:177], v[106:109]
	v_mfma_f32_16x16x32_bf16 v[98:101], v[198:201], v[174:177], v[98:101]
	v_mfma_f32_16x16x32_bf16 v[90:93], v[190:193], v[182:185], v[90:93]
	v_mfma_f32_16x16x32_bf16 v[82:85], v[198:201], v[182:185], v[82:85]
	v_mfma_f32_16x16x32_bf16 v[138:141], v[194:197], v[150:153], v[138:141]
	v_mfma_f32_16x16x32_bf16 v[130:133], v[202:205], v[150:153], v[130:133]
	v_mfma_f32_16x16x32_bf16 v[122:125], v[194:197], v[170:173], v[122:125]
	v_mfma_f32_16x16x32_bf16 v[114:117], v[202:205], v[170:173], v[114:117]
	v_mfma_f32_16x16x32_bf16 v[106:109], v[194:197], v[178:181], v[106:109]
	v_mfma_f32_16x16x32_bf16 v[98:101], v[202:205], v[178:181], v[98:101]
	v_mfma_f32_16x16x32_bf16 v[90:93], v[194:197], v[186:189], v[90:93]
	v_mfma_f32_16x16x32_bf16 v[82:85], v[202:205], v[186:189], v[82:85]
	s_setprio 0
	s_mov_b32 m0, s39
	v_lshl_add_u64 v[210:211], s[60:61], 0, v[160:161]
	s_barrier
	ds_read_b128 v[146:149], v226 offset:16384
	ds_read_b128 v[150:153], v226 offset:17408
	ds_read_b128 v[166:169], v226 offset:18432
	ds_read_b128 v[170:173], v226 offset:19456
	ds_read_b128 v[174:177], v226 offset:20480
	ds_read_b128 v[178:181], v226 offset:21504
	ds_read_b128 v[182:185], v226 offset:22528
	ds_read_b128 v[186:189], v226 offset:23552
	global_load_lds_dwordx4 v[210:211], off
	v_lshl_add_u64 v[212:213], s[60:61], 0, v[156:157]
	s_mov_b32 m0, s53
	s_nop 0
	global_load_lds_dwordx4 v[212:213], off
	s_waitcnt vmcnt(10)
	s_barrier
	s_waitcnt lgkmcnt(0)
	s_setprio 1
	s_waitcnt lgkmcnt(0)
	v_mfma_f32_16x16x32_bf16 v[78:81], v[26:29], v[146:149], v[78:81]
	v_mfma_f32_16x16x32_bf16 v[70:73], v[42:45], v[146:149], v[70:73]
	v_mfma_f32_16x16x32_bf16 v[62:65], v[26:29], v[166:169], v[62:65]
	v_mfma_f32_16x16x32_bf16 v[54:57], v[42:45], v[166:169], v[54:57]
	v_mfma_f32_16x16x32_bf16 v[38:41], v[26:29], v[174:177], v[38:41]
	v_mfma_f32_16x16x32_bf16 v[22:25], v[42:45], v[174:177], v[22:25]
	v_mfma_f32_16x16x32_bf16 v[14:17], v[26:29], v[182:185], v[14:17]
	v_mfma_f32_16x16x32_bf16 v[6:9], v[42:45], v[182:185], v[6:9]
	v_mfma_f32_16x16x32_bf16 v[78:81], v[30:33], v[150:153], v[78:81]
	v_mfma_f32_16x16x32_bf16 v[70:73], v[46:49], v[150:153], v[70:73]
	v_mfma_f32_16x16x32_bf16 v[62:65], v[30:33], v[170:173], v[62:65]
	v_mfma_f32_16x16x32_bf16 v[54:57], v[46:49], v[170:173], v[54:57]
	v_mfma_f32_16x16x32_bf16 v[38:41], v[30:33], v[178:181], v[38:41]
	v_mfma_f32_16x16x32_bf16 v[22:25], v[46:49], v[178:181], v[22:25]
	v_mfma_f32_16x16x32_bf16 v[14:17], v[30:33], v[186:189], v[14:17]
	v_mfma_f32_16x16x32_bf16 v[6:9], v[46:49], v[186:189], v[6:9]
	s_setprio 0
	s_barrier
	s_mov_b32 m0, s1
	v_lshl_add_u64 v[26:27], s[58:59], 0, v[158:159]
	global_load_lds_dwordx4 v[26:27], off
	v_lshl_add_u64 v[26:27], s[58:59], 0, v[154:155]
	s_mov_b32 m0, s96
	s_nop 0
	global_load_lds_dwordx4 v[26:27], off
	s_waitcnt vmcnt(10)
	s_barrier
	s_setprio 1
	v_mfma_f32_16x16x32_bf16 v[34:37], v[190:193], v[174:177], v[34:37]
	v_mfma_f32_16x16x32_bf16 v[18:21], v[198:201], v[174:177], v[18:21]
	v_mfma_f32_16x16x32_bf16 v[10:13], v[190:193], v[182:185], v[10:13]
	v_mfma_f32_16x16x32_bf16 v[2:5], v[198:201], v[182:185], v[2:5]
	v_mfma_f32_16x16x32_bf16 v[26:29], v[190:193], v[146:149], v[74:77]
	v_mfma_f32_16x16x32_bf16 v[30:33], v[198:201], v[146:149], v[66:69]
	v_mfma_f32_16x16x32_bf16 v[42:45], v[190:193], v[166:169], v[58:61]
	v_mfma_f32_16x16x32_bf16 v[46:49], v[198:201], v[166:169], v[50:53]
	v_mfma_f32_16x16x32_bf16 v[34:37], v[194:197], v[178:181], v[34:37]
	v_mfma_f32_16x16x32_bf16 v[18:21], v[202:205], v[178:181], v[18:21]
	v_mfma_f32_16x16x32_bf16 v[10:13], v[194:197], v[186:189], v[10:13]
	v_mfma_f32_16x16x32_bf16 v[2:5], v[202:205], v[186:189], v[2:5]
	v_mfma_f32_16x16x32_bf16 v[26:29], v[194:197], v[150:153], v[26:29]
	v_mfma_f32_16x16x32_bf16 v[30:33], v[202:205], v[150:153], v[30:33]
	v_mfma_f32_16x16x32_bf16 v[42:45], v[194:197], v[170:173], v[42:45]
	v_mfma_f32_16x16x32_bf16 v[46:49], v[202:205], v[170:173], v[46:49]
	s_setprio 0
	v_add_u32_e32 v74, s81, v224
	s_barrier
	ds_read_b128 v[50:53], v74
	ds_read_b128 v[58:61], v74 offset:1024
	ds_read_b128 v[66:69], v74 offset:2048
	ds_read_b128 v[74:77], v74 offset:3072
	s_mov_b32 m0, s66
	v_lshl_add_u64 v[190:191], s[56:57], 0, v[160:161]
	ds_read_b128 v[146:149], v226 offset:32768
	ds_read_b128 v[150:153], v226 offset:33792
	ds_read_b128 v[166:169], v226 offset:34816
	ds_read_b128 v[170:173], v226 offset:35840
	ds_read_b128 v[174:177], v226 offset:36864
	ds_read_b128 v[178:181], v226 offset:37888
	ds_read_b128 v[182:185], v226 offset:38912
	ds_read_b128 v[186:189], v226 offset:39936
	global_load_lds_dwordx4 v[190:191], off
	v_lshl_add_u64 v[190:191], s[56:57], 0, v[156:157]
	s_mov_b32 m0, s67
	s_nop 0
	global_load_lds_dwordx4 v[190:191], off
	s_waitcnt lgkmcnt(8)
	s_waitcnt vmcnt(10)
	s_barrier
	s_waitcnt lgkmcnt(0)
	s_setprio 1
	s_waitcnt lgkmcnt(0)
	v_mfma_f32_16x16x32_bf16 v[142:145], v[50:53], v[146:149], v[142:145]
	v_mfma_f32_16x16x32_bf16 v[134:137], v[66:69], v[146:149], v[134:137]
	v_mfma_f32_16x16x32_bf16 v[126:129], v[50:53], v[166:169], v[126:129]
	v_mfma_f32_16x16x32_bf16 v[118:121], v[66:69], v[166:169], v[118:121]
	v_mfma_f32_16x16x32_bf16 v[110:113], v[50:53], v[174:177], v[110:113]
	v_mfma_f32_16x16x32_bf16 v[102:105], v[66:69], v[174:177], v[102:105]
	v_mfma_f32_16x16x32_bf16 v[94:97], v[50:53], v[182:185], v[94:97]
	v_mfma_f32_16x16x32_bf16 v[86:89], v[66:69], v[182:185], v[86:89]
	v_mfma_f32_16x16x32_bf16 v[142:145], v[58:61], v[150:153], v[142:145]
	v_mfma_f32_16x16x32_bf16 v[134:137], v[74:77], v[150:153], v[134:137]
	v_mfma_f32_16x16x32_bf16 v[126:129], v[58:61], v[170:173], v[126:129]
	v_mfma_f32_16x16x32_bf16 v[118:121], v[74:77], v[170:173], v[118:121]
	v_mfma_f32_16x16x32_bf16 v[110:113], v[58:61], v[178:181], v[110:113]
	v_mfma_f32_16x16x32_bf16 v[102:105], v[74:77], v[178:181], v[102:105]
	v_mfma_f32_16x16x32_bf16 v[94:97], v[58:61], v[186:189], v[94:97]
	v_mfma_f32_16x16x32_bf16 v[86:89], v[74:77], v[186:189], v[86:89]
	s_setprio 0
	s_barrier
	s_mov_b32 m0, s78
	v_add_u32_e32 v202, s79, v224
	v_lshl_add_u64 v[206:207], v[206:207], 0, s[26:27]
	ds_read_b128 v[190:193], v202
	ds_read_b128 v[194:197], v202 offset:1024
	ds_read_b128 v[198:201], v202 offset:2048
	ds_read_b128 v[202:205], v202 offset:3072
	global_load_lds_dwordx4 v[206:207], off
	v_lshl_add_u64 v[206:207], v[208:209], 0, s[26:27]
	s_mov_b32 m0, s80
	s_nop 0
	global_load_lds_dwordx4 v[206:207], off
	s_waitcnt vmcnt(10)
	s_barrier
	s_waitcnt lgkmcnt(0)
	s_setprio 1
	s_waitcnt lgkmcnt(0)
	v_mfma_f32_16x16x32_bf16 v[138:141], v[190:193], v[146:149], v[138:141]
	v_mfma_f32_16x16x32_bf16 v[130:133], v[198:201], v[146:149], v[130:133]
	v_mfma_f32_16x16x32_bf16 v[122:125], v[190:193], v[166:169], v[122:125]
	v_mfma_f32_16x16x32_bf16 v[114:117], v[198:201], v[166:169], v[114:117]
	v_mfma_f32_16x16x32_bf16 v[106:109], v[190:193], v[174:177], v[106:109]
	v_mfma_f32_16x16x32_bf16 v[98:101], v[198:201], v[174:177], v[98:101]
	v_mfma_f32_16x16x32_bf16 v[90:93], v[190:193], v[182:185], v[90:93]
	v_mfma_f32_16x16x32_bf16 v[82:85], v[198:201], v[182:185], v[82:85]
	v_mfma_f32_16x16x32_bf16 v[138:141], v[194:197], v[150:153], v[138:141]
	v_mfma_f32_16x16x32_bf16 v[130:133], v[202:205], v[150:153], v[130:133]
	v_mfma_f32_16x16x32_bf16 v[122:125], v[194:197], v[170:173], v[122:125]
	v_mfma_f32_16x16x32_bf16 v[114:117], v[202:205], v[170:173], v[114:117]
	v_mfma_f32_16x16x32_bf16 v[106:109], v[194:197], v[178:181], v[106:109]
	v_mfma_f32_16x16x32_bf16 v[98:101], v[202:205], v[178:181], v[98:101]
	v_mfma_f32_16x16x32_bf16 v[90:93], v[194:197], v[186:189], v[90:93]
	v_mfma_f32_16x16x32_bf16 v[82:85], v[202:205], v[186:189], v[82:85]
	s_setprio 0
	s_mov_b32 m0, s6
	v_lshl_add_u64 v[206:207], v[210:211], 0, s[26:27]
	s_barrier
	ds_read_b128 v[146:149], v226 offset:49152
	ds_read_b128 v[150:153], v226 offset:50176
	ds_read_b128 v[166:169], v226 offset:51200
	ds_read_b128 v[170:173], v226 offset:52224
	ds_read_b128 v[174:177], v226 offset:53248
	ds_read_b128 v[178:181], v226 offset:54272
	ds_read_b128 v[182:185], v226 offset:55296
	ds_read_b128 v[186:189], v226 offset:56320
	global_load_lds_dwordx4 v[206:207], off
	v_lshl_add_u64 v[206:207], v[212:213], 0, s[26:27]
	s_mov_b32 m0, s7
	s_nop 0
	global_load_lds_dwordx4 v[206:207], off
	s_waitcnt vmcnt(10)
	s_barrier
	s_waitcnt lgkmcnt(0)
	s_setprio 1
	s_waitcnt lgkmcnt(0)
	v_mfma_f32_16x16x32_bf16 v[78:81], v[50:53], v[146:149], v[78:81]
	v_mfma_f32_16x16x32_bf16 v[70:73], v[66:69], v[146:149], v[70:73]
	v_mfma_f32_16x16x32_bf16 v[62:65], v[50:53], v[166:169], v[62:65]
	v_mfma_f32_16x16x32_bf16 v[54:57], v[66:69], v[166:169], v[54:57]
	v_mfma_f32_16x16x32_bf16 v[38:41], v[50:53], v[174:177], v[38:41]
	v_mfma_f32_16x16x32_bf16 v[22:25], v[66:69], v[174:177], v[22:25]
	v_mfma_f32_16x16x32_bf16 v[14:17], v[50:53], v[182:185], v[14:17]
	v_mfma_f32_16x16x32_bf16 v[6:9], v[66:69], v[182:185], v[6:9]
	v_mfma_f32_16x16x32_bf16 v[78:81], v[58:61], v[150:153], v[78:81]
	v_mfma_f32_16x16x32_bf16 v[70:73], v[74:77], v[150:153], v[70:73]
	v_mfma_f32_16x16x32_bf16 v[62:65], v[58:61], v[170:173], v[62:65]
	v_mfma_f32_16x16x32_bf16 v[54:57], v[74:77], v[170:173], v[54:57]
	v_mfma_f32_16x16x32_bf16 v[38:41], v[58:61], v[178:181], v[38:41]
	v_mfma_f32_16x16x32_bf16 v[22:25], v[74:77], v[178:181], v[22:25]
	v_mfma_f32_16x16x32_bf16 v[14:17], v[58:61], v[186:189], v[14:17]
	v_mfma_f32_16x16x32_bf16 v[6:9], v[74:77], v[186:189], v[6:9]
	s_setprio 0
	s_barrier
	s_mov_b32 m0, vcc_hi
	v_lshl_add_u64 v[50:51], s[54:55], 0, v[158:159]
	global_load_lds_dwordx4 v[50:51], off
	v_lshl_add_u64 v[50:51], s[54:55], 0, v[154:155]
	s_mov_b32 m0, vcc_lo
	s_nop 0
	global_load_lds_dwordx4 v[50:51], off
	s_waitcnt vmcnt(10)
	s_barrier
	s_setprio 1
	v_mfma_f32_16x16x32_bf16 v[26:29], v[190:193], v[146:149], v[26:29]
	v_mfma_f32_16x16x32_bf16 v[74:77], v[194:197], v[150:153], v[26:29]
	v_mfma_f32_16x16x32_bf16 v[26:29], v[198:201], v[146:149], v[30:33]
	v_mfma_f32_16x16x32_bf16 v[66:69], v[202:205], v[150:153], v[26:29]
	v_mfma_f32_16x16x32_bf16 v[26:29], v[190:193], v[166:169], v[42:45]
	v_mfma_f32_16x16x32_bf16 v[58:61], v[194:197], v[170:173], v[26:29]
	v_mfma_f32_16x16x32_bf16 v[26:29], v[198:201], v[166:169], v[46:49]
	v_mfma_f32_16x16x32_bf16 v[50:53], v[202:205], v[170:173], v[26:29]
	v_mfma_f32_16x16x32_bf16 v[26:29], v[190:193], v[174:177], v[34:37]
	v_mfma_f32_16x16x32_bf16 v[18:21], v[198:201], v[174:177], v[18:21]
	v_mfma_f32_16x16x32_bf16 v[10:13], v[190:193], v[182:185], v[10:13]
	v_mfma_f32_16x16x32_bf16 v[2:5], v[198:201], v[182:185], v[2:5]
	v_mfma_f32_16x16x32_bf16 v[34:37], v[194:197], v[178:181], v[26:29]
	v_mfma_f32_16x16x32_bf16 v[18:21], v[202:205], v[178:181], v[18:21]
	v_mfma_f32_16x16x32_bf16 v[10:13], v[194:197], v[186:189], v[10:13]
	v_mfma_f32_16x16x32_bf16 v[2:5], v[202:205], v[186:189], v[2:5]
	s_setprio 0
	s_movk_i32 s56, 0x100
	s_andn2_b64 vcc, exec, s[50:51]
	s_mov_b64 s[54:55], -1
	s_mov_b64 s[50:51], 0
	s_barrier
	s_cbranch_vccz .LBB0_1645
	s_lshl_b32 s0, s82, 7
	s_and_b32 s1, s0, 0x380
	v_mov_b32_e32 v167, v222
	v_mov_b32_e32 v26, v223
	s_or_b32 s1, s1, s11
	s_cmp_lt_u32 s82, 8
	v_lshl_add_u32 v166, v26, 3, s1
	s_mov_b32 s1, 0x32100000
	s_cselect_b32 s1, s1, 0x1a100000
	s_cselect_b32 s49, s9, s17
	s_cselect_b32 s48, s8, s16
	s_add_u32 s50, s18, s1
	s_addc_u32 s51, s19, 0
	s_and_b32 s0, s0, 0xfffffc00
	v_add_u32_e32 v26, s0, v166
	s_load_dwordx2 s[0:1], s[20:21], 0x78
	v_ashrrev_i32_e32 v27, 31, v26
	v_readlane_b32 s56, v254, 5
	v_lshlrev_b64 v[146:147], 2, v[26:27]
	v_readlane_b32 s57, v254, 6
	v_readlane_b32 s58, v254, 7
	v_readlane_b32 s59, v254, 8
	s_waitcnt lgkmcnt(0)
	v_lshl_add_u64 v[26:27], s[0:1], 0, v[146:147]
	v_lshl_add_u64 v[42:43], s[56:57], 0, v[146:147]
	v_lshl_add_u64 v[150:151], s[58:59], 0, v[146:147]
	global_load_dwordx4 v[30:33], v[26:27], off offset:16
	global_load_dwordx4 v[46:49], v[26:27], off
	s_nop 0
	global_load_dwordx4 v[26:29], v[42:43], off offset:16
	s_nop 0
	global_load_dwordx4 v[42:45], v[42:43], off
	s_nop 0
	global_load_dwordx4 v[146:149], v[150:151], off offset:16
	s_nop 0
	global_load_dwordx4 v[150:153], v[150:151], off
	s_lshl_b32 s0, s52, 8
	s_add_i32 s0, s0, s10
	s_waitcnt vmcnt(0)
	v_add_f32_e32 v134, v134, v30
	v_add_f32_e32 v142, v142, v46
	v_add_f32_e32 v138, v138, v42
	v_max_f32_e32 v168, v150, v150
	v_mul_f32_e64 v150, |v150|, s5
	v_exp_f32_e32 v232, v150
	v_mul_f32_e32 v138, 0xbfb8aa3b, v138
	v_exp_f32_e32 v138, v138
	v_mul_f32_e32 v142, 0xbfb8aa3b, v142
	v_add_f32_e32 v172, 1.0, v232
	v_add_f32_e32 v150, -1.0, v172
	v_sub_f32_e32 v169, v150, v172
	v_add_f32_e32 v169, 1.0, v169
	v_sub_f32_e32 v150, v232, v150
	v_add_f32_e32 v174, v150, v169
	v_max_f32_e32 v150, v151, v151
	v_min_f32_e32 v169, 0, v150
	v_mul_f32_e64 v150, |v151|, s5
	v_exp_f32_e32 v233, v150
	v_cvt_f64_f32_e32 v[170:171], v172
	v_frexp_exp_i32_f64_e32 v170, v[170:171]
	v_frexp_mant_f32_e32 v173, v172
	v_add_f32_e32 v171, 1.0, v233
	v_add_f32_e32 v150, -1.0, v171
	v_sub_f32_e32 v151, v150, v171
	v_add_f32_e32 v151, 1.0, v151
	v_sub_f32_e32 v150, v233, v150
	v_add_f32_e32 v175, v150, v151
	v_frexp_mant_f32_e32 v176, v171
	v_cvt_f64_f32_e32 v[150:151], v171
	v_cmp_gt_f32_e32 vcc, s72, v173
	v_frexp_exp_i32_f64_e32 v150, v[150:151]
	v_cmp_gt_f32_e64 s[14:15], s72, v176
	v_subbrev_co_u32_e32 v176, vcc, 0, v170, vcc
	s_nop 0
	v_subbrev_co_u32_e64 v173, s[14:15], 0, v150, s[14:15]
	v_sub_u32_e32 v151, 0, v176
	v_ldexp_f32 v150, v172, v151
	v_sub_u32_e32 v172, 0, v173
	v_ldexp_f32 v170, v174, v151
	v_ldexp_f32 v151, v171, v172
	v_ldexp_f32 v171, v175, v172
	v_pk_add_f32 v[174:175], v[150:151], 1.0 op_sel_hi:[1,0]
	v_pk_add_f32 v[184:185], v[150:151], -1.0 op_sel_hi:[1,0]
	v_pk_add_f32 v[178:179], v[174:175], -1.0 op_sel_hi:[1,0]
	v_pk_add_f32 v[186:187], v[184:185], 1.0 op_sel_hi:[1,0]
	v_pk_add_f32 v[178:179], v[150:151], v[178:179] neg_lo:[0,1] neg_hi:[0,1]
	v_pk_add_f32 v[150:151], v[150:151], v[186:187] neg_lo:[0,1] neg_hi:[0,1]
	v_pk_add_f32 v[178:179], v[170:171], v[178:179]
	v_pk_add_f32 v[150:151], v[170:171], v[150:151]
	v_pk_add_f32 v[180:181], v[174:175], v[178:179]
	v_pk_add_f32 v[170:171], v[184:185], v[150:151]
	v_rcp_f32_e32 v182, v180
	v_rcp_f32_e32 v183, v181
	v_pk_add_f32 v[174:175], v[180:181], v[174:175] neg_lo:[0,1] neg_hi:[0,1]
	v_pk_add_f32 v[184:185], v[170:171], v[184:185] neg_lo:[0,1] neg_hi:[0,1]
	v_pk_add_f32 v[174:175], v[178:179], v[174:175] neg_lo:[0,1] neg_hi:[0,1]
	v_pk_mul_f32 v[186:187], v[170:171], v[182:183]
	v_pk_add_f32 v[150:151], v[150:151], v[184:185] neg_lo:[0,1] neg_hi:[0,1]
	v_pk_mul_f32 v[178:179], v[180:181], v[186:187]
	s_mov_b32 s14, 0x3ecc95a3
	v_pk_fma_f32 v[184:185], v[186:187], v[180:181], v[178:179] neg_lo:[0,0,1] neg_hi:[0,0,1]
	v_cvt_f32_i32_e32 v177, v173
	v_pk_fma_f32 v[184:185], v[186:187], v[174:175], v[184:185]
	v_cvt_f32_i32_e32 v176, v176
	v_pk_add_f32 v[188:189], v[178:179], v[184:185]
	v_add_f32_e32 v138, 1.0, v138
	v_pk_add_f32 v[190:191], v[170:171], v[188:189] neg_lo:[0,1] neg_hi:[0,1]
	v_pk_add_f32 v[178:179], v[188:189], v[178:179] neg_lo:[0,1] neg_hi:[0,1]
	v_pk_add_f32 v[170:171], v[170:171], v[190:191] neg_lo:[0,1] neg_hi:[0,1]
	v_rcp_f32_e32 v249, v138
	v_pk_add_f32 v[170:171], v[170:171], v[188:189] neg_lo:[0,1] neg_hi:[0,1]
	v_add_f32_e32 v138, v143, v47
	v_pk_add_f32 v[150:151], v[150:151], v[170:171]
	v_pk_add_f32 v[170:171], v[178:179], v[184:185] neg_lo:[0,1] neg_hi:[0,1]
	v_mul_f32_e32 v138, 0xbfb8aa3b, v138
	v_pk_add_f32 v[150:151], v[170:171], v[150:151]
	v_exp_f32_e32 v138, v138
	v_pk_add_f32 v[170:171], v[190:191], v[150:151]
	v_exp_f32_e32 v142, v142
	v_pk_mul_f32 v[178:179], v[182:183], v[170:171]
	v_pk_add_f32 v[190:191], v[190:191], v[170:171] neg_lo:[0,1] neg_hi:[0,1]
	v_pk_mul_f32 v[184:185], v[180:181], v[178:179]
	v_pk_add_f32 v[150:151], v[150:151], v[190:191]
	v_pk_fma_f32 v[180:181], v[178:179], v[180:181], v[184:185] neg_lo:[0,0,1] neg_hi:[0,0,1]
	v_pk_add_f32 v[196:197], v[186:187], v[178:179]
	v_pk_fma_f32 v[174:175], v[178:179], v[174:175], v[180:181]
	v_add_f32_e32 v138, 1.0, v138
	v_pk_add_f32 v[180:181], v[184:185], v[174:175]
	v_rcp_f32_e32 v143, v138
	v_pk_add_f32 v[192:193], v[170:171], v[180:181] neg_lo:[0,1] neg_hi:[0,1]
	v_pk_add_f32 v[188:189], v[180:181], v[184:185] neg_lo:[0,1] neg_hi:[0,1]
	v_pk_add_f32 v[194:195], v[170:171], v[192:193] neg_lo:[0,1] neg_hi:[0,1]
	v_mov_b32_e32 v170, v181
	v_mov_b32_e32 v184, v185
	v_mov_b32_e32 v185, v193
	v_pk_add_f32 v[194:195], v[194:195], v[180:181] neg_lo:[0,1] neg_hi:[0,1]
	v_pk_add_f32 v[170:171], v[170:171], v[184:185] neg_lo:[0,1] neg_hi:[0,1]
	v_mov_b32_e32 v180, v175
	v_pk_add_f32 v[170:171], v[170:171], v[180:181] neg_lo:[0,1] neg_hi:[0,1]
	v_pk_add_f32 v[188:189], v[188:189], v[174:175] neg_lo:[0,1] neg_hi:[0,1]
	v_mov_b32_e32 v195, v171
	v_pk_add_f32 v[150:151], v[150:151], v[194:195]
	v_mov_b32_e32 v189, v170
	v_pk_add_f32 v[150:151], v[188:189], v[150:151]
	v_pk_add_f32 v[170:171], v[196:197], v[186:187] neg_lo:[0,1] neg_hi:[0,1]
	v_pk_add_f32 v[150:151], v[192:193], v[150:151]
	v_pk_add_f32 v[170:171], v[178:179], v[170:171] neg_lo:[0,1] neg_hi:[0,1]
	v_pk_mul_f32 v[150:151], v[182:183], v[150:151]
	v_pk_mul_f32 v[182:183], v[176:177], s[34:35] op_sel_hi:[1,0]
	v_pk_add_f32 v[150:151], v[170:171], v[150:151]
	v_pk_fma_f32 v[184:185], v[176:177], s[34:35], v[182:183] op_sel_hi:[1,0,1] neg_lo:[0,0,1] neg_hi:[0,0,1]
	v_pk_add_f32 v[174:175], v[196:197], v[150:151]
	v_pk_fma_f32 v[184:185], v[176:177], s[36:37], v[184:185] op_sel_hi:[1,0,1]
	v_pk_add_f32 v[170:171], v[174:175], v[196:197] neg_lo:[0,1] neg_hi:[0,1]
	v_pk_mul_f32 v[178:179], v[174:175], v[174:175]
	v_pk_add_f32 v[170:171], v[150:151], v[170:171] neg_lo:[0,1] neg_hi:[0,1]
	v_mov_b64_e32 v[150:151], s[14:15]
	v_pk_fma_f32 v[180:181], v[178:179], s[28:29], v[150:151] op_sel_hi:[1,0,0]
	v_ldexp_f32 v172, v174, 1
	v_pk_fma_f32 v[180:181], v[178:179], v[180:181], s[30:31] op_sel_hi:[1,1,0]
	v_ldexp_f32 v173, v175, 1
	v_pk_mul_f32 v[174:175], v[174:175], v[178:179]
	v_ldexp_f32 v170, v170, 1
	v_pk_mul_f32 v[174:175], v[174:175], v[180:181]
	v_ldexp_f32 v171, v171, 1
	v_pk_add_f32 v[178:179], v[172:173], v[174:175]
	v_pk_add_f32 v[176:177], v[182:183], v[184:185]
	v_pk_add_f32 v[172:173], v[178:179], v[172:173] neg_lo:[0,1] neg_hi:[0,1]
	v_pk_add_f32 v[182:183], v[176:177], v[182:183] neg_lo:[0,1] neg_hi:[0,1]
	v_pk_add_f32 v[172:173], v[174:175], v[172:173] neg_lo:[0,1] neg_hi:[0,1]
	v_pk_add_f32 v[182:183], v[184:185], v[182:183] neg_lo:[0,1] neg_hi:[0,1]
	v_pk_add_f32 v[170:171], v[170:171], v[172:173]
	v_add_f32_e32 v138, v139, v43
	v_pk_add_f32 v[190:191], v[178:179], v[170:171]
	v_mul_f32_e32 v138, 0xbfb8aa3b, v138
	v_pk_add_f32 v[172:173], v[190:191], v[178:179] neg_lo:[0,1] neg_hi:[0,1]
	v_exp_f32_e32 v138, v138
	v_pk_add_f32 v[170:171], v[170:171], v[172:173] neg_lo:[0,1] neg_hi:[0,1]
	v_add_f32_e32 v142, 1.0, v142
	v_pk_add_f32 v[184:185], v[182:183], v[170:171]
	v_add_f32_e32 v138, 1.0, v138
	v_pk_add_f32 v[172:173], v[184:185], v[182:183] neg_lo:[0,1] neg_hi:[0,1]
	v_rcp_f32_e32 v250, v138
	v_pk_add_f32 v[188:189], v[170:171], v[172:173] neg_lo:[0,1] neg_hi:[0,1]
	v_max_f32_e32 v170, v152, v152
	v_mul_f32_e64 v152, |v152|, s5
	v_exp_f32_e32 v236, v152
	v_pk_add_f32 v[174:175], v[184:185], v[172:173] neg_lo:[0,1] neg_hi:[0,1]
	v_min_f32_e32 v180, 0, v170
	v_pk_add_f32 v[186:187], v[182:183], v[174:175] neg_lo:[0,1] neg_hi:[0,1]
	v_add_f32_e32 v172, 1.0, v236
	v_add_f32_e32 v152, -1.0, v172
	v_sub_f32_e32 v170, v152, v172
	v_add_f32_e32 v170, 1.0, v170
	v_sub_f32_e32 v152, v236, v152
	v_add_f32_e32 v173, v152, v170
	v_max_f32_e32 v152, v153, v153
	v_min_f32_e32 v181, 0, v152
	v_mul_f32_e64 v152, |v153|, s5
	v_exp_f32_e32 v238, v152
	v_cvt_f64_f32_e32 v[170:171], v172
	v_frexp_exp_i32_f64_e32 v170, v[170:171]
	v_frexp_mant_f32_e32 v174, v172
	v_add_f32_e32 v171, 1.0, v238
	v_add_f32_e32 v152, -1.0, v171
	v_sub_f32_e32 v153, v152, v171
	v_add_f32_e32 v153, 1.0, v153
	v_sub_f32_e32 v152, v238, v152
	v_add_f32_e32 v175, v152, v153
	v_frexp_mant_f32_e32 v178, v171
	v_cvt_f64_f32_e32 v[152:153], v171
	v_cmp_gt_f32_e32 vcc, s72, v174
	v_frexp_exp_i32_f64_e32 v152, v[152:153]
	v_cmp_gt_f32_e64 s[14:15], s72, v178
	v_subbrev_co_u32_e32 v207, vcc, 0, v170, vcc
	s_nop 0
	v_subbrev_co_u32_e64 v206, s[14:15], 0, v152, s[14:15]
	v_sub_u32_e32 v153, 0, v207
	v_ldexp_f32 v152, v172, v153
	v_sub_u32_e32 v172, 0, v206
	v_ldexp_f32 v170, v173, v153
	v_ldexp_f32 v153, v171, v172
	v_ldexp_f32 v171, v175, v172
	v_pk_add_f32 v[172:173], v[152:153], 1.0 op_sel_hi:[1,0]
	v_pk_add_f32 v[192:193], v[152:153], -1.0 op_sel_hi:[1,0]
	v_pk_add_f32 v[174:175], v[172:173], -1.0 op_sel_hi:[1,0]
	v_pk_add_f32 v[194:195], v[192:193], 1.0 op_sel_hi:[1,0]
	v_pk_add_f32 v[174:175], v[152:153], v[174:175] neg_lo:[0,1] neg_hi:[0,1]
	v_pk_add_f32 v[152:153], v[152:153], v[194:195] neg_lo:[0,1] neg_hi:[0,1]
	v_pk_add_f32 v[174:175], v[170:171], v[174:175]
	v_pk_add_f32 v[152:153], v[170:171], v[152:153]
	v_pk_add_f32 v[178:179], v[172:173], v[174:175]
	v_pk_add_f32 v[170:171], v[192:193], v[152:153]
	v_rcp_f32_e32 v182, v178
	v_rcp_f32_e32 v183, v179
	v_pk_add_f32 v[172:173], v[178:179], v[172:173] neg_lo:[0,1] neg_hi:[0,1]
	v_pk_add_f32 v[192:193], v[170:171], v[192:193] neg_lo:[0,1] neg_hi:[0,1]
	v_pk_add_f32 v[172:173], v[174:175], v[172:173] neg_lo:[0,1] neg_hi:[0,1]
	v_pk_mul_f32 v[194:195], v[170:171], v[182:183]
	v_pk_add_f32 v[152:153], v[152:153], v[192:193] neg_lo:[0,1] neg_hi:[0,1]
	v_pk_mul_f32 v[174:175], v[178:179], v[194:195]
	v_add_f32_e32 v138, v144, v48
	v_pk_fma_f32 v[192:193], v[194:195], v[178:179], v[174:175] neg_lo:[0,0,1] neg_hi:[0,0,1]
	v_mul_f32_e32 v138, 0xbfb8aa3b, v138
	v_pk_fma_f32 v[192:193], v[194:195], v[172:173], v[192:193]
	v_exp_f32_e32 v138, v138
	v_pk_add_f32 v[196:197], v[174:175], v[192:193]
	v_rcp_f32_e32 v142, v142
	v_pk_add_f32 v[198:199], v[170:171], v[196:197] neg_lo:[0,1] neg_hi:[0,1]
	v_pk_add_f32 v[174:175], v[196:197], v[174:175] neg_lo:[0,1] neg_hi:[0,1]
	v_pk_add_f32 v[170:171], v[170:171], v[198:199] neg_lo:[0,1] neg_hi:[0,1]
	v_add_f32_e32 v138, 1.0, v138
	v_pk_add_f32 v[170:171], v[170:171], v[196:197] neg_lo:[0,1] neg_hi:[0,1]
	v_min_f32_e32 v168, 0, v168
	v_pk_add_f32 v[152:153], v[152:153], v[170:171]
	v_pk_add_f32 v[170:171], v[174:175], v[192:193] neg_lo:[0,1] neg_hi:[0,1]
	v_add_f32_e32 v130, v130, v26
	v_pk_add_f32 v[152:153], v[170:171], v[152:153]
	v_mul_f32_e32 v130, 0xbfb8aa3b, v130
	v_pk_add_f32 v[170:171], v[198:199], v[152:153]
	v_exp_f32_e32 v130, v130
	v_pk_mul_f32 v[174:175], v[182:183], v[170:171]
	v_pk_add_f32 v[198:199], v[198:199], v[170:171] neg_lo:[0,1] neg_hi:[0,1]
	v_pk_mul_f32 v[192:193], v[178:179], v[174:175]
	v_pk_add_f32 v[152:153], v[152:153], v[198:199]
	v_pk_fma_f32 v[178:179], v[174:175], v[178:179], v[192:193] neg_lo:[0,0,1] neg_hi:[0,0,1]
	v_pk_add_f32 v[204:205], v[194:195], v[174:175]
	v_pk_fma_f32 v[172:173], v[174:175], v[172:173], v[178:179]
	v_add_f32_e32 v130, 1.0, v130
	v_pk_add_f32 v[178:179], v[192:193], v[172:173]
	v_mul_f32_e32 v134, 0xbfb8aa3b, v134
	v_pk_add_f32 v[200:201], v[170:171], v[178:179] neg_lo:[0,1] neg_hi:[0,1]
	v_pk_add_f32 v[196:197], v[178:179], v[192:193] neg_lo:[0,1] neg_hi:[0,1]
	v_pk_add_f32 v[202:203], v[170:171], v[200:201] neg_lo:[0,1] neg_hi:[0,1]
	v_mov_b32_e32 v170, v179
	v_mov_b32_e32 v192, v193
	v_mov_b32_e32 v193, v201
	v_pk_add_f32 v[202:203], v[202:203], v[178:179] neg_lo:[0,1] neg_hi:[0,1]
	v_pk_add_f32 v[170:171], v[170:171], v[192:193] neg_lo:[0,1] neg_hi:[0,1]
	v_mov_b32_e32 v178, v173
	v_pk_add_f32 v[170:171], v[170:171], v[178:179] neg_lo:[0,1] neg_hi:[0,1]
	v_pk_add_f32 v[196:197], v[196:197], v[172:173] neg_lo:[0,1] neg_hi:[0,1]
	v_mov_b32_e32 v203, v171
	v_pk_add_f32 v[152:153], v[152:153], v[202:203]
	v_mov_b32_e32 v197, v170
	v_pk_add_f32 v[152:153], v[196:197], v[152:153]
	v_pk_add_f32 v[170:171], v[204:205], v[194:195] neg_lo:[0,1] neg_hi:[0,1]
	v_pk_add_f32 v[152:153], v[200:201], v[152:153]
	v_pk_add_f32 v[170:171], v[174:175], v[170:171] neg_lo:[0,1] neg_hi:[0,1]
	v_pk_mul_f32 v[152:153], v[182:183], v[152:153]
	v_cvt_f32_i32_e32 v183, v206
	v_pk_add_f32 v[152:153], v[170:171], v[152:153]
	v_cvt_f32_i32_e32 v182, v207
	v_pk_add_f32 v[170:171], v[204:205], v[152:153]
	v_exp_f32_e32 v134, v134
	v_pk_mul_f32 v[174:175], v[170:171], v[170:171]
	v_pk_add_f32 v[172:173], v[170:171], v[204:205] neg_lo:[0,1] neg_hi:[0,1]
	v_pk_fma_f32 v[178:179], v[174:175], s[28:29], v[150:151] op_sel_hi:[1,0,0]
	v_pk_add_f32 v[152:153], v[152:153], v[172:173] neg_lo:[0,1] neg_hi:[0,1]
	v_ldexp_f32 v172, v170, 1
	v_pk_fma_f32 v[178:179], v[174:175], v[178:179], s[30:31] op_sel_hi:[1,1,0]
	v_ldexp_f32 v173, v171, 1
	v_pk_mul_f32 v[170:171], v[170:171], v[174:175]
	v_pk_mul_f32 v[192:193], v[182:183], s[34:35] op_sel_hi:[1,0]
	v_pk_mul_f32 v[170:171], v[170:171], v[178:179]
	v_ldexp_f32 v152, v152, 1
	v_pk_add_f32 v[174:175], v[172:173], v[170:171]
	v_pk_fma_f32 v[194:195], v[182:183], s[34:35], v[192:193] op_sel_hi:[1,0,1] neg_lo:[0,0,1] neg_hi:[0,0,1]
	v_pk_add_f32 v[172:173], v[174:175], v[172:173] neg_lo:[0,1] neg_hi:[0,1]
	v_ldexp_f32 v153, v153, 1
	v_pk_add_f32 v[170:171], v[170:171], v[172:173] neg_lo:[0,1] neg_hi:[0,1]
	v_pk_fma_f32 v[182:183], v[182:183], s[36:37], v[194:195] op_sel_hi:[1,0,1]
	v_pk_add_f32 v[152:153], v[152:153], v[170:171]
	v_pk_add_f32 v[202:203], v[192:193], v[182:183]
	v_pk_add_f32 v[210:211], v[174:175], v[152:153]
	v_pk_add_f32 v[192:193], v[202:203], v[192:193] neg_lo:[0,1] neg_hi:[0,1]
	v_pk_add_f32 v[170:171], v[210:211], v[174:175] neg_lo:[0,1] neg_hi:[0,1]
	v_pk_add_f32 v[182:183], v[182:183], v[192:193] neg_lo:[0,1] neg_hi:[0,1]
	v_pk_add_f32 v[152:153], v[152:153], v[170:171] neg_lo:[0,1] neg_hi:[0,1]
	v_add_f32_e32 v134, 1.0, v134
	v_pk_add_f32 v[204:205], v[182:183], v[152:153]
	v_rcp_f32_e32 v134, v134
	v_pk_add_f32 v[170:171], v[204:205], v[182:183] neg_lo:[0,1] neg_hi:[0,1]
	v_add_f32_e32 v126, v126, v46
	v_pk_add_f32 v[208:209], v[152:153], v[170:171] neg_lo:[0,1] neg_hi:[0,1]
	v_max_f32_e32 v152, v146, v146
	v_mul_f32_e64 v146, |v146|, s5
	v_exp_f32_e32 v235, v146
	v_pk_add_f32 v[172:173], v[204:205], v[170:171] neg_lo:[0,1] neg_hi:[0,1]
	v_min_f32_e32 v178, 0, v152
	v_pk_add_f32 v[206:207], v[182:183], v[172:173] neg_lo:[0,1] neg_hi:[0,1]
	v_add_f32_e32 v170, 1.0, v235
	v_add_f32_e32 v146, -1.0, v170
	v_sub_f32_e32 v152, v146, v170
	v_add_f32_e32 v152, 1.0, v152
	v_sub_f32_e32 v146, v235, v146
	v_add_f32_e32 v171, v146, v152
	v_max_f32_e32 v146, v147, v147
	v_min_f32_e32 v179, 0, v146
	v_mul_f32_e64 v146, |v147|, s5
	v_exp_f32_e32 v237, v146
	v_cvt_f64_f32_e32 v[152:153], v170
	v_frexp_exp_i32_f64_e32 v152, v[152:153]
	v_frexp_mant_f32_e32 v172, v170
	v_add_f32_e32 v153, 1.0, v237
	v_add_f32_e32 v146, -1.0, v153
	v_sub_f32_e32 v147, v146, v153
	v_add_f32_e32 v147, 1.0, v147
	v_sub_f32_e32 v146, v237, v146
	v_add_f32_e32 v173, v146, v147
	v_frexp_mant_f32_e32 v174, v153
	v_cvt_f64_f32_e32 v[146:147], v153
	v_cmp_gt_f32_e32 vcc, s72, v172
	v_frexp_exp_i32_f64_e32 v146, v[146:147]
	v_cmp_gt_f32_e64 s[14:15], s72, v174
	v_subbrev_co_u32_e32 v217, vcc, 0, v152, vcc
	s_nop 0
	v_subbrev_co_u32_e64 v216, s[14:15], 0, v146, s[14:15]
	v_sub_u32_e32 v147, 0, v217
	v_ldexp_f32 v146, v170, v147
	v_sub_u32_e32 v170, 0, v216
	v_ldexp_f32 v152, v171, v147
	v_ldexp_f32 v147, v153, v170
	v_ldexp_f32 v153, v173, v170
	v_pk_add_f32 v[170:171], v[146:147], 1.0 op_sel_hi:[1,0]
	v_pk_add_f32 v[192:193], v[146:147], -1.0 op_sel_hi:[1,0]
	v_pk_add_f32 v[172:173], v[170:171], -1.0 op_sel_hi:[1,0]
	v_pk_add_f32 v[194:195], v[192:193], 1.0 op_sel_hi:[1,0]
	v_pk_add_f32 v[172:173], v[146:147], v[172:173] neg_lo:[0,1] neg_hi:[0,1]
	v_pk_add_f32 v[146:147], v[146:147], v[194:195] neg_lo:[0,1] neg_hi:[0,1]
	v_pk_add_f32 v[172:173], v[152:153], v[172:173]
	v_pk_add_f32 v[146:147], v[152:153], v[146:147]
	v_pk_add_f32 v[174:175], v[170:171], v[172:173]
	v_pk_add_f32 v[152:153], v[192:193], v[146:147]
	v_rcp_f32_e32 v182, v174
	v_rcp_f32_e32 v183, v175
	v_pk_add_f32 v[170:171], v[174:175], v[170:171] neg_lo:[0,1] neg_hi:[0,1]
	v_pk_add_f32 v[192:193], v[152:153], v[192:193] neg_lo:[0,1] neg_hi:[0,1]
	v_pk_add_f32 v[170:171], v[172:173], v[170:171] neg_lo:[0,1] neg_hi:[0,1]
	v_pk_mul_f32 v[194:195], v[152:153], v[182:183]
	v_pk_add_f32 v[146:147], v[146:147], v[192:193] neg_lo:[0,1] neg_hi:[0,1]
	v_pk_mul_f32 v[172:173], v[174:175], v[194:195]
	v_mul_f32_e32 v126, 0xbfb8aa3b, v126
	v_pk_fma_f32 v[192:193], v[194:195], v[174:175], v[172:173] neg_lo:[0,0,1] neg_hi:[0,0,1]
	v_exp_f32_e32 v126, v126
	v_pk_fma_f32 v[192:193], v[194:195], v[170:171], v[192:193]
	v_add_f32_e32 v122, v122, v42
	v_pk_add_f32 v[196:197], v[172:173], v[192:193]
	v_add_f32_e32 v126, 1.0, v126
	v_pk_add_f32 v[198:199], v[152:153], v[196:197] neg_lo:[0,1] neg_hi:[0,1]
	v_pk_add_f32 v[172:173], v[196:197], v[172:173] neg_lo:[0,1] neg_hi:[0,1]
	v_pk_add_f32 v[152:153], v[152:153], v[198:199] neg_lo:[0,1] neg_hi:[0,1]
	v_rcp_f32_e32 v126, v126
	v_pk_add_f32 v[152:153], v[152:153], v[196:197] neg_lo:[0,1] neg_hi:[0,1]
	v_mul_f32_e32 v122, 0xbfb8aa3b, v122
	v_pk_add_f32 v[146:147], v[146:147], v[152:153]
	v_pk_add_f32 v[152:153], v[172:173], v[192:193] neg_lo:[0,1] neg_hi:[0,1]
	v_exp_f32_e32 v122, v122
	v_pk_add_f32 v[146:147], v[152:153], v[146:147]
	v_add_f32_e32 v123, v123, v43
	v_pk_add_f32 v[152:153], v[198:199], v[146:147]
	v_add_f32_e32 v122, 1.0, v122
	v_pk_mul_f32 v[172:173], v[182:183], v[152:153]
	v_pk_add_f32 v[198:199], v[198:199], v[152:153] neg_lo:[0,1] neg_hi:[0,1]
	v_pk_mul_f32 v[192:193], v[174:175], v[172:173]
	v_pk_add_f32 v[146:147], v[146:147], v[198:199]
	v_pk_fma_f32 v[174:175], v[172:173], v[174:175], v[192:193] neg_lo:[0,0,1] neg_hi:[0,0,1]
	v_pk_add_f32 v[214:215], v[194:195], v[172:173]
	v_pk_fma_f32 v[170:171], v[172:173], v[170:171], v[174:175]
	v_rcp_f32_e32 v122, v122
	v_pk_add_f32 v[174:175], v[192:193], v[170:171]
	v_mul_f32_e32 v123, 0xbfb8aa3b, v123
	v_pk_add_f32 v[200:201], v[152:153], v[174:175] neg_lo:[0,1] neg_hi:[0,1]
	v_pk_add_f32 v[196:197], v[174:175], v[192:193] neg_lo:[0,1] neg_hi:[0,1]
	v_pk_add_f32 v[212:213], v[152:153], v[200:201] neg_lo:[0,1] neg_hi:[0,1]
	v_mov_b32_e32 v152, v175
	v_mov_b32_e32 v192, v193
	v_mov_b32_e32 v193, v201
	v_pk_add_f32 v[212:213], v[212:213], v[174:175] neg_lo:[0,1] neg_hi:[0,1]
	v_pk_add_f32 v[152:153], v[152:153], v[192:193] neg_lo:[0,1] neg_hi:[0,1]
	v_mov_b32_e32 v174, v171
	v_pk_add_f32 v[152:153], v[152:153], v[174:175] neg_lo:[0,1] neg_hi:[0,1]
	v_pk_add_f32 v[196:197], v[196:197], v[170:171] neg_lo:[0,1] neg_hi:[0,1]
	v_mov_b32_e32 v213, v153
	v_pk_add_f32 v[146:147], v[146:147], v[212:213]
	v_mov_b32_e32 v197, v152
	v_pk_add_f32 v[146:147], v[196:197], v[146:147]
	v_pk_add_f32 v[152:153], v[214:215], v[194:195] neg_lo:[0,1] neg_hi:[0,1]
	v_pk_add_f32 v[146:147], v[200:201], v[146:147]
	v_pk_add_f32 v[152:153], v[172:173], v[152:153] neg_lo:[0,1] neg_hi:[0,1]
	v_pk_mul_f32 v[146:147], v[182:183], v[146:147]
	v_cvt_f32_i32_e32 v183, v216
	v_pk_add_f32 v[146:147], v[152:153], v[146:147]
	v_cvt_f32_i32_e32 v182, v217
	v_pk_add_f32 v[152:153], v[214:215], v[146:147]
	v_exp_f32_e32 v123, v123
	v_pk_mul_f32 v[172:173], v[152:153], v[152:153]
	v_pk_add_f32 v[170:171], v[152:153], v[214:215] neg_lo:[0,1] neg_hi:[0,1]
	v_pk_fma_f32 v[174:175], v[172:173], s[28:29], v[150:151] op_sel_hi:[1,0,0]
	v_pk_add_f32 v[146:147], v[146:147], v[170:171] neg_lo:[0,1] neg_hi:[0,1]
	v_ldexp_f32 v170, v152, 1
	v_pk_fma_f32 v[174:175], v[172:173], v[174:175], s[30:31] op_sel_hi:[1,1,0]
	v_ldexp_f32 v171, v153, 1
	v_pk_mul_f32 v[152:153], v[152:153], v[172:173]
	v_pk_mul_f32 v[194:195], v[182:183], s[34:35] op_sel_hi:[1,0]
	v_pk_mul_f32 v[152:153], v[152:153], v[174:175]
	v_ldexp_f32 v146, v146, 1
	v_pk_add_f32 v[172:173], v[170:171], v[152:153]
	v_pk_fma_f32 v[192:193], v[182:183], s[34:35], v[194:195] op_sel_hi:[1,0,1] neg_lo:[0,0,1] neg_hi:[0,0,1]
	v_pk_add_f32 v[170:171], v[172:173], v[170:171] neg_lo:[0,1] neg_hi:[0,1]
	v_ldexp_f32 v147, v147, 1
	v_pk_add_f32 v[152:153], v[152:153], v[170:171] neg_lo:[0,1] neg_hi:[0,1]
	v_pk_fma_f32 v[182:183], v[182:183], s[36:37], v[192:193] op_sel_hi:[1,0,1]
	v_pk_add_f32 v[146:147], v[146:147], v[152:153]
	v_pk_add_f32 v[192:193], v[194:195], v[182:183]
	v_pk_add_f32 v[200:201], v[172:173], v[146:147]
	v_pk_add_f32 v[194:195], v[192:193], v[194:195] neg_lo:[0,1] neg_hi:[0,1]
	v_pk_add_f32 v[152:153], v[200:201], v[172:173] neg_lo:[0,1] neg_hi:[0,1]
	v_pk_add_f32 v[182:183], v[182:183], v[194:195] neg_lo:[0,1] neg_hi:[0,1]
	v_pk_add_f32 v[146:147], v[146:147], v[152:153] neg_lo:[0,1] neg_hi:[0,1]
	v_add_f32_e32 v123, 1.0, v123
	v_pk_add_f32 v[194:195], v[182:183], v[146:147]
	v_rcp_f32_e32 v123, v123
	v_pk_add_f32 v[152:153], v[194:195], v[182:183] neg_lo:[0,1] neg_hi:[0,1]
	v_add_f32_e32 v124, v124, v44
	v_pk_add_f32 v[170:171], v[194:195], v[152:153] neg_lo:[0,1] neg_hi:[0,1]
	v_pk_add_f32 v[198:199], v[146:147], v[152:153] neg_lo:[0,1] neg_hi:[0,1]
	v_max_f32_e32 v146, v148, v148
	v_pk_add_f32 v[196:197], v[182:183], v[170:171] neg_lo:[0,1] neg_hi:[0,1]
	v_min_f32_e32 v182, 0, v146
	v_mul_f32_e64 v146, |v148|, s5
	v_exp_f32_e32 v239, v146
	v_mul_f32_e32 v124, 0xbfb8aa3b, v124
	v_exp_f32_e32 v124, v124
	v_add_f32_e32 v118, v118, v30
	v_add_f32_e32 v148, 1.0, v239
	v_add_f32_e32 v146, -1.0, v148
	v_sub_f32_e32 v147, v146, v148
	v_add_f32_e32 v147, 1.0, v147
	v_sub_f32_e32 v146, v239, v146
	v_add_f32_e32 v152, v146, v147
	v_cvt_f64_f32_e32 v[146:147], v148
	v_frexp_exp_i32_f64_e32 v170, v[146:147]
	v_max_f32_e32 v146, v149, v149
	v_min_f32_e32 v183, 0, v146
	v_mul_f32_e64 v146, |v149|, s5
	v_exp_f32_e32 v240, v146
	v_frexp_mant_f32_e32 v153, v148
	v_cmp_gt_f32_e32 vcc, s72, v153
	v_add_f32_e32 v124, 1.0, v124
	v_add_f32_e32 v149, 1.0, v240
	v_add_f32_e32 v146, -1.0, v149
	v_sub_f32_e32 v147, v146, v149
	v_add_f32_e32 v147, 1.0, v147
	v_sub_f32_e32 v146, v240, v146
	v_add_f32_e32 v171, v146, v147
	v_frexp_mant_f32_e32 v172, v149
	v_cvt_f64_f32_e32 v[146:147], v149
	v_frexp_exp_i32_f64_e32 v146, v[146:147]
	v_cmp_gt_f32_e64 s[14:15], s72, v172
	v_subbrev_co_u32_e32 v241, vcc, 0, v170, vcc
	s_nop 0
	v_subbrev_co_u32_e64 v234, s[14:15], 0, v146, s[14:15]
	v_sub_u32_e32 v147, 0, v241
	v_ldexp_f32 v146, v148, v147
	v_ldexp_f32 v148, v152, v147
	v_sub_u32_e32 v152, 0, v234
	v_ldexp_f32 v147, v149, v152
	v_ldexp_f32 v149, v171, v152
	v_pk_add_f32 v[152:153], v[146:147], 1.0 op_sel_hi:[1,0]
	v_pk_add_f32 v[212:213], v[146:147], -1.0 op_sel_hi:[1,0]
	v_pk_add_f32 v[170:171], v[152:153], -1.0 op_sel_hi:[1,0]
	v_pk_add_f32 v[214:215], v[212:213], 1.0 op_sel_hi:[1,0]
	v_pk_add_f32 v[170:171], v[146:147], v[170:171] neg_lo:[0,1] neg_hi:[0,1]
	v_pk_add_f32 v[146:147], v[146:147], v[214:215] neg_lo:[0,1] neg_hi:[0,1]
	v_pk_add_f32 v[170:171], v[148:149], v[170:171]
	v_pk_add_f32 v[146:147], v[148:149], v[146:147]
	v_pk_add_f32 v[172:173], v[152:153], v[170:171]
	v_pk_add_f32 v[148:149], v[212:213], v[146:147]
	v_rcp_f32_e32 v174, v172
	v_rcp_f32_e32 v175, v173
	v_pk_add_f32 v[152:153], v[172:173], v[152:153] neg_lo:[0,1] neg_hi:[0,1]
	v_pk_add_f32 v[212:213], v[148:149], v[212:213] neg_lo:[0,1] neg_hi:[0,1]
	v_pk_add_f32 v[152:153], v[170:171], v[152:153] neg_lo:[0,1] neg_hi:[0,1]
	v_pk_mul_f32 v[214:215], v[148:149], v[174:175]
	v_pk_add_f32 v[146:147], v[146:147], v[212:213] neg_lo:[0,1] neg_hi:[0,1]
	v_pk_mul_f32 v[170:171], v[172:173], v[214:215]
	v_cmp_lt_f32_e64 s[14:15], |v233|, s77
	v_pk_fma_f32 v[212:213], v[214:215], v[172:173], v[170:171] neg_lo:[0,0,1] neg_hi:[0,0,1]
	v_rcp_f32_e32 v124, v124
	v_pk_fma_f32 v[212:213], v[214:215], v[152:153], v[212:213]
	v_add_f32_e32 v125, v125, v45
	v_pk_add_f32 v[216:217], v[170:171], v[212:213]
	v_mul_f32_e32 v118, 0xbfb8aa3b, v118
	v_pk_add_f32 v[218:219], v[148:149], v[216:217] neg_lo:[0,1] neg_hi:[0,1]
	v_pk_add_f32 v[170:171], v[216:217], v[170:171] neg_lo:[0,1] neg_hi:[0,1]
	v_pk_add_f32 v[148:149], v[148:149], v[218:219] neg_lo:[0,1] neg_hi:[0,1]
	v_mul_f32_e32 v125, 0xbfb8aa3b, v125
	v_pk_add_f32 v[148:149], v[148:149], v[216:217] neg_lo:[0,1] neg_hi:[0,1]
	v_exp_f32_e32 v118, v118
	v_pk_add_f32 v[146:147], v[146:147], v[148:149]
	v_pk_add_f32 v[148:149], v[170:171], v[212:213] neg_lo:[0,1] neg_hi:[0,1]
	v_exp_f32_e32 v125, v125
	v_pk_add_f32 v[146:147], v[148:149], v[146:147]
	v_add_f32_e32 v118, 1.0, v118
	v_pk_add_f32 v[148:149], v[218:219], v[146:147]
	v_add_f32_e32 v125, 1.0, v125
	v_pk_mul_f32 v[170:171], v[174:175], v[148:149]
	v_pk_add_f32 v[218:219], v[218:219], v[148:149] neg_lo:[0,1] neg_hi:[0,1]
	v_pk_mul_f32 v[212:213], v[172:173], v[170:171]
	v_pk_add_f32 v[146:147], v[146:147], v[218:219]
	v_pk_fma_f32 v[172:173], v[170:171], v[172:173], v[212:213] neg_lo:[0,0,1] neg_hi:[0,0,1]
	v_pk_add_f32 v[244:245], v[214:215], v[170:171]
	v_pk_fma_f32 v[152:153], v[170:171], v[152:153], v[172:173]
	v_rcp_f32_e32 v118, v118
	v_pk_add_f32 v[172:173], v[212:213], v[152:153]
	v_rcp_f32_e32 v125, v125
	v_pk_add_f32 v[220:221], v[148:149], v[172:173] neg_lo:[0,1] neg_hi:[0,1]
	v_pk_add_f32 v[216:217], v[172:173], v[212:213] neg_lo:[0,1] neg_hi:[0,1]
	v_pk_add_f32 v[242:243], v[148:149], v[220:221] neg_lo:[0,1] neg_hi:[0,1]
	v_mov_b32_e32 v148, v173
	v_mov_b32_e32 v212, v213
	v_mov_b32_e32 v213, v221
	v_pk_add_f32 v[242:243], v[242:243], v[172:173] neg_lo:[0,1] neg_hi:[0,1]
	v_pk_add_f32 v[148:149], v[148:149], v[212:213] neg_lo:[0,1] neg_hi:[0,1]
	v_mov_b32_e32 v172, v153
	v_pk_add_f32 v[148:149], v[148:149], v[172:173] neg_lo:[0,1] neg_hi:[0,1]
	v_pk_add_f32 v[216:217], v[216:217], v[152:153] neg_lo:[0,1] neg_hi:[0,1]
	v_mov_b32_e32 v243, v149
	v_pk_add_f32 v[146:147], v[146:147], v[242:243]
	v_mov_b32_e32 v217, v148
	v_pk_add_f32 v[146:147], v[216:217], v[146:147]
	v_pk_add_f32 v[148:149], v[244:245], v[214:215] neg_lo:[0,1] neg_hi:[0,1]
	v_pk_add_f32 v[146:147], v[220:221], v[146:147]
	v_pk_add_f32 v[148:149], v[170:171], v[148:149] neg_lo:[0,1] neg_hi:[0,1]
	v_pk_mul_f32 v[146:147], v[174:175], v[146:147]
	v_cvt_f32_i32_e32 v173, v234
	v_pk_add_f32 v[146:147], v[148:149], v[146:147]
	v_cvt_f32_i32_e32 v172, v241
	v_pk_add_f32 v[148:149], v[244:245], v[146:147]
	v_add_u32_e32 v234, s0, v167
	v_pk_mul_f32 v[170:171], v[148:149], v[148:149]
	v_pk_add_f32 v[152:153], v[148:149], v[244:245] neg_lo:[0,1] neg_hi:[0,1]
	v_pk_fma_f32 v[150:151], v[170:171], s[28:29], v[150:151] op_sel_hi:[1,0,0]
	v_pk_add_f32 v[146:147], v[146:147], v[152:153] neg_lo:[0,1] neg_hi:[0,1]
	v_ldexp_f32 v152, v148, 1
	v_pk_fma_f32 v[150:151], v[170:171], v[150:151], s[30:31] op_sel_hi:[1,1,0]
	v_ldexp_f32 v153, v149, 1
	v_pk_mul_f32 v[148:149], v[148:149], v[170:171]
	v_pk_mul_f32 v[174:175], v[172:173], s[34:35] op_sel_hi:[1,0]
	v_pk_mul_f32 v[148:149], v[148:149], v[150:151]
	v_ldexp_f32 v146, v146, 1
	v_pk_add_f32 v[150:151], v[152:153], v[148:149]
	v_pk_fma_f32 v[212:213], v[172:173], s[34:35], v[174:175] op_sel_hi:[1,0,1] neg_lo:[0,0,1] neg_hi:[0,0,1]
	v_pk_add_f32 v[152:153], v[150:151], v[152:153] neg_lo:[0,1] neg_hi:[0,1]
	v_ldexp_f32 v147, v147, 1
	v_pk_add_f32 v[148:149], v[148:149], v[152:153] neg_lo:[0,1] neg_hi:[0,1]
	v_pk_fma_f32 v[172:173], v[172:173], s[36:37], v[212:213] op_sel_hi:[1,0,1]
	v_pk_add_f32 v[146:147], v[146:147], v[148:149]
	v_pk_add_f32 v[212:213], v[174:175], v[172:173]
	v_pk_add_f32 v[220:221], v[150:151], v[146:147]
	v_pk_add_f32 v[174:175], v[212:213], v[174:175] neg_lo:[0,1] neg_hi:[0,1]
	v_pk_add_f32 v[148:149], v[220:221], v[150:151] neg_lo:[0,1] neg_hi:[0,1]
	v_pk_add_f32 v[172:173], v[172:173], v[174:175] neg_lo:[0,1] neg_hi:[0,1]
	v_pk_add_f32 v[146:147], v[146:147], v[148:149] neg_lo:[0,1] neg_hi:[0,1]
	v_ashrrev_i32_e32 v167, 31, v166
	v_pk_add_f32 v[214:215], v[172:173], v[146:147]
	v_mov_b32_e32 v242, v190
	v_pk_add_f32 v[148:149], v[214:215], v[172:173] neg_lo:[0,1] neg_hi:[0,1]
	v_mov_b32_e32 v243, v176
	v_pk_add_f32 v[218:219], v[146:147], v[148:149] neg_lo:[0,1] neg_hi:[0,1]
	v_mov_b32_e32 v146, v234
	v_pk_add_f32 v[150:151], v[214:215], v[148:149] neg_lo:[0,1] neg_hi:[0,1]
	v_ashrrev_i32_e32 v147, 31, v146
	v_lshlrev_b64 v[146:147], 10, v[146:147]
	v_lshl_add_u64 v[146:147], v[146:147], 0, v[166:167]
	v_lshlrev_b64 v[148:149], 1, v[146:147]
	v_lshl_add_u64 v[174:175], s[24:25], 0, v[148:149]
	v_pk_add_f32 v[216:217], v[172:173], v[150:151] neg_lo:[0,1] neg_hi:[0,1]
	flat_load_dwordx4 v[150:153], v[174:175]
	v_lshl_add_u64 v[170:171], s[50:51], 0, v[146:147]
	v_add_co_u32_e32 v146, vcc, s84, v174
	v_lshl_add_u64 v[172:173], s[48:49], 0, v[148:149]
	s_nop 0
	v_addc_co_u32_e32 v147, vcc, 0, v175, vcc
	flat_load_dwordx4 v[146:149], v[146:147]
	v_cmp_neq_f32_e32 vcc, s73, v232
	v_add_f32_e32 v114, v114, v26
	v_add_f32_e32 v119, v119, v31
	v_mul_f32_e32 v114, 0xbfb8aa3b, v114
	v_mul_f32_e32 v119, 0xbfb8aa3b, v119
	v_exp_f32_e32 v114, v114
	v_exp_f32_e32 v119, v119
	v_add_f32_e32 v120, v120, v32
	v_add_f32_e32 v115, v115, v27
	v_add_f32_e32 v114, 1.0, v114
	v_add_f32_e32 v119, 1.0, v119
	v_rcp_f32_e32 v114, v114
	v_rcp_f32_e32 v119, v119
	v_mul_f32_e32 v120, 0xbfb8aa3b, v120
	v_mul_f32_e32 v115, 0xbfb8aa3b, v115
	v_exp_f32_e32 v120, v120
	v_exp_f32_e32 v115, v115
	v_add_f32_e32 v121, v121, v33
	v_add_f32_e32 v116, v116, v28
	v_add_f32_e32 v120, 1.0, v120
	v_add_f32_e32 v115, 1.0, v115
	v_rcp_f32_e32 v120, v120
	v_rcp_f32_e32 v115, v115
	v_mul_f32_e32 v121, 0xbfb8aa3b, v121
	v_mul_f32_e32 v116, 0xbfb8aa3b, v116
	v_exp_f32_e32 v121, v121
	v_exp_f32_e32 v116, v116
	v_add_f32_e32 v117, v117, v29
	v_mul_f32_e32 v117, 0xbfb8aa3b, v117
	v_add_f32_e32 v121, 1.0, v121
	v_add_f32_e32 v116, 1.0, v116
	v_rcp_f32_e32 v121, v121
	v_rcp_f32_e32 v116, v116
	v_exp_f32_e32 v117, v117
	s_waitcnt vmcnt(0) lgkmcnt(0)
	v_lshlrev_b32_e32 v241, 16, v150
	v_and_b32_e32 v246, 0xffff0000, v150
	v_rcp_f32_e32 v150, v138
	v_add_f32_e32 v138, v140, v44
	v_mul_f32_e32 v138, 0xbfb8aa3b, v138
	v_exp_f32_e32 v138, v138
	v_lshlrev_b32_e32 v247, 16, v151
	v_and_b32_e32 v248, 0xffff0000, v151
	v_add_f32_e32 v117, 1.0, v117
	v_add_f32_e32 v138, 1.0, v138
	v_rcp_f32_e32 v251, v138
	v_add_f32_e32 v138, v145, v49
	v_mul_f32_e32 v138, 0xbfb8aa3b, v138
	v_exp_f32_e32 v138, v138
	v_rcp_f32_e32 v117, v117
	v_add_f32_e32 v138, 1.0, v138
	v_rcp_f32_e32 v151, v138
	v_add_f32_e32 v138, v141, v45
	v_mul_f32_e32 v138, 0xbfb8aa3b, v138
	v_exp_f32_e32 v138, v138
	s_nop 0
	v_add_f32_e32 v138, 1.0, v138
	v_rcp_f32_e32 v252, v138
	v_pk_add_f32 v[138:139], v[176:177], v[190:191]
	s_nop 0
	v_pk_add_f32 v[140:141], v[138:139], v[176:177] neg_lo:[0,1] neg_hi:[0,1]
	v_mov_b32_e32 v176, v191
	v_pk_add_f32 v[144:145], v[138:139], v[140:141] neg_lo:[0,1] neg_hi:[0,1]
	v_mov_b32_e32 v244, v140
	v_mov_b32_e32 v245, v144
	v_mov_b32_e32 v144, v141
	v_pk_add_f32 v[242:243], v[242:243], v[244:245] neg_lo:[0,1] neg_hi:[0,1]
	v_pk_add_f32 v[140:141], v[176:177], v[144:145] neg_lo:[0,1] neg_hi:[0,1]
	v_pk_add_f32 v[242:243], v[242:243], v[242:243] op_sel:[0,1] op_sel_hi:[1,0]
	v_pk_add_f32 v[140:141], v[140:141], v[140:141] op_sel_hi:[0,1]
	v_mov_b32_e32 v243, v185
	v_mov_b32_e32 v185, v141
	v_pk_add_f32 v[140:141], v[242:243], v[184:185]
	v_pk_add_f32 v[176:177], v[188:189], v[186:187]
	v_pk_add_f32 v[144:145], v[138:139], v[140:141]
	s_nop 0
	v_pk_add_f32 v[138:139], v[144:145], v[138:139] neg_lo:[0,1] neg_hi:[0,1]
	s_nop 0
	v_pk_add_f32 v[138:139], v[140:141], v[138:139] neg_lo:[0,1] neg_hi:[0,1]
	s_nop 0
	v_pk_add_f32 v[138:139], v[176:177], v[138:139]
	v_mov_b32_e32 v176, v210
	v_pk_add_f32 v[138:139], v[144:145], v[138:139]
	v_mov_b32_e32 v177, v202
	v_cndmask_b32_e32 v138, v228, v138, vcc
	v_cmp_neq_f32_e32 vcc, s73, v233
	s_nop 1
	v_cndmask_b32_e32 v139, v228, v139, vcc
	v_cmp_ngt_f32_e32 vcc, -1.0, v233
	s_nop 1
	v_cndmask_b32_e32 v139, v229, v139, vcc
	v_cmp_ngt_f32_e32 vcc, -1.0, v232
	s_nop 1
	v_cndmask_b32_e32 v138, v229, v138, vcc
	v_cmp_neq_f32_e32 vcc, -1.0, v232
	s_nop 1
	v_cndmask_b32_e32 v138, v230, v138, vcc
	v_cmp_neq_f32_e32 vcc, -1.0, v233
	s_nop 1
	v_cndmask_b32_e32 v139, v230, v139, vcc
	v_cmp_lt_f32_e64 vcc, |v232|, s77
	v_cndmask_b32_e64 v139, v139, v233, s[14:15]
	v_cmp_lt_f32_e64 s[14:15], |v238|, s77
	v_cndmask_b32_e32 v138, v138, v232, vcc
	v_pk_add_f32 v[138:139], v[168:169], v[138:139] neg_lo:[0,1] neg_hi:[0,1]
	v_cmp_neq_f32_e32 vcc, s73, v236
	v_pk_mul_f32 v[144:145], v[138:139], s[38:39] op_sel_hi:[1,0]
	s_nop 0
	v_pk_mul_f32 v[138:139], v[142:143], v[144:145]
	v_mul_f32_e32 v126, v126, v144
	v_add_f32_e32 v140, v138, v138
	v_mul_f32_e32 v140, 0x3fb8aa3b, v140
	v_exp_f32_e32 v140, v140
	v_cvt_pk_bf16_f32 v138, v138, v139
	v_sub_f32_e32 v140, 1.0, v140
	v_max_f32_e32 v140, 0, v140
	v_sqrt_f32_e32 v140, v140
	s_nop 0
	v_mul_f32_e32 v140, v249, v140
	v_mul_f32_e32 v186, v140, v241
	v_add_f32_e32 v140, v139, v139
	v_mul_f32_e32 v140, 0x3fb8aa3b, v140
	v_exp_f32_e32 v140, v140
	s_nop 0
	v_sub_f32_e32 v140, 1.0, v140
	v_max_f32_e32 v140, 0, v140
	v_sqrt_f32_e32 v140, v140
	s_nop 0
	v_mul_f32_e32 v140, v250, v140
	v_mul_f32_e32 v187, v140, v246
	v_pk_add_f32 v[140:141], v[202:203], v[210:211]
	s_nop 0
	v_pk_add_f32 v[142:143], v[140:141], v[202:203] neg_lo:[0,1] neg_hi:[0,1]
	v_mov_b32_e32 v202, v211
	v_pk_add_f32 v[168:169], v[140:141], v[142:143] neg_lo:[0,1] neg_hi:[0,1]
	v_mov_b32_e32 v184, v142
	v_mov_b32_e32 v185, v168
	v_mov_b32_e32 v168, v143
	v_pk_add_f32 v[176:177], v[176:177], v[184:185] neg_lo:[0,1] neg_hi:[0,1]
	v_pk_add_f32 v[142:143], v[202:203], v[168:169] neg_lo:[0,1] neg_hi:[0,1]
	v_pk_add_f32 v[176:177], v[176:177], v[176:177] op_sel:[0,1] op_sel_hi:[1,0]
	v_pk_add_f32 v[142:143], v[142:143], v[142:143] op_sel_hi:[0,1]
	v_mov_b32_e32 v177, v205
	v_mov_b32_e32 v205, v143
	v_pk_add_f32 v[142:143], v[176:177], v[204:205]
	v_pk_add_f32 v[176:177], v[208:209], v[206:207]
	v_pk_add_f32 v[168:169], v[140:141], v[142:143]
	s_nop 0
	v_pk_add_f32 v[140:141], v[168:169], v[140:141] neg_lo:[0,1] neg_hi:[0,1]
	s_nop 0
	v_pk_add_f32 v[140:141], v[142:143], v[140:141] neg_lo:[0,1] neg_hi:[0,1]
	s_nop 0
	v_pk_add_f32 v[140:141], v[176:177], v[140:141]
	v_rcp_f32_e32 v177, v130
	v_add_f32_e32 v130, v135, v31
	v_pk_add_f32 v[140:141], v[168:169], v[140:141]
	v_mul_f32_e32 v130, 0xbfb8aa3b, v130
	v_cndmask_b32_e32 v139, v228, v140, vcc
	v_cmp_neq_f32_e32 vcc, s73, v238
	v_exp_f32_e32 v130, v130
	v_and_b32_e32 v176, 0xffff0000, v152
	v_cndmask_b32_e32 v140, v228, v141, vcc
	v_cmp_ngt_f32_e32 vcc, -1.0, v238
	v_add_f32_e32 v130, 1.0, v130
	v_rcp_f32_e32 v135, v130
	v_cndmask_b32_e32 v140, v229, v140, vcc
	v_cmp_ngt_f32_e32 vcc, -1.0, v236
	v_add_f32_e32 v130, v131, v27
	v_mul_f32_e32 v130, 0xbfb8aa3b, v130
	v_cndmask_b32_e32 v139, v229, v139, vcc
	v_cmp_neq_f32_e32 vcc, -1.0, v236
	v_exp_f32_e32 v130, v130
	s_nop 0
	v_cndmask_b32_e32 v139, v230, v139, vcc
	v_cmp_neq_f32_e32 vcc, -1.0, v238
	v_add_f32_e32 v130, 1.0, v130
	v_rcp_f32_e32 v184, v130
	v_cndmask_b32_e32 v140, v230, v140, vcc
	v_cmp_lt_f32_e64 vcc, |v236|, s77
	v_cndmask_b32_e64 v141, v140, v238, s[14:15]
	v_add_f32_e32 v130, v136, v32
	v_cndmask_b32_e32 v140, v139, v236, vcc
	v_pk_add_f32 v[140:141], v[180:181], v[140:141] neg_lo:[0,1] neg_hi:[0,1]
	v_mul_f32_e32 v130, 0xbfb8aa3b, v130
	v_pk_mul_f32 v[142:143], v[140:141], s[38:39] op_sel_hi:[1,0]
	v_exp_f32_e32 v130, v130
	v_pk_mul_f32 v[140:141], v[150:151], v[142:143]
	v_lshlrev_b32_e32 v180, 16, v153
	v_add_f32_e32 v139, v140, v140
	v_mul_f32_e32 v139, 0x3fb8aa3b, v139
	v_exp_f32_e32 v139, v139
	v_add_f32_e32 v130, 1.0, v130
	v_rcp_f32_e32 v136, v130
	v_add_f32_e32 v130, v132, v28
	v_sub_f32_e32 v139, 1.0, v139
	v_max_f32_e32 v139, 0, v139
	v_sqrt_f32_e32 v139, v139
	v_mul_f32_e32 v130, 0xbfb8aa3b, v130
	v_exp_f32_e32 v130, v130
	v_and_b32_e32 v181, 0xffff0000, v153
	v_mul_f32_e32 v139, v251, v139
	v_mul_f32_e32 v150, v139, v247
	v_add_f32_e32 v139, v141, v141
	v_mul_f32_e32 v139, 0x3fb8aa3b, v139
	v_exp_f32_e32 v139, v139
	v_add_f32_e32 v130, 1.0, v130
	v_rcp_f32_e32 v185, v130
	v_add_f32_e32 v130, v137, v33
	v_mul_f32_e32 v130, 0xbfb8aa3b, v130
	v_exp_f32_e32 v130, v130
	v_sub_f32_e32 v139, 1.0, v139
	v_max_f32_e32 v139, 0, v139
	v_sqrt_f32_e32 v139, v139
	v_add_f32_e32 v130, 1.0, v130
	v_rcp_f32_e32 v137, v130
	v_add_f32_e32 v130, v133, v29
	v_mul_f32_e32 v130, 0xbfb8aa3b, v130
	v_mul_f32_e32 v139, v252, v139
	v_exp_f32_e32 v130, v130
	v_mul_f32_e32 v151, v139, v248
	v_cvt_pk_bf16_f32 v139, v140, v141
	v_mul_f32_e32 v140, 0x42000000, v186
	v_mul_f32_e32 v141, 0x42000000, v187
	v_mul_f32_e32 v168, 0x42000000, v150
	v_med3_f32 v140, v140, s29, v231
	v_med3_f32 v141, v141, s29, v231
	v_mov_b32_e32 v150, 0
	v_cvt_pk_fp8_f32 v150, v140, v141
	v_add_f32_e32 v130, 1.0, v130
	v_mul_f32_e32 v151, 0x42000000, v151
	v_rcp_f32_e32 v186, v130
	v_pk_add_f32 v[130:131], v[192:193], v[200:201]
	v_med3_f32 v140, v168, s29, v231
	v_med3_f32 v141, v151, s29, v231
	v_pk_add_f32 v[132:133], v[130:131], v[192:193] neg_lo:[0,1] neg_hi:[0,1]
	v_cvt_pk_fp8_f32 v150, v140, v141 op_sel:[0,0,1]
	v_pk_add_f32 v[140:141], v[130:131], v[132:133] neg_lo:[0,1] neg_hi:[0,1]
	v_lshlrev_b32_e32 v151, 16, v152
	v_mov_b32_e32 v152, v200
	v_mov_b32_e32 v153, v192
	v_mov_b32_e32 v168, v132
	v_mov_b32_e32 v169, v140
	v_mov_b32_e32 v192, v201
	v_mov_b32_e32 v140, v133
	v_pk_add_f32 v[152:153], v[152:153], v[168:169] neg_lo:[0,1] neg_hi:[0,1]
	v_pk_add_f32 v[132:133], v[192:193], v[140:141] neg_lo:[0,1] neg_hi:[0,1]
	v_pk_add_f32 v[152:153], v[152:153], v[152:153] op_sel:[0,1] op_sel_hi:[1,0]
	v_pk_add_f32 v[132:133], v[132:133], v[132:133] op_sel_hi:[0,1]
	v_mov_b32_e32 v153, v195
	v_mov_b32_e32 v195, v133
	v_pk_add_f32 v[132:133], v[152:153], v[194:195]
	v_pk_add_f32 v[152:153], v[198:199], v[196:197]
	v_pk_add_f32 v[140:141], v[130:131], v[132:133]
	v_cmp_neq_f32_e32 vcc, s73, v235
	v_pk_add_f32 v[130:131], v[140:141], v[130:131] neg_lo:[0,1] neg_hi:[0,1]
	v_cmp_lt_f32_e64 s[14:15], |v237|, s77
	v_pk_add_f32 v[130:131], v[132:133], v[130:131] neg_lo:[0,1] neg_hi:[0,1]
	v_mov_b32_e32 v168, v220
	v_pk_add_f32 v[130:131], v[152:153], v[130:131]
	v_mov_b32_e32 v169, v212
	v_pk_add_f32 v[130:131], v[140:141], v[130:131]
	s_nop 0
	v_cndmask_b32_e32 v130, v228, v130, vcc
	v_cmp_neq_f32_e32 vcc, s73, v237
	s_nop 1
	v_cndmask_b32_e32 v131, v228, v131, vcc
	v_cmp_ngt_f32_e32 vcc, -1.0, v237
	s_nop 1
	v_cndmask_b32_e32 v131, v229, v131, vcc
	v_cmp_ngt_f32_e32 vcc, -1.0, v235
	s_nop 1
	v_cndmask_b32_e32 v130, v229, v130, vcc
	v_cmp_neq_f32_e32 vcc, -1.0, v235
	s_nop 1
	v_cndmask_b32_e32 v130, v230, v130, vcc
	v_cmp_neq_f32_e32 vcc, -1.0, v237
	s_nop 1
	v_cndmask_b32_e32 v131, v230, v131, vcc
	v_cmp_lt_f32_e64 vcc, |v235|, s77
	v_cndmask_b32_e64 v131, v131, v237, s[14:15]
	v_cmp_lt_f32_e64 s[14:15], |v240|, s77
	v_cndmask_b32_e32 v130, v130, v235, vcc
	v_pk_add_f32 v[130:131], v[178:179], v[130:131] neg_lo:[0,1] neg_hi:[0,1]
	v_cmp_neq_f32_e32 vcc, s73, v239
	v_pk_mul_f32 v[130:131], v[130:131], s[38:39] op_sel_hi:[1,0]
	s_nop 0
	v_pk_mul_f32 v[132:133], v[134:135], v[130:131]
	v_mul_f32_e32 v118, v118, v130
	v_add_f32_e32 v134, v132, v132
	v_mul_f32_e32 v134, 0x3fb8aa3b, v134
	v_exp_f32_e32 v134, v134
	v_cvt_pk_bf16_f32 v140, v132, v133
	v_mul_f32_e32 v119, v119, v131
	v_sub_f32_e32 v134, 1.0, v134
	v_max_f32_e32 v134, 0, v134
	v_sqrt_f32_e32 v134, v134
	s_nop 0
	v_mul_f32_e32 v134, v177, v134
	v_mul_f32_e32 v151, v134, v151
	v_add_f32_e32 v134, v133, v133
	v_mul_f32_e32 v134, 0x3fb8aa3b, v134
	v_exp_f32_e32 v134, v134
	v_pk_add_f32 v[132:133], v[212:213], v[220:221]
	v_sub_f32_e32 v134, 1.0, v134
	v_max_f32_e32 v134, 0, v134
	v_sqrt_f32_e32 v134, v134
	s_nop 0
	v_mul_f32_e32 v134, v184, v134
	v_mul_f32_e32 v178, v134, v176
	v_pk_add_f32 v[134:135], v[132:133], v[212:213] neg_lo:[0,1] neg_hi:[0,1]
	v_mov_b32_e32 v212, v221
	v_pk_add_f32 v[152:153], v[132:133], v[134:135] neg_lo:[0,1] neg_hi:[0,1]
	v_mov_b32_e32 v176, v134
	v_mov_b32_e32 v177, v152
	v_mov_b32_e32 v152, v135
	v_pk_add_f32 v[168:169], v[168:169], v[176:177] neg_lo:[0,1] neg_hi:[0,1]
	v_pk_add_f32 v[134:135], v[212:213], v[152:153] neg_lo:[0,1] neg_hi:[0,1]
	v_pk_add_f32 v[168:169], v[168:169], v[168:169] op_sel:[0,1] op_sel_hi:[1,0]
	v_pk_add_f32 v[134:135], v[134:135], v[134:135] op_sel_hi:[0,1]
	v_mov_b32_e32 v169, v215
	v_mov_b32_e32 v215, v135
	v_pk_add_f32 v[134:135], v[168:169], v[214:215]
	v_pk_add_f32 v[168:169], v[218:219], v[216:217]
	v_pk_add_f32 v[152:153], v[132:133], v[134:135]
	s_nop 0
	v_pk_add_f32 v[132:133], v[152:153], v[132:133] neg_lo:[0,1] neg_hi:[0,1]
	s_nop 0
	v_pk_add_f32 v[132:133], v[134:135], v[132:133] neg_lo:[0,1] neg_hi:[0,1]
	s_nop 0
	v_pk_add_f32 v[132:133], v[168:169], v[132:133]
	s_nop 0
	v_pk_add_f32 v[132:133], v[152:153], v[132:133]
	s_nop 0
	v_cndmask_b32_e32 v132, v228, v132, vcc
	v_cmp_neq_f32_e32 vcc, s73, v240
	s_nop 1
	v_cndmask_b32_e32 v133, v228, v133, vcc
	v_cmp_ngt_f32_e32 vcc, -1.0, v240
	s_nop 1
	v_cndmask_b32_e32 v133, v229, v133, vcc
	v_cmp_ngt_f32_e32 vcc, -1.0, v239
	s_nop 1
	v_cndmask_b32_e32 v132, v229, v132, vcc
	v_cmp_neq_f32_e32 vcc, -1.0, v239
	s_nop 1
	v_cndmask_b32_e32 v132, v230, v132, vcc
	v_cmp_neq_f32_e32 vcc, -1.0, v240
	s_nop 1
	v_cndmask_b32_e32 v133, v230, v133, vcc
	v_cmp_lt_f32_e64 vcc, |v239|, s77
	v_cndmask_b32_e64 v133, v133, v240, s[14:15]
	s_nop 0
	v_cndmask_b32_e32 v132, v132, v239, vcc
	v_pk_add_f32 v[132:133], v[182:183], v[132:133] neg_lo:[0,1] neg_hi:[0,1]
	s_nop 0
	v_pk_mul_f32 v[132:133], v[132:133], s[38:39] op_sel_hi:[1,0]
	s_nop 0
	v_pk_mul_f32 v[134:135], v[136:137], v[132:133]
	v_mul_f32_e32 v120, v120, v132
	v_add_f32_e32 v136, v134, v134
	v_add_f32_e32 v137, v135, v135
	v_mul_f32_e32 v136, 0x3fb8aa3b, v136
	v_mul_f32_e32 v137, 0x3fb8aa3b, v137
	v_exp_f32_e32 v136, v136
	v_exp_f32_e32 v137, v137
	v_cvt_pk_bf16_f32 v141, v134, v135
	v_mul_f32_e32 v134, 0x42000000, v151
	v_sub_f32_e32 v136, 1.0, v136
	v_sub_f32_e32 v137, 1.0, v137
	v_max_f32_e32 v136, 0, v136
	v_max_f32_e32 v137, 0, v137
	v_sqrt_f32_e32 v136, v136
	v_sqrt_f32_e32 v137, v137
	v_mul_f32_e32 v135, 0x42000000, v178
	v_med3_f32 v134, v134, s29, v231
	v_med3_f32 v135, v135, s29, v231
	v_mov_b32_e32 v151, 0
	v_mul_f32_e32 v136, v185, v136
	v_mul_f32_e32 v137, v186, v137
	v_cvt_pk_fp8_f32 v151, v134, v135
	v_mul_f32_e32 v136, v136, v180
	v_mul_f32_e32 v137, v137, v181
	v_mul_f32_e32 v136, 0x42000000, v136
	v_mul_f32_e32 v137, 0x42000000, v137
	v_med3_f32 v134, v136, s29, v231
	v_med3_f32 v135, v137, s29, v231
	v_cvt_pk_fp8_f32 v151, v134, v135 op_sel:[0,0,1]
	flat_store_dwordx4 v[172:173], v[138:141] nt
	flat_store_dwordx2 v[170:171], v[150:151] nt
	s_nop 0
	v_add_f32_e32 v138, v126, v126
	v_mul_f32_e32 v138, 0x3fb8aa3b, v138
	v_exp_f32_e32 v138, v138
	v_lshlrev_b32_e32 v134, 16, v146
	v_and_b32_e32 v135, 0xffff0000, v146
	v_lshlrev_b32_e32 v136, 16, v147
	v_sub_f32_e32 v138, 1.0, v138
	v_max_f32_e32 v138, 0, v138
	v_sqrt_f32_e32 v138, v138
	v_and_b32_e32 v137, 0xffff0000, v147
	v_mul_f32_e32 v121, v121, v133
	v_mul_f32_e32 v122, v122, v138
	v_mul_f32_e32 v134, v122, v134
	v_add_f32_e32 v122, v127, v47
	v_mul_f32_e32 v122, 0xbfb8aa3b, v122
	v_exp_f32_e32 v122, v122
	s_nop 0
	v_add_f32_e32 v122, 1.0, v122
	v_rcp_f32_e32 v122, v122
	s_nop 0
	v_mul_f32_e32 v122, v122, v145
	v_add_f32_e32 v127, v122, v122
	v_mul_f32_e32 v127, 0x3fb8aa3b, v127
	v_exp_f32_e32 v127, v127
	v_cvt_pk_bf16_f32 v122, v126, v122
	v_mul_f32_e32 v126, 0x42000000, v134
	v_sub_f32_e32 v127, 1.0, v127
	v_max_f32_e32 v127, 0, v127
	v_sqrt_f32_e32 v127, v127
	s_nop 0
	v_mul_f32_e32 v123, v123, v127
	v_mul_f32_e32 v127, v123, v135
	v_add_f32_e32 v123, v128, v48
	v_mul_f32_e32 v123, 0xbfb8aa3b, v123
	v_exp_f32_e32 v123, v123
	v_mul_f32_e32 v127, 0x42000000, v127
	v_med3_f32 v127, v127, s29, v231
	v_add_f32_e32 v123, 1.0, v123
	v_rcp_f32_e32 v123, v123
	s_nop 0
	v_mul_f32_e32 v123, v123, v142
	v_add_f32_e32 v128, v123, v123
	v_mul_f32_e32 v128, 0x3fb8aa3b, v128
	v_exp_f32_e32 v128, v128
	s_nop 0
	v_sub_f32_e32 v128, 1.0, v128
	v_max_f32_e32 v128, 0, v128
	v_sqrt_f32_e32 v128, v128
	s_nop 0
	v_mul_f32_e32 v124, v124, v128
	v_add_f32_e32 v128, v129, v49
	v_mul_f32_e32 v128, 0xbfb8aa3b, v128
	v_exp_f32_e32 v128, v128
	v_mul_f32_e32 v124, v124, v136
	v_mul_f32_e32 v124, 0x42000000, v124
	v_med3_f32 v124, v124, s29, v231
	v_add_f32_e32 v128, 1.0, v128
	v_rcp_f32_e32 v128, v128
	s_nop 0
	v_mul_f32_e32 v128, v128, v143
	v_add_f32_e32 v129, v128, v128
	v_mul_f32_e32 v129, 0x3fb8aa3b, v129
	v_exp_f32_e32 v129, v129
	v_cvt_pk_bf16_f32 v123, v123, v128
	v_med3_f32 v128, v126, s29, v231
	v_mov_b32_e32 v126, 0
	v_sub_f32_e32 v129, 1.0, v129
	v_max_f32_e32 v129, 0, v129
	v_sqrt_f32_e32 v129, v129
	v_cvt_pk_fp8_f32 v126, v128, v127
	v_lshlrev_b32_e32 v127, 16, v149
	v_and_b32_e32 v128, 0xffff0000, v149
	v_mul_f32_e32 v125, v125, v129
	v_add_f32_e32 v129, v118, v118
	v_mul_f32_e32 v129, 0x3fb8aa3b, v129
	v_exp_f32_e32 v129, v129
	v_mul_f32_e32 v125, v125, v137
	v_mul_f32_e32 v125, 0x42000000, v125
	v_med3_f32 v125, v125, s29, v231
	v_sub_f32_e32 v129, 1.0, v129
	v_max_f32_e32 v129, 0, v129
	v_sqrt_f32_e32 v129, v129
	v_cvt_pk_fp8_f32 v126, v124, v125 op_sel:[0,0,1]
	v_lshlrev_b32_e32 v124, 16, v148
	v_and_b32_e32 v125, 0xffff0000, v148
	v_mul_f32_e32 v114, v114, v129
	v_mul_f32_e32 v114, v114, v124
	v_add_f32_e32 v124, v119, v119
	v_mul_f32_e32 v124, 0x3fb8aa3b, v124
	v_exp_f32_e32 v124, v124
	v_mul_f32_e32 v114, 0x42000000, v114
	v_med3_f32 v114, v114, s29, v231
	v_sub_f32_e32 v124, 1.0, v124
	v_max_f32_e32 v124, 0, v124
	v_sqrt_f32_e32 v124, v124
	s_nop 0
	v_mul_f32_e32 v115, v115, v124
	v_add_f32_e32 v124, v120, v120
	v_mul_f32_e32 v124, 0x3fb8aa3b, v124
	v_exp_f32_e32 v124, v124
	v_mul_f32_e32 v115, v115, v125
	v_mul_f32_e32 v115, 0x42000000, v115
	v_med3_f32 v115, v115, s29, v231
	v_sub_f32_e32 v124, 1.0, v124
	v_max_f32_e32 v124, 0, v124
	v_sqrt_f32_e32 v124, v124
	v_cvt_pk_bf16_f32 v125, v120, v121
	v_mul_f32_e32 v116, v116, v124
	v_add_f32_e32 v124, v121, v121
	v_mul_f32_e32 v124, 0x3fb8aa3b, v124
	v_exp_f32_e32 v124, v124
	v_mul_f32_e32 v116, v116, v127
	v_mov_b32_e32 v127, 0
	v_cvt_pk_fp8_f32 v127, v114, v115
	v_sub_f32_e32 v124, 1.0, v124
	v_max_f32_e32 v124, 0, v124
	v_sqrt_f32_e32 v124, v124
	v_mul_f32_e32 v116, 0x42000000, v116
	v_med3_f32 v114, v116, s29, v231
	v_mul_f32_e32 v117, v117, v124
	v_mul_f32_e32 v117, v117, v128
	v_mul_f32_e32 v117, 0x42000000, v117
	v_med3_f32 v115, v117, s29, v231
	v_cvt_pk_fp8_f32 v127, v114, v115 op_sel:[0,0,1]
	v_add_co_u32_e32 v114, vcc, s84, v172
	v_cvt_pk_bf16_f32 v124, v118, v119
	s_nop 0
	v_addc_co_u32_e32 v115, vcc, 0, v173, vcc
	flat_store_dwordx4 v[114:115], v[122:125] nt
	v_add_co_u32_e32 v114, vcc, s93, v170
	s_nop 1
	v_addc_co_u32_e32 v115, vcc, 0, v171, vcc
	flat_store_dwordx2 v[114:115], v[126:127] nt
	v_add_co_u32_e32 v114, vcc, s92, v174
	v_add_f32_e32 v110, v110, v46
	s_nop 0
	v_addc_co_u32_e32 v115, vcc, 0, v175, vcc
	flat_load_dwordx4 v[114:117], v[114:115]
	v_mul_f32_e32 v110, 0xbfb8aa3b, v110
	v_add_f32_e32 v111, v111, v47
	v_exp_f32_e32 v110, v110
	v_mul_f32_e32 v111, 0xbfb8aa3b, v111
	v_exp_f32_e32 v111, v111
	v_add_f32_e32 v112, v112, v48
	v_add_f32_e32 v113, v113, v49
	v_add_f32_e32 v110, 1.0, v110
	v_mul_f32_e32 v112, 0xbfb8aa3b, v112
	v_mul_f32_e32 v113, 0xbfb8aa3b, v113
	v_rcp_f32_e32 v110, v110
	v_exp_f32_e32 v112, v112
	v_exp_f32_e32 v113, v113
	v_add_f32_e32 v111, 1.0, v111
	v_rcp_f32_e32 v111, v111
	v_add_co_u32_e32 v118, vcc, s89, v174
	v_add_f32_e32 v120, v106, v42
	s_nop 0
	v_addc_co_u32_e32 v119, vcc, 0, v175, vcc
	v_add_f32_e32 v122, v108, v44
	v_mul_f32_e32 v110, v110, v144
	v_add_f32_e32 v121, v107, v43
	v_add_f32_e32 v123, v109, v45
	flat_load_dwordx4 v[106:109], v[118:119]
	v_mul_f32_e32 v118, 0xbfb8aa3b, v120
	v_mul_f32_e32 v120, 0xbfb8aa3b, v122
	v_add_f32_e32 v112, 1.0, v112
	v_add_f32_e32 v113, 1.0, v113
	v_add_f32_e32 v122, v110, v110
	v_rcp_f32_e32 v112, v112
	v_rcp_f32_e32 v113, v113
	v_mul_f32_e32 v111, v111, v145
	v_mul_f32_e32 v122, 0x3fb8aa3b, v122
	v_mul_f32_e32 v119, 0xbfb8aa3b, v121
	v_mul_f32_e32 v121, 0xbfb8aa3b, v123
	v_add_f32_e32 v123, v111, v111
	v_exp_f32_e32 v122, v122
	v_exp_f32_e32 v118, v118
	v_mul_f32_e32 v123, 0x3fb8aa3b, v123
	v_exp_f32_e32 v123, v123
	v_exp_f32_e32 v119, v119
	v_mul_f32_e32 v112, v112, v142
	v_mul_f32_e32 v113, v113, v143
	v_add_f32_e32 v124, v112, v112
	v_add_f32_e32 v125, v113, v113
	v_sub_f32_e32 v122, 1.0, v122
	v_add_f32_e32 v118, 1.0, v118
	v_mul_f32_e32 v124, 0x3fb8aa3b, v124
	v_mul_f32_e32 v125, 0x3fb8aa3b, v125
	v_max_f32_e32 v122, 0, v122
	v_rcp_f32_e32 v118, v118
	v_exp_f32_e32 v124, v124
	v_exp_f32_e32 v125, v125
	v_sub_f32_e32 v123, 1.0, v123
	v_sqrt_f32_e32 v122, v122
	v_exp_f32_e32 v120, v120
	v_exp_f32_e32 v121, v121
	v_add_f32_e32 v119, 1.0, v119
	v_max_f32_e32 v123, 0, v123
	v_rcp_f32_e32 v119, v119
	v_sqrt_f32_e32 v123, v123
	v_add_f32_e32 v102, v102, v30
	v_mul_f32_e32 v102, 0xbfb8aa3b, v102
	v_sub_f32_e32 v124, 1.0, v124
	v_sub_f32_e32 v125, 1.0, v125
	v_mul_f32_e32 v118, v118, v122
	v_exp_f32_e32 v102, v102
	v_add_f32_e32 v120, 1.0, v120
	v_add_f32_e32 v121, 1.0, v121
	v_max_f32_e32 v124, 0, v124
	v_rcp_f32_e32 v120, v120
	v_rcp_f32_e32 v121, v121
	v_sqrt_f32_e32 v124, v124
	v_mul_f32_e32 v119, v119, v123
	v_cvt_pk_bf16_f32 v110, v110, v111
	v_cvt_pk_bf16_f32 v111, v112, v113
	v_add_f32_e32 v102, 1.0, v102
	v_rcp_f32_e32 v102, v102
	s_waitcnt vmcnt(0) lgkmcnt(0)
	v_lshlrev_b32_e32 v122, 16, v114
	v_mul_f32_e32 v118, v118, v122
	v_max_f32_e32 v122, 0, v125
	v_and_b32_e32 v114, 0xffff0000, v114
	v_sqrt_f32_e32 v122, v122
	v_mul_f32_e32 v114, v119, v114
	v_mul_f32_e32 v112, 0x42000000, v118
	v_mul_f32_e32 v113, 0x42000000, v114
	v_med3_f32 v112, v112, s29, v231
	v_med3_f32 v113, v113, s29, v231
	v_mov_b32_e32 v114, 0
	v_lshlrev_b32_e32 v123, 16, v115
	v_and_b32_e32 v115, 0xffff0000, v115
	v_mul_f32_e32 v119, v120, v124
	v_mul_f32_e32 v120, v121, v122
	v_cvt_pk_fp8_f32 v114, v112, v113
	v_mul_f32_e32 v119, v119, v123
	v_mul_f32_e32 v115, v120, v115
	v_mul_f32_e32 v118, 0x42000000, v119
	v_mul_f32_e32 v112, 0x42000000, v115
	v_med3_f32 v113, v118, s29, v231
	v_med3_f32 v112, v112, s29, v231
	v_mul_f32_e32 v102, v102, v130
	v_cvt_pk_fp8_f32 v114, v113, v112 op_sel:[0,0,1]
	v_lshlrev_b32_e32 v112, 16, v116
	v_and_b32_e32 v113, 0xffff0000, v116
	v_add_f32_e32 v116, v102, v102
	v_add_f32_e32 v103, v103, v31
	v_add_f32_e32 v98, v98, v26
	v_mul_f32_e32 v116, 0x3fb8aa3b, v116
	v_mul_f32_e32 v103, 0xbfb8aa3b, v103
	v_mul_f32_e32 v98, 0xbfb8aa3b, v98
	v_exp_f32_e32 v116, v116
	v_exp_f32_e32 v103, v103
	v_exp_f32_e32 v98, v98
	v_add_f32_e32 v104, v104, v32
	v_sub_f32_e32 v116, 1.0, v116
	v_add_f32_e32 v103, 1.0, v103
	v_add_f32_e32 v98, 1.0, v98
	v_max_f32_e32 v116, 0, v116
	v_rcp_f32_e32 v103, v103
	v_rcp_f32_e32 v98, v98
	v_sqrt_f32_e32 v116, v116
	v_add_f32_e32 v105, v105, v33
	v_mul_f32_e32 v103, v103, v131
	v_add_f32_e32 v99, v99, v27
	v_mul_f32_e32 v98, v98, v116
	v_add_f32_e32 v116, v103, v103
	v_mul_f32_e32 v116, 0x3fb8aa3b, v116
	v_mul_f32_e32 v104, 0xbfb8aa3b, v104
	v_mul_f32_e32 v105, 0xbfb8aa3b, v105
	v_mul_f32_e32 v99, 0xbfb8aa3b, v99
	v_exp_f32_e32 v116, v116
	v_exp_f32_e32 v104, v104
	v_exp_f32_e32 v105, v105
	v_exp_f32_e32 v99, v99
	v_sub_f32_e32 v116, 1.0, v116
	v_add_f32_e32 v104, 1.0, v104
	v_add_f32_e32 v105, 1.0, v105
	v_add_f32_e32 v99, 1.0, v99
	v_max_f32_e32 v116, 0, v116
	v_rcp_f32_e32 v104, v104
	v_rcp_f32_e32 v105, v105
	v_rcp_f32_e32 v99, v99
	v_sqrt_f32_e32 v116, v116
	v_mul_f32_e32 v104, v104, v132
	v_mul_f32_e32 v105, v105, v133
	v_mul_f32_e32 v98, v98, v112
	v_mul_f32_e32 v99, v99, v116
	v_add_f32_e32 v112, v104, v104
	v_add_f32_e32 v116, v105, v105
	v_add_f32_e32 v100, v100, v28
	v_mul_f32_e32 v112, 0x3fb8aa3b, v112
	v_add_f32_e32 v101, v101, v29
	v_mul_f32_e32 v116, 0x3fb8aa3b, v116
	v_mul_f32_e32 v100, 0xbfb8aa3b, v100
	v_exp_f32_e32 v112, v112
	v_mul_f32_e32 v101, 0xbfb8aa3b, v101
	v_exp_f32_e32 v116, v116
	v_add_f32_e32 v94, v94, v46
	v_exp_f32_e32 v100, v100
	v_exp_f32_e32 v101, v101
	v_mul_f32_e32 v94, 0xbfb8aa3b, v94
	v_exp_f32_e32 v94, v94
	v_sub_f32_e32 v112, 1.0, v112
	v_sub_f32_e32 v116, 1.0, v116
	v_add_f32_e32 v100, 1.0, v100
	v_max_f32_e32 v112, 0, v112
	v_add_f32_e32 v101, 1.0, v101
	v_max_f32_e32 v116, 0, v116
	v_rcp_f32_e32 v100, v100
	v_sqrt_f32_e32 v112, v112
	v_rcp_f32_e32 v101, v101
	v_sqrt_f32_e32 v116, v116
	v_add_f32_e32 v94, 1.0, v94
	v_rcp_f32_e32 v94, v94
	v_mul_f32_e32 v99, v99, v113
	v_lshlrev_b32_e32 v115, 16, v117
	v_and_b32_e32 v117, 0xffff0000, v117
	v_mul_f32_e32 v100, v100, v112
	v_mul_f32_e32 v101, v101, v116
	v_mul_f32_e32 v98, 0x42000000, v98
	v_mul_f32_e32 v99, 0x42000000, v99
	v_mul_f32_e32 v100, v100, v115
	v_mul_f32_e32 v101, v101, v117
	v_med3_f32 v98, v98, s29, v231
	v_med3_f32 v99, v99, s29, v231
	v_mov_b32_e32 v115, 0
	v_mul_f32_e32 v94, v94, v144
	v_cvt_pk_fp8_f32 v115, v98, v99
	v_mul_f32_e32 v98, 0x42000000, v101
	v_add_f32_e32 v101, v94, v94
	v_add_f32_e32 v95, v95, v47
	v_add_f32_e32 v90, v90, v42
	v_mul_f32_e32 v101, 0x3fb8aa3b, v101
	v_mul_f32_e32 v95, 0xbfb8aa3b, v95
	v_mul_f32_e32 v90, 0xbfb8aa3b, v90
	v_exp_f32_e32 v101, v101
	v_exp_f32_e32 v95, v95
	v_exp_f32_e32 v90, v90
	v_add_f32_e32 v91, v91, v43
	v_sub_f32_e32 v101, 1.0, v101
	v_add_f32_e32 v95, 1.0, v95
	v_add_f32_e32 v90, 1.0, v90
	v_max_f32_e32 v101, 0, v101
	v_rcp_f32_e32 v95, v95
	v_rcp_f32_e32 v90, v90
	v_sqrt_f32_e32 v101, v101
	v_add_f32_e32 v96, v96, v48
	v_mul_f32_e32 v95, v95, v145
	v_mul_f32_e32 v91, 0xbfb8aa3b, v91
	v_mul_f32_e32 v90, v90, v101
	v_add_f32_e32 v101, v95, v95
	v_mul_f32_e32 v101, 0x3fb8aa3b, v101
	v_exp_f32_e32 v101, v101
	v_mul_f32_e32 v96, 0xbfb8aa3b, v96
	v_add_f32_e32 v97, v97, v49
	v_exp_f32_e32 v91, v91
	v_exp_f32_e32 v96, v96
	v_mul_f32_e32 v97, 0xbfb8aa3b, v97
	v_exp_f32_e32 v97, v97
	v_mul_f32_e32 v100, 0x42000000, v100
	v_med3_f32 v99, v100, s29, v231
	v_med3_f32 v98, v98, s29, v231
	v_sub_f32_e32 v101, 1.0, v101
	v_add_f32_e32 v92, v92, v44
	v_cvt_pk_fp8_f32 v115, v99, v98 op_sel:[0,0,1]
	v_add_co_u32_e32 v98, vcc, s92, v172
	v_add_f32_e32 v91, 1.0, v91
	v_max_f32_e32 v101, 0, v101
	v_add_f32_e32 v96, 1.0, v96
	v_mul_f32_e32 v92, 0xbfb8aa3b, v92
	v_cvt_pk_bf16_f32 v112, v102, v103
	v_cvt_pk_bf16_f32 v113, v104, v105
	v_addc_co_u32_e32 v99, vcc, 0, v173, vcc
	v_rcp_f32_e32 v91, v91
	v_sqrt_f32_e32 v101, v101
	v_exp_f32_e32 v92, v92
	v_rcp_f32_e32 v96, v96
	v_add_f32_e32 v97, 1.0, v97
	flat_store_dwordx4 v[98:99], v[110:113] nt
	v_add_co_u32_e32 v98, vcc, s84, v170
	v_rcp_f32_e32 v97, v97
	s_nop 0
	v_addc_co_u32_e32 v99, vcc, 0, v171, vcc
	flat_store_dwordx2 v[98:99], v[114:115] nt
	v_lshlrev_b32_e32 v98, 16, v106
	v_mul_f32_e32 v98, v90, v98
	v_mul_f32_e32 v90, v91, v101
	v_add_f32_e32 v91, 1.0, v92
	v_mul_f32_e32 v92, v96, v142
	v_add_f32_e32 v96, v92, v92
	v_mul_f32_e32 v97, v97, v143
	v_mul_f32_e32 v96, 0x3fb8aa3b, v96
	v_add_f32_e32 v101, v97, v97
	v_exp_f32_e32 v96, v96
	v_add_f32_e32 v93, v93, v45
	v_mul_f32_e32 v101, 0x3fb8aa3b, v101
	v_mul_f32_e32 v93, 0xbfb8aa3b, v93
	v_exp_f32_e32 v101, v101
	v_exp_f32_e32 v93, v93
	v_add_f32_e32 v86, v86, v30
	v_mul_f32_e32 v86, 0xbfb8aa3b, v86
	v_sub_f32_e32 v96, 1.0, v96
	v_exp_f32_e32 v86, v86
	v_max_f32_e32 v96, 0, v96
	v_sub_f32_e32 v101, 1.0, v101
	v_rcp_f32_e32 v91, v91
	v_sqrt_f32_e32 v96, v96
	v_add_f32_e32 v93, 1.0, v93
	v_max_f32_e32 v101, 0, v101
	v_rcp_f32_e32 v93, v93
	v_sqrt_f32_e32 v101, v101
	v_add_f32_e32 v86, 1.0, v86
	v_and_b32_e32 v99, 0xffff0000, v106
	v_rcp_f32_e32 v86, v86
	v_lshlrev_b32_e32 v100, 16, v107
	v_mul_f32_e32 v99, v90, v99
	v_mul_f32_e32 v90, v91, v96
	v_and_b32_e32 v102, 0xffff0000, v107
	v_mul_f32_e32 v96, v90, v100
	v_mul_f32_e32 v90, v93, v101
	v_mul_f32_e32 v93, v90, v102
	v_cvt_pk_bf16_f32 v90, v94, v95
	v_cvt_pk_bf16_f32 v91, v92, v97
	v_mul_f32_e32 v92, 0x42000000, v98
	v_mul_f32_e32 v94, 0x42000000, v99
	v_mul_f32_e32 v95, 0x42000000, v96
	v_med3_f32 v92, v92, s29, v231
	v_med3_f32 v96, v94, s29, v231
	v_mov_b32_e32 v94, 0
	v_mul_f32_e32 v86, v86, v130
	v_cvt_pk_fp8_f32 v94, v92, v96
	v_add_f32_e32 v96, v86, v86
	v_add_f32_e32 v87, v87, v31
	v_add_f32_e32 v82, v82, v26
	v_mul_f32_e32 v96, 0x3fb8aa3b, v96
	v_mul_f32_e32 v87, 0xbfb8aa3b, v87
	v_mul_f32_e32 v82, 0xbfb8aa3b, v82
	v_exp_f32_e32 v96, v96
	v_exp_f32_e32 v87, v87
	v_exp_f32_e32 v82, v82
	v_add_f32_e32 v88, v88, v32
	v_sub_f32_e32 v96, 1.0, v96
	v_add_f32_e32 v87, 1.0, v87
	v_add_f32_e32 v82, 1.0, v82
	v_max_f32_e32 v96, 0, v96
	v_rcp_f32_e32 v87, v87
	v_rcp_f32_e32 v82, v82
	v_sqrt_f32_e32 v96, v96
	v_mul_f32_e32 v88, 0xbfb8aa3b, v88
	v_mul_f32_e32 v87, v87, v131
	v_exp_f32_e32 v88, v88
	v_mul_f32_e32 v82, v82, v96
	v_add_f32_e32 v96, v87, v87
	v_add_f32_e32 v89, v89, v33
	v_add_f32_e32 v83, v83, v27
	v_mul_f32_e32 v96, 0x3fb8aa3b, v96
	v_mul_f32_e32 v89, 0xbfb8aa3b, v89
	v_mul_f32_e32 v83, 0xbfb8aa3b, v83
	v_exp_f32_e32 v96, v96
	v_exp_f32_e32 v89, v89
	v_exp_f32_e32 v83, v83
	v_add_f32_e32 v88, 1.0, v88
	v_rcp_f32_e32 v88, v88
	v_sub_f32_e32 v96, 1.0, v96
	v_add_f32_e32 v89, 1.0, v89
	v_mul_f32_e32 v92, 0x42000000, v93
	v_add_f32_e32 v83, 1.0, v83
	v_max_f32_e32 v96, 0, v96
	v_rcp_f32_e32 v89, v89
	v_med3_f32 v93, v95, s29, v231
	v_med3_f32 v92, v92, s29, v231
	v_rcp_f32_e32 v83, v83
	v_sqrt_f32_e32 v96, v96
	v_cvt_pk_fp8_f32 v94, v93, v92 op_sel:[0,0,1]
	v_lshlrev_b32_e32 v92, 16, v108
	v_mul_f32_e32 v88, v88, v132
	v_mul_f32_e32 v82, v82, v92
	v_add_f32_e32 v92, v88, v88
	v_add_f32_e32 v84, v84, v28
	v_mul_f32_e32 v92, 0x3fb8aa3b, v92
	v_mul_f32_e32 v89, v89, v133
	v_mul_f32_e32 v84, 0xbfb8aa3b, v84
	v_mul_f32_e32 v83, v83, v96
	v_exp_f32_e32 v92, v92
	v_add_f32_e32 v96, v89, v89
	v_exp_f32_e32 v84, v84
	v_add_f32_e32 v85, v85, v29
	v_mul_f32_e32 v96, 0x3fb8aa3b, v96
	v_mul_f32_e32 v85, 0xbfb8aa3b, v85
	v_exp_f32_e32 v96, v96
	v_exp_f32_e32 v85, v85
	v_sub_f32_e32 v92, 1.0, v92
	v_add_f32_e32 v84, 1.0, v84
	v_max_f32_e32 v92, 0, v92
	v_rcp_f32_e32 v84, v84
	v_sqrt_f32_e32 v92, v92
	v_sub_f32_e32 v96, 1.0, v96
	v_add_f32_e32 v85, 1.0, v85
	v_max_f32_e32 v96, 0, v96
	v_and_b32_e32 v93, 0xffff0000, v108
	v_rcp_f32_e32 v85, v85
	v_sqrt_f32_e32 v96, v96
	v_mul_f32_e32 v83, v83, v93
	v_lshlrev_b32_e32 v95, 16, v109
	v_mul_f32_e32 v84, v84, v92
	v_mul_f32_e32 v82, 0x42000000, v82
	v_mul_f32_e32 v83, 0x42000000, v83
	v_mul_f32_e32 v84, v84, v95
	v_med3_f32 v82, v82, s29, v231
	v_med3_f32 v83, v83, s29, v231
	v_mov_b32_e32 v95, 0
	v_and_b32_e32 v97, 0xffff0000, v109
	v_mul_f32_e32 v85, v85, v96
	v_cvt_pk_fp8_f32 v95, v82, v83
	v_mul_f32_e32 v85, v85, v97
	v_mul_f32_e32 v84, 0x42000000, v84
	v_mul_f32_e32 v82, 0x42000000, v85
	v_med3_f32 v83, v84, s29, v231
	v_med3_f32 v82, v82, s29, v231
	v_cvt_pk_fp8_f32 v95, v83, v82 op_sel:[0,0,1]
	v_add_co_u32_e32 v82, vcc, s89, v172
	v_cvt_pk_bf16_f32 v92, v86, v87
	v_cvt_pk_bf16_f32 v93, v88, v89
	v_addc_co_u32_e32 v83, vcc, 0, v173, vcc
	s_mov_b32 s0, 0xc000
	flat_store_dwordx4 v[82:83], v[90:93] nt
	v_add_co_u32_e32 v82, vcc, s0, v170
	s_nop 1
	v_addc_co_u32_e32 v83, vcc, 0, v171, vcc
	flat_store_dwordx2 v[82:83], v[94:95] nt
	v_add_u32_e32 v82, 0x80, v234
	v_add_f32_e32 v78, v78, v46
	v_ashrrev_i32_e32 v83, 31, v82
	v_lshlrev_b64 v[82:83], 10, v[82:83]
	v_lshl_add_u64 v[88:89], v[82:83], 0, v[166:167]
	v_lshlrev_b64 v[90:91], 1, v[88:89]
	v_lshl_add_u64 v[82:83], s[24:25], 0, v[90:91]
	flat_load_dwordx4 v[84:87], v[82:83]
	v_mul_f32_e32 v78, 0xbfb8aa3b, v78
	v_exp_f32_e32 v92, v78
	v_add_f32_e32 v79, v79, v47
	v_add_f32_e32 v80, v80, v48
	v_mul_f32_e32 v79, 0xbfb8aa3b, v79
	v_add_f32_e32 v74, v74, v42
	v_add_f32_e32 v81, v81, v49
	v_mul_f32_e32 v80, 0xbfb8aa3b, v80
	v_exp_f32_e32 v93, v79
	v_add_f32_e32 v75, v75, v43
	v_add_f32_e32 v76, v76, v44
	v_add_f32_e32 v77, v77, v45
	v_mul_f32_e32 v74, 0xbfb8aa3b, v74
	v_mul_f32_e32 v81, 0xbfb8aa3b, v81
	v_exp_f32_e32 v94, v80
	v_lshl_add_u64 v[78:79], s[50:51], 0, v[88:89]
	v_add_f32_e32 v88, 1.0, v92
	v_mul_f32_e32 v75, 0xbfb8aa3b, v75
	v_mul_f32_e32 v76, 0xbfb8aa3b, v76
	v_mul_f32_e32 v77, 0xbfb8aa3b, v77
	v_exp_f32_e32 v74, v74
	v_exp_f32_e32 v95, v81
	v_rcp_f32_e32 v88, v88
	v_exp_f32_e32 v75, v75
	v_exp_f32_e32 v76, v76
	v_exp_f32_e32 v77, v77
	v_lshl_add_u64 v[80:81], s[48:49], 0, v[90:91]
	v_add_f32_e32 v90, 1.0, v93
	v_add_f32_e32 v92, 1.0, v94
	v_rcp_f32_e32 v90, v90
	v_add_f32_e32 v89, 1.0, v74
	v_add_f32_e32 v93, 1.0, v95
	v_add_co_u32_e32 v74, vcc, s84, v82
	v_rcp_f32_e32 v92, v92
	v_mul_f32_e32 v88, v88, v144
	v_add_f32_e32 v91, 1.0, v75
	v_add_f32_e32 v76, 1.0, v76
	v_add_f32_e32 v77, 1.0, v77
	v_addc_co_u32_e32 v75, vcc, 0, v83, vcc
	v_rcp_f32_e32 v93, v93
	v_add_f32_e32 v96, v88, v88
	v_rcp_f32_e32 v94, v76
	v_rcp_f32_e32 v95, v77
	flat_load_dwordx4 v[74:77], v[74:75]
	v_mul_f32_e32 v96, 0x3fb8aa3b, v96
	v_mul_f32_e32 v90, v90, v145
	v_exp_f32_e32 v96, v96
	v_mul_f32_e32 v92, v92, v142
	v_add_f32_e32 v97, v90, v90
	v_mul_f32_e32 v93, v93, v143
	v_add_f32_e32 v98, v92, v92
	v_mul_f32_e32 v97, 0x3fb8aa3b, v97
	v_add_f32_e32 v99, v93, v93
	v_mul_f32_e32 v98, 0x3fb8aa3b, v98
	v_exp_f32_e32 v97, v97
	v_mul_f32_e32 v99, 0x3fb8aa3b, v99
	v_exp_f32_e32 v98, v98
	v_sub_f32_e32 v96, 1.0, v96
	v_exp_f32_e32 v99, v99
	v_max_f32_e32 v96, 0, v96
	v_rcp_f32_e32 v89, v89
	v_sqrt_f32_e32 v96, v96
	v_add_f32_e32 v70, v70, v30
	v_sub_f32_e32 v97, 1.0, v97
	v_mul_f32_e32 v70, 0xbfb8aa3b, v70
	v_sub_f32_e32 v98, 1.0, v98
	v_max_f32_e32 v97, 0, v97
	v_exp_f32_e32 v70, v70
	v_rcp_f32_e32 v91, v91
	v_sub_f32_e32 v99, 1.0, v99
	v_max_f32_e32 v98, 0, v98
	v_sqrt_f32_e32 v97, v97
	v_max_f32_e32 v99, 0, v99
	v_sqrt_f32_e32 v98, v98
	v_mul_f32_e32 v89, v89, v96
	v_add_f32_e32 v70, 1.0, v70
	v_mul_f32_e32 v91, v91, v97
	s_waitcnt vmcnt(0) lgkmcnt(0)
	v_lshlrev_b32_e32 v96, 16, v84
	v_mul_f32_e32 v89, v89, v96
	v_sqrt_f32_e32 v96, v99
	v_and_b32_e32 v84, 0xffff0000, v84
	v_rcp_f32_e32 v70, v70
	v_lshlrev_b32_e32 v97, 16, v85
	v_mul_f32_e32 v91, v91, v84
	v_mul_f32_e32 v84, v94, v98
	v_and_b32_e32 v85, 0xffff0000, v85
	v_mul_f32_e32 v94, v84, v97
	v_mul_f32_e32 v84, v95, v96
	v_mul_f32_e32 v95, v84, v85
	v_cvt_pk_bf16_f32 v84, v88, v90
	v_mul_f32_e32 v88, 0x42000000, v89
	v_mul_f32_e32 v89, 0x42000000, v91
	v_med3_f32 v91, v88, s29, v231
	v_med3_f32 v89, v89, s29, v231
	v_mov_b32_e32 v88, 0
	v_mul_f32_e32 v70, v70, v130
	v_cvt_pk_fp8_f32 v88, v91, v89
	v_add_f32_e32 v91, v70, v70
	v_add_f32_e32 v71, v71, v31
	v_add_f32_e32 v66, v66, v26
	v_mul_f32_e32 v91, 0x3fb8aa3b, v91
	v_mul_f32_e32 v71, 0xbfb8aa3b, v71
	v_mul_f32_e32 v66, 0xbfb8aa3b, v66
	v_exp_f32_e32 v91, v91
	v_exp_f32_e32 v71, v71
	v_exp_f32_e32 v66, v66
	v_add_f32_e32 v73, v73, v33
	v_sub_f32_e32 v91, 1.0, v91
	v_add_f32_e32 v71, 1.0, v71
	v_add_f32_e32 v66, 1.0, v66
	v_max_f32_e32 v91, 0, v91
	v_rcp_f32_e32 v71, v71
	v_rcp_f32_e32 v66, v66
	v_sqrt_f32_e32 v91, v91
	v_add_f32_e32 v67, v67, v27
	v_mul_f32_e32 v71, v71, v131
	v_add_f32_e32 v72, v72, v32
	v_mul_f32_e32 v66, v66, v91
	v_add_f32_e32 v91, v71, v71
	v_mul_f32_e32 v91, 0x3fb8aa3b, v91
	v_mul_f32_e32 v73, 0xbfb8aa3b, v73
	v_mul_f32_e32 v67, 0xbfb8aa3b, v67
	v_exp_f32_e32 v91, v91
	v_mul_f32_e32 v72, 0xbfb8aa3b, v72
	v_exp_f32_e32 v73, v73
	v_exp_f32_e32 v67, v67
	v_exp_f32_e32 v72, v72
	v_sub_f32_e32 v91, 1.0, v91
	v_add_f32_e32 v73, 1.0, v73
	v_add_f32_e32 v67, 1.0, v67
	v_max_f32_e32 v91, 0, v91
	v_add_f32_e32 v72, 1.0, v72
	v_rcp_f32_e32 v73, v73
	v_rcp_f32_e32 v67, v67
	v_sqrt_f32_e32 v91, v91
	v_rcp_f32_e32 v72, v72
	v_mul_f32_e32 v90, 0x42000000, v94
	v_mul_f32_e32 v89, 0x42000000, v95
	v_med3_f32 v90, v90, s29, v231
	v_med3_f32 v89, v89, s29, v231
	v_mul_f32_e32 v73, v73, v133
	v_cvt_pk_fp8_f32 v88, v90, v89 op_sel:[0,0,1]
	v_lshlrev_b32_e32 v89, 16, v86
	v_mul_f32_e32 v67, v67, v91
	v_mul_f32_e32 v72, v72, v132
	v_add_f32_e32 v91, v73, v73
	v_mul_f32_e32 v66, v66, v89
	v_add_f32_e32 v89, v72, v72
	v_add_f32_e32 v69, v69, v29
	v_mul_f32_e32 v91, 0x3fb8aa3b, v91
	v_add_f32_e32 v68, v68, v28
	v_mul_f32_e32 v89, 0x3fb8aa3b, v89
	v_mul_f32_e32 v69, 0xbfb8aa3b, v69
	v_exp_f32_e32 v91, v91
	v_add_f32_e32 v62, v62, v46
	v_mul_f32_e32 v68, 0xbfb8aa3b, v68
	v_exp_f32_e32 v89, v89
	v_exp_f32_e32 v69, v69
	v_mul_f32_e32 v62, 0xbfb8aa3b, v62
	v_exp_f32_e32 v68, v68
	v_exp_f32_e32 v62, v62
	v_sub_f32_e32 v91, 1.0, v91
	v_sub_f32_e32 v89, 1.0, v89
	v_add_f32_e32 v69, 1.0, v69
	v_max_f32_e32 v91, 0, v91
	v_add_f32_e32 v68, 1.0, v68
	v_max_f32_e32 v89, 0, v89
	v_rcp_f32_e32 v69, v69
	v_sqrt_f32_e32 v91, v91
	v_add_f32_e32 v62, 1.0, v62
	v_rcp_f32_e32 v68, v68
	v_sqrt_f32_e32 v89, v89
	v_rcp_f32_e32 v62, v62
	v_and_b32_e32 v86, 0xffff0000, v86
	v_mul_f32_e32 v67, v67, v86
	v_lshlrev_b32_e32 v90, 16, v87
	v_and_b32_e32 v87, 0xffff0000, v87
	v_mul_f32_e32 v69, v69, v91
	v_mul_f32_e32 v66, 0x42000000, v66
	v_mul_f32_e32 v67, 0x42000000, v67
	v_mul_f32_e32 v68, v68, v89
	v_mul_f32_e32 v69, v69, v87
	v_med3_f32 v66, v66, s29, v231
	v_med3_f32 v67, v67, s29, v231
	v_mov_b32_e32 v89, 0
	v_mul_f32_e32 v62, v62, v144
	v_cvt_pk_fp8_f32 v89, v66, v67
	v_mul_f32_e32 v66, 0x42000000, v69
	v_add_f32_e32 v69, v62, v62
	v_add_f32_e32 v63, v63, v47
	v_add_f32_e32 v58, v58, v42
	v_mul_f32_e32 v69, 0x3fb8aa3b, v69
	v_mul_f32_e32 v63, 0xbfb8aa3b, v63
	v_mul_f32_e32 v58, 0xbfb8aa3b, v58
	v_exp_f32_e32 v69, v69
	v_exp_f32_e32 v63, v63
	v_exp_f32_e32 v58, v58
	v_add_f32_e32 v59, v59, v43
	v_sub_f32_e32 v69, 1.0, v69
	v_add_f32_e32 v63, 1.0, v63
	v_add_f32_e32 v58, 1.0, v58
	v_max_f32_e32 v69, 0, v69
	v_rcp_f32_e32 v63, v63
	v_rcp_f32_e32 v58, v58
	v_sqrt_f32_e32 v69, v69
	v_add_f32_e32 v64, v64, v48
	v_mul_f32_e32 v63, v63, v145
	v_mul_f32_e32 v59, 0xbfb8aa3b, v59
	v_mul_f32_e32 v58, v58, v69
	v_add_f32_e32 v69, v63, v63
	v_mul_f32_e32 v69, 0x3fb8aa3b, v69
	v_exp_f32_e32 v69, v69
	v_mul_f32_e32 v64, 0xbfb8aa3b, v64
	v_add_f32_e32 v65, v65, v49
	v_exp_f32_e32 v59, v59
	v_exp_f32_e32 v64, v64
	v_mul_f32_e32 v65, 0xbfb8aa3b, v65
	v_exp_f32_e32 v65, v65
	v_sub_f32_e32 v69, 1.0, v69
	v_add_f32_e32 v60, v60, v44
	v_add_f32_e32 v59, 1.0, v59
	v_max_f32_e32 v69, 0, v69
	v_add_f32_e32 v64, 1.0, v64
	v_mul_f32_e32 v60, 0xbfb8aa3b, v60
	v_mul_f32_e32 v68, v68, v90
	v_rcp_f32_e32 v59, v59
	v_sqrt_f32_e32 v69, v69
	v_exp_f32_e32 v60, v60
	v_rcp_f32_e32 v64, v64
	v_add_f32_e32 v65, 1.0, v65
	v_mul_f32_e32 v68, 0x42000000, v68
	v_rcp_f32_e32 v65, v65
	v_med3_f32 v67, v68, s29, v231
	v_med3_f32 v66, v66, s29, v231
	v_cvt_pk_fp8_f32 v89, v67, v66 op_sel:[0,0,1]
	v_lshlrev_b32_e32 v66, 16, v74
	v_mul_f32_e32 v66, v58, v66
	v_mul_f32_e32 v58, v59, v69
	v_add_f32_e32 v59, 1.0, v60
	v_mul_f32_e32 v60, v64, v142
	v_add_f32_e32 v64, v60, v60
	v_mul_f32_e32 v65, v65, v143
	v_mul_f32_e32 v64, 0x3fb8aa3b, v64
	v_add_f32_e32 v69, v65, v65
	v_exp_f32_e32 v64, v64
	v_add_f32_e32 v61, v61, v45
	v_mul_f32_e32 v69, 0x3fb8aa3b, v69
	v_mul_f32_e32 v61, 0xbfb8aa3b, v61
	v_exp_f32_e32 v69, v69
	v_exp_f32_e32 v61, v61
	v_add_f32_e32 v54, v54, v30
	v_mul_f32_e32 v54, 0xbfb8aa3b, v54
	v_sub_f32_e32 v64, 1.0, v64
	v_exp_f32_e32 v54, v54
	v_max_f32_e32 v64, 0, v64
	v_sub_f32_e32 v69, 1.0, v69
	v_rcp_f32_e32 v59, v59
	v_sqrt_f32_e32 v64, v64
	v_add_f32_e32 v61, 1.0, v61
	v_max_f32_e32 v69, 0, v69
	v_rcp_f32_e32 v61, v61
	v_sqrt_f32_e32 v69, v69
	v_add_f32_e32 v54, 1.0, v54
	v_and_b32_e32 v67, 0xffff0000, v74
	v_rcp_f32_e32 v54, v54
	v_lshlrev_b32_e32 v68, 16, v75
	v_mul_f32_e32 v67, v58, v67
	v_mul_f32_e32 v58, v59, v64
	v_cvt_pk_bf16_f32 v86, v70, v71
	v_and_b32_e32 v70, 0xffff0000, v75
	v_mul_f32_e32 v64, v58, v68
	v_mul_f32_e32 v58, v61, v69
	v_mul_f32_e32 v61, v58, v70
	v_cvt_pk_bf16_f32 v58, v62, v63
	v_cvt_pk_bf16_f32 v59, v60, v65
	v_mul_f32_e32 v60, 0x42000000, v66
	v_mul_f32_e32 v62, 0x42000000, v67
	v_mul_f32_e32 v63, 0x42000000, v64
	v_med3_f32 v60, v60, s29, v231
	v_med3_f32 v64, v62, s29, v231
	v_mov_b32_e32 v62, 0
	v_mul_f32_e32 v54, v54, v130
	v_cvt_pk_fp8_f32 v62, v60, v64
	v_add_f32_e32 v64, v54, v54
	v_add_f32_e32 v55, v55, v31
	v_add_f32_e32 v50, v50, v26
	v_mul_f32_e32 v64, 0x3fb8aa3b, v64
	v_mul_f32_e32 v55, 0xbfb8aa3b, v55
	v_mul_f32_e32 v50, 0xbfb8aa3b, v50
	v_exp_f32_e32 v64, v64
	v_exp_f32_e32 v55, v55
	v_exp_f32_e32 v50, v50
	v_add_f32_e32 v56, v56, v32
	v_sub_f32_e32 v64, 1.0, v64
	v_add_f32_e32 v55, 1.0, v55
	v_add_f32_e32 v50, 1.0, v50
	v_max_f32_e32 v64, 0, v64
	v_rcp_f32_e32 v55, v55
	v_rcp_f32_e32 v50, v50
	v_sqrt_f32_e32 v64, v64
	v_mul_f32_e32 v56, 0xbfb8aa3b, v56
	v_mul_f32_e32 v55, v55, v131
	v_exp_f32_e32 v56, v56
	v_mul_f32_e32 v50, v50, v64
	v_add_f32_e32 v64, v55, v55
	v_add_f32_e32 v57, v57, v33
	v_add_f32_e32 v51, v51, v27
	v_mul_f32_e32 v64, 0x3fb8aa3b, v64
	v_mul_f32_e32 v57, 0xbfb8aa3b, v57
	v_mul_f32_e32 v51, 0xbfb8aa3b, v51
	v_exp_f32_e32 v64, v64
	v_exp_f32_e32 v57, v57
	v_exp_f32_e32 v51, v51
	v_add_f32_e32 v56, 1.0, v56
	v_rcp_f32_e32 v56, v56
	v_sub_f32_e32 v64, 1.0, v64
	v_add_f32_e32 v57, 1.0, v57
	v_mul_f32_e32 v60, 0x42000000, v61
	v_add_f32_e32 v51, 1.0, v51
	v_max_f32_e32 v64, 0, v64
	v_rcp_f32_e32 v57, v57
	v_med3_f32 v61, v63, s29, v231
	v_med3_f32 v60, v60, s29, v231
	v_rcp_f32_e32 v51, v51
	v_sqrt_f32_e32 v64, v64
	v_cvt_pk_fp8_f32 v62, v61, v60 op_sel:[0,0,1]
	v_lshlrev_b32_e32 v60, 16, v76
	v_mul_f32_e32 v56, v56, v132
	v_mul_f32_e32 v50, v50, v60
	v_add_f32_e32 v60, v56, v56
	v_add_f32_e32 v52, v52, v28
	v_mul_f32_e32 v60, 0x3fb8aa3b, v60
	v_mul_f32_e32 v57, v57, v133
	v_mul_f32_e32 v52, 0xbfb8aa3b, v52
	v_mul_f32_e32 v51, v51, v64
	v_exp_f32_e32 v60, v60
	v_add_f32_e32 v64, v57, v57
	v_exp_f32_e32 v52, v52
	v_add_f32_e32 v53, v53, v29
	v_mul_f32_e32 v64, 0x3fb8aa3b, v64
	v_mul_f32_e32 v53, 0xbfb8aa3b, v53
	v_exp_f32_e32 v64, v64
	v_exp_f32_e32 v53, v53
	v_sub_f32_e32 v60, 1.0, v60
	v_add_f32_e32 v52, 1.0, v52
	v_max_f32_e32 v60, 0, v60
	v_rcp_f32_e32 v52, v52
	v_sqrt_f32_e32 v60, v60
	v_sub_f32_e32 v64, 1.0, v64
	v_add_f32_e32 v53, 1.0, v53
	v_max_f32_e32 v64, 0, v64
	v_and_b32_e32 v61, 0xffff0000, v76
	v_rcp_f32_e32 v53, v53
	v_sqrt_f32_e32 v64, v64
	v_mul_f32_e32 v51, v51, v61
	v_lshlrev_b32_e32 v63, 16, v77
	v_mul_f32_e32 v52, v52, v60
	v_mul_f32_e32 v50, 0x42000000, v50
	v_mul_f32_e32 v51, 0x42000000, v51
	v_mul_f32_e32 v52, v52, v63
	v_med3_f32 v50, v50, s29, v231
	v_med3_f32 v51, v51, s29, v231
	v_mov_b32_e32 v63, 0
	v_and_b32_e32 v65, 0xffff0000, v77
	v_mul_f32_e32 v53, v53, v64
	v_cvt_pk_fp8_f32 v63, v50, v51
	v_mul_f32_e32 v53, v53, v65
	v_mul_f32_e32 v52, 0x42000000, v52
	v_mul_f32_e32 v50, 0x42000000, v53
	v_med3_f32 v51, v52, s29, v231
	v_med3_f32 v50, v50, s29, v231
	v_cvt_pk_fp8_f32 v63, v51, v50 op_sel:[0,0,1]
	v_add_co_u32_e32 v50, vcc, s84, v80
	v_cvt_pk_bf16_f32 v85, v92, v93
	v_cvt_pk_bf16_f32 v87, v72, v73
	v_cvt_pk_bf16_f32 v60, v54, v55
	v_cvt_pk_bf16_f32 v61, v56, v57
	v_addc_co_u32_e32 v51, vcc, 0, v81, vcc
	flat_store_dwordx4 v[80:81], v[84:87] nt
	flat_store_dwordx2 v[78:79], v[88:89] nt
	flat_store_dwordx4 v[50:51], v[58:61] nt
	v_add_co_u32_e32 v50, vcc, s93, v78
	s_nop 1
	v_addc_co_u32_e32 v51, vcc, 0, v79, vcc
	flat_store_dwordx2 v[50:51], v[62:63] nt
	v_add_co_u32_e32 v50, vcc, s92, v82
	v_add_f32_e32 v38, v38, v46
	s_nop 0
	v_addc_co_u32_e32 v51, vcc, 0, v83, vcc
	flat_load_dwordx4 v[54:57], v[50:51]
	v_mul_f32_e32 v38, 0xbfb8aa3b, v38
	v_exp_f32_e32 v38, v38
	v_add_f32_e32 v34, v34, v42
	v_mul_f32_e32 v34, 0xbfb8aa3b, v34
	v_exp_f32_e32 v34, v34
	v_add_f32_e32 v38, 1.0, v38
	v_rcp_f32_e32 v38, v38
	v_add_f32_e32 v39, v39, v47
	v_add_f32_e32 v34, 1.0, v34
	v_mul_f32_e32 v39, 0xbfb8aa3b, v39
	v_exp_f32_e32 v39, v39
	v_add_f32_e32 v35, v35, v43
	v_mul_f32_e32 v35, 0xbfb8aa3b, v35
	v_exp_f32_e32 v35, v35
	v_add_f32_e32 v39, 1.0, v39
	v_rcp_f32_e32 v39, v39
	v_add_f32_e32 v36, v36, v44
	v_add_f32_e32 v35, 1.0, v35
	v_rcp_f32_e32 v35, v35
	v_mul_f32_e32 v39, v39, v145
	v_mul_f32_e32 v36, 0xbfb8aa3b, v36
	v_exp_f32_e32 v36, v36
	v_add_co_u32_e32 v50, vcc, s89, v82
	v_add_f32_e32 v22, v22, v30
	v_add_f32_e32 v36, 1.0, v36
	v_rcp_f32_e32 v36, v36
	v_addc_co_u32_e32 v51, vcc, 0, v83, vcc
	flat_load_dwordx4 v[50:53], v[50:51]
	v_add_f32_e32 v37, v37, v45
	v_mul_f32_e32 v22, 0xbfb8aa3b, v22
	v_mul_f32_e32 v37, 0xbfb8aa3b, v37
	v_exp_f32_e32 v22, v22
	v_exp_f32_e32 v37, v37
	v_add_f32_e32 v18, v18, v26
	v_add_f32_e32 v23, v23, v31
	v_add_f32_e32 v22, 1.0, v22
	v_add_f32_e32 v37, 1.0, v37
	v_rcp_f32_e32 v22, v22
	v_rcp_f32_e32 v37, v37
	v_mul_f32_e32 v18, 0xbfb8aa3b, v18
	v_mul_f32_e32 v23, 0xbfb8aa3b, v23
	v_mul_f32_e32 v22, v22, v130
	v_exp_f32_e32 v18, v18
	v_exp_f32_e32 v23, v23
	v_add_f32_e32 v24, v24, v32
	v_add_f32_e32 v19, v19, v27
	v_add_f32_e32 v18, 1.0, v18
	v_add_f32_e32 v23, 1.0, v23
	v_rcp_f32_e32 v18, v18
	v_rcp_f32_e32 v23, v23
	v_mul_f32_e32 v24, 0xbfb8aa3b, v24
	v_mul_f32_e32 v19, 0xbfb8aa3b, v19
	v_exp_f32_e32 v24, v24
	v_mul_f32_e32 v23, v23, v131
	v_exp_f32_e32 v19, v19
	v_add_f32_e32 v25, v25, v33
	v_add_f32_e32 v24, 1.0, v24
	v_rcp_f32_e32 v24, v24
	v_add_f32_e32 v19, 1.0, v19
	v_rcp_f32_e32 v19, v19
	v_add_f32_e32 v20, v20, v28
	v_mul_f32_e32 v24, v24, v132
	v_mul_f32_e32 v25, 0xbfb8aa3b, v25
	v_mul_f32_e32 v20, 0xbfb8aa3b, v20
	v_exp_f32_e32 v25, v25
	v_exp_f32_e32 v20, v20
	v_add_f32_e32 v14, v14, v46
	v_add_f32_e32 v21, v21, v29
	v_add_f32_e32 v25, 1.0, v25
	v_add_f32_e32 v20, 1.0, v20
	v_rcp_f32_e32 v25, v25
	v_rcp_f32_e32 v20, v20
	v_mul_f32_e32 v14, 0xbfb8aa3b, v14
	v_mul_f32_e32 v21, 0xbfb8aa3b, v21
	v_mul_f32_e32 v25, v25, v133
	v_exp_f32_e32 v14, v14
	v_exp_f32_e32 v21, v21
	s_waitcnt vmcnt(0) lgkmcnt(0)
	v_lshlrev_b32_e32 v58, 16, v54
	v_and_b32_e32 v59, 0xffff0000, v54
	v_lshlrev_b32_e32 v60, 16, v55
	v_and_b32_e32 v54, 0xffff0000, v55
	v_rcp_f32_e32 v55, v34
	v_mul_f32_e32 v34, v38, v144
	v_add_f32_e32 v38, v34, v34
	v_mul_f32_e32 v38, 0x3fb8aa3b, v38
	v_exp_f32_e32 v38, v38
	v_cvt_pk_bf16_f32 v34, v34, v39
	v_add_f32_e32 v14, 1.0, v14
	v_add_f32_e32 v21, 1.0, v21
	v_sub_f32_e32 v38, 1.0, v38
	v_max_f32_e32 v38, 0, v38
	v_sqrt_f32_e32 v38, v38
	v_rcp_f32_e32 v14, v14
	v_rcp_f32_e32 v21, v21
	v_add_f32_e32 v10, v10, v42
	v_mul_f32_e32 v38, v55, v38
	v_add_f32_e32 v55, v39, v39
	v_mul_f32_e32 v55, 0x3fb8aa3b, v55
	v_exp_f32_e32 v55, v55
	v_mul_f32_e32 v38, v38, v58
	v_mul_f32_e32 v38, 0x42000000, v38
	v_mul_f32_e32 v14, v14, v144
	v_sub_f32_e32 v55, 1.0, v55
	v_max_f32_e32 v55, 0, v55
	v_sqrt_f32_e32 v55, v55
	v_mul_f32_e32 v10, 0xbfb8aa3b, v10
	v_exp_f32_e32 v10, v10
	v_add_f32_e32 v11, v11, v43
	v_mul_f32_e32 v35, v35, v55
	v_mul_f32_e32 v55, v35, v59
	v_add_f32_e32 v35, v40, v48
	v_mul_f32_e32 v35, 0xbfb8aa3b, v35
	v_exp_f32_e32 v35, v35
	v_mul_f32_e32 v39, 0x42000000, v55
	v_med3_f32 v39, v39, s29, v231
	v_add_f32_e32 v10, 1.0, v10
	v_add_f32_e32 v35, 1.0, v35
	v_rcp_f32_e32 v35, v35
	v_rcp_f32_e32 v10, v10
	v_mul_f32_e32 v11, 0xbfb8aa3b, v11
	v_exp_f32_e32 v11, v11
	v_mul_f32_e32 v35, v35, v142
	v_add_f32_e32 v40, v35, v35
	v_mul_f32_e32 v40, 0x3fb8aa3b, v40
	v_exp_f32_e32 v40, v40
	v_add_f32_e32 v11, 1.0, v11
	v_rcp_f32_e32 v11, v11
	v_add_f32_e32 v12, v12, v44
	v_sub_f32_e32 v40, 1.0, v40
	v_max_f32_e32 v40, 0, v40
	v_sqrt_f32_e32 v40, v40
	v_mul_f32_e32 v12, 0xbfb8aa3b, v12
	v_exp_f32_e32 v12, v12
	v_add_f32_e32 v6, v6, v30
	v_mul_f32_e32 v36, v36, v40
	v_add_f32_e32 v40, v41, v49
	v_mul_f32_e32 v40, 0xbfb8aa3b, v40
	v_exp_f32_e32 v40, v40
	v_mul_f32_e32 v36, v36, v60
	v_mul_f32_e32 v36, 0x42000000, v36
	v_med3_f32 v36, v36, s29, v231
	v_add_f32_e32 v40, 1.0, v40
	v_rcp_f32_e32 v40, v40
	v_add_f32_e32 v12, 1.0, v12
	v_rcp_f32_e32 v12, v12
	v_add_f32_e32 v13, v13, v45
	v_mul_f32_e32 v40, v40, v143
	v_add_f32_e32 v41, v40, v40
	v_mul_f32_e32 v41, 0x3fb8aa3b, v41
	v_exp_f32_e32 v41, v41
	v_cvt_pk_bf16_f32 v35, v35, v40
	v_med3_f32 v40, v38, s29, v231
	v_mov_b32_e32 v38, 0
	v_sub_f32_e32 v41, 1.0, v41
	v_max_f32_e32 v41, 0, v41
	v_sqrt_f32_e32 v41, v41
	v_cvt_pk_fp8_f32 v38, v40, v39
	v_lshlrev_b32_e32 v39, 16, v57
	v_and_b32_e32 v40, 0xffff0000, v57
	v_mul_f32_e32 v37, v37, v41
	v_add_f32_e32 v41, v22, v22
	v_mul_f32_e32 v41, 0x3fb8aa3b, v41
	v_exp_f32_e32 v41, v41
	v_mul_f32_e32 v37, v37, v54
	v_mul_f32_e32 v37, 0x42000000, v37
	v_med3_f32 v37, v37, s29, v231
	v_sub_f32_e32 v41, 1.0, v41
	v_max_f32_e32 v41, 0, v41
	v_sqrt_f32_e32 v41, v41
	v_cvt_pk_fp8_f32 v38, v36, v37 op_sel:[0,0,1]
	v_lshlrev_b32_e32 v36, 16, v56
	v_and_b32_e32 v37, 0xffff0000, v56
	v_mul_f32_e32 v18, v18, v41
	v_mul_f32_e32 v18, v18, v36
	v_add_f32_e32 v36, v23, v23
	v_mul_f32_e32 v36, 0x3fb8aa3b, v36
	v_exp_f32_e32 v36, v36
	v_mul_f32_e32 v18, 0x42000000, v18
	v_med3_f32 v18, v18, s29, v231
	v_mul_f32_e32 v6, 0xbfb8aa3b, v6
	v_sub_f32_e32 v36, 1.0, v36
	v_max_f32_e32 v36, 0, v36
	v_sqrt_f32_e32 v36, v36
	v_mul_f32_e32 v13, 0xbfb8aa3b, v13
	v_exp_f32_e32 v6, v6
	v_exp_f32_e32 v13, v13
	v_mul_f32_e32 v19, v19, v36
	v_add_f32_e32 v36, v24, v24
	v_mul_f32_e32 v36, 0x3fb8aa3b, v36
	v_exp_f32_e32 v36, v36
	v_mul_f32_e32 v19, v19, v37
	v_mul_f32_e32 v19, 0x42000000, v19
	v_med3_f32 v19, v19, s29, v231
	v_sub_f32_e32 v36, 1.0, v36
	v_max_f32_e32 v36, 0, v36
	v_sqrt_f32_e32 v36, v36
	v_cvt_pk_bf16_f32 v37, v24, v25
	v_add_f32_e32 v6, 1.0, v6
	v_add_f32_e32 v13, 1.0, v13
	v_mul_f32_e32 v20, v20, v36
	v_add_f32_e32 v36, v25, v25
	v_mul_f32_e32 v36, 0x3fb8aa3b, v36
	v_exp_f32_e32 v36, v36
	v_mul_f32_e32 v20, v20, v39
	v_mov_b32_e32 v39, 0
	v_cvt_pk_fp8_f32 v39, v18, v19
	v_sub_f32_e32 v36, 1.0, v36
	v_max_f32_e32 v36, 0, v36
	v_sqrt_f32_e32 v36, v36
	v_mul_f32_e32 v20, 0x42000000, v20
	v_med3_f32 v18, v20, s29, v231
	v_rcp_f32_e32 v6, v6
	v_mul_f32_e32 v21, v21, v36
	v_cvt_pk_bf16_f32 v36, v22, v23
	v_add_f32_e32 v22, v14, v14
	v_mul_f32_e32 v22, 0x3fb8aa3b, v22
	v_exp_f32_e32 v22, v22
	v_mul_f32_e32 v21, v21, v40
	v_mul_f32_e32 v21, 0x42000000, v21
	v_med3_f32 v19, v21, s29, v231
	v_sub_f32_e32 v22, 1.0, v22
	v_max_f32_e32 v22, 0, v22
	v_cvt_pk_fp8_f32 v39, v18, v19 op_sel:[0,0,1]
	v_add_co_u32_e32 v18, vcc, s92, v80
	v_sqrt_f32_e32 v22, v22
	s_nop 0
	v_addc_co_u32_e32 v19, vcc, 0, v81, vcc
	flat_store_dwordx4 v[18:19], v[34:37] nt
	v_add_co_u32_e32 v18, vcc, s84, v78
	v_mul_f32_e32 v10, v10, v22
	s_nop 0
	v_addc_co_u32_e32 v19, vcc, 0, v79, vcc
	flat_store_dwordx2 v[18:19], v[38:39] nt
	v_lshlrev_b32_e32 v18, 16, v50
	v_mul_f32_e32 v18, v10, v18
	v_add_f32_e32 v10, v15, v47
	v_mul_f32_e32 v10, 0xbfb8aa3b, v10
	v_exp_f32_e32 v10, v10
	v_and_b32_e32 v19, 0xffff0000, v50
	v_rcp_f32_e32 v13, v13
	v_mul_f32_e32 v6, v6, v130
	v_add_f32_e32 v10, 1.0, v10
	v_rcp_f32_e32 v10, v10
	v_add_f32_e32 v2, v2, v26
	v_add_f32_e32 v7, v7, v31
	v_mul_f32_e32 v2, 0xbfb8aa3b, v2
	v_mul_f32_e32 v10, v10, v145
	v_add_f32_e32 v15, v10, v10
	v_mul_f32_e32 v15, 0x3fb8aa3b, v15
	v_exp_f32_e32 v15, v15
	v_mul_f32_e32 v7, 0xbfb8aa3b, v7
	v_exp_f32_e32 v2, v2
	v_exp_f32_e32 v7, v7
	v_sub_f32_e32 v15, 1.0, v15
	v_max_f32_e32 v15, 0, v15
	v_sqrt_f32_e32 v15, v15
	v_cvt_pk_bf16_f32 v10, v14, v10
	v_mul_f32_e32 v14, 0x42000000, v18
	v_add_f32_e32 v2, 1.0, v2
	v_mul_f32_e32 v11, v11, v15
	v_mul_f32_e32 v15, v11, v19
	v_add_f32_e32 v11, v16, v48
	v_mul_f32_e32 v11, 0xbfb8aa3b, v11
	v_exp_f32_e32 v11, v11
	v_mul_f32_e32 v15, 0x42000000, v15
	v_med3_f32 v15, v15, s29, v231
	v_add_f32_e32 v7, 1.0, v7
	v_add_f32_e32 v11, 1.0, v11
	v_rcp_f32_e32 v11, v11
	v_lshlrev_b32_e32 v20, 16, v51
	v_and_b32_e32 v21, 0xffff0000, v51
	v_rcp_f32_e32 v2, v2
	v_mul_f32_e32 v11, v11, v142
	v_add_f32_e32 v16, v11, v11
	v_mul_f32_e32 v16, 0x3fb8aa3b, v16
	v_exp_f32_e32 v16, v16
	v_rcp_f32_e32 v7, v7
	v_add_f32_e32 v8, v8, v32
	v_add_f32_e32 v3, v3, v27
	v_sub_f32_e32 v16, 1.0, v16
	v_max_f32_e32 v16, 0, v16
	v_sqrt_f32_e32 v16, v16
	v_mul_f32_e32 v7, v7, v131
	v_mul_f32_e32 v8, 0xbfb8aa3b, v8
	v_mul_f32_e32 v3, 0xbfb8aa3b, v3
	v_mul_f32_e32 v12, v12, v16
	v_add_f32_e32 v16, v17, v49
	v_mul_f32_e32 v16, 0xbfb8aa3b, v16
	v_exp_f32_e32 v16, v16
	v_mul_f32_e32 v12, v12, v20
	v_mul_f32_e32 v12, 0x42000000, v12
	v_med3_f32 v12, v12, s29, v231
	v_add_f32_e32 v16, 1.0, v16
	v_rcp_f32_e32 v16, v16
	v_exp_f32_e32 v8, v8
	v_exp_f32_e32 v3, v3
	v_add_f32_e32 v9, v9, v33
	v_mul_f32_e32 v16, v16, v143
	v_add_f32_e32 v17, v16, v16
	v_mul_f32_e32 v17, 0x3fb8aa3b, v17
	v_exp_f32_e32 v17, v17
	v_cvt_pk_bf16_f32 v11, v11, v16
	v_med3_f32 v16, v14, s29, v231
	v_mov_b32_e32 v14, 0
	v_sub_f32_e32 v17, 1.0, v17
	v_max_f32_e32 v17, 0, v17
	v_sqrt_f32_e32 v17, v17
	v_cvt_pk_fp8_f32 v14, v16, v15
	v_add_f32_e32 v8, 1.0, v8
	v_add_f32_e32 v3, 1.0, v3
	v_mul_f32_e32 v13, v13, v17
	v_add_f32_e32 v17, v6, v6
	v_mul_f32_e32 v17, 0x3fb8aa3b, v17
	v_exp_f32_e32 v17, v17
	v_mul_f32_e32 v13, v13, v21
	v_mul_f32_e32 v13, 0x42000000, v13
	v_med3_f32 v13, v13, s29, v231
	v_sub_f32_e32 v17, 1.0, v17
	v_max_f32_e32 v17, 0, v17
	v_sqrt_f32_e32 v17, v17
	v_cvt_pk_fp8_f32 v14, v12, v13 op_sel:[0,0,1]
	v_lshlrev_b32_e32 v12, 16, v52
	v_rcp_f32_e32 v8, v8
	v_mul_f32_e32 v2, v2, v17
	v_mul_f32_e32 v2, v2, v12
	v_add_f32_e32 v12, v7, v7
	v_mul_f32_e32 v12, 0x3fb8aa3b, v12
	v_exp_f32_e32 v12, v12
	v_rcp_f32_e32 v3, v3
	v_mul_f32_e32 v8, v8, v132
	v_add_f32_e32 v4, v4, v28
	v_sub_f32_e32 v12, 1.0, v12
	v_max_f32_e32 v12, 0, v12
	v_sqrt_f32_e32 v12, v12
	v_mul_f32_e32 v9, 0xbfb8aa3b, v9
	v_mul_f32_e32 v4, 0xbfb8aa3b, v4
	v_exp_f32_e32 v9, v9
	v_mul_f32_e32 v3, v3, v12
	v_add_f32_e32 v12, v8, v8
	v_mul_f32_e32 v12, 0x3fb8aa3b, v12
	v_exp_f32_e32 v12, v12
	v_exp_f32_e32 v4, v4
	v_add_f32_e32 v9, 1.0, v9
	v_rcp_f32_e32 v9, v9
	v_sub_f32_e32 v12, 1.0, v12
	v_add_f32_e32 v4, 1.0, v4
	v_max_f32_e32 v12, 0, v12
	v_rcp_f32_e32 v4, v4
	v_sqrt_f32_e32 v12, v12
	v_mul_f32_e32 v9, v9, v133
	v_add_f32_e32 v5, v5, v29
	v_mul_f32_e32 v5, 0xbfb8aa3b, v5
	v_mul_f32_e32 v4, v4, v12
	v_add_f32_e32 v12, v9, v9
	v_mul_f32_e32 v12, 0x3fb8aa3b, v12
	v_exp_f32_e32 v12, v12
	v_exp_f32_e32 v5, v5
	v_and_b32_e32 v13, 0xffff0000, v52
	v_mul_f32_e32 v3, v3, v13
	v_sub_f32_e32 v12, 1.0, v12
	v_add_f32_e32 v5, 1.0, v5
	v_max_f32_e32 v12, 0, v12
	v_rcp_f32_e32 v5, v5
	v_sqrt_f32_e32 v12, v12
	v_lshlrev_b32_e32 v15, 16, v53
	v_mul_f32_e32 v2, 0x42000000, v2
	v_mul_f32_e32 v3, 0x42000000, v3
	v_mul_f32_e32 v4, v4, v15
	v_med3_f32 v2, v2, s29, v231
	v_med3_f32 v3, v3, s29, v231
	v_mov_b32_e32 v15, 0
	v_and_b32_e32 v16, 0xffff0000, v53
	v_mul_f32_e32 v5, v5, v12
	v_cvt_pk_fp8_f32 v15, v2, v3
	v_mul_f32_e32 v5, v5, v16
	v_mul_f32_e32 v4, 0x42000000, v4
	v_mul_f32_e32 v5, 0x42000000, v5
	v_med3_f32 v2, v4, s29, v231
	v_med3_f32 v3, v5, s29, v231
	v_cvt_pk_fp8_f32 v15, v2, v3 op_sel:[0,0,1]
	v_add_co_u32_e32 v2, vcc, 0x18000, v80
	v_cvt_pk_bf16_f32 v12, v6, v7
	v_cvt_pk_bf16_f32 v13, v8, v9
	v_addc_co_u32_e32 v3, vcc, 0, v81, vcc
	flat_store_dwordx4 v[2:3], v[10:13] nt
	v_add_co_u32_e32 v2, vcc, 0xc000, v78
	s_nop 1
	v_addc_co_u32_e32 v3, vcc, 0, v79, vcc
	flat_store_dwordx2 v[2:3], v[14:15] nt
	s_and_b64 vcc, exec, s[12:13]
	s_mov_b32 s82, s40
	s_mov_b32 s52, s42
	s_mov_b64 s[14:15], s[46:47]
	s_mov_b64 s[48:49], s[44:45]
	s_mov_b32 s94, s23
	s_cbranch_vccz .LBB0_1638
	s_waitcnt vmcnt(0)
	s_cmpk_gt_u32 s22, 0xff
	v_readlane_b32 s81, v253, 46
	v_readlane_b32 s80, v253, 45
	v_readlane_b32 s89, v253, 44
	s_cbranch_scc1 .LBB0_1649
	s_barrier

.LBB0_2041:
	s_add_u32 s14, s38, 0x100
	s_addc_u32 s15, s39, 0
	s_add_u32 s36, s35, s38
	s_addc_u32 s37, s55, s39
	s_cmpk_eq_i32 s38, 0x300
	s_cselect_b64 vcc, -1, 0
	s_and_b64 s[0:1], vcc, exec
	s_cselect_b32 s1, 0, s14
	s_cselect_b32 s0, 0, s15
	s_cselect_b32 s36, s31, s36
	s_cselect_b32 s37, s29, s37
	s_add_u32 s40, s18, s1
	s_addc_u32 s41, s19, s0
	s_add_i32 s1, 0, 0x10000
	v_add_u32_e32 v14, s1, v197
	ds_read_b128 v[2:5], v14
	ds_read_b128 v[6:9], v14 offset:1024
	ds_read_b128 v[10:13], v14 offset:2048
	ds_read_b128 v[14:17], v14 offset:3072
	v_cndmask_b32_e32 v162, v168, v171, vcc
	v_cndmask_b32_e32 v184, v170, v198, vcc
	v_cndmask_b32_e32 v175, v172, v199, vcc
	v_cndmask_b32_e32 v173, v174, v200, vcc
	v_lshl_add_u64 v[18:19], v[178:179], 0, s[38:39]
	s_add_i32 m0, s45, 0xc000
	ds_read_b128 v[202:205], v169
	ds_read_b128 v[206:209], v169 offset:1024
	ds_read_b128 v[210:213], v169 offset:2048
	ds_read_b128 v[214:217], v169 offset:3072
	ds_read_b128 v[218:221], v169 offset:4096
	ds_read_b128 v[222:225], v169 offset:5120
	ds_read_b128 v[226:229], v169 offset:6144
	ds_read_b128 v[230:233], v169 offset:7168
	global_load_lds_dwordx4 v[18:19], off
	v_lshl_add_u64 v[18:19], v[176:177], 0, s[38:39]
	s_add_i32 m0, s45, 0xe000
	s_nop 0
	global_load_lds_dwordx4 v[18:19], off
	s_waitcnt lgkmcnt(8)
	s_waitcnt vmcnt(10)
	s_barrier
	s_waitcnt lgkmcnt(0)
	s_setprio 1
	s_waitcnt lgkmcnt(0)
	v_mfma_scale_f32_16x16x128_f8f6f4 v[158:161], v[2:9], v[202:209], v[158:161], v188, v188 op_sel_hi:[0,0,0]
	v_mfma_scale_f32_16x16x128_f8f6f4 v[150:153], v[10:17], v[202:209], v[150:153], v188, v188 op_sel_hi:[0,0,0]
	v_mfma_scale_f32_16x16x128_f8f6f4 v[142:145], v[2:9], v[210:217], v[142:145], v188, v188 op_sel_hi:[0,0,0]
	v_mfma_scale_f32_16x16x128_f8f6f4 v[134:137], v[10:17], v[210:217], v[134:137], v188, v188 op_sel_hi:[0,0,0]
	v_mfma_scale_f32_16x16x128_f8f6f4 v[126:129], v[2:9], v[218:225], v[126:129], v188, v188 op_sel_hi:[0,0,0]
	v_mfma_scale_f32_16x16x128_f8f6f4 v[118:121], v[10:17], v[218:225], v[118:121], v188, v188 op_sel_hi:[0,0,0]
	v_mfma_scale_f32_16x16x128_f8f6f4 v[110:113], v[2:9], v[226:233], v[110:113], v188, v188 op_sel_hi:[0,0,0]
	v_mfma_scale_f32_16x16x128_f8f6f4 v[102:105], v[10:17], v[226:233], v[102:105], v188, v188 op_sel_hi:[0,0,0]
	s_setprio 0
	s_barrier
	s_add_i32 s0, 0, 0x14000
	s_add_i32 s1, s1, s43
	v_add_u32_e32 v30, s0, v197
	v_lshl_add_u64 v[180:181], s[36:37], 0, v[164:165]
	s_mov_b32 m0, s1
	ds_read_b128 v[18:21], v30
	ds_read_b128 v[22:25], v30 offset:1024
	ds_read_b128 v[26:29], v30 offset:2048
	ds_read_b128 v[30:33], v30 offset:3072
	global_load_lds_dwordx4 v[180:181], off
	v_lshl_add_u64 v[182:183], s[36:37], 0, v[166:167]
	s_add_i32 m0, s1, 0x2000
	s_nop 0
	global_load_lds_dwordx4 v[182:183], off
	s_waitcnt vmcnt(10)
	s_barrier
	s_waitcnt lgkmcnt(0)
	s_setprio 1
	s_waitcnt lgkmcnt(0)
	v_mfma_scale_f32_16x16x128_f8f6f4 v[154:157], v[18:25], v[202:209], v[154:157], v188, v188 op_sel_hi:[0,0,0]
	v_mfma_scale_f32_16x16x128_f8f6f4 v[146:149], v[26:33], v[202:209], v[146:149], v188, v188 op_sel_hi:[0,0,0]
	v_mfma_scale_f32_16x16x128_f8f6f4 v[138:141], v[18:25], v[210:217], v[138:141], v188, v188 op_sel_hi:[0,0,0]
	v_mfma_scale_f32_16x16x128_f8f6f4 v[130:133], v[26:33], v[210:217], v[130:133], v188, v188 op_sel_hi:[0,0,0]
	v_mfma_scale_f32_16x16x128_f8f6f4 v[122:125], v[18:25], v[218:225], v[122:125], v188, v188 op_sel_hi:[0,0,0]
	v_mfma_scale_f32_16x16x128_f8f6f4 v[114:117], v[26:33], v[218:225], v[114:117], v188, v188 op_sel_hi:[0,0,0]
	v_mfma_scale_f32_16x16x128_f8f6f4 v[106:109], v[18:25], v[226:233], v[106:109], v188, v188 op_sel_hi:[0,0,0]
	v_mfma_scale_f32_16x16x128_f8f6f4 v[98:101], v[26:33], v[226:233], v[98:101], v188, v188 op_sel_hi:[0,0,0]
	s_setprio 0
	s_mov_b32 m0, s45
	s_barrier
	ds_read_b128 v[202:205], v169 offset:16384
	ds_read_b128 v[206:209], v169 offset:17408
	ds_read_b128 v[210:213], v169 offset:18432
	ds_read_b128 v[214:217], v169 offset:19456
	ds_read_b128 v[218:221], v169 offset:20480
	ds_read_b128 v[222:225], v169 offset:21504
	ds_read_b128 v[226:229], v169 offset:22528
	ds_read_b128 v[230:233], v169 offset:23552
	global_load_lds_dwordx4 v162, s[40:41]
	s_mov_b32 m0, s46
	v_mov_b32_e32 v185, v163
	global_load_lds_dwordx4 v184, s[40:41]
	s_waitcnt vmcnt(10)
	s_barrier
	s_waitcnt lgkmcnt(0)
	v_lshl_add_u64 v[186:187], s[40:41], 0, v[162:163]
	v_lshl_add_u64 v[184:185], s[40:41], 0, v[184:185]
	s_setprio 1
	s_waitcnt lgkmcnt(0)
	v_mfma_scale_f32_16x16x128_f8f6f4 v[94:97], v[2:9], v[202:209], v[94:97], v188, v188 op_sel_hi:[0,0,0]
	v_mfma_scale_f32_16x16x128_f8f6f4 v[86:89], v[10:17], v[202:209], v[86:89], v188, v188 op_sel_hi:[0,0,0]
	v_mfma_scale_f32_16x16x128_f8f6f4 v[78:81], v[2:9], v[210:217], v[78:81], v188, v188 op_sel_hi:[0,0,0]
	v_mfma_scale_f32_16x16x128_f8f6f4 v[70:73], v[10:17], v[210:217], v[70:73], v188, v188 op_sel_hi:[0,0,0]
	v_mfma_scale_f32_16x16x128_f8f6f4 v[62:65], v[2:9], v[218:225], v[62:65], v188, v188 op_sel_hi:[0,0,0]
	v_mfma_scale_f32_16x16x128_f8f6f4 v[54:57], v[10:17], v[218:225], v[54:57], v188, v188 op_sel_hi:[0,0,0]
	v_mfma_scale_f32_16x16x128_f8f6f4 v[46:49], v[2:9], v[226:233], v[46:49], v188, v188 op_sel_hi:[0,0,0]
	v_mfma_scale_f32_16x16x128_f8f6f4 v[38:41], v[10:17], v[226:233], v[38:41], v188, v188 op_sel_hi:[0,0,0]
	s_setprio 0
	s_barrier
	s_add_u32 s38, s36, 0x20000
	s_addc_u32 s39, s37, 0
	s_add_i32 s0, s0, s43
	v_lshl_add_u64 v[2:3], s[38:39], 0, v[164:165]
	s_mov_b32 m0, s0
	s_nop 0
	global_load_lds_dwordx4 v[2:3], off
	v_lshl_add_u64 v[2:3], s[38:39], 0, v[166:167]
	s_add_i32 m0, s0, 0x2000
	s_nop 0
	global_load_lds_dwordx4 v[2:3], off
	s_waitcnt vmcnt(10)
	s_barrier
	s_setprio 1
	v_mfma_scale_f32_16x16x128_f8f6f4 v[90:93], v[18:25], v[202:209], v[90:93], v188, v188 op_sel_hi:[0,0,0]
	v_mfma_scale_f32_16x16x128_f8f6f4 v[82:85], v[26:33], v[202:209], v[82:85], v188, v188 op_sel_hi:[0,0,0]
	v_mfma_scale_f32_16x16x128_f8f6f4 v[74:77], v[18:25], v[210:217], v[74:77], v188, v188 op_sel_hi:[0,0,0]
	v_mfma_scale_f32_16x16x128_f8f6f4 v[66:69], v[26:33], v[210:217], v[66:69], v188, v188 op_sel_hi:[0,0,0]
	v_mfma_scale_f32_16x16x128_f8f6f4 v[58:61], v[18:25], v[218:225], v[58:61], v188, v188 op_sel_hi:[0,0,0]
	v_mfma_scale_f32_16x16x128_f8f6f4 v[50:53], v[26:33], v[218:225], v[50:53], v188, v188 op_sel_hi:[0,0,0]
	v_mfma_scale_f32_16x16x128_f8f6f4 v[42:45], v[18:25], v[226:233], v[42:45], v188, v188 op_sel_hi:[0,0,0]
	v_mfma_scale_f32_16x16x128_f8f6f4 v[34:37], v[26:33], v[226:233], v[34:37], v188, v188 op_sel_hi:[0,0,0]
	s_setprio 0
	s_add_i32 s0, 0, 0x18000
	v_add_u32_e32 v14, s0, v197
	s_barrier
	ds_read_b128 v[2:5], v14
	ds_read_b128 v[6:9], v14 offset:1024
	ds_read_b128 v[10:13], v14 offset:2048
	ds_read_b128 v[14:17], v14 offset:3072
	s_mov_b32 m0, s47
	ds_read_b128 v[18:21], v169 offset:32768
	ds_read_b128 v[22:25], v169 offset:33792
	ds_read_b128 v[26:29], v169 offset:34816
	ds_read_b128 v[30:33], v169 offset:35840
	ds_read_b128 v[202:205], v169 offset:36864
	ds_read_b128 v[206:209], v169 offset:37888
	ds_read_b128 v[210:213], v169 offset:38912
	ds_read_b128 v[214:217], v169 offset:39936
	global_load_lds_dwordx4 v175, s[40:41]
	s_mov_b32 m0, s48
	s_nop 0
	global_load_lds_dwordx4 v173, s[40:41]
	s_waitcnt lgkmcnt(8)
	s_waitcnt vmcnt(10)
	s_barrier
	s_waitcnt lgkmcnt(0)
	s_setprio 1
	s_waitcnt lgkmcnt(0)
	v_mfma_scale_f32_16x16x128_f8f6f4 v[158:161], v[2:9], v[18:25], v[158:161], v188, v188 op_sel_hi:[0,0,0]
	v_mfma_scale_f32_16x16x128_f8f6f4 v[150:153], v[10:17], v[18:25], v[150:153], v188, v188 op_sel_hi:[0,0,0]
	v_mfma_scale_f32_16x16x128_f8f6f4 v[142:145], v[2:9], v[26:33], v[142:145], v188, v188 op_sel_hi:[0,0,0]
	v_mfma_scale_f32_16x16x128_f8f6f4 v[134:137], v[10:17], v[26:33], v[134:137], v188, v188 op_sel_hi:[0,0,0]
	v_mfma_scale_f32_16x16x128_f8f6f4 v[126:129], v[2:9], v[202:209], v[126:129], v188, v188 op_sel_hi:[0,0,0]
	v_mfma_scale_f32_16x16x128_f8f6f4 v[118:121], v[10:17], v[202:209], v[118:121], v188, v188 op_sel_hi:[0,0,0]
	v_mfma_scale_f32_16x16x128_f8f6f4 v[110:113], v[2:9], v[210:217], v[110:113], v188, v188 op_sel_hi:[0,0,0]
	v_mfma_scale_f32_16x16x128_f8f6f4 v[102:105], v[10:17], v[210:217], v[102:105], v188, v188 op_sel_hi:[0,0,0]
	s_setprio 0
	s_barrier
	s_add_i32 s38, 0, 0x1c000
	s_add_i32 s0, s0, s43
	v_add_u32_e32 v162, s38, v197
	v_lshl_add_u64 v[180:181], v[180:181], 0, s[24:25]
	s_mov_b32 m0, s0
	ds_read_b128 v[218:221], v162
	ds_read_b128 v[222:225], v162 offset:1024
	ds_read_b128 v[226:229], v162 offset:2048
	ds_read_b128 v[230:233], v162 offset:3072
	global_load_lds_dwordx4 v[180:181], off
	v_lshl_add_u64 v[180:181], v[182:183], 0, s[24:25]
	s_add_i32 m0, s0, 0x2000
	s_nop 0
	global_load_lds_dwordx4 v[180:181], off
	s_waitcnt vmcnt(10)
	s_barrier
	s_waitcnt lgkmcnt(0)
	s_setprio 1
	s_waitcnt lgkmcnt(0)
	v_mfma_scale_f32_16x16x128_f8f6f4 v[154:157], v[218:225], v[18:25], v[154:157], v188, v188 op_sel_hi:[0,0,0]
	v_mfma_scale_f32_16x16x128_f8f6f4 v[146:149], v[226:233], v[18:25], v[146:149], v188, v188 op_sel_hi:[0,0,0]
	v_mfma_scale_f32_16x16x128_f8f6f4 v[138:141], v[218:225], v[26:33], v[138:141], v188, v188 op_sel_hi:[0,0,0]
	v_mfma_scale_f32_16x16x128_f8f6f4 v[130:133], v[226:233], v[26:33], v[130:133], v188, v188 op_sel_hi:[0,0,0]
	v_mfma_scale_f32_16x16x128_f8f6f4 v[122:125], v[218:225], v[202:209], v[122:125], v188, v188 op_sel_hi:[0,0,0]
	v_mfma_scale_f32_16x16x128_f8f6f4 v[114:117], v[226:233], v[202:209], v[114:117], v188, v188 op_sel_hi:[0,0,0]
	v_mfma_scale_f32_16x16x128_f8f6f4 v[106:109], v[218:225], v[210:217], v[106:109], v188, v188 op_sel_hi:[0,0,0]
	v_mfma_scale_f32_16x16x128_f8f6f4 v[98:101], v[226:233], v[210:217], v[98:101], v188, v188 op_sel_hi:[0,0,0]
	s_setprio 0
	s_mov_b32 m0, s51
	v_lshl_add_u64 v[180:181], v[186:187], 0, s[24:25]
	s_barrier
	ds_read_b128 v[18:21], v169 offset:49152
	ds_read_b128 v[22:25], v169 offset:50176
	ds_read_b128 v[26:29], v169 offset:51200
	ds_read_b128 v[30:33], v169 offset:52224
	ds_read_b128 v[202:205], v169 offset:53248
	ds_read_b128 v[206:209], v169 offset:54272
	ds_read_b128 v[210:213], v169 offset:55296
	ds_read_b128 v[214:217], v169 offset:56320
	global_load_lds_dwordx4 v[180:181], off
	v_lshl_add_u64 v[180:181], v[184:185], 0, s[24:25]
	s_mov_b32 m0, s52
	s_nop 0
	global_load_lds_dwordx4 v[180:181], off
	s_waitcnt vmcnt(10)
	s_barrier
	s_waitcnt lgkmcnt(0)
	s_setprio 1
	s_waitcnt lgkmcnt(0)
	v_mfma_scale_f32_16x16x128_f8f6f4 v[94:97], v[2:9], v[18:25], v[94:97], v188, v188 op_sel_hi:[0,0,0]
	v_mfma_scale_f32_16x16x128_f8f6f4 v[86:89], v[10:17], v[18:25], v[86:89], v188, v188 op_sel_hi:[0,0,0]
	v_mfma_scale_f32_16x16x128_f8f6f4 v[78:81], v[2:9], v[26:33], v[78:81], v188, v188 op_sel_hi:[0,0,0]
	v_mfma_scale_f32_16x16x128_f8f6f4 v[70:73], v[10:17], v[26:33], v[70:73], v188, v188 op_sel_hi:[0,0,0]
	v_mfma_scale_f32_16x16x128_f8f6f4 v[62:65], v[2:9], v[202:209], v[62:65], v188, v188 op_sel_hi:[0,0,0]
	v_mfma_scale_f32_16x16x128_f8f6f4 v[54:57], v[10:17], v[202:209], v[54:57], v188, v188 op_sel_hi:[0,0,0]
	v_mfma_scale_f32_16x16x128_f8f6f4 v[46:49], v[2:9], v[210:217], v[46:49], v188, v188 op_sel_hi:[0,0,0]
	v_mfma_scale_f32_16x16x128_f8f6f4 v[38:41], v[10:17], v[210:217], v[38:41], v188, v188 op_sel_hi:[0,0,0]
	s_setprio 0
	s_barrier
	s_add_u32 s0, s36, 0x20080
	s_addc_u32 s1, s37, 0
	s_add_i32 s36, s38, s43
	v_lshl_add_u64 v[2:3], s[0:1], 0, v[164:165]
	s_mov_b32 m0, s36
	s_nop 0
	global_load_lds_dwordx4 v[2:3], off
	v_lshl_add_u64 v[2:3], s[0:1], 0, v[166:167]
	s_add_i32 m0, s36, 0x2000
	s_nop 0
	global_load_lds_dwordx4 v[2:3], off
	s_waitcnt vmcnt(10)
	s_barrier
	s_setprio 1
	v_mfma_scale_f32_16x16x128_f8f6f4 v[90:93], v[218:225], v[18:25], v[90:93], v188, v188 op_sel_hi:[0,0,0]
	v_mfma_scale_f32_16x16x128_f8f6f4 v[82:85], v[226:233], v[18:25], v[82:85], v188, v188 op_sel_hi:[0,0,0]
	v_mfma_scale_f32_16x16x128_f8f6f4 v[74:77], v[218:225], v[26:33], v[74:77], v188, v188 op_sel_hi:[0,0,0]
	v_mfma_scale_f32_16x16x128_f8f6f4 v[66:69], v[226:233], v[26:33], v[66:69], v188, v188 op_sel_hi:[0,0,0]
	v_mfma_scale_f32_16x16x128_f8f6f4 v[58:61], v[218:225], v[202:209], v[58:61], v188, v188 op_sel_hi:[0,0,0]
	v_mfma_scale_f32_16x16x128_f8f6f4 v[50:53], v[226:233], v[202:209], v[50:53], v188, v188 op_sel_hi:[0,0,0]
	v_mfma_scale_f32_16x16x128_f8f6f4 v[42:45], v[218:225], v[210:217], v[42:45], v188, v188 op_sel_hi:[0,0,0]
	v_mfma_scale_f32_16x16x128_f8f6f4 v[34:37], v[226:233], v[210:217], v[34:37], v188, v188 op_sel_hi:[0,0,0]
	s_setprio 0
	s_add_i32 s56, s56, 2
	s_cmp_gt_u32 s56, 5
	s_mov_b64 s[38:39], s[14:15]
	s_barrier
	s_cbranch_scc0 .LBB0_2041
	v_mul_f32_e32 v5, 0x3c800000, v158
	v_mul_f32_e32 v6, 0xbfb8aa3b, v5
	v_exp_f32_e32 v6, v6
	s_ashr_i32 s35, s34, 31
	s_ashr_i32 s31, s30, 31
	s_lshl_b64 s[14:15], s[34:35], 18
	v_add_f32_e32 v6, 1.0, v6
	v_rcp_f32_e32 v6, v6
	s_lshl_b64 s[30:31], s[30:31], 15
	v_mov_b32_e32 v3, v195
	s_add_u32 s0, s6, s14
	v_mul_f32_e32 v5, v5, v6
	v_mul_f32_e32 v6, 0x3c800000, v159
	v_mul_f32_e32 v7, 0xbfb8aa3b, v6
	v_exp_f32_e32 v7, v7
	v_mul_f32_e32 v5, v5, v154
	v_mul_f32_e32 v5, 0x3e000000, v5
	v_med3_f32 v5, v5, s10, v190
	v_add_f32_e32 v7, 1.0, v7
	v_rcp_f32_e32 v7, v7
	s_nop 15
	s_nop 15
	v_mov_b32_e32 v2, v196
	v_mul_f32_e32 v6, v6, v7
	v_mul_f32_e32 v7, 0x3c800000, v160
	v_mul_f32_e32 v8, 0xbfb8aa3b, v7
	v_exp_f32_e32 v8, v8
	v_mul_f32_e32 v6, v6, v155
	v_mul_f32_e32 v6, 0x3e000000, v6
	v_add_u32_e32 v4, s49, v3
	v_add_f32_e32 v8, 1.0, v8
	v_rcp_f32_e32 v8, v8
	s_addc_u32 s1, s7, s15
	s_add_u32 s14, s0, s30
	v_mul_f32_e32 v7, v7, v8
	v_mul_f32_e32 v8, 0x3c800000, v161
	v_mul_f32_e32 v9, 0xbfb8aa3b, v8
	v_exp_f32_e32 v9, v9
	v_mul_f32_e32 v7, v7, v156
	v_mul_f32_e32 v7, 0x3e000000, v7
	v_lshl_add_u32 v2, v2, 3, s50
	v_add_f32_e32 v9, 1.0, v9
	v_rcp_f32_e32 v9, v9
	s_addc_u32 s15, s1, s31
	v_ashrrev_i32_e32 v3, 31, v2
	s_and_b64 vcc, exec, s[12:13]
	v_mul_f32_e32 v8, v8, v9
	v_mul_f32_e32 v9, 0x3c800000, v150
	v_mul_f32_e32 v10, 0xbfb8aa3b, v9
	v_exp_f32_e32 v10, v10
	v_mul_f32_e32 v8, v8, v157
	v_mul_f32_e32 v8, 0x3e000000, v8
	v_mov_b32_e32 v174, v200
	v_add_f32_e32 v10, 1.0, v10
	v_rcp_f32_e32 v10, v10
	v_mov_b32_e32 v172, v199
	v_mov_b32_e32 v170, v198
	v_mov_b32_e32 v168, v171
	v_mul_f32_e32 v9, v9, v10
	v_mul_f32_e32 v10, 0x3c800000, v151
	v_mul_f32_e32 v11, 0xbfb8aa3b, v10
	v_exp_f32_e32 v11, v11
	v_mul_f32_e32 v9, v9, v146
	v_mul_f32_e32 v9, 0x3e000000, v9
	s_mov_b32 s30, s28
	v_add_f32_e32 v11, 1.0, v11
	v_rcp_f32_e32 v11, v11
	s_mov_b32 s34, s54
	s_mov_b64 s[36:37], s[16:17]
	v_mul_f32_e32 v10, v10, v11
	v_mul_f32_e32 v11, 0x3c800000, v152
	v_mul_f32_e32 v12, 0xbfb8aa3b, v11
	v_exp_f32_e32 v12, v12
	v_mul_f32_e32 v10, v10, v147
	v_mul_f32_e32 v10, 0x3e000000, v10
	v_add_f32_e32 v12, 1.0, v12
	v_rcp_f32_e32 v12, v12
	s_nop 0
	v_mul_f32_e32 v11, v11, v12
	v_mul_f32_e32 v12, 0x3c800000, v153
	v_mul_f32_e32 v13, 0xbfb8aa3b, v12
	v_exp_f32_e32 v13, v13
	v_mul_f32_e32 v11, v11, v148
	v_mul_f32_e32 v11, 0x3e000000, v11
	v_add_f32_e32 v13, 1.0, v13
	v_rcp_f32_e32 v13, v13
	s_nop 0
	v_mul_f32_e32 v12, v12, v13
	v_med3_f32 v13, v6, s10, v190
	v_mov_b32_e32 v6, v163
	v_cvt_pk_fp8_f32 v6, v5, v13
	v_med3_f32 v5, v7, s10, v190
	v_med3_f32 v7, v8, s10, v190
	v_med3_f32 v8, v10, s10, v190
	v_cvt_pk_fp8_f32 v6, v5, v7 op_sel:[0,0,1]
	v_med3_f32 v5, v9, s10, v190
	v_mov_b32_e32 v7, v163
	v_cvt_pk_fp8_f32 v7, v5, v8
	v_mul_f32_e32 v12, v12, v149
	v_mul_f32_e32 v12, 0x3e000000, v12
	v_med3_f32 v5, v11, s10, v190
	v_med3_f32 v8, v12, s10, v190
	v_cvt_pk_fp8_f32 v7, v5, v8 op_sel:[0,0,1]
	v_ashrrev_i32_e32 v5, 31, v4
	v_lshlrev_b64 v[8:9], 7, v[4:5]
	v_lshl_add_u64 v[8:9], s[14:15], 0, v[8:9]
	v_lshl_add_u64 v[8:9], v[8:9], 0, v[2:3]
	v_mul_f32_e32 v5, 0x3c800000, v142
	flat_store_dwordx2 v[8:9], v[6:7] nt
	v_mul_f32_e32 v6, 0xbfb8aa3b, v5
	v_exp_f32_e32 v6, v6
	s_nop 0
	v_add_f32_e32 v6, 1.0, v6
	v_rcp_f32_e32 v6, v6
	s_nop 0
	v_mul_f32_e32 v5, v5, v6
	v_mul_f32_e32 v6, 0x3c800000, v143
	v_mul_f32_e32 v7, 0xbfb8aa3b, v6
	v_exp_f32_e32 v7, v7
	v_mul_f32_e32 v5, v5, v138
	v_mul_f32_e32 v5, 0x3e000000, v5
	v_med3_f32 v5, v5, s10, v190
	v_add_f32_e32 v7, 1.0, v7
	v_rcp_f32_e32 v7, v7
	s_nop 0
	v_mul_f32_e32 v6, v6, v7
	v_mul_f32_e32 v6, v6, v139
	v_mul_f32_e32 v7, 0x3e000000, v6
	v_mul_f32_e32 v6, 0x3c800000, v144
	v_mul_f32_e32 v8, 0xbfb8aa3b, v6
	v_exp_f32_e32 v8, v8
	v_med3_f32 v7, v7, s10, v190
	v_add_f32_e32 v8, 1.0, v8
	v_rcp_f32_e32 v8, v8
	s_nop 0
	v_mul_f32_e32 v6, v6, v8
	v_mul_f32_e32 v6, v6, v140
	v_mul_f32_e32 v9, 0x3e000000, v6
	v_mul_f32_e32 v6, 0x3c800000, v145
	v_mul_f32_e32 v8, 0xbfb8aa3b, v6
	v_exp_f32_e32 v8, v8
	s_nop 0
	v_add_f32_e32 v8, 1.0, v8
	v_rcp_f32_e32 v8, v8
	s_nop 0
	v_mul_f32_e32 v6, v6, v8
	v_mul_f32_e32 v6, v6, v141
	v_mul_f32_e32 v10, 0x3e000000, v6
	v_mul_f32_e32 v6, 0x3c800000, v134
	v_mul_f32_e32 v8, 0xbfb8aa3b, v6
	v_exp_f32_e32 v8, v8
	s_nop 0
	v_add_f32_e32 v8, 1.0, v8
	v_rcp_f32_e32 v8, v8
	s_nop 0
	v_mul_f32_e32 v6, v6, v8
	v_mul_f32_e32 v6, v6, v130
	v_mul_f32_e32 v11, 0x3e000000, v6
	v_mul_f32_e32 v6, 0x3c800000, v135
	v_mul_f32_e32 v8, 0xbfb8aa3b, v6
	v_exp_f32_e32 v8, v8
	s_nop 0
	v_add_f32_e32 v8, 1.0, v8
	v_rcp_f32_e32 v8, v8
	s_nop 0
	v_mul_f32_e32 v6, v6, v8
	v_mul_f32_e32 v6, v6, v131
	v_mul_f32_e32 v12, 0x3e000000, v6
	v_mul_f32_e32 v6, 0x3c800000, v136
	v_mul_f32_e32 v8, 0xbfb8aa3b, v6
	v_exp_f32_e32 v8, v8
	s_nop 0
	v_add_f32_e32 v8, 1.0, v8
	v_rcp_f32_e32 v8, v8
	s_nop 0
	v_mul_f32_e32 v6, v6, v8
	v_mul_f32_e32 v6, v6, v132
	v_mul_f32_e32 v13, 0x3e000000, v6
	v_mul_f32_e32 v6, 0x3c800000, v137
	v_mul_f32_e32 v8, 0xbfb8aa3b, v6
	v_exp_f32_e32 v8, v8
	s_nop 0
	v_add_f32_e32 v8, 1.0, v8
	v_rcp_f32_e32 v8, v8
	s_nop 0
	v_mul_f32_e32 v6, v6, v8
	v_mov_b32_e32 v8, v163
	v_cvt_pk_fp8_f32 v8, v5, v7
	v_med3_f32 v5, v9, s10, v190
	v_med3_f32 v7, v10, s10, v190
	v_mov_b32_e32 v9, v163
	v_cvt_pk_fp8_f32 v8, v5, v7 op_sel:[0,0,1]
	v_med3_f32 v5, v11, s10, v190
	v_med3_f32 v7, v12, s10, v190
	v_cvt_pk_fp8_f32 v9, v5, v7
	v_mul_f32_e32 v6, v6, v133
	v_mul_f32_e32 v14, 0x3e000000, v6
	v_add_u32_e32 v6, 16, v4
	v_med3_f32 v5, v13, s10, v190
	v_med3_f32 v7, v14, s10, v190
	v_cvt_pk_fp8_f32 v9, v5, v7 op_sel:[0,0,1]
	v_ashrrev_i32_e32 v7, 31, v6
	v_lshlrev_b64 v[6:7], 7, v[6:7]
	v_lshl_add_u64 v[6:7], s[14:15], 0, v[6:7]
	v_lshl_add_u64 v[6:7], v[6:7], 0, v[2:3]
	v_mul_f32_e32 v5, 0x3c800000, v126
	flat_store_dwordx2 v[6:7], v[8:9] nt
	v_mul_f32_e32 v6, 0xbfb8aa3b, v5
	v_exp_f32_e32 v6, v6
	s_nop 0
	v_add_f32_e32 v6, 1.0, v6
	v_rcp_f32_e32 v6, v6
	s_nop 0
	v_mul_f32_e32 v5, v5, v6
	v_mul_f32_e32 v6, 0x3c800000, v127
	v_mul_f32_e32 v7, 0xbfb8aa3b, v6
	v_exp_f32_e32 v7, v7
	v_mul_f32_e32 v5, v5, v122
	v_mul_f32_e32 v5, 0x3e000000, v5
	v_med3_f32 v5, v5, s10, v190
	v_add_f32_e32 v7, 1.0, v7
	v_rcp_f32_e32 v7, v7
	s_nop 0
	v_mul_f32_e32 v6, v6, v7
	v_mul_f32_e32 v6, v6, v123
	v_mul_f32_e32 v7, 0x3e000000, v6
	v_mul_f32_e32 v6, 0x3c800000, v128
	v_mul_f32_e32 v8, 0xbfb8aa3b, v6
	v_exp_f32_e32 v8, v8
	v_med3_f32 v7, v7, s10, v190
	v_add_f32_e32 v8, 1.0, v8
	v_rcp_f32_e32 v8, v8
	s_nop 0
	v_mul_f32_e32 v6, v6, v8
	v_mul_f32_e32 v6, v6, v124
	v_mul_f32_e32 v9, 0x3e000000, v6
	v_mul_f32_e32 v6, 0x3c800000, v129
	v_mul_f32_e32 v8, 0xbfb8aa3b, v6
	v_exp_f32_e32 v8, v8
	s_nop 0
	v_add_f32_e32 v8, 1.0, v8
	v_rcp_f32_e32 v8, v8
	s_nop 0
	v_mul_f32_e32 v6, v6, v8
	v_mul_f32_e32 v6, v6, v125
	v_mul_f32_e32 v10, 0x3e000000, v6
	v_mul_f32_e32 v6, 0x3c800000, v118
	v_mul_f32_e32 v8, 0xbfb8aa3b, v6
	v_exp_f32_e32 v8, v8
	s_nop 0
	v_add_f32_e32 v8, 1.0, v8
	v_rcp_f32_e32 v8, v8
	s_nop 0
	v_mul_f32_e32 v6, v6, v8
	v_mul_f32_e32 v6, v6, v114
	v_mul_f32_e32 v11, 0x3e000000, v6
	v_mul_f32_e32 v6, 0x3c800000, v119
	v_mul_f32_e32 v8, 0xbfb8aa3b, v6
	v_exp_f32_e32 v8, v8
	s_nop 0
	v_add_f32_e32 v8, 1.0, v8
	v_rcp_f32_e32 v8, v8
	s_nop 0
	v_mul_f32_e32 v6, v6, v8
	v_mul_f32_e32 v6, v6, v115
	v_mul_f32_e32 v12, 0x3e000000, v6
	v_mul_f32_e32 v6, 0x3c800000, v120
	v_mul_f32_e32 v8, 0xbfb8aa3b, v6
	v_exp_f32_e32 v8, v8
	s_nop 0
	v_add_f32_e32 v8, 1.0, v8
	v_rcp_f32_e32 v8, v8
	s_nop 0
	v_mul_f32_e32 v6, v6, v8
	v_mul_f32_e32 v6, v6, v116
	v_mul_f32_e32 v13, 0x3e000000, v6
	v_mul_f32_e32 v6, 0x3c800000, v121
	v_mul_f32_e32 v8, 0xbfb8aa3b, v6
	v_exp_f32_e32 v8, v8
	s_nop 0
	v_add_f32_e32 v8, 1.0, v8
	v_rcp_f32_e32 v8, v8
	s_nop 0
	v_mul_f32_e32 v6, v6, v8
	v_mov_b32_e32 v8, v163
	v_cvt_pk_fp8_f32 v8, v5, v7
	v_med3_f32 v5, v9, s10, v190
	v_med3_f32 v7, v10, s10, v190
	v_mov_b32_e32 v9, v163
	v_cvt_pk_fp8_f32 v8, v5, v7 op_sel:[0,0,1]
	v_med3_f32 v5, v11, s10, v190
	v_med3_f32 v7, v12, s10, v190
	v_cvt_pk_fp8_f32 v9, v5, v7
	v_mul_f32_e32 v6, v6, v117
	v_mul_f32_e32 v14, 0x3e000000, v6
	v_add_u32_e32 v6, 32, v4
	v_med3_f32 v5, v13, s10, v190
	v_med3_f32 v7, v14, s10, v190
	v_cvt_pk_fp8_f32 v9, v5, v7 op_sel:[0,0,1]
	v_ashrrev_i32_e32 v7, 31, v6
	v_lshlrev_b64 v[6:7], 7, v[6:7]
	v_lshl_add_u64 v[6:7], s[14:15], 0, v[6:7]
	v_lshl_add_u64 v[6:7], v[6:7], 0, v[2:3]
	v_mul_f32_e32 v5, 0x3c800000, v110
	flat_store_dwordx2 v[6:7], v[8:9] nt
	v_mul_f32_e32 v6, 0xbfb8aa3b, v5
	v_exp_f32_e32 v6, v6
	s_nop 0
	v_add_f32_e32 v6, 1.0, v6
	v_rcp_f32_e32 v6, v6
	s_nop 0
	v_mul_f32_e32 v5, v5, v6
	v_mul_f32_e32 v6, 0x3c800000, v111
	v_mul_f32_e32 v7, 0xbfb8aa3b, v6
	v_exp_f32_e32 v7, v7
	v_mul_f32_e32 v5, v5, v106
	v_mul_f32_e32 v5, 0x3e000000, v5
	v_med3_f32 v5, v5, s10, v190
	v_add_f32_e32 v7, 1.0, v7
	v_rcp_f32_e32 v7, v7
	s_nop 0
	v_mul_f32_e32 v6, v6, v7
	v_mul_f32_e32 v6, v6, v107
	v_mul_f32_e32 v7, 0x3e000000, v6
	v_mul_f32_e32 v6, 0x3c800000, v112
	v_mul_f32_e32 v8, 0xbfb8aa3b, v6
	v_exp_f32_e32 v8, v8
	v_med3_f32 v7, v7, s10, v190
	v_add_f32_e32 v8, 1.0, v8
	v_rcp_f32_e32 v8, v8
	s_nop 0
	v_mul_f32_e32 v6, v6, v8
	v_mul_f32_e32 v6, v6, v108
	v_mul_f32_e32 v9, 0x3e000000, v6
	v_mul_f32_e32 v6, 0x3c800000, v113
	v_mul_f32_e32 v8, 0xbfb8aa3b, v6
	v_exp_f32_e32 v8, v8
	s_nop 0
	v_add_f32_e32 v8, 1.0, v8
	v_rcp_f32_e32 v8, v8
	s_nop 0
	v_mul_f32_e32 v6, v6, v8
	v_mul_f32_e32 v6, v6, v109
	v_mul_f32_e32 v10, 0x3e000000, v6
	v_mul_f32_e32 v6, 0x3c800000, v102
	v_mul_f32_e32 v8, 0xbfb8aa3b, v6
	v_exp_f32_e32 v8, v8
	s_nop 0
	v_add_f32_e32 v8, 1.0, v8
	v_rcp_f32_e32 v8, v8
	s_nop 0
	v_mul_f32_e32 v6, v6, v8
	v_mul_f32_e32 v6, v6, v98
	v_mul_f32_e32 v11, 0x3e000000, v6
	v_mul_f32_e32 v6, 0x3c800000, v103
	v_mul_f32_e32 v8, 0xbfb8aa3b, v6
	v_exp_f32_e32 v8, v8
	s_nop 0
	v_add_f32_e32 v8, 1.0, v8
	v_rcp_f32_e32 v8, v8
	s_nop 0
	v_mul_f32_e32 v6, v6, v8
	v_mul_f32_e32 v6, v6, v99
	v_mul_f32_e32 v12, 0x3e000000, v6
	v_mul_f32_e32 v6, 0x3c800000, v104
	v_mul_f32_e32 v8, 0xbfb8aa3b, v6
	v_exp_f32_e32 v8, v8
	s_nop 0
	v_add_f32_e32 v8, 1.0, v8
	v_rcp_f32_e32 v8, v8
	s_nop 0
	v_mul_f32_e32 v6, v6, v8
	v_mul_f32_e32 v6, v6, v100
	v_mul_f32_e32 v13, 0x3e000000, v6
	v_mul_f32_e32 v6, 0x3c800000, v105
	v_mul_f32_e32 v8, 0xbfb8aa3b, v6
	v_exp_f32_e32 v8, v8
	s_nop 0
	v_add_f32_e32 v8, 1.0, v8
	v_rcp_f32_e32 v8, v8
	s_nop 0
	v_mul_f32_e32 v6, v6, v8
	v_mov_b32_e32 v8, v163
	v_cvt_pk_fp8_f32 v8, v5, v7
	v_med3_f32 v5, v9, s10, v190
	v_med3_f32 v7, v10, s10, v190
	v_mov_b32_e32 v9, v163
	v_cvt_pk_fp8_f32 v8, v5, v7 op_sel:[0,0,1]
	v_med3_f32 v5, v11, s10, v190
	v_med3_f32 v7, v12, s10, v190
	v_cvt_pk_fp8_f32 v9, v5, v7
	v_mul_f32_e32 v6, v6, v101
	v_mul_f32_e32 v14, 0x3e000000, v6
	v_add_u32_e32 v6, 48, v4
	v_med3_f32 v5, v13, s10, v190
	v_med3_f32 v7, v14, s10, v190
	v_cvt_pk_fp8_f32 v9, v5, v7 op_sel:[0,0,1]
	v_ashrrev_i32_e32 v7, 31, v6
	v_lshlrev_b64 v[6:7], 7, v[6:7]
	v_lshl_add_u64 v[6:7], s[14:15], 0, v[6:7]
	v_lshl_add_u64 v[6:7], v[6:7], 0, v[2:3]
	v_mul_f32_e32 v5, 0x3c800000, v94
	flat_store_dwordx2 v[6:7], v[8:9] nt
	v_mul_f32_e32 v7, 0xbfb8aa3b, v5
	v_exp_f32_e32 v7, v7
	v_add_u32_e32 v6, 0x80, v4
	v_add_f32_e32 v7, 1.0, v7
	v_rcp_f32_e32 v7, v7
	s_nop 0
	v_mul_f32_e32 v5, v5, v7
	v_mul_f32_e32 v7, 0x3c800000, v95
	v_mul_f32_e32 v8, 0xbfb8aa3b, v7
	v_exp_f32_e32 v8, v8
	v_mul_f32_e32 v5, v5, v90
	v_mul_f32_e32 v5, 0x3e000000, v5
	v_med3_f32 v5, v5, s10, v190
	v_add_f32_e32 v8, 1.0, v8
	v_rcp_f32_e32 v8, v8
	s_nop 0
	v_mul_f32_e32 v7, v7, v8
	v_mul_f32_e32 v8, 0x3c800000, v96
	v_mul_f32_e32 v9, 0xbfb8aa3b, v8
	v_exp_f32_e32 v9, v9
	v_mul_f32_e32 v7, v7, v91
	v_mul_f32_e32 v7, 0x3e000000, v7
	v_med3_f32 v7, v7, s10, v190
	v_add_f32_e32 v9, 1.0, v9
	v_rcp_f32_e32 v9, v9
	s_nop 0
	v_mul_f32_e32 v8, v8, v9
	v_mul_f32_e32 v8, v8, v92
	v_mul_f32_e32 v9, 0x3e000000, v8
	v_mul_f32_e32 v8, 0x3c800000, v97
	v_mul_f32_e32 v10, 0xbfb8aa3b, v8
	v_exp_f32_e32 v10, v10
	s_nop 0
	v_add_f32_e32 v10, 1.0, v10
	v_rcp_f32_e32 v10, v10
	s_nop 0
	v_mul_f32_e32 v8, v8, v10
	v_mul_f32_e32 v8, v8, v93
	v_mul_f32_e32 v10, 0x3e000000, v8
	v_mul_f32_e32 v8, 0x3c800000, v86
	v_mul_f32_e32 v11, 0xbfb8aa3b, v8
	v_exp_f32_e32 v11, v11
	s_nop 0
	v_add_f32_e32 v11, 1.0, v11
	v_rcp_f32_e32 v11, v11
	s_nop 0
	v_mul_f32_e32 v8, v8, v11
	v_mul_f32_e32 v8, v8, v82
	v_mul_f32_e32 v11, 0x3e000000, v8
	v_mul_f32_e32 v8, 0x3c800000, v87
	v_mul_f32_e32 v12, 0xbfb8aa3b, v8
	v_exp_f32_e32 v12, v12
	s_nop 0
	v_add_f32_e32 v12, 1.0, v12
	v_rcp_f32_e32 v12, v12
	s_nop 0
	v_mul_f32_e32 v8, v8, v12
	v_mul_f32_e32 v8, v8, v83
	v_mul_f32_e32 v12, 0x3e000000, v8
	v_mul_f32_e32 v8, 0x3c800000, v88
	v_mul_f32_e32 v13, 0xbfb8aa3b, v8
	v_exp_f32_e32 v13, v13
	s_nop 0
	v_add_f32_e32 v13, 1.0, v13
	v_rcp_f32_e32 v13, v13
	s_nop 0
	v_mul_f32_e32 v8, v8, v13
	v_mul_f32_e32 v8, v8, v84
	v_mul_f32_e32 v13, 0x3e000000, v8
	v_mul_f32_e32 v8, 0x3c800000, v89
	v_mul_f32_e32 v14, 0xbfb8aa3b, v8
	v_exp_f32_e32 v14, v14
	s_nop 0
	v_add_f32_e32 v14, 1.0, v14
	v_rcp_f32_e32 v14, v14
	s_nop 0
	v_mul_f32_e32 v8, v8, v14
	v_mul_f32_e32 v8, v8, v85
	v_mul_f32_e32 v14, 0x3e000000, v8
	v_mov_b32_e32 v8, v163
	v_cvt_pk_fp8_f32 v8, v5, v7
	v_med3_f32 v5, v9, s10, v190
	v_med3_f32 v7, v10, s10, v190
	v_mov_b32_e32 v9, v163
	v_cvt_pk_fp8_f32 v8, v5, v7 op_sel:[0,0,1]
	v_med3_f32 v5, v11, s10, v190
	v_med3_f32 v7, v12, s10, v190
	v_cvt_pk_fp8_f32 v9, v5, v7
	v_med3_f32 v5, v13, s10, v190
	v_med3_f32 v7, v14, s10, v190
	v_cvt_pk_fp8_f32 v9, v5, v7 op_sel:[0,0,1]
	v_ashrrev_i32_e32 v7, 31, v6
	v_lshlrev_b64 v[6:7], 7, v[6:7]
	v_lshl_add_u64 v[6:7], s[14:15], 0, v[6:7]
	v_lshl_add_u64 v[6:7], v[6:7], 0, v[2:3]
	v_mul_f32_e32 v5, 0x3c800000, v78
	flat_store_dwordx2 v[6:7], v[8:9] nt
	v_mul_f32_e32 v6, 0xbfb8aa3b, v5
	v_exp_f32_e32 v6, v6
	s_nop 0
	v_add_f32_e32 v6, 1.0, v6
	v_rcp_f32_e32 v6, v6
	s_nop 0
	v_mul_f32_e32 v5, v5, v6
	v_mul_f32_e32 v6, 0x3c800000, v79
	v_mul_f32_e32 v7, 0xbfb8aa3b, v6
	v_exp_f32_e32 v7, v7
	v_mul_f32_e32 v5, v5, v74
	v_mul_f32_e32 v5, 0x3e000000, v5
	v_med3_f32 v5, v5, s10, v190
	v_add_f32_e32 v7, 1.0, v7
	v_rcp_f32_e32 v7, v7
	s_nop 0
	v_mul_f32_e32 v6, v6, v7
	v_mul_f32_e32 v6, v6, v75
	v_mul_f32_e32 v7, 0x3e000000, v6
	v_mul_f32_e32 v6, 0x3c800000, v80
	v_mul_f32_e32 v8, 0xbfb8aa3b, v6
	v_exp_f32_e32 v8, v8
	v_med3_f32 v7, v7, s10, v190
	v_add_f32_e32 v8, 1.0, v8
	v_rcp_f32_e32 v8, v8
	s_nop 0
	v_mul_f32_e32 v6, v6, v8
	v_mul_f32_e32 v6, v6, v76
	v_mul_f32_e32 v9, 0x3e000000, v6
	v_mul_f32_e32 v6, 0x3c800000, v81
	v_mul_f32_e32 v8, 0xbfb8aa3b, v6
	v_exp_f32_e32 v8, v8
	s_nop 0
	v_add_f32_e32 v8, 1.0, v8
	v_rcp_f32_e32 v8, v8
	s_nop 0
	v_mul_f32_e32 v6, v6, v8
	v_mul_f32_e32 v6, v6, v77
	v_mul_f32_e32 v10, 0x3e000000, v6
	v_mul_f32_e32 v6, 0x3c800000, v70
	v_mul_f32_e32 v8, 0xbfb8aa3b, v6
	v_exp_f32_e32 v8, v8
	s_nop 0
	v_add_f32_e32 v8, 1.0, v8
	v_rcp_f32_e32 v8, v8
	s_nop 0
	v_mul_f32_e32 v6, v6, v8
	v_mul_f32_e32 v6, v6, v66
	v_mul_f32_e32 v11, 0x3e000000, v6
	v_mul_f32_e32 v6, 0x3c800000, v71
	v_mul_f32_e32 v8, 0xbfb8aa3b, v6
	v_exp_f32_e32 v8, v8
	s_nop 0
	v_add_f32_e32 v8, 1.0, v8
	v_rcp_f32_e32 v8, v8
	s_nop 0
	v_mul_f32_e32 v6, v6, v8
	v_mul_f32_e32 v6, v6, v67
	v_mul_f32_e32 v12, 0x3e000000, v6
	v_mul_f32_e32 v6, 0x3c800000, v72
	v_mul_f32_e32 v8, 0xbfb8aa3b, v6
	v_exp_f32_e32 v8, v8
	s_nop 0
	v_add_f32_e32 v8, 1.0, v8
	v_rcp_f32_e32 v8, v8
	s_nop 0
	v_mul_f32_e32 v6, v6, v8
	v_mul_f32_e32 v6, v6, v68
	v_mul_f32_e32 v13, 0x3e000000, v6
	v_mul_f32_e32 v6, 0x3c800000, v73
	v_mul_f32_e32 v8, 0xbfb8aa3b, v6
	v_exp_f32_e32 v8, v8
	s_nop 0
	v_add_f32_e32 v8, 1.0, v8
	v_rcp_f32_e32 v8, v8
	s_nop 0
	v_mul_f32_e32 v6, v6, v8
	v_mov_b32_e32 v8, v163
	v_cvt_pk_fp8_f32 v8, v5, v7
	v_med3_f32 v5, v9, s10, v190
	v_med3_f32 v7, v10, s10, v190
	v_mov_b32_e32 v9, v163
	v_cvt_pk_fp8_f32 v8, v5, v7 op_sel:[0,0,1]
	v_med3_f32 v5, v11, s10, v190
	v_med3_f32 v7, v12, s10, v190
	v_cvt_pk_fp8_f32 v9, v5, v7
	v_mul_f32_e32 v6, v6, v69
	v_mul_f32_e32 v14, 0x3e000000, v6
	v_add_u32_e32 v6, 0x90, v4
	v_med3_f32 v5, v13, s10, v190
	v_med3_f32 v7, v14, s10, v190
	v_cvt_pk_fp8_f32 v9, v5, v7 op_sel:[0,0,1]
	v_ashrrev_i32_e32 v7, 31, v6
	v_lshlrev_b64 v[6:7], 7, v[6:7]
	v_lshl_add_u64 v[6:7], s[14:15], 0, v[6:7]
	v_lshl_add_u64 v[6:7], v[6:7], 0, v[2:3]
	v_mul_f32_e32 v5, 0x3c800000, v62
	flat_store_dwordx2 v[6:7], v[8:9] nt
	v_mul_f32_e32 v6, 0xbfb8aa3b, v5
	v_exp_f32_e32 v6, v6
	s_nop 0
	v_add_f32_e32 v6, 1.0, v6
	v_rcp_f32_e32 v6, v6
	s_nop 0
	v_mul_f32_e32 v5, v5, v6
	v_mul_f32_e32 v6, 0x3c800000, v63
	v_mul_f32_e32 v7, 0xbfb8aa3b, v6
	v_exp_f32_e32 v7, v7
	v_mul_f32_e32 v5, v5, v58
	v_mul_f32_e32 v5, 0x3e000000, v5
	v_med3_f32 v5, v5, s10, v190
	v_add_f32_e32 v7, 1.0, v7
	v_rcp_f32_e32 v7, v7
	s_nop 0
	v_mul_f32_e32 v6, v6, v7
	v_mul_f32_e32 v6, v6, v59
	v_mul_f32_e32 v7, 0x3e000000, v6
	v_mul_f32_e32 v6, 0x3c800000, v64
	v_mul_f32_e32 v8, 0xbfb8aa3b, v6
	v_exp_f32_e32 v8, v8
	v_med3_f32 v7, v7, s10, v190
	v_add_f32_e32 v8, 1.0, v8
	v_rcp_f32_e32 v8, v8
	s_nop 0
	v_mul_f32_e32 v6, v6, v8
	v_mul_f32_e32 v6, v6, v60
	v_mul_f32_e32 v9, 0x3e000000, v6
	v_mul_f32_e32 v6, 0x3c800000, v65
	v_mul_f32_e32 v8, 0xbfb8aa3b, v6
	v_exp_f32_e32 v8, v8
	s_nop 0
	v_add_f32_e32 v8, 1.0, v8
	v_rcp_f32_e32 v8, v8
	s_nop 0
	v_mul_f32_e32 v6, v6, v8
	v_mul_f32_e32 v6, v6, v61
	v_mul_f32_e32 v10, 0x3e000000, v6
	v_mul_f32_e32 v6, 0x3c800000, v54
	v_mul_f32_e32 v8, 0xbfb8aa3b, v6
	v_exp_f32_e32 v8, v8
	s_nop 0
	v_add_f32_e32 v8, 1.0, v8
	v_rcp_f32_e32 v8, v8
	s_nop 0
	v_mul_f32_e32 v6, v6, v8
	v_mul_f32_e32 v6, v6, v50
	v_mul_f32_e32 v11, 0x3e000000, v6
	v_mul_f32_e32 v6, 0x3c800000, v55
	v_mul_f32_e32 v8, 0xbfb8aa3b, v6
	v_exp_f32_e32 v8, v8
	s_nop 0
	v_add_f32_e32 v8, 1.0, v8
	v_rcp_f32_e32 v8, v8
	s_nop 0
	v_mul_f32_e32 v6, v6, v8
	v_mul_f32_e32 v6, v6, v51
	v_mul_f32_e32 v12, 0x3e000000, v6
	v_mul_f32_e32 v6, 0x3c800000, v56
	v_mul_f32_e32 v8, 0xbfb8aa3b, v6
	v_exp_f32_e32 v8, v8
	s_nop 0
	v_add_f32_e32 v8, 1.0, v8
	v_rcp_f32_e32 v8, v8
	s_nop 0
	v_mul_f32_e32 v6, v6, v8
	v_mul_f32_e32 v6, v6, v52
	v_mul_f32_e32 v13, 0x3e000000, v6
	v_mul_f32_e32 v6, 0x3c800000, v57
	v_mul_f32_e32 v8, 0xbfb8aa3b, v6
	v_exp_f32_e32 v8, v8
	s_nop 0
	v_add_f32_e32 v8, 1.0, v8
	v_rcp_f32_e32 v8, v8
	s_nop 0
	v_mul_f32_e32 v6, v6, v8
	v_mov_b32_e32 v8, v163
	v_cvt_pk_fp8_f32 v8, v5, v7
	v_med3_f32 v5, v9, s10, v190
	v_med3_f32 v7, v10, s10, v190
	v_mov_b32_e32 v9, v163
	v_cvt_pk_fp8_f32 v8, v5, v7 op_sel:[0,0,1]
	v_med3_f32 v5, v11, s10, v190
	v_med3_f32 v7, v12, s10, v190
	v_cvt_pk_fp8_f32 v9, v5, v7
	v_mul_f32_e32 v6, v6, v53
	v_mul_f32_e32 v14, 0x3e000000, v6
	v_add_u32_e32 v6, 0xa0, v4
	v_med3_f32 v5, v13, s10, v190
	v_med3_f32 v7, v14, s10, v190
	v_cvt_pk_fp8_f32 v9, v5, v7 op_sel:[0,0,1]
	v_ashrrev_i32_e32 v7, 31, v6
	v_lshlrev_b64 v[6:7], 7, v[6:7]
	v_lshl_add_u64 v[6:7], s[14:15], 0, v[6:7]
	v_lshl_add_u64 v[6:7], v[6:7], 0, v[2:3]
	v_mul_f32_e32 v5, 0x3c800000, v46
	flat_store_dwordx2 v[6:7], v[8:9] nt
	v_mul_f32_e32 v6, 0xbfb8aa3b, v5
	v_exp_f32_e32 v6, v6
	v_add_u32_e32 v4, 0xb0, v4
	v_add_f32_e32 v6, 1.0, v6
	v_rcp_f32_e32 v6, v6
	s_nop 0
	v_mul_f32_e32 v5, v5, v6
	v_mul_f32_e32 v6, 0x3c800000, v47
	v_mul_f32_e32 v7, 0xbfb8aa3b, v6
	v_exp_f32_e32 v7, v7
	v_mul_f32_e32 v5, v5, v42
	v_mul_f32_e32 v5, 0x3e000000, v5
	v_med3_f32 v5, v5, s10, v190
	v_add_f32_e32 v7, 1.0, v7
	v_rcp_f32_e32 v7, v7
	s_nop 0
	v_mul_f32_e32 v6, v6, v7
	v_mul_f32_e32 v7, 0x3c800000, v48
	v_mul_f32_e32 v8, 0xbfb8aa3b, v7
	v_exp_f32_e32 v8, v8
	v_mul_f32_e32 v6, v6, v43
	v_mul_f32_e32 v6, 0x3e000000, v6
	v_add_f32_e32 v8, 1.0, v8
	v_rcp_f32_e32 v8, v8
	s_nop 0
	v_mul_f32_e32 v7, v7, v8
	v_mul_f32_e32 v8, 0x3c800000, v49
	v_mul_f32_e32 v9, 0xbfb8aa3b, v8
	v_exp_f32_e32 v9, v9
	v_mul_f32_e32 v7, v7, v44
	v_mul_f32_e32 v7, 0x3e000000, v7
	v_add_f32_e32 v9, 1.0, v9
	v_rcp_f32_e32 v9, v9
	s_nop 0
	v_mul_f32_e32 v8, v8, v9
	v_mul_f32_e32 v9, 0x3c800000, v38
	v_mul_f32_e32 v10, 0xbfb8aa3b, v9
	v_exp_f32_e32 v10, v10
	v_mul_f32_e32 v8, v8, v45
	v_mul_f32_e32 v8, 0x3e000000, v8
	v_add_f32_e32 v10, 1.0, v10
	v_rcp_f32_e32 v10, v10
	s_nop 0
	v_mul_f32_e32 v9, v9, v10
	v_mul_f32_e32 v10, 0x3c800000, v39
	v_mul_f32_e32 v11, 0xbfb8aa3b, v10
	v_exp_f32_e32 v11, v11
	v_mul_f32_e32 v9, v9, v34
	v_mul_f32_e32 v9, 0x3e000000, v9
	v_add_f32_e32 v11, 1.0, v11
	v_rcp_f32_e32 v11, v11
	s_nop 0
	v_mul_f32_e32 v10, v10, v11
	v_mul_f32_e32 v11, 0x3c800000, v40
	v_mul_f32_e32 v12, 0xbfb8aa3b, v11
	v_exp_f32_e32 v12, v12
	v_mul_f32_e32 v10, v10, v35
	v_mul_f32_e32 v10, 0x3e000000, v10
	v_add_f32_e32 v12, 1.0, v12
	v_rcp_f32_e32 v12, v12
	s_nop 0
	v_mul_f32_e32 v11, v11, v12
	v_mul_f32_e32 v12, 0x3c800000, v41
	v_mul_f32_e32 v13, 0xbfb8aa3b, v12
	v_exp_f32_e32 v13, v13
	v_mul_f32_e32 v11, v11, v36
	v_mul_f32_e32 v11, 0x3e000000, v11
	v_add_f32_e32 v13, 1.0, v13
	v_rcp_f32_e32 v13, v13
	s_nop 0
	v_mul_f32_e32 v12, v12, v13
	v_med3_f32 v13, v6, s10, v190
	v_mov_b32_e32 v6, v163
	v_cvt_pk_fp8_f32 v6, v5, v13
	v_med3_f32 v5, v7, s10, v190
	v_med3_f32 v7, v8, s10, v190
	v_med3_f32 v8, v10, s10, v190
	v_cvt_pk_fp8_f32 v6, v5, v7 op_sel:[0,0,1]
	v_med3_f32 v5, v9, s10, v190
	v_mov_b32_e32 v7, v163
	v_cvt_pk_fp8_f32 v7, v5, v8
	v_mul_f32_e32 v12, v12, v37
	v_mul_f32_e32 v12, 0x3e000000, v12
	v_med3_f32 v5, v11, s10, v190
	v_med3_f32 v8, v12, s10, v190
	v_cvt_pk_fp8_f32 v7, v5, v8 op_sel:[0,0,1]
	v_ashrrev_i32_e32 v5, 31, v4
	v_lshlrev_b64 v[4:5], 7, v[4:5]
	v_lshl_add_u64 v[4:5], s[14:15], 0, v[4:5]
	v_lshl_add_u64 v[2:3], v[4:5], 0, v[2:3]
	flat_store_dwordx2 v[2:3], v[6:7] nt
	s_cbranch_vccz .LBB0_2030
	s_waitcnt vmcnt(0)
	s_cmpk_gt_u32 s42, 0xff
	s_cbranch_scc1 .LBB0_1976
	s_barrier
	s_branch .LBB0_1976

.LBB0_2108:
	ds_read_b128 v[2:5], v169
	ds_read_b128 v[6:9], v169 offset:1024
	ds_read_b128 v[10:13], v169 offset:2048
	ds_read_b128 v[14:17], v169 offset:3072
	s_add_u32 s0, s30, 0x4000
	s_addc_u32 s1, s31, 0
	s_cmp_eq_u32 s53, 4
	s_cselect_b32 s38, s49, s0
	s_cselect_b32 s39, s23, s1
	s_cselect_b32 s34, s50, s51
	s_cselect_b32 s35, s21, s52
	s_add_u32 s36, s38, 0x8000
	s_addc_u32 s37, s39, 0
	v_lshl_add_u64 v[162:163], s[30:31], 0, v[156:157]
	s_add_i32 m0, s10, 0xc000
	ds_read_b128 v[174:177], v170
	ds_read_b128 v[178:181], v170 offset:1024
	ds_read_b128 v[182:185], v170 offset:2048
	ds_read_b128 v[186:189], v170 offset:3072
	ds_read_b128 v[190:193], v170 offset:4096
	ds_read_b128 v[194:197], v170 offset:5120
	ds_read_b128 v[198:201], v170 offset:6144
	ds_read_b128 v[202:205], v170 offset:7168
	global_load_lds_dwordx4 v[162:163], off
	v_lshl_add_u64 v[162:163], s[30:31], 0, v[154:155]
	s_add_i32 m0, s10, 0xe000
	s_nop 0
	global_load_lds_dwordx4 v[162:163], off
	s_waitcnt lgkmcnt(8)
	s_waitcnt vmcnt(10)
	s_barrier
	s_waitcnt lgkmcnt(0)
	s_setprio 1
	s_waitcnt lgkmcnt(0)
	v_mfma_scale_f32_16x16x128_f8f6f4 v[142:145], v[2:9], v[174:181], v[142:145], v171, v171 op_sel_hi:[0,0,0]
	v_mfma_scale_f32_16x16x128_f8f6f4 v[138:141], v[10:17], v[174:181], v[138:141], v171, v171 op_sel_hi:[0,0,0]
	v_mfma_scale_f32_16x16x128_f8f6f4 v[126:129], v[2:9], v[182:189], v[126:129], v171, v171 op_sel_hi:[0,0,0]
	v_mfma_scale_f32_16x16x128_f8f6f4 v[122:125], v[10:17], v[182:189], v[122:125], v171, v171 op_sel_hi:[0,0,0]
	v_mfma_scale_f32_16x16x128_f8f6f4 v[110:113], v[2:9], v[190:197], v[110:113], v171, v171 op_sel_hi:[0,0,0]
	v_mfma_scale_f32_16x16x128_f8f6f4 v[106:109], v[10:17], v[190:197], v[106:109], v171, v171 op_sel_hi:[0,0,0]
	v_mfma_scale_f32_16x16x128_f8f6f4 v[94:97], v[2:9], v[198:205], v[94:97], v171, v171 op_sel_hi:[0,0,0]
	v_mfma_scale_f32_16x16x128_f8f6f4 v[90:93], v[10:17], v[198:205], v[90:93], v171, v171 op_sel_hi:[0,0,0]
	s_setprio 0
	s_barrier
	s_add_i32 s0, s45, s9
	v_lshl_add_u64 v[162:163], s[34:35], 0, v[150:151]
	s_mov_b32 m0, s0
	ds_read_b128 v[206:209], v172
	ds_read_b128 v[210:213], v172 offset:1024
	ds_read_b128 v[214:217], v172 offset:2048
	ds_read_b128 v[218:221], v172 offset:3072
	global_load_lds_dwordx4 v[162:163], off
	v_lshl_add_u64 v[164:165], s[34:35], 0, v[146:147]
	s_add_i32 m0, s0, 0x2000
	s_nop 0
	global_load_lds_dwordx4 v[164:165], off
	s_waitcnt vmcnt(10)
	s_barrier
	s_waitcnt lgkmcnt(0)
	s_setprio 1
	s_waitcnt lgkmcnt(0)
	v_mfma_scale_f32_16x16x128_f8f6f4 v[134:137], v[206:213], v[174:181], v[134:137], v171, v171 op_sel_hi:[0,0,0]
	v_mfma_scale_f32_16x16x128_f8f6f4 v[130:133], v[214:221], v[174:181], v[130:133], v171, v171 op_sel_hi:[0,0,0]
	v_mfma_scale_f32_16x16x128_f8f6f4 v[118:121], v[206:213], v[182:189], v[118:121], v171, v171 op_sel_hi:[0,0,0]
	v_mfma_scale_f32_16x16x128_f8f6f4 v[114:117], v[214:221], v[182:189], v[114:117], v171, v171 op_sel_hi:[0,0,0]
	v_mfma_scale_f32_16x16x128_f8f6f4 v[102:105], v[206:213], v[190:197], v[102:105], v171, v171 op_sel_hi:[0,0,0]
	v_mfma_scale_f32_16x16x128_f8f6f4 v[98:101], v[214:221], v[190:197], v[98:101], v171, v171 op_sel_hi:[0,0,0]
	v_mfma_scale_f32_16x16x128_f8f6f4 v[86:89], v[206:213], v[198:205], v[86:89], v171, v171 op_sel_hi:[0,0,0]
	v_mfma_scale_f32_16x16x128_f8f6f4 v[82:85], v[214:221], v[198:205], v[82:85], v171, v171 op_sel_hi:[0,0,0]
	s_setprio 0
	s_mov_b32 m0, s10
	v_lshl_add_u64 v[222:223], s[38:39], 0, v[152:153]
	s_barrier
	ds_read_b128 v[174:177], v170 offset:16384
	ds_read_b128 v[178:181], v170 offset:17408
	ds_read_b128 v[182:185], v170 offset:18432
	ds_read_b128 v[186:189], v170 offset:19456
	ds_read_b128 v[190:193], v170 offset:20480
	ds_read_b128 v[194:197], v170 offset:21504
	ds_read_b128 v[198:201], v170 offset:22528
	ds_read_b128 v[202:205], v170 offset:23552
	global_load_lds_dwordx4 v[222:223], off
	v_lshl_add_u64 v[222:223], s[38:39], 0, v[148:149]
	s_mov_b32 m0, s11
	s_nop 0
	global_load_lds_dwordx4 v[222:223], off
	s_waitcnt vmcnt(10)
	s_barrier
	s_waitcnt lgkmcnt(0)
	s_setprio 1
	s_waitcnt lgkmcnt(0)
	v_mfma_scale_f32_16x16x128_f8f6f4 v[78:81], v[2:9], v[174:181], v[78:81], v171, v171 op_sel_hi:[0,0,0]
	v_mfma_scale_f32_16x16x128_f8f6f4 v[74:77], v[10:17], v[174:181], v[74:77], v171, v171 op_sel_hi:[0,0,0]
	v_mfma_scale_f32_16x16x128_f8f6f4 v[62:65], v[2:9], v[182:189], v[62:65], v171, v171 op_sel_hi:[0,0,0]
	v_mfma_scale_f32_16x16x128_f8f6f4 v[58:61], v[10:17], v[182:189], v[58:61], v171, v171 op_sel_hi:[0,0,0]
	v_mfma_scale_f32_16x16x128_f8f6f4 v[46:49], v[2:9], v[190:197], v[46:49], v171, v171 op_sel_hi:[0,0,0]
	v_mfma_scale_f32_16x16x128_f8f6f4 v[42:45], v[10:17], v[190:197], v[42:45], v171, v171 op_sel_hi:[0,0,0]
	v_mfma_scale_f32_16x16x128_f8f6f4 v[30:33], v[2:9], v[198:205], v[30:33], v171, v171 op_sel_hi:[0,0,0]
	v_mfma_scale_f32_16x16x128_f8f6f4 v[26:29], v[10:17], v[198:205], v[26:29], v171, v171 op_sel_hi:[0,0,0]
	s_setprio 0
	s_barrier
	s_add_u32 s0, s34, 0x20000
	s_addc_u32 s1, s35, 0
	s_add_i32 s54, s46, s9
	v_lshl_add_u64 v[2:3], s[0:1], 0, v[150:151]
	s_mov_b32 m0, s54
	s_nop 0
	global_load_lds_dwordx4 v[2:3], off
	v_lshl_add_u64 v[2:3], s[0:1], 0, v[146:147]
	s_add_i32 m0, s54, 0x2000
	s_nop 0
	global_load_lds_dwordx4 v[2:3], off
	s_waitcnt vmcnt(10)
	s_barrier
	s_setprio 1
	v_mfma_scale_f32_16x16x128_f8f6f4 v[70:73], v[206:213], v[174:181], v[70:73], v171, v171 op_sel_hi:[0,0,0]
	v_mfma_scale_f32_16x16x128_f8f6f4 v[66:69], v[214:221], v[174:181], v[66:69], v171, v171 op_sel_hi:[0,0,0]
	v_mfma_scale_f32_16x16x128_f8f6f4 v[54:57], v[206:213], v[182:189], v[54:57], v171, v171 op_sel_hi:[0,0,0]
	v_mfma_scale_f32_16x16x128_f8f6f4 v[50:53], v[214:221], v[182:189], v[50:53], v171, v171 op_sel_hi:[0,0,0]
	v_mfma_scale_f32_16x16x128_f8f6f4 v[38:41], v[206:213], v[190:197], v[38:41], v171, v171 op_sel_hi:[0,0,0]
	v_mfma_scale_f32_16x16x128_f8f6f4 v[34:37], v[214:221], v[190:197], v[34:37], v171, v171 op_sel_hi:[0,0,0]
	v_mfma_scale_f32_16x16x128_f8f6f4 v[22:25], v[206:213], v[198:205], v[22:25], v171, v171 op_sel_hi:[0,0,0]
	v_mfma_scale_f32_16x16x128_f8f6f4 v[18:21], v[214:221], v[198:205], v[18:21], v171, v171 op_sel_hi:[0,0,0]
	s_setprio 0
	s_add_i32 s54, 0, 0x18000
	v_add_u32_e32 v14, s54, v168
	s_barrier
	ds_read_b128 v[2:5], v14
	ds_read_b128 v[6:9], v14 offset:1024
	ds_read_b128 v[10:13], v14 offset:2048
	ds_read_b128 v[14:17], v14 offset:3072
	s_add_u32 s0, s38, 0x4000
	s_addc_u32 s1, s39, 0
	s_mov_b32 m0, s19
	v_lshl_add_u64 v[206:207], s[0:1], 0, v[152:153]
	ds_read_b128 v[174:177], v170 offset:32768
	ds_read_b128 v[178:181], v170 offset:33792
	ds_read_b128 v[182:185], v170 offset:34816
	ds_read_b128 v[186:189], v170 offset:35840
	ds_read_b128 v[190:193], v170 offset:36864
	ds_read_b128 v[194:197], v170 offset:37888
	ds_read_b128 v[198:201], v170 offset:38912
	ds_read_b128 v[202:205], v170 offset:39936
	global_load_lds_dwordx4 v[206:207], off
	v_lshl_add_u64 v[206:207], s[0:1], 0, v[148:149]
	s_mov_b32 m0, s29
	s_nop 0
	global_load_lds_dwordx4 v[206:207], off
	s_waitcnt lgkmcnt(8)
	s_waitcnt vmcnt(10)
	s_barrier
	s_waitcnt lgkmcnt(0)
	s_setprio 1
	s_waitcnt lgkmcnt(0)
	v_mfma_scale_f32_16x16x128_f8f6f4 v[142:145], v[2:9], v[174:181], v[142:145], v171, v171 op_sel_hi:[0,0,0]
	v_mfma_scale_f32_16x16x128_f8f6f4 v[138:141], v[10:17], v[174:181], v[138:141], v171, v171 op_sel_hi:[0,0,0]
	v_mfma_scale_f32_16x16x128_f8f6f4 v[126:129], v[2:9], v[182:189], v[126:129], v171, v171 op_sel_hi:[0,0,0]
	v_mfma_scale_f32_16x16x128_f8f6f4 v[122:125], v[10:17], v[182:189], v[122:125], v171, v171 op_sel_hi:[0,0,0]
	v_mfma_scale_f32_16x16x128_f8f6f4 v[110:113], v[2:9], v[190:197], v[110:113], v171, v171 op_sel_hi:[0,0,0]
	v_mfma_scale_f32_16x16x128_f8f6f4 v[106:109], v[10:17], v[190:197], v[106:109], v171, v171 op_sel_hi:[0,0,0]
	v_mfma_scale_f32_16x16x128_f8f6f4 v[94:97], v[2:9], v[198:205], v[94:97], v171, v171 op_sel_hi:[0,0,0]
	v_mfma_scale_f32_16x16x128_f8f6f4 v[90:93], v[10:17], v[198:205], v[90:93], v171, v171 op_sel_hi:[0,0,0]
	s_setprio 0
	s_barrier
	s_add_i32 s38, 0, 0x1c000
	s_add_i32 s0, s54, s9
	v_add_u32_e32 v218, s38, v168
	v_lshl_add_u64 v[162:163], v[162:163], 0, s[16:17]
	s_mov_b32 m0, s0
	ds_read_b128 v[206:209], v218
	ds_read_b128 v[210:213], v218 offset:1024
	ds_read_b128 v[214:217], v218 offset:2048
	ds_read_b128 v[218:221], v218 offset:3072
	global_load_lds_dwordx4 v[162:163], off
	v_lshl_add_u64 v[162:163], v[164:165], 0, s[16:17]
	s_add_i32 m0, s0, 0x2000
	s_nop 0
	global_load_lds_dwordx4 v[162:163], off
	s_waitcnt vmcnt(10)
	s_barrier
	s_waitcnt lgkmcnt(0)
	s_setprio 1
	s_waitcnt lgkmcnt(0)
	v_mfma_scale_f32_16x16x128_f8f6f4 v[134:137], v[206:213], v[174:181], v[134:137], v171, v171 op_sel_hi:[0,0,0]
	v_mfma_scale_f32_16x16x128_f8f6f4 v[130:133], v[214:221], v[174:181], v[130:133], v171, v171 op_sel_hi:[0,0,0]
	v_mfma_scale_f32_16x16x128_f8f6f4 v[118:121], v[206:213], v[182:189], v[118:121], v171, v171 op_sel_hi:[0,0,0]
	v_mfma_scale_f32_16x16x128_f8f6f4 v[114:117], v[214:221], v[182:189], v[114:117], v171, v171 op_sel_hi:[0,0,0]
	v_mfma_scale_f32_16x16x128_f8f6f4 v[102:105], v[206:213], v[190:197], v[102:105], v171, v171 op_sel_hi:[0,0,0]
	v_mfma_scale_f32_16x16x128_f8f6f4 v[98:101], v[214:221], v[190:197], v[98:101], v171, v171 op_sel_hi:[0,0,0]
	v_mfma_scale_f32_16x16x128_f8f6f4 v[86:89], v[206:213], v[198:205], v[86:89], v171, v171 op_sel_hi:[0,0,0]
	v_mfma_scale_f32_16x16x128_f8f6f4 v[82:85], v[214:221], v[198:205], v[82:85], v171, v171 op_sel_hi:[0,0,0]
	s_setprio 0
	s_mov_b32 m0, s43
	v_lshl_add_u64 v[162:163], s[36:37], 0, v[152:153]
	s_barrier
	ds_read_b128 v[174:177], v170 offset:49152
	ds_read_b128 v[178:181], v170 offset:50176
	ds_read_b128 v[182:185], v170 offset:51200
	ds_read_b128 v[186:189], v170 offset:52224
	ds_read_b128 v[190:193], v170 offset:53248
	ds_read_b128 v[194:197], v170 offset:54272
	ds_read_b128 v[198:201], v170 offset:55296
	ds_read_b128 v[202:205], v170 offset:56320
	global_load_lds_dwordx4 v[162:163], off
	v_lshl_add_u64 v[162:163], s[36:37], 0, v[148:149]
	s_mov_b32 m0, s44
	s_nop 0
	global_load_lds_dwordx4 v[162:163], off
	s_waitcnt vmcnt(10)
	s_barrier
	s_waitcnt lgkmcnt(0)
	s_setprio 1
	s_waitcnt lgkmcnt(0)
	v_mfma_scale_f32_16x16x128_f8f6f4 v[78:81], v[2:9], v[174:181], v[78:81], v171, v171 op_sel_hi:[0,0,0]
	v_mfma_scale_f32_16x16x128_f8f6f4 v[74:77], v[10:17], v[174:181], v[74:77], v171, v171 op_sel_hi:[0,0,0]
	v_mfma_scale_f32_16x16x128_f8f6f4 v[62:65], v[2:9], v[182:189], v[62:65], v171, v171 op_sel_hi:[0,0,0]
	v_mfma_scale_f32_16x16x128_f8f6f4 v[58:61], v[10:17], v[182:189], v[58:61], v171, v171 op_sel_hi:[0,0,0]
	v_mfma_scale_f32_16x16x128_f8f6f4 v[46:49], v[2:9], v[190:197], v[46:49], v171, v171 op_sel_hi:[0,0,0]
	v_mfma_scale_f32_16x16x128_f8f6f4 v[42:45], v[10:17], v[190:197], v[42:45], v171, v171 op_sel_hi:[0,0,0]
	v_mfma_scale_f32_16x16x128_f8f6f4 v[30:33], v[2:9], v[198:205], v[30:33], v171, v171 op_sel_hi:[0,0,0]
	v_mfma_scale_f32_16x16x128_f8f6f4 v[26:29], v[10:17], v[198:205], v[26:29], v171, v171 op_sel_hi:[0,0,0]
	s_setprio 0
	s_barrier
	s_add_u32 s0, s34, 0x20080
	s_addc_u32 s1, s35, 0
	s_add_i32 s34, s38, s9
	v_lshl_add_u64 v[2:3], s[0:1], 0, v[150:151]
	s_mov_b32 m0, s34
	s_nop 0
	global_load_lds_dwordx4 v[2:3], off
	v_lshl_add_u64 v[2:3], s[0:1], 0, v[146:147]
	s_add_i32 m0, s34, 0x2000
	s_nop 0
	global_load_lds_dwordx4 v[2:3], off
	s_waitcnt vmcnt(10)
	s_barrier
	s_setprio 1
	v_mfma_scale_f32_16x16x128_f8f6f4 v[70:73], v[206:213], v[174:181], v[70:73], v171, v171 op_sel_hi:[0,0,0]
	v_mfma_scale_f32_16x16x128_f8f6f4 v[66:69], v[214:221], v[174:181], v[66:69], v171, v171 op_sel_hi:[0,0,0]
	v_mfma_scale_f32_16x16x128_f8f6f4 v[54:57], v[206:213], v[182:189], v[54:57], v171, v171 op_sel_hi:[0,0,0]
	v_mfma_scale_f32_16x16x128_f8f6f4 v[50:53], v[214:221], v[182:189], v[50:53], v171, v171 op_sel_hi:[0,0,0]
	v_mfma_scale_f32_16x16x128_f8f6f4 v[38:41], v[206:213], v[190:197], v[38:41], v171, v171 op_sel_hi:[0,0,0]
	v_mfma_scale_f32_16x16x128_f8f6f4 v[34:37], v[214:221], v[190:197], v[34:37], v171, v171 op_sel_hi:[0,0,0]
	v_mfma_scale_f32_16x16x128_f8f6f4 v[22:25], v[206:213], v[198:205], v[22:25], v171, v171 op_sel_hi:[0,0,0]
	v_mfma_scale_f32_16x16x128_f8f6f4 v[18:21], v[214:221], v[198:205], v[18:21], v171, v171 op_sel_hi:[0,0,0]
	s_setprio 0
	s_add_i32 s53, s53, 2
	s_add_u32 s51, s51, 0x100
	s_addc_u32 s52, s52, 0
	s_add_u32 s30, s30, 0x10000
	s_addc_u32 s31, s31, 0
	s_cmp_gt_u32 s53, 5
	s_barrier
	s_cbranch_scc0 .LBB0_2108
	v_pk_mul_f32 v[10:11], v[142:143], s[18:19] op_sel_hi:[1,0]
	v_pk_mul_f32 v[8:9], v[144:145], s[18:19] op_sel_hi:[1,0]
	v_med3_f32 v5, v10, s47, v173
	v_med3_f32 v11, v11, s47, v173
	v_mov_b32_e32 v10, 0
	v_cvt_pk_fp8_f32 v10, v5, v11
	v_mov_b32_e32 v3, v166
	v_mov_b32_e32 v2, v167
	s_lshl_b32 s0, s48, 8
	v_pk_mul_f32 v[14:15], v[138:139], s[18:19] op_sel_hi:[1,0]
	v_med3_f32 v5, v8, s47, v173
	v_med3_f32 v8, v9, s47, v173
	s_nop 15
	s_nop 15
	s_or_b32 s0, s0, s42
	v_cvt_pk_fp8_f32 v10, v5, v8 op_sel:[0,0,1]
	v_med3_f32 v5, v14, s47, v173
	v_med3_f32 v8, v15, s47, v173
	v_mov_b32_e32 v11, 0
	v_lshl_add_u32 v2, v2, 3, s0
	s_lshl_b32 s0, s28, 8
	v_cvt_pk_fp8_f32 v11, v5, v8
	s_add_i32 s0, s0, s41
	v_add_u32_e32 v4, s0, v3
	v_pk_mul_f32 v[12:13], v[140:141], s[18:19] op_sel_hi:[1,0]
	v_mov_b32_e32 v6, v4
	v_med3_f32 v5, v12, s47, v173
	v_med3_f32 v8, v13, s47, v173
	v_cvt_pk_fp8_f32 v11, v5, v8 op_sel:[0,0,1]
	v_ashrrev_i32_e32 v7, 31, v6
	v_lshlrev_b64 v[6:7], 10, v[6:7]
	v_ashrrev_i32_e32 v3, 31, v2
	v_lshl_add_u64 v[6:7], s[14:15], 0, v[6:7]
	v_lshl_add_u64 v[6:7], v[6:7], 0, v[2:3]
	flat_store_dwordx2 v[6:7], v[10:11] nt
	v_pk_mul_f32 v[10:11], v[134:135], s[18:19] op_sel_hi:[1,0]
	v_pk_mul_f32 v[8:9], v[136:137], s[18:19] op_sel_hi:[1,0]
	v_med3_f32 v5, v10, s47, v173
	v_med3_f32 v11, v11, s47, v173
	v_mov_b32_e32 v10, 0
	v_cvt_pk_fp8_f32 v10, v5, v11
	v_pk_mul_f32 v[14:15], v[130:131], s[18:19] op_sel_hi:[1,0]
	v_med3_f32 v5, v8, s47, v173
	v_med3_f32 v8, v9, s47, v173
	v_cvt_pk_fp8_f32 v10, v5, v8 op_sel:[0,0,1]
	v_med3_f32 v5, v14, s47, v173
	v_med3_f32 v8, v15, s47, v173
	v_mov_b32_e32 v11, 0
	v_cvt_pk_fp8_f32 v11, v5, v8
	v_pk_mul_f32 v[12:13], v[132:133], s[18:19] op_sel_hi:[1,0]
	v_pk_mul_f32 v[14:15], v[122:123], s[18:19] op_sel_hi:[1,0]
	v_med3_f32 v5, v12, s47, v173
	v_med3_f32 v8, v13, s47, v173
	v_cvt_pk_fp8_f32 v11, v5, v8 op_sel:[0,0,1]
	v_pk_mul_f32 v[8:9], v[128:129], s[18:19] op_sel_hi:[1,0]
	v_pk_mul_f32 v[12:13], v[124:125], s[18:19] op_sel_hi:[1,0]
	s_and_b64 vcc, exec, s[12:13]
	flat_store_dwordx2 v[6:7], v[10:11] offset:128 nt
	v_pk_mul_f32 v[10:11], v[126:127], s[18:19] op_sel_hi:[1,0]
	v_add_u32_e32 v6, 16, v4
	v_med3_f32 v5, v10, s47, v173
	v_med3_f32 v11, v11, s47, v173
	v_mov_b32_e32 v10, 0
	v_cvt_pk_fp8_f32 v10, v5, v11
	v_med3_f32 v5, v8, s47, v173
	v_med3_f32 v8, v9, s47, v173
	v_mov_b32_e32 v11, 0
	v_cvt_pk_fp8_f32 v10, v5, v8 op_sel:[0,0,1]
	v_med3_f32 v5, v14, s47, v173
	v_med3_f32 v8, v15, s47, v173
	v_cvt_pk_fp8_f32 v11, v5, v8
	v_med3_f32 v5, v12, s47, v173
	v_med3_f32 v8, v13, s47, v173
	v_cvt_pk_fp8_f32 v11, v5, v8 op_sel:[0,0,1]
	v_ashrrev_i32_e32 v7, 31, v6
	v_lshlrev_b64 v[6:7], 10, v[6:7]
	v_lshl_add_u64 v[6:7], s[14:15], 0, v[6:7]
	v_lshl_add_u64 v[6:7], v[6:7], 0, v[2:3]
	flat_store_dwordx2 v[6:7], v[10:11] nt
	v_pk_mul_f32 v[10:11], v[118:119], s[18:19] op_sel_hi:[1,0]
	v_pk_mul_f32 v[8:9], v[120:121], s[18:19] op_sel_hi:[1,0]
	v_med3_f32 v5, v10, s47, v173
	v_med3_f32 v11, v11, s47, v173
	v_mov_b32_e32 v10, 0
	v_cvt_pk_fp8_f32 v10, v5, v11
	v_pk_mul_f32 v[14:15], v[114:115], s[18:19] op_sel_hi:[1,0]
	v_med3_f32 v5, v8, s47, v173
	v_med3_f32 v8, v9, s47, v173
	v_cvt_pk_fp8_f32 v10, v5, v8 op_sel:[0,0,1]
	v_med3_f32 v5, v14, s47, v173
	v_med3_f32 v8, v15, s47, v173
	v_mov_b32_e32 v11, 0
	v_cvt_pk_fp8_f32 v11, v5, v8
	v_pk_mul_f32 v[12:13], v[116:117], s[18:19] op_sel_hi:[1,0]
	v_pk_mul_f32 v[14:15], v[106:107], s[18:19] op_sel_hi:[1,0]
	v_med3_f32 v5, v12, s47, v173
	v_med3_f32 v8, v13, s47, v173
	v_cvt_pk_fp8_f32 v11, v5, v8 op_sel:[0,0,1]
	v_pk_mul_f32 v[8:9], v[112:113], s[18:19] op_sel_hi:[1,0]
	v_pk_mul_f32 v[12:13], v[108:109], s[18:19] op_sel_hi:[1,0]
	s_mov_b32 s48, s20
	flat_store_dwordx2 v[6:7], v[10:11] offset:128 nt
	v_pk_mul_f32 v[10:11], v[110:111], s[18:19] op_sel_hi:[1,0]
	v_add_u32_e32 v6, 32, v4
	v_med3_f32 v5, v10, s47, v173
	v_med3_f32 v11, v11, s47, v173
	v_mov_b32_e32 v10, 0
	v_cvt_pk_fp8_f32 v10, v5, v11
	v_med3_f32 v5, v8, s47, v173
	v_med3_f32 v8, v9, s47, v173
	v_mov_b32_e32 v11, 0
	v_cvt_pk_fp8_f32 v10, v5, v8 op_sel:[0,0,1]
	v_med3_f32 v5, v14, s47, v173
	v_med3_f32 v8, v15, s47, v173
	v_cvt_pk_fp8_f32 v11, v5, v8
	v_med3_f32 v5, v12, s47, v173
	v_med3_f32 v8, v13, s47, v173
	v_cvt_pk_fp8_f32 v11, v5, v8 op_sel:[0,0,1]
	v_ashrrev_i32_e32 v7, 31, v6
	v_lshlrev_b64 v[6:7], 10, v[6:7]
	v_lshl_add_u64 v[6:7], s[14:15], 0, v[6:7]
	v_lshl_add_u64 v[6:7], v[6:7], 0, v[2:3]
	flat_store_dwordx2 v[6:7], v[10:11] nt
	v_pk_mul_f32 v[10:11], v[102:103], s[18:19] op_sel_hi:[1,0]
	v_pk_mul_f32 v[8:9], v[104:105], s[18:19] op_sel_hi:[1,0]
	v_med3_f32 v5, v10, s47, v173
	v_med3_f32 v11, v11, s47, v173
	v_mov_b32_e32 v10, 0
	v_cvt_pk_fp8_f32 v10, v5, v11
	v_pk_mul_f32 v[14:15], v[98:99], s[18:19] op_sel_hi:[1,0]
	v_med3_f32 v5, v8, s47, v173
	v_med3_f32 v8, v9, s47, v173
	v_cvt_pk_fp8_f32 v10, v5, v8 op_sel:[0,0,1]
	v_med3_f32 v5, v14, s47, v173
	v_med3_f32 v8, v15, s47, v173
	v_mov_b32_e32 v11, 0
	v_cvt_pk_fp8_f32 v11, v5, v8
	v_pk_mul_f32 v[12:13], v[100:101], s[18:19] op_sel_hi:[1,0]
	v_pk_mul_f32 v[14:15], v[90:91], s[18:19] op_sel_hi:[1,0]
	v_med3_f32 v5, v12, s47, v173
	v_med3_f32 v8, v13, s47, v173
	v_cvt_pk_fp8_f32 v11, v5, v8 op_sel:[0,0,1]
	v_pk_mul_f32 v[8:9], v[96:97], s[18:19] op_sel_hi:[1,0]
	v_pk_mul_f32 v[12:13], v[92:93], s[18:19] op_sel_hi:[1,0]
	s_mov_b32 s28, s22
	flat_store_dwordx2 v[6:7], v[10:11] offset:128 nt
	v_pk_mul_f32 v[10:11], v[94:95], s[18:19] op_sel_hi:[1,0]
	v_add_u32_e32 v6, 48, v4
	v_med3_f32 v5, v10, s47, v173
	v_med3_f32 v11, v11, s47, v173
	v_mov_b32_e32 v10, 0
	v_cvt_pk_fp8_f32 v10, v5, v11
	v_med3_f32 v5, v8, s47, v173
	v_med3_f32 v8, v9, s47, v173
	v_mov_b32_e32 v11, 0
	v_cvt_pk_fp8_f32 v10, v5, v8 op_sel:[0,0,1]
	v_med3_f32 v5, v14, s47, v173
	v_med3_f32 v8, v15, s47, v173
	v_cvt_pk_fp8_f32 v11, v5, v8
	v_med3_f32 v5, v12, s47, v173
	v_med3_f32 v8, v13, s47, v173
	v_cvt_pk_fp8_f32 v11, v5, v8 op_sel:[0,0,1]
	v_ashrrev_i32_e32 v7, 31, v6
	v_lshlrev_b64 v[6:7], 10, v[6:7]
	v_lshl_add_u64 v[6:7], s[14:15], 0, v[6:7]
	v_lshl_add_u64 v[6:7], v[6:7], 0, v[2:3]
	flat_store_dwordx2 v[6:7], v[10:11] nt
	v_pk_mul_f32 v[10:11], v[86:87], s[18:19] op_sel_hi:[1,0]
	v_pk_mul_f32 v[8:9], v[88:89], s[18:19] op_sel_hi:[1,0]
	v_med3_f32 v5, v10, s47, v173
	v_med3_f32 v11, v11, s47, v173
	v_mov_b32_e32 v10, 0
	v_cvt_pk_fp8_f32 v10, v5, v11
	v_pk_mul_f32 v[14:15], v[82:83], s[18:19] op_sel_hi:[1,0]
	v_med3_f32 v5, v8, s47, v173
	v_med3_f32 v8, v9, s47, v173
	v_cvt_pk_fp8_f32 v10, v5, v8 op_sel:[0,0,1]
	v_med3_f32 v5, v14, s47, v173
	v_med3_f32 v8, v15, s47, v173
	v_mov_b32_e32 v11, 0
	v_cvt_pk_fp8_f32 v11, v5, v8
	v_pk_mul_f32 v[12:13], v[84:85], s[18:19] op_sel_hi:[1,0]
	v_pk_mul_f32 v[14:15], v[74:75], s[18:19] op_sel_hi:[1,0]
	v_med3_f32 v5, v12, s47, v173
	v_med3_f32 v8, v13, s47, v173
	v_cvt_pk_fp8_f32 v11, v5, v8 op_sel:[0,0,1]
	v_pk_mul_f32 v[8:9], v[80:81], s[18:19] op_sel_hi:[1,0]
	v_pk_mul_f32 v[12:13], v[76:77], s[18:19] op_sel_hi:[1,0]
	s_mov_b64 s[30:31], s[26:27]
	flat_store_dwordx2 v[6:7], v[10:11] offset:128 nt
	v_pk_mul_f32 v[10:11], v[78:79], s[18:19] op_sel_hi:[1,0]
	v_add_u32_e32 v6, 0x80, v4
	v_med3_f32 v5, v10, s47, v173
	v_med3_f32 v11, v11, s47, v173
	v_mov_b32_e32 v10, 0
	v_cvt_pk_fp8_f32 v10, v5, v11
	v_med3_f32 v5, v8, s47, v173
	v_med3_f32 v8, v9, s47, v173
	v_mov_b32_e32 v11, 0
	v_cvt_pk_fp8_f32 v10, v5, v8 op_sel:[0,0,1]
	v_med3_f32 v5, v14, s47, v173
	v_med3_f32 v8, v15, s47, v173
	v_cvt_pk_fp8_f32 v11, v5, v8
	v_med3_f32 v5, v12, s47, v173
	v_med3_f32 v8, v13, s47, v173
	v_cvt_pk_fp8_f32 v11, v5, v8 op_sel:[0,0,1]
	v_ashrrev_i32_e32 v7, 31, v6
	v_lshlrev_b64 v[6:7], 10, v[6:7]
	v_lshl_add_u64 v[6:7], s[14:15], 0, v[6:7]
	v_lshl_add_u64 v[6:7], v[6:7], 0, v[2:3]
	flat_store_dwordx2 v[6:7], v[10:11] nt
	v_pk_mul_f32 v[10:11], v[70:71], s[18:19] op_sel_hi:[1,0]
	v_pk_mul_f32 v[8:9], v[72:73], s[18:19] op_sel_hi:[1,0]
	v_med3_f32 v5, v10, s47, v173
	v_med3_f32 v11, v11, s47, v173
	v_mov_b32_e32 v10, 0
	v_cvt_pk_fp8_f32 v10, v5, v11
	v_pk_mul_f32 v[14:15], v[66:67], s[18:19] op_sel_hi:[1,0]
	v_med3_f32 v5, v8, s47, v173
	v_med3_f32 v8, v9, s47, v173
	v_cvt_pk_fp8_f32 v10, v5, v8 op_sel:[0,0,1]
	v_med3_f32 v5, v14, s47, v173
	v_med3_f32 v8, v15, s47, v173
	v_mov_b32_e32 v11, 0
	v_cvt_pk_fp8_f32 v11, v5, v8
	v_pk_mul_f32 v[12:13], v[68:69], s[18:19] op_sel_hi:[1,0]
	v_pk_mul_f32 v[14:15], v[58:59], s[18:19] op_sel_hi:[1,0]
	v_med3_f32 v5, v12, s47, v173
	v_med3_f32 v8, v13, s47, v173
	v_cvt_pk_fp8_f32 v11, v5, v8 op_sel:[0,0,1]
	v_pk_mul_f32 v[8:9], v[64:65], s[18:19] op_sel_hi:[1,0]
	v_pk_mul_f32 v[12:13], v[60:61], s[18:19] op_sel_hi:[1,0]
	s_mov_b64 s[34:35], s[24:25]
	flat_store_dwordx2 v[6:7], v[10:11] offset:128 nt
	v_pk_mul_f32 v[10:11], v[62:63], s[18:19] op_sel_hi:[1,0]
	v_add_u32_e32 v6, 0x90, v4
	v_med3_f32 v5, v10, s47, v173
	v_med3_f32 v11, v11, s47, v173
	v_mov_b32_e32 v10, 0
	v_cvt_pk_fp8_f32 v10, v5, v11
	v_med3_f32 v5, v8, s47, v173
	v_med3_f32 v8, v9, s47, v173
	v_mov_b32_e32 v11, 0
	v_cvt_pk_fp8_f32 v10, v5, v8 op_sel:[0,0,1]
	v_med3_f32 v5, v14, s47, v173
	v_med3_f32 v8, v15, s47, v173
	v_cvt_pk_fp8_f32 v11, v5, v8
	v_med3_f32 v5, v12, s47, v173
	v_med3_f32 v8, v13, s47, v173
	v_cvt_pk_fp8_f32 v11, v5, v8 op_sel:[0,0,1]
	v_ashrrev_i32_e32 v7, 31, v6
	v_lshlrev_b64 v[6:7], 10, v[6:7]
	v_lshl_add_u64 v[6:7], s[14:15], 0, v[6:7]
	v_lshl_add_u64 v[6:7], v[6:7], 0, v[2:3]
	flat_store_dwordx2 v[6:7], v[10:11] nt
	v_pk_mul_f32 v[10:11], v[54:55], s[18:19] op_sel_hi:[1,0]
	v_pk_mul_f32 v[8:9], v[56:57], s[18:19] op_sel_hi:[1,0]
	v_med3_f32 v5, v10, s47, v173
	v_med3_f32 v11, v11, s47, v173
	v_mov_b32_e32 v10, 0
	v_cvt_pk_fp8_f32 v10, v5, v11
	v_pk_mul_f32 v[14:15], v[50:51], s[18:19] op_sel_hi:[1,0]
	v_med3_f32 v5, v8, s47, v173
	v_med3_f32 v8, v9, s47, v173
	v_cvt_pk_fp8_f32 v10, v5, v8 op_sel:[0,0,1]
	v_med3_f32 v5, v14, s47, v173
	v_med3_f32 v8, v15, s47, v173
	v_mov_b32_e32 v11, 0
	v_cvt_pk_fp8_f32 v11, v5, v8
	v_pk_mul_f32 v[12:13], v[52:53], s[18:19] op_sel_hi:[1,0]
	v_pk_mul_f32 v[14:15], v[42:43], s[18:19] op_sel_hi:[1,0]
	v_med3_f32 v5, v12, s47, v173
	v_med3_f32 v8, v13, s47, v173
	v_cvt_pk_fp8_f32 v11, v5, v8 op_sel:[0,0,1]
	v_pk_mul_f32 v[8:9], v[48:49], s[18:19] op_sel_hi:[1,0]
	v_pk_mul_f32 v[12:13], v[44:45], s[18:19] op_sel_hi:[1,0]
	flat_store_dwordx2 v[6:7], v[10:11] offset:128 nt
	v_pk_mul_f32 v[10:11], v[46:47], s[18:19] op_sel_hi:[1,0]
	v_add_u32_e32 v6, 0xa0, v4
	v_med3_f32 v5, v10, s47, v173
	v_med3_f32 v11, v11, s47, v173
	v_mov_b32_e32 v10, 0
	v_cvt_pk_fp8_f32 v10, v5, v11
	v_med3_f32 v5, v8, s47, v173
	v_med3_f32 v8, v9, s47, v173
	v_mov_b32_e32 v11, 0
	v_cvt_pk_fp8_f32 v10, v5, v8 op_sel:[0,0,1]
	v_med3_f32 v5, v14, s47, v173
	v_med3_f32 v8, v15, s47, v173
	v_cvt_pk_fp8_f32 v11, v5, v8
	v_med3_f32 v5, v12, s47, v173
	v_med3_f32 v8, v13, s47, v173
	v_cvt_pk_fp8_f32 v11, v5, v8 op_sel:[0,0,1]
	v_ashrrev_i32_e32 v7, 31, v6
	v_lshlrev_b64 v[6:7], 10, v[6:7]
	v_lshl_add_u64 v[6:7], s[14:15], 0, v[6:7]
	v_lshl_add_u64 v[6:7], v[6:7], 0, v[2:3]
	flat_store_dwordx2 v[6:7], v[10:11] nt
	v_pk_mul_f32 v[10:11], v[38:39], s[18:19] op_sel_hi:[1,0]
	v_pk_mul_f32 v[8:9], v[40:41], s[18:19] op_sel_hi:[1,0]
	v_med3_f32 v5, v10, s47, v173
	v_med3_f32 v11, v11, s47, v173
	v_mov_b32_e32 v10, 0
	v_cvt_pk_fp8_f32 v10, v5, v11
	v_pk_mul_f32 v[14:15], v[34:35], s[18:19] op_sel_hi:[1,0]
	v_med3_f32 v5, v8, s47, v173
	v_med3_f32 v8, v9, s47, v173
	v_cvt_pk_fp8_f32 v10, v5, v8 op_sel:[0,0,1]
	v_med3_f32 v5, v14, s47, v173
	v_med3_f32 v8, v15, s47, v173
	v_mov_b32_e32 v11, 0
	v_cvt_pk_fp8_f32 v11, v5, v8
	v_pk_mul_f32 v[12:13], v[36:37], s[18:19] op_sel_hi:[1,0]
	v_add_u32_e32 v4, 0xb0, v4
	v_med3_f32 v5, v12, s47, v173
	v_med3_f32 v8, v13, s47, v173
	v_cvt_pk_fp8_f32 v11, v5, v8 op_sel:[0,0,1]
	v_pk_mul_f32 v[8:9], v[28:29], s[18:19] op_sel_hi:[1,0]
	flat_store_dwordx2 v[6:7], v[10:11] offset:128 nt
	v_pk_mul_f32 v[6:7], v[30:31], s[18:19] op_sel_hi:[1,0]
	v_pk_mul_f32 v[10:11], v[26:27], s[18:19] op_sel_hi:[1,0]
	v_ashrrev_i32_e32 v5, 31, v4
	v_med3_f32 v12, v6, s47, v173
	v_med3_f32 v7, v7, s47, v173
	v_mov_b32_e32 v6, 0
	v_lshlrev_b64 v[4:5], 10, v[4:5]
	v_cvt_pk_fp8_f32 v6, v12, v7
	v_lshl_add_u64 v[4:5], s[14:15], 0, v[4:5]
	v_lshl_add_u64 v[2:3], v[4:5], 0, v[2:3]
	v_pk_mul_f32 v[4:5], v[32:33], s[18:19] op_sel_hi:[1,0]
	v_mov_b32_e32 v7, 0
	v_med3_f32 v4, v4, s47, v173
	v_med3_f32 v5, v5, s47, v173
	v_cvt_pk_fp8_f32 v6, v4, v5 op_sel:[0,0,1]
	v_med3_f32 v4, v10, s47, v173
	v_med3_f32 v5, v11, s47, v173
	v_cvt_pk_fp8_f32 v7, v4, v5
	v_med3_f32 v4, v8, s47, v173
	v_med3_f32 v5, v9, s47, v173
	v_pk_mul_f32 v[10:11], v[18:19], s[18:19] op_sel_hi:[1,0]
	v_cvt_pk_fp8_f32 v7, v4, v5 op_sel:[0,0,1]
	v_pk_mul_f32 v[4:5], v[24:25], s[18:19] op_sel_hi:[1,0]
	v_pk_mul_f32 v[8:9], v[20:21], s[18:19] op_sel_hi:[1,0]
	v_med3_f32 v4, v4, s47, v173
	flat_store_dwordx2 v[2:3], v[6:7] nt
	v_pk_mul_f32 v[6:7], v[22:23], s[18:19] op_sel_hi:[1,0]
	v_med3_f32 v5, v5, s47, v173
	v_med3_f32 v12, v6, s47, v173
	v_med3_f32 v7, v7, s47, v173
	v_mov_b32_e32 v6, 0
	v_cvt_pk_fp8_f32 v6, v12, v7
	v_mov_b32_e32 v7, 0
	v_cvt_pk_fp8_f32 v6, v4, v5 op_sel:[0,0,1]
	v_med3_f32 v4, v10, s47, v173
	v_med3_f32 v5, v11, s47, v173
	v_cvt_pk_fp8_f32 v7, v4, v5
	v_med3_f32 v4, v8, s47, v173
	v_med3_f32 v5, v9, s47, v173
	v_cvt_pk_fp8_f32 v7, v4, v5 op_sel:[0,0,1]
	flat_store_dwordx2 v[2:3], v[6:7] offset:128 nt
	s_cbranch_vccz .LBB0_2101
	s_waitcnt vmcnt(0)
	s_cmpk_gt_u32 s4, 0xff
	s_cbranch_scc1 .LBB0_2112
	s_barrier

.LBB0_2325:
	ds_read_b128 v[130:133], v165
	ds_read_b128 v[134:137], v165 offset:1024
	ds_read_b128 v[154:157], v165 offset:2048
	ds_read_b128 v[158:161], v165 offset:3072
	s_add_u32 s36, s34, 0x100
	s_addc_u32 s37, s35, 0
	s_cmp_eq_u32 s59, 2
	s_cselect_b32 s41, s13, s37
	s_cselect_b32 s40, s12, s36
	s_cselect_b32 s39, s15, s58
	s_cselect_b32 s38, s14, s20
	v_lshl_add_u64 v[202:203], s[34:35], 0, v[148:149]
	s_add_i32 m0, s17, 0xc000
	ds_read_b128 v[170:173], v166
	ds_read_b128 v[174:177], v166 offset:1024
	ds_read_b128 v[178:181], v166 offset:2048
	ds_read_b128 v[182:185], v166 offset:3072
	ds_read_b128 v[186:189], v166 offset:4096
	ds_read_b128 v[190:193], v166 offset:5120
	ds_read_b128 v[194:197], v166 offset:6144
	ds_read_b128 v[198:201], v166 offset:7168
	global_load_lds_dwordx4 v[202:203], off
	v_lshl_add_u64 v[202:203], s[34:35], 0, v[146:147]
	s_add_i32 m0, s17, 0xe000
	s_nop 0
	global_load_lds_dwordx4 v[202:203], off
	s_waitcnt lgkmcnt(8)
	s_waitcnt vmcnt(10)
	s_barrier
	s_waitcnt lgkmcnt(0)
	s_setprio 1
	s_waitcnt lgkmcnt(0)
	v_mfma_f32_16x16x32_bf16 v[126:129], v[130:133], v[170:173], v[126:129]
	v_mfma_f32_16x16x32_bf16 v[122:125], v[154:157], v[170:173], v[122:125]
	v_mfma_f32_16x16x32_bf16 v[114:117], v[130:133], v[178:181], v[114:117]
	v_mfma_f32_16x16x32_bf16 v[106:109], v[154:157], v[178:181], v[106:109]
	v_mfma_f32_16x16x32_bf16 v[98:101], v[130:133], v[186:189], v[98:101]
	v_mfma_f32_16x16x32_bf16 v[90:93], v[154:157], v[186:189], v[90:93]
	v_mfma_f32_16x16x32_bf16 v[82:85], v[130:133], v[194:197], v[82:85]
	v_mfma_f32_16x16x32_bf16 v[74:77], v[154:157], v[194:197], v[74:77]
	v_mfma_f32_16x16x32_bf16 v[126:129], v[134:137], v[174:177], v[126:129]
	v_mfma_f32_16x16x32_bf16 v[122:125], v[158:161], v[174:177], v[122:125]
	v_mfma_f32_16x16x32_bf16 v[114:117], v[134:137], v[182:185], v[114:117]
	v_mfma_f32_16x16x32_bf16 v[106:109], v[158:161], v[182:185], v[106:109]
	v_mfma_f32_16x16x32_bf16 v[98:101], v[134:137], v[190:193], v[98:101]
	v_mfma_f32_16x16x32_bf16 v[90:93], v[158:161], v[190:193], v[90:93]
	v_mfma_f32_16x16x32_bf16 v[82:85], v[134:137], v[198:201], v[82:85]
	v_mfma_f32_16x16x32_bf16 v[74:77], v[158:161], v[198:201], v[74:77]
	s_setprio 0
	s_barrier
	s_add_i32 s0, s49, s8
	v_lshl_add_u64 v[218:219], s[38:39], 0, v[142:143]
	s_mov_b32 m0, s0
	ds_read_b128 v[202:205], v167
	ds_read_b128 v[206:209], v167 offset:1024
	ds_read_b128 v[210:213], v167 offset:2048
	ds_read_b128 v[214:217], v167 offset:3072
	global_load_lds_dwordx4 v[218:219], off
	v_lshl_add_u64 v[220:221], s[38:39], 0, v[138:139]
	s_add_i32 m0, s0, 0x2000
	s_nop 0
	global_load_lds_dwordx4 v[220:221], off
	s_waitcnt vmcnt(10)
	s_barrier
	s_waitcnt lgkmcnt(0)
	s_setprio 1
	s_waitcnt lgkmcnt(0)
	v_mfma_f32_16x16x32_bf16 v[118:121], v[202:205], v[170:173], v[118:121]
	v_mfma_f32_16x16x32_bf16 v[110:113], v[210:213], v[170:173], v[110:113]
	v_mfma_f32_16x16x32_bf16 v[102:105], v[202:205], v[178:181], v[102:105]
	v_mfma_f32_16x16x32_bf16 v[94:97], v[210:213], v[178:181], v[94:97]
	v_mfma_f32_16x16x32_bf16 v[86:89], v[202:205], v[186:189], v[86:89]
	v_mfma_f32_16x16x32_bf16 v[78:81], v[210:213], v[186:189], v[78:81]
	v_mfma_f32_16x16x32_bf16 v[70:73], v[202:205], v[194:197], v[70:73]
	v_mfma_f32_16x16x32_bf16 v[66:69], v[210:213], v[194:197], v[66:69]
	v_mfma_f32_16x16x32_bf16 v[118:121], v[206:209], v[174:177], v[118:121]
	v_mfma_f32_16x16x32_bf16 v[110:113], v[214:217], v[174:177], v[110:113]
	v_mfma_f32_16x16x32_bf16 v[102:105], v[206:209], v[182:185], v[102:105]
	v_mfma_f32_16x16x32_bf16 v[94:97], v[214:217], v[182:185], v[94:97]
	v_mfma_f32_16x16x32_bf16 v[86:89], v[206:209], v[190:193], v[86:89]
	v_mfma_f32_16x16x32_bf16 v[78:81], v[214:217], v[190:193], v[78:81]
	v_mfma_f32_16x16x32_bf16 v[70:73], v[206:209], v[198:201], v[70:73]
	v_mfma_f32_16x16x32_bf16 v[66:69], v[214:217], v[198:201], v[66:69]
	s_setprio 0
	s_mov_b32 m0, s17
	v_lshl_add_u64 v[222:223], s[40:41], 0, v[144:145]
	s_barrier
	ds_read_b128 v[170:173], v166 offset:16384
	ds_read_b128 v[174:177], v166 offset:17408
	ds_read_b128 v[178:181], v166 offset:18432
	ds_read_b128 v[182:185], v166 offset:19456
	ds_read_b128 v[186:189], v166 offset:20480
	ds_read_b128 v[190:193], v166 offset:21504
	ds_read_b128 v[194:197], v166 offset:22528
	ds_read_b128 v[198:201], v166 offset:23552
	global_load_lds_dwordx4 v[222:223], off
	v_lshl_add_u64 v[224:225], s[40:41], 0, v[140:141]
	s_mov_b32 m0, s42
	s_nop 0
	global_load_lds_dwordx4 v[224:225], off
	s_waitcnt vmcnt(10)
	s_barrier
	s_waitcnt lgkmcnt(0)
	s_setprio 1
	s_waitcnt lgkmcnt(0)
	v_mfma_f32_16x16x32_bf16 v[62:65], v[130:133], v[170:173], v[62:65]
	v_mfma_f32_16x16x32_bf16 v[58:61], v[154:157], v[170:173], v[58:61]
	v_mfma_f32_16x16x32_bf16 v[50:53], v[130:133], v[178:181], v[50:53]
	v_mfma_f32_16x16x32_bf16 v[42:45], v[154:157], v[178:181], v[42:45]
	v_mfma_f32_16x16x32_bf16 v[34:37], v[130:133], v[186:189], v[34:37]
	v_mfma_f32_16x16x32_bf16 v[26:29], v[154:157], v[186:189], v[26:29]
	v_mfma_f32_16x16x32_bf16 v[18:21], v[130:133], v[194:197], v[18:21]
	v_mfma_f32_16x16x32_bf16 v[10:13], v[154:157], v[194:197], v[10:13]
	v_mfma_f32_16x16x32_bf16 v[62:65], v[134:137], v[174:177], v[62:65]
	v_mfma_f32_16x16x32_bf16 v[58:61], v[158:161], v[174:177], v[58:61]
	v_mfma_f32_16x16x32_bf16 v[50:53], v[134:137], v[182:185], v[50:53]
	v_mfma_f32_16x16x32_bf16 v[42:45], v[158:161], v[182:185], v[42:45]
	v_mfma_f32_16x16x32_bf16 v[34:37], v[134:137], v[190:193], v[34:37]
	v_mfma_f32_16x16x32_bf16 v[26:29], v[158:161], v[190:193], v[26:29]
	v_mfma_f32_16x16x32_bf16 v[18:21], v[134:137], v[198:201], v[18:21]
	v_mfma_f32_16x16x32_bf16 v[10:13], v[158:161], v[198:201], v[10:13]
	s_setprio 0
	s_barrier
	s_add_u32 s0, s38, 0x18000
	s_addc_u32 s1, s39, 0
	s_add_i32 s34, s50, s8
	v_lshl_add_u64 v[130:131], s[0:1], 0, v[142:143]
	s_mov_b32 m0, s34
	s_nop 0
	global_load_lds_dwordx4 v[130:131], off
	v_lshl_add_u64 v[130:131], s[0:1], 0, v[138:139]
	s_add_i32 m0, s34, 0x2000
	s_nop 0
	global_load_lds_dwordx4 v[130:131], off
	s_waitcnt vmcnt(10)
	s_barrier
	s_setprio 1
	v_mfma_f32_16x16x32_bf16 v[54:57], v[202:205], v[170:173], v[54:57]
	v_mfma_f32_16x16x32_bf16 v[46:49], v[210:213], v[170:173], v[46:49]
	v_mfma_f32_16x16x32_bf16 v[38:41], v[202:205], v[178:181], v[38:41]
	v_mfma_f32_16x16x32_bf16 v[30:33], v[210:213], v[178:181], v[30:33]
	v_mfma_f32_16x16x32_bf16 v[22:25], v[202:205], v[186:189], v[22:25]
	v_mfma_f32_16x16x32_bf16 v[14:17], v[210:213], v[186:189], v[14:17]
	v_mfma_f32_16x16x32_bf16 v[6:9], v[202:205], v[194:197], v[6:9]
	v_mfma_f32_16x16x32_bf16 v[2:5], v[210:213], v[194:197], v[2:5]
	v_mfma_f32_16x16x32_bf16 v[54:57], v[206:209], v[174:177], v[54:57]
	v_mfma_f32_16x16x32_bf16 v[46:49], v[214:217], v[174:177], v[46:49]
	v_mfma_f32_16x16x32_bf16 v[38:41], v[206:209], v[182:185], v[38:41]
	v_mfma_f32_16x16x32_bf16 v[30:33], v[214:217], v[182:185], v[30:33]
	v_mfma_f32_16x16x32_bf16 v[22:25], v[206:209], v[190:193], v[22:25]
	v_mfma_f32_16x16x32_bf16 v[14:17], v[214:217], v[190:193], v[14:17]
	v_mfma_f32_16x16x32_bf16 v[6:9], v[206:209], v[198:201], v[6:9]
	v_mfma_f32_16x16x32_bf16 v[2:5], v[214:217], v[198:201], v[2:5]
	s_setprio 0
	s_add_i32 s34, 0, 0x18000
	v_add_u32_e32 v158, s34, v164
	s_barrier
	ds_read_b128 v[130:133], v158
	ds_read_b128 v[134:137], v158 offset:1024
	ds_read_b128 v[154:157], v158 offset:2048
	ds_read_b128 v[158:161], v158 offset:3072
	s_add_u32 s0, s40, 0x18000
	s_addc_u32 s1, s41, 0
	s_mov_b32 m0, s43
	v_lshl_add_u64 v[202:203], s[0:1], 0, v[144:145]
	ds_read_b128 v[170:173], v166 offset:32768
	ds_read_b128 v[174:177], v166 offset:33792
	ds_read_b128 v[178:181], v166 offset:34816
	ds_read_b128 v[182:185], v166 offset:35840
	ds_read_b128 v[186:189], v166 offset:36864
	ds_read_b128 v[190:193], v166 offset:37888
	ds_read_b128 v[194:197], v166 offset:38912
	ds_read_b128 v[198:201], v166 offset:39936
	global_load_lds_dwordx4 v[202:203], off
	v_lshl_add_u64 v[202:203], s[0:1], 0, v[140:141]
	s_mov_b32 m0, s44
	s_nop 0
	global_load_lds_dwordx4 v[202:203], off
	s_waitcnt lgkmcnt(8)
	s_waitcnt vmcnt(10)
	s_barrier
	s_waitcnt lgkmcnt(0)
	s_setprio 1
	s_waitcnt lgkmcnt(0)
	v_mfma_f32_16x16x32_bf16 v[126:129], v[130:133], v[170:173], v[126:129]
	v_mfma_f32_16x16x32_bf16 v[122:125], v[154:157], v[170:173], v[122:125]
	v_mfma_f32_16x16x32_bf16 v[114:117], v[130:133], v[178:181], v[114:117]
	v_mfma_f32_16x16x32_bf16 v[106:109], v[154:157], v[178:181], v[106:109]
	v_mfma_f32_16x16x32_bf16 v[98:101], v[130:133], v[186:189], v[98:101]
	v_mfma_f32_16x16x32_bf16 v[90:93], v[154:157], v[186:189], v[90:93]
	v_mfma_f32_16x16x32_bf16 v[82:85], v[130:133], v[194:197], v[82:85]
	v_mfma_f32_16x16x32_bf16 v[74:77], v[154:157], v[194:197], v[74:77]
	v_mfma_f32_16x16x32_bf16 v[126:129], v[134:137], v[174:177], v[126:129]
	v_mfma_f32_16x16x32_bf16 v[122:125], v[158:161], v[174:177], v[122:125]
	v_mfma_f32_16x16x32_bf16 v[114:117], v[134:137], v[182:185], v[114:117]
	v_mfma_f32_16x16x32_bf16 v[106:109], v[158:161], v[182:185], v[106:109]
	v_mfma_f32_16x16x32_bf16 v[98:101], v[134:137], v[190:193], v[98:101]
	v_mfma_f32_16x16x32_bf16 v[90:93], v[158:161], v[190:193], v[90:93]
	v_mfma_f32_16x16x32_bf16 v[82:85], v[134:137], v[198:201], v[82:85]
	v_mfma_f32_16x16x32_bf16 v[74:77], v[158:161], v[198:201], v[74:77]
	s_setprio 0
	s_barrier
	s_add_i32 s35, 0, 0x1c000
	s_add_i32 s0, s34, s8
	v_add_u32_e32 v169, s35, v164
	v_lshl_add_u64 v[218:219], v[218:219], 0, s[30:31]
	s_mov_b32 m0, s0
	ds_read_b128 v[202:205], v169
	ds_read_b128 v[206:209], v169 offset:1024
	ds_read_b128 v[210:213], v169 offset:2048
	ds_read_b128 v[214:217], v169 offset:3072
	global_load_lds_dwordx4 v[218:219], off
	v_lshl_add_u64 v[218:219], v[220:221], 0, s[30:31]
	s_add_i32 m0, s0, 0x2000
	s_nop 0
	global_load_lds_dwordx4 v[218:219], off
	s_waitcnt vmcnt(10)
	s_barrier
	s_waitcnt lgkmcnt(0)
	s_setprio 1
	s_waitcnt lgkmcnt(0)
	v_mfma_f32_16x16x32_bf16 v[118:121], v[202:205], v[170:173], v[118:121]
	v_mfma_f32_16x16x32_bf16 v[110:113], v[210:213], v[170:173], v[110:113]
	v_mfma_f32_16x16x32_bf16 v[102:105], v[202:205], v[178:181], v[102:105]
	v_mfma_f32_16x16x32_bf16 v[94:97], v[210:213], v[178:181], v[94:97]
	v_mfma_f32_16x16x32_bf16 v[86:89], v[202:205], v[186:189], v[86:89]
	v_mfma_f32_16x16x32_bf16 v[78:81], v[210:213], v[186:189], v[78:81]
	v_mfma_f32_16x16x32_bf16 v[70:73], v[202:205], v[194:197], v[70:73]
	v_mfma_f32_16x16x32_bf16 v[66:69], v[210:213], v[194:197], v[66:69]
	v_mfma_f32_16x16x32_bf16 v[118:121], v[206:209], v[174:177], v[118:121]
	v_mfma_f32_16x16x32_bf16 v[110:113], v[214:217], v[174:177], v[110:113]
	v_mfma_f32_16x16x32_bf16 v[102:105], v[206:209], v[182:185], v[102:105]
	v_mfma_f32_16x16x32_bf16 v[94:97], v[214:217], v[182:185], v[94:97]
	v_mfma_f32_16x16x32_bf16 v[86:89], v[206:209], v[190:193], v[86:89]
	v_mfma_f32_16x16x32_bf16 v[78:81], v[214:217], v[190:193], v[78:81]
	v_mfma_f32_16x16x32_bf16 v[70:73], v[206:209], v[198:201], v[70:73]
	v_mfma_f32_16x16x32_bf16 v[66:69], v[214:217], v[198:201], v[66:69]
	s_setprio 0
	s_mov_b32 m0, s46
	v_lshl_add_u64 v[218:219], v[222:223], 0, s[30:31]
	s_barrier
	ds_read_b128 v[170:173], v166 offset:49152
	ds_read_b128 v[174:177], v166 offset:50176
	ds_read_b128 v[178:181], v166 offset:51200
	ds_read_b128 v[182:185], v166 offset:52224
	ds_read_b128 v[186:189], v166 offset:53248
	ds_read_b128 v[190:193], v166 offset:54272
	ds_read_b128 v[194:197], v166 offset:55296
	ds_read_b128 v[198:201], v166 offset:56320
	global_load_lds_dwordx4 v[218:219], off
	v_lshl_add_u64 v[218:219], v[224:225], 0, s[30:31]
	s_mov_b32 m0, s47
	s_nop 0
	global_load_lds_dwordx4 v[218:219], off
	s_waitcnt vmcnt(10)
	s_barrier
	s_waitcnt lgkmcnt(0)
	s_setprio 1
	s_waitcnt lgkmcnt(0)
	v_mfma_f32_16x16x32_bf16 v[62:65], v[130:133], v[170:173], v[62:65]
	v_mfma_f32_16x16x32_bf16 v[58:61], v[154:157], v[170:173], v[58:61]
	v_mfma_f32_16x16x32_bf16 v[50:53], v[130:133], v[178:181], v[50:53]
	v_mfma_f32_16x16x32_bf16 v[42:45], v[154:157], v[178:181], v[42:45]
	v_mfma_f32_16x16x32_bf16 v[34:37], v[130:133], v[186:189], v[34:37]
	v_mfma_f32_16x16x32_bf16 v[26:29], v[154:157], v[186:189], v[26:29]
	v_mfma_f32_16x16x32_bf16 v[18:21], v[130:133], v[194:197], v[18:21]
	v_mfma_f32_16x16x32_bf16 v[10:13], v[154:157], v[194:197], v[10:13]
	v_mfma_f32_16x16x32_bf16 v[62:65], v[134:137], v[174:177], v[62:65]
	v_mfma_f32_16x16x32_bf16 v[58:61], v[158:161], v[174:177], v[58:61]
	v_mfma_f32_16x16x32_bf16 v[50:53], v[134:137], v[182:185], v[50:53]
	v_mfma_f32_16x16x32_bf16 v[42:45], v[158:161], v[182:185], v[42:45]
	v_mfma_f32_16x16x32_bf16 v[34:37], v[134:137], v[190:193], v[34:37]
	v_mfma_f32_16x16x32_bf16 v[26:29], v[158:161], v[190:193], v[26:29]
	v_mfma_f32_16x16x32_bf16 v[18:21], v[134:137], v[198:201], v[18:21]
	v_mfma_f32_16x16x32_bf16 v[10:13], v[158:161], v[198:201], v[10:13]
	s_setprio 0
	s_barrier
	s_add_u32 s0, s38, 0x18080
	s_addc_u32 s1, s39, 0
	s_add_i32 s34, s35, s8
	v_lshl_add_u64 v[130:131], s[0:1], 0, v[142:143]
	s_mov_b32 m0, s34
	s_nop 0
	global_load_lds_dwordx4 v[130:131], off
	v_lshl_add_u64 v[130:131], s[0:1], 0, v[138:139]
	s_add_i32 m0, s34, 0x2000
	s_nop 0
	global_load_lds_dwordx4 v[130:131], off
	s_waitcnt vmcnt(10)
	s_barrier
	s_setprio 1
	v_mfma_f32_16x16x32_bf16 v[54:57], v[202:205], v[170:173], v[54:57]
	v_mfma_f32_16x16x32_bf16 v[46:49], v[210:213], v[170:173], v[46:49]
	v_mfma_f32_16x16x32_bf16 v[38:41], v[202:205], v[178:181], v[38:41]
	v_mfma_f32_16x16x32_bf16 v[30:33], v[210:213], v[178:181], v[30:33]
	v_mfma_f32_16x16x32_bf16 v[22:25], v[202:205], v[186:189], v[22:25]
	v_mfma_f32_16x16x32_bf16 v[14:17], v[210:213], v[186:189], v[14:17]
	v_mfma_f32_16x16x32_bf16 v[6:9], v[202:205], v[194:197], v[6:9]
	v_mfma_f32_16x16x32_bf16 v[2:5], v[210:213], v[194:197], v[2:5]
	v_mfma_f32_16x16x32_bf16 v[54:57], v[206:209], v[174:177], v[54:57]
	v_mfma_f32_16x16x32_bf16 v[46:49], v[214:217], v[174:177], v[46:49]
	v_mfma_f32_16x16x32_bf16 v[38:41], v[206:209], v[182:185], v[38:41]
	v_mfma_f32_16x16x32_bf16 v[30:33], v[214:217], v[182:185], v[30:33]
	v_mfma_f32_16x16x32_bf16 v[22:25], v[206:209], v[190:193], v[22:25]
	v_mfma_f32_16x16x32_bf16 v[14:17], v[214:217], v[190:193], v[14:17]
	v_mfma_f32_16x16x32_bf16 v[6:9], v[206:209], v[198:201], v[6:9]
	v_mfma_f32_16x16x32_bf16 v[2:5], v[214:217], v[198:201], v[2:5]
	s_setprio 0
	s_add_i32 s59, s59, 2
	s_add_u32 s20, s20, 0x100
	s_addc_u32 s58, s58, 0
	s_cmp_gt_u32 s59, 3
	s_mov_b64 s[34:35], s[36:37]
	s_barrier
	s_cbranch_scc0 .LBB0_2325
	v_mov_b32_e32 v169, v162
	v_mov_b32_e32 v130, v163
	s_mov_b64 s[34:35], -1
	v_lshlrev_b32_e32 v154, 3, v130
	s_cmp_gt_i32 s57, 3
	v_ashrrev_i32_e32 v155, 31, v154
	s_cbranch_scc0 .LBB0_2328
	s_lshl_b32 s0, s56, 8
	s_add_i32 s0, s0, s45
	v_add_u32_e32 v248, s0, v169
	v_mov_b32_e32 v136, v248
	v_lshlrev_b64 v[132:133], 2, v[154:155]
	v_ashrrev_i32_e32 v137, 31, v136
	v_lshl_add_u64 v[130:131], s[26:27], 0, v[132:133]
	v_lshlrev_b64 v[134:135], 7, v[136:137]
	v_lshl_add_u64 v[156:157], v[130:131], 0, v[134:135]
	v_lshl_add_u64 v[132:133], s[24:25], 0, v[132:133]
	flat_load_dwordx4 v[170:173], v[156:157]
	flat_load_dwordx4 v[174:177], v[156:157] offset:16
	v_lshl_add_u64 v[134:135], v[132:133], 0, v[134:135]
	flat_load_dwordx4 v[178:181], v[134:135]
	flat_load_dwordx4 v[182:185], v[134:135] offset:16
	v_add_u32_e32 v160, 16, v136
	v_ashrrev_i32_e32 v161, 31, v160
	v_lshlrev_b64 v[134:135], 7, v[160:161]
	v_lshl_add_u64 v[156:157], v[130:131], 0, v[134:135]
	flat_load_dwordx4 v[186:189], v[156:157]
	flat_load_dwordx4 v[194:197], v[156:157] offset:16
	v_lshl_add_u64 v[134:135], v[132:133], 0, v[134:135]
	flat_load_dwordx4 v[190:193], v[134:135]
	flat_load_dwordx4 v[198:201], v[134:135] offset:16
	v_add_u32_e32 v238, 32, v136
	v_add_u32_e32 v134, 48, v136
	v_ashrrev_i32_e32 v239, 31, v238
	v_ashrrev_i32_e32 v135, 31, v134
	v_lshlrev_b64 v[202:203], 7, v[238:239]
	v_lshlrev_b64 v[204:205], 7, v[134:135]
	v_lshl_add_u64 v[206:207], v[132:133], 0, v[202:203]
	v_lshl_add_u64 v[214:215], v[130:131], 0, v[202:203]
	v_lshl_add_u64 v[222:223], v[132:133], 0, v[204:205]
	v_lshl_add_u64 v[230:231], v[130:131], 0, v[204:205]
	flat_load_dwordx4 v[202:205], v[206:207]
	s_nop 0
	flat_load_dwordx4 v[206:209], v[206:207] offset:16
	s_nop 0
	flat_load_dwordx4 v[210:213], v[214:215]
	s_nop 0
	flat_load_dwordx4 v[214:217], v[214:215] offset:16
	s_nop 0
	flat_load_dwordx4 v[218:221], v[222:223]
	s_nop 0
	flat_load_dwordx4 v[222:225], v[222:223] offset:16
	s_nop 0
	flat_load_dwordx4 v[226:229], v[230:231]
	s_nop 0
	flat_load_dwordx4 v[230:233], v[230:231] offset:16
	v_mov_b32_e32 v234, 0
	v_mov_b32_e32 v235, 0
	v_mov_b32_e32 v236, 0
	v_mov_b32_e32 v237, 0
	s_lshl_b32 s0, s57, 2
	s_add_i32 s0, s48, s0
	v_mov_b64_e32 v[156:157], s[22:23]
	s_mul_i32 s20, s0, 0xc0
	v_lshl_add_u64 v[158:159], s[20:21], 0, v[154:155]
	v_mad_i64_i32 v[136:137], s[0:1], v136, s52, v[156:157]
	v_lshl_add_u64 v[136:137], v[136:137], 0, v[158:159]
	s_mov_b64 s[34:35], 0
	s_waitcnt vmcnt(0) lgkmcnt(0)
	v_pk_mul_f32 v[240:241], v[120:121], v[172:173]
	v_pk_mul_f32 v[242:243], v[118:119], v[170:171]
	v_pk_mul_f32 v[172:173], v[128:129], v[172:173]
	v_pk_mul_f32 v[246:247], v[110:111], v[174:175]
	v_pk_mul_f32 v[170:171], v[126:127], v[170:171]
	v_pk_mul_f32 v[174:175], v[122:123], v[174:175]
	v_pk_fma_f32 v[240:241], v[128:129], v[180:181], v[240:241] neg_lo:[0,0,1] neg_hi:[0,0,1]
	v_pk_fma_f32 v[242:243], v[126:127], v[178:179], v[242:243] neg_lo:[0,0,1] neg_hi:[0,0,1]
	v_pk_fma_f32 v[172:173], v[120:121], v[180:181], v[172:173]
	v_pk_fma_f32 v[180:181], v[122:123], v[182:183], v[246:247] neg_lo:[0,0,1] neg_hi:[0,0,1]
	v_pk_fma_f32 v[170:171], v[118:119], v[178:179], v[170:171]
	v_pk_fma_f32 v[174:175], v[110:111], v[182:183], v[174:175]
	v_med3_f32 v135, v242, s51, v168
	v_med3_f32 v161, v243, s51, v168
	v_med3_f32 v180, v180, s51, v168
	v_med3_f32 v181, v181, s51, v168
	v_med3_f32 v170, v170, s51, v168
	v_med3_f32 v171, v171, s51, v168
	v_med3_f32 v174, v174, s51, v168
	v_med3_f32 v175, v175, s51, v168
	v_cvt_pk_fp8_f32 v234, v135, v161
	v_cvt_pk_fp8_f32 v235, v180, v181
	v_pk_mul_f32 v[244:245], v[112:113], v[176:177]
	v_cvt_pk_fp8_f32 v236, v170, v171
	v_cvt_pk_fp8_f32 v237, v174, v175
	v_pk_mul_f32 v[176:177], v[124:125], v[176:177]
	v_pk_fma_f32 v[178:179], v[124:125], v[184:185], v[244:245] neg_lo:[0,0,1] neg_hi:[0,0,1]
	v_pk_fma_f32 v[176:177], v[112:113], v[184:185], v[176:177]
	v_med3_f32 v184, v240, s51, v168
	v_med3_f32 v185, v241, s51, v168
	v_med3_f32 v178, v178, s51, v168
	v_med3_f32 v179, v179, s51, v168
	v_med3_f32 v172, v172, s51, v168
	v_med3_f32 v173, v173, s51, v168
	v_med3_f32 v176, v176, s51, v168
	v_med3_f32 v177, v177, s51, v168
	v_cvt_pk_fp8_f32 v234, v184, v185 op_sel:[0,0,1]
	v_cvt_pk_fp8_f32 v235, v178, v179 op_sel:[0,0,1]
	v_cvt_pk_fp8_f32 v236, v172, v173 op_sel:[0,0,1]
	v_cvt_pk_fp8_f32 v237, v176, v177 op_sel:[0,0,1]
	v_pk_mul_f32 v[170:171], v[102:103], v[186:187]
	v_pk_mul_f32 v[182:183], v[104:105], v[188:189]
	flat_store_dwordx2 v[136:137], v[234:235] offset:128 nt
	flat_store_dwordx2 v[136:137], v[236:237] offset:160 nt
	v_pk_fma_f32 v[136:137], v[114:115], v[190:191], v[170:171] neg_lo:[0,0,1] neg_hi:[0,0,1]
	v_pk_mul_f32 v[178:179], v[94:95], v[194:195]
	v_pk_fma_f32 v[172:173], v[116:117], v[192:193], v[182:183] neg_lo:[0,0,1] neg_hi:[0,0,1]
	v_pk_fma_f32 v[178:179], v[106:107], v[198:199], v[178:179] neg_lo:[0,0,1] neg_hi:[0,0,1]
	v_med3_f32 v135, v136, s51, v168
	v_med3_f32 v137, v137, s51, v168
	v_mov_b32_e32 v136, 0
	v_cvt_pk_fp8_f32 v136, v135, v137
	v_med3_f32 v135, v172, s51, v168
	v_med3_f32 v161, v173, s51, v168
	v_med3_f32 v172, v178, s51, v168
	v_med3_f32 v173, v179, s51, v168
	v_mov_b32_e32 v137, 0
	v_cvt_pk_fp8_f32 v137, v172, v173
	v_pk_mul_f32 v[176:177], v[96:97], v[196:197]
	v_pk_mul_f32 v[174:175], v[114:115], v[186:187]
	v_pk_fma_f32 v[176:177], v[108:109], v[200:201], v[176:177] neg_lo:[0,0,1] neg_hi:[0,0,1]
	v_pk_mul_f32 v[170:171], v[116:117], v[188:189]
	v_pk_fma_f32 v[174:175], v[102:103], v[190:191], v[174:175]
	v_pk_mul_f32 v[182:183], v[106:107], v[194:195]
	v_cvt_pk_fp8_f32 v136, v135, v161 op_sel:[0,0,1]
	v_med3_f32 v135, v176, s51, v168
	v_med3_f32 v161, v177, s51, v168
	v_pk_fma_f32 v[170:171], v[104:105], v[192:193], v[170:171]
	v_pk_fma_f32 v[182:183], v[94:95], v[198:199], v[182:183]
	v_cvt_pk_fp8_f32 v137, v135, v161 op_sel:[0,0,1]
	v_med3_f32 v135, v174, s51, v168
	v_med3_f32 v161, v175, s51, v168
	v_mov_b32_e32 v172, 0
	v_cvt_pk_fp8_f32 v172, v135, v161
	v_med3_f32 v135, v170, s51, v168
	v_med3_f32 v161, v171, s51, v168
	v_med3_f32 v170, v182, s51, v168
	v_med3_f32 v171, v183, s51, v168
	v_mov_b32_e32 v173, 0
	v_cvt_pk_fp8_f32 v173, v170, v171
	v_pk_mul_f32 v[180:181], v[108:109], v[196:197]
	v_cvt_pk_fp8_f32 v172, v135, v161 op_sel:[0,0,1]
	v_pk_fma_f32 v[180:181], v[96:97], v[200:201], v[180:181]
	v_pk_mul_f32 v[176:177], v[78:79], v[214:215]
	v_med3_f32 v135, v180, s51, v168
	v_med3_f32 v161, v181, s51, v168
	v_cvt_pk_fp8_f32 v173, v135, v161 op_sel:[0,0,1]
	v_mad_i64_i32 v[160:161], s[0:1], v160, s52, v[156:157]
	v_lshl_add_u64 v[160:161], v[160:161], 0, v[158:159]
	flat_store_dwordx2 v[160:161], v[136:137] offset:128 nt
	flat_store_dwordx2 v[160:161], v[172:173] offset:160 nt
	v_pk_mul_f32 v[160:161], v[86:87], v[210:211]
	v_pk_mul_f32 v[136:137], v[88:89], v[212:213]
	v_pk_fma_f32 v[160:161], v[98:99], v[202:203], v[160:161] neg_lo:[0,0,1] neg_hi:[0,0,1]
	v_pk_fma_f32 v[136:137], v[100:101], v[204:205], v[136:137] neg_lo:[0,0,1] neg_hi:[0,0,1]
	v_pk_fma_f32 v[176:177], v[90:91], v[206:207], v[176:177] neg_lo:[0,0,1] neg_hi:[0,0,1]
	v_med3_f32 v135, v160, s51, v168
	v_med3_f32 v161, v161, s51, v168
	v_mov_b32_e32 v160, 0
	v_cvt_pk_fp8_f32 v160, v135, v161
	v_med3_f32 v135, v136, s51, v168
	v_med3_f32 v136, v137, s51, v168
	v_med3_f32 v137, v176, s51, v168
	v_med3_f32 v176, v177, s51, v168
	v_mov_b32_e32 v161, 0
	v_cvt_pk_fp8_f32 v161, v137, v176
	v_pk_mul_f32 v[174:175], v[80:81], v[216:217]
	v_pk_mul_f32 v[172:173], v[98:99], v[210:211]
	v_pk_fma_f32 v[174:175], v[92:93], v[208:209], v[174:175] neg_lo:[0,0,1] neg_hi:[0,0,1]
	v_pk_mul_f32 v[170:171], v[100:101], v[212:213]
	v_pk_fma_f32 v[172:173], v[86:87], v[202:203], v[172:173]
	v_pk_mul_f32 v[180:181], v[90:91], v[214:215]
	v_cvt_pk_fp8_f32 v160, v135, v136 op_sel:[0,0,1]
	v_med3_f32 v135, v174, s51, v168
	v_med3_f32 v136, v175, s51, v168
	v_pk_fma_f32 v[170:171], v[88:89], v[204:205], v[170:171]
	v_pk_fma_f32 v[180:181], v[78:79], v[206:207], v[180:181]
	v_cvt_pk_fp8_f32 v161, v135, v136 op_sel:[0,0,1]
	v_med3_f32 v135, v172, s51, v168
	v_med3_f32 v137, v173, s51, v168
	v_mov_b32_e32 v136, 0
	v_cvt_pk_fp8_f32 v136, v135, v137
	v_med3_f32 v135, v170, s51, v168
	v_med3_f32 v170, v171, s51, v168
	v_med3_f32 v171, v180, s51, v168
	v_med3_f32 v172, v181, s51, v168
	v_mov_b32_e32 v137, 0
	v_cvt_pk_fp8_f32 v137, v171, v172
	v_pk_mul_f32 v[178:179], v[92:93], v[216:217]
	v_cvt_pk_fp8_f32 v136, v135, v170 op_sel:[0,0,1]
	v_pk_fma_f32 v[178:179], v[80:81], v[208:209], v[178:179]
	v_pk_mul_f32 v[176:177], v[66:67], v[230:231]
	v_med3_f32 v135, v178, s51, v168
	v_med3_f32 v170, v179, s51, v168
	v_cvt_pk_fp8_f32 v137, v135, v170 op_sel:[0,0,1]
	v_mad_i64_i32 v[170:171], s[0:1], v238, s52, v[156:157]
	v_lshl_add_u64 v[170:171], v[170:171], 0, v[158:159]
	flat_store_dwordx2 v[170:171], v[160:161] offset:128 nt
	flat_store_dwordx2 v[170:171], v[136:137] offset:160 nt
	v_pk_mul_f32 v[160:161], v[70:71], v[226:227]
	v_pk_mul_f32 v[136:137], v[72:73], v[228:229]
	v_pk_fma_f32 v[160:161], v[82:83], v[218:219], v[160:161] neg_lo:[0,0,1] neg_hi:[0,0,1]
	v_pk_fma_f32 v[136:137], v[84:85], v[220:221], v[136:137] neg_lo:[0,0,1] neg_hi:[0,0,1]
	v_pk_fma_f32 v[176:177], v[74:75], v[222:223], v[176:177] neg_lo:[0,0,1] neg_hi:[0,0,1]
	v_med3_f32 v135, v160, s51, v168
	v_med3_f32 v161, v161, s51, v168
	v_mov_b32_e32 v160, 0
	v_cvt_pk_fp8_f32 v160, v135, v161
	v_med3_f32 v135, v136, s51, v168
	v_med3_f32 v136, v137, s51, v168
	v_med3_f32 v137, v176, s51, v168
	v_med3_f32 v176, v177, s51, v168
	v_mov_b32_e32 v161, 0
	v_cvt_pk_fp8_f32 v161, v137, v176
	v_pk_mul_f32 v[174:175], v[68:69], v[232:233]
	v_pk_mul_f32 v[172:173], v[82:83], v[226:227]
	v_pk_fma_f32 v[174:175], v[76:77], v[224:225], v[174:175] neg_lo:[0,0,1] neg_hi:[0,0,1]
	v_pk_mul_f32 v[170:171], v[84:85], v[228:229]
	v_pk_fma_f32 v[172:173], v[70:71], v[218:219], v[172:173]
	v_pk_mul_f32 v[180:181], v[74:75], v[230:231]
	v_cvt_pk_fp8_f32 v160, v135, v136 op_sel:[0,0,1]
	v_med3_f32 v135, v174, s51, v168
	v_med3_f32 v136, v175, s51, v168
	v_pk_fma_f32 v[170:171], v[72:73], v[220:221], v[170:171]
	v_pk_fma_f32 v[180:181], v[66:67], v[222:223], v[180:181]
	v_cvt_pk_fp8_f32 v161, v135, v136 op_sel:[0,0,1]
	v_med3_f32 v135, v172, s51, v168
	v_med3_f32 v137, v173, s51, v168
	v_mov_b32_e32 v136, 0
	v_cvt_pk_fp8_f32 v136, v135, v137
	v_med3_f32 v135, v170, s51, v168
	v_med3_f32 v170, v171, s51, v168
	v_med3_f32 v171, v180, s51, v168
	v_med3_f32 v172, v181, s51, v168
	v_mov_b32_e32 v137, 0
	v_cvt_pk_fp8_f32 v137, v171, v172
	v_pk_mul_f32 v[178:179], v[76:77], v[232:233]
	v_cvt_pk_fp8_f32 v136, v135, v170 op_sel:[0,0,1]
	v_pk_fma_f32 v[178:179], v[68:69], v[224:225], v[178:179]
	v_add_u32_e32 v226, 0x80, v248
	v_med3_f32 v135, v178, s51, v168
	v_med3_f32 v170, v179, s51, v168
	v_cvt_pk_fp8_f32 v137, v135, v170 op_sel:[0,0,1]
	v_mad_i64_i32 v[134:135], s[0:1], v134, s52, v[156:157]
	v_lshl_add_u64 v[134:135], v[134:135], 0, v[158:159]
	flat_store_dwordx2 v[134:135], v[160:161] offset:128 nt
	flat_store_dwordx2 v[134:135], v[136:137] offset:160 nt
	s_nop 0
	v_ashrrev_i32_e32 v227, 31, v226
	v_lshlrev_b64 v[134:135], 7, v[226:227]
	v_lshl_add_u64 v[136:137], v[130:131], 0, v[134:135]
	flat_load_dwordx4 v[170:173], v[136:137]
	v_lshl_add_u64 v[134:135], v[132:133], 0, v[134:135]
	flat_load_dwordx4 v[174:177], v[134:135]
	flat_load_dwordx4 v[178:181], v[136:137] offset:16
	flat_load_dwordx4 v[182:185], v[134:135] offset:16
	v_add_u32_e32 v228, 16, v226
	v_ashrrev_i32_e32 v229, 31, v228
	v_lshlrev_b64 v[134:135], 7, v[228:229]
	v_lshl_add_u64 v[136:137], v[130:131], 0, v[134:135]
	flat_load_dwordx4 v[186:189], v[136:137]
	v_lshl_add_u64 v[134:135], v[132:133], 0, v[134:135]
	flat_load_dwordx4 v[190:193], v[134:135]
	flat_load_dwordx4 v[194:197], v[136:137] offset:16
	flat_load_dwordx4 v[198:201], v[134:135] offset:16
	v_add_u32_e32 v230, 32, v226
	v_ashrrev_i32_e32 v231, 31, v230
	v_lshlrev_b64 v[134:135], 7, v[230:231]
	v_lshl_add_u64 v[136:137], v[132:133], 0, v[134:135]
	v_lshl_add_u64 v[134:135], v[130:131], 0, v[134:135]
	flat_load_dwordx4 v[202:205], v[136:137]
	flat_load_dwordx4 v[206:209], v[136:137] offset:16
	flat_load_dwordx4 v[210:213], v[134:135]
	flat_load_dwordx4 v[214:217], v[134:135] offset:16
	v_add_u32_e32 v160, 48, v226
	v_ashrrev_i32_e32 v161, 31, v160
	v_lshlrev_b64 v[134:135], 7, v[160:161]
	v_lshl_add_u64 v[132:133], v[132:133], 0, v[134:135]
	v_lshl_add_u64 v[134:135], v[130:131], 0, v[134:135]
	flat_load_dwordx4 v[218:221], v[132:133]
	s_nop 0
	flat_load_dwordx4 v[130:133], v[132:133] offset:16
	s_nop 0
	flat_load_dwordx4 v[222:225], v[134:135]
	s_nop 0
	flat_load_dwordx4 v[134:137], v[134:135] offset:16
	s_waitcnt vmcnt(0) lgkmcnt(0)
	v_pk_mul_f32 v[232:233], v[56:57], v[172:173]
	v_pk_mul_f32 v[234:235], v[54:55], v[170:171]
	v_pk_mul_f32 v[172:173], v[64:65], v[172:173]
	v_pk_fma_f32 v[232:233], v[64:65], v[176:177], v[232:233] neg_lo:[0,0,1] neg_hi:[0,0,1]
	v_pk_fma_f32 v[234:235], v[62:63], v[174:175], v[234:235] neg_lo:[0,0,1] neg_hi:[0,0,1]
	v_pk_fma_f32 v[172:173], v[56:57], v[176:177], v[172:173]
	v_pk_mul_f32 v[176:177], v[46:47], v[178:179]
	v_pk_mul_f32 v[178:179], v[58:59], v[178:179]
	v_pk_fma_f32 v[176:177], v[58:59], v[182:183], v[176:177] neg_lo:[0,0,1] neg_hi:[0,0,1]
	v_pk_fma_f32 v[178:179], v[46:47], v[182:183], v[178:179]
	v_med3_f32 v161, v234, s51, v168
	v_med3_f32 v183, v235, s51, v168
	v_mov_b32_e32 v182, 0
	v_cvt_pk_fp8_f32 v182, v161, v183
	v_med3_f32 v176, v176, s51, v168
	v_med3_f32 v177, v177, s51, v168
	v_mov_b32_e32 v183, 0
	v_pk_mul_f32 v[170:171], v[62:63], v[170:171]
	v_cvt_pk_fp8_f32 v183, v176, v177
	v_pk_fma_f32 v[170:171], v[54:55], v[174:175], v[170:171]
	v_pk_mul_f32 v[174:175], v[48:49], v[180:181]
	v_pk_mul_f32 v[180:181], v[60:61], v[180:181]
	v_pk_fma_f32 v[174:175], v[60:61], v[184:185], v[174:175] neg_lo:[0,0,1] neg_hi:[0,0,1]
	v_pk_fma_f32 v[180:181], v[48:49], v[184:185], v[180:181]
	v_med3_f32 v161, v232, s51, v168
	v_med3_f32 v184, v233, s51, v168
	v_cvt_pk_fp8_f32 v182, v161, v184 op_sel:[0,0,1]
	v_med3_f32 v161, v174, s51, v168
	v_med3_f32 v174, v175, s51, v168
	v_cvt_pk_fp8_f32 v183, v161, v174 op_sel:[0,0,1]
	v_med3_f32 v161, v170, s51, v168
	v_med3_f32 v171, v171, s51, v168
	v_mov_b32_e32 v170, 0
	v_cvt_pk_fp8_f32 v170, v161, v171
	v_med3_f32 v161, v172, s51, v168
	v_med3_f32 v172, v173, s51, v168
	v_med3_f32 v173, v178, s51, v168
	v_med3_f32 v174, v179, s51, v168
	v_mov_b32_e32 v171, 0
	v_cvt_pk_fp8_f32 v171, v173, v174
	v_cvt_pk_fp8_f32 v170, v161, v172 op_sel:[0,0,1]
	v_med3_f32 v161, v180, s51, v168
	v_med3_f32 v172, v181, s51, v168
	v_cvt_pk_fp8_f32 v171, v161, v172 op_sel:[0,0,1]
	v_mad_i64_i32 v[172:173], s[0:1], v226, s52, v[156:157]
	v_lshl_add_u64 v[172:173], v[172:173], 0, v[158:159]
	flat_store_dwordx2 v[172:173], v[182:183] offset:128 nt
	flat_store_dwordx2 v[172:173], v[170:171] offset:160 nt
	v_pk_mul_f32 v[172:173], v[38:39], v[186:187]
	v_pk_mul_f32 v[170:171], v[40:41], v[188:189]
	v_pk_fma_f32 v[172:173], v[50:51], v[190:191], v[172:173] neg_lo:[0,0,1] neg_hi:[0,0,1]
	v_pk_mul_f32 v[180:181], v[30:31], v[194:195]
	v_pk_fma_f32 v[170:171], v[52:53], v[192:193], v[170:171] neg_lo:[0,0,1] neg_hi:[0,0,1]
	v_pk_fma_f32 v[180:181], v[42:43], v[198:199], v[180:181] neg_lo:[0,0,1] neg_hi:[0,0,1]
	v_med3_f32 v161, v172, s51, v168
	v_med3_f32 v173, v173, s51, v168
	v_mov_b32_e32 v172, 0
	v_cvt_pk_fp8_f32 v172, v161, v173
	v_med3_f32 v161, v170, s51, v168
	v_med3_f32 v170, v171, s51, v168
	v_med3_f32 v171, v180, s51, v168
	v_med3_f32 v180, v181, s51, v168
	v_mov_b32_e32 v173, 0
	v_cvt_pk_fp8_f32 v173, v171, v180
	v_pk_mul_f32 v[178:179], v[32:33], v[196:197]
	v_pk_mul_f32 v[176:177], v[50:51], v[186:187]
	v_pk_fma_f32 v[178:179], v[44:45], v[200:201], v[178:179] neg_lo:[0,0,1] neg_hi:[0,0,1]
	v_pk_mul_f32 v[174:175], v[52:53], v[188:189]
	v_pk_fma_f32 v[176:177], v[38:39], v[190:191], v[176:177]
	v_pk_mul_f32 v[184:185], v[42:43], v[194:195]
	v_cvt_pk_fp8_f32 v172, v161, v170 op_sel:[0,0,1]
	v_med3_f32 v161, v178, s51, v168
	v_med3_f32 v170, v179, s51, v168
	v_pk_fma_f32 v[174:175], v[40:41], v[192:193], v[174:175]
	v_pk_fma_f32 v[184:185], v[30:31], v[198:199], v[184:185]
	v_cvt_pk_fp8_f32 v173, v161, v170 op_sel:[0,0,1]
	v_med3_f32 v161, v176, s51, v168
	v_med3_f32 v171, v177, s51, v168
	v_mov_b32_e32 v170, 0
	v_cvt_pk_fp8_f32 v170, v161, v171
	v_med3_f32 v161, v174, s51, v168
	v_med3_f32 v174, v175, s51, v168
	v_med3_f32 v175, v184, s51, v168
	v_med3_f32 v176, v185, s51, v168
	v_mov_b32_e32 v171, 0
	v_cvt_pk_fp8_f32 v171, v175, v176
	v_pk_mul_f32 v[182:183], v[44:45], v[196:197]
	v_cvt_pk_fp8_f32 v170, v161, v174 op_sel:[0,0,1]
	v_pk_fma_f32 v[182:183], v[32:33], v[200:201], v[182:183]
	v_pk_mul_f32 v[180:181], v[14:15], v[214:215]
	v_med3_f32 v161, v182, s51, v168
	v_med3_f32 v174, v183, s51, v168
	v_cvt_pk_fp8_f32 v171, v161, v174 op_sel:[0,0,1]
	v_mad_i64_i32 v[174:175], s[0:1], v228, s52, v[156:157]
	v_lshl_add_u64 v[174:175], v[174:175], 0, v[158:159]
	flat_store_dwordx2 v[174:175], v[172:173] offset:128 nt
	flat_store_dwordx2 v[174:175], v[170:171] offset:160 nt
	v_pk_mul_f32 v[172:173], v[22:23], v[210:211]
	v_pk_mul_f32 v[170:171], v[24:25], v[212:213]
	v_pk_fma_f32 v[172:173], v[34:35], v[202:203], v[172:173] neg_lo:[0,0,1] neg_hi:[0,0,1]
	v_pk_fma_f32 v[170:171], v[36:37], v[204:205], v[170:171] neg_lo:[0,0,1] neg_hi:[0,0,1]
	v_pk_fma_f32 v[180:181], v[26:27], v[206:207], v[180:181] neg_lo:[0,0,1] neg_hi:[0,0,1]
	v_med3_f32 v161, v172, s51, v168
	v_med3_f32 v173, v173, s51, v168
	v_mov_b32_e32 v172, 0
	v_cvt_pk_fp8_f32 v172, v161, v173
	v_med3_f32 v161, v170, s51, v168
	v_med3_f32 v170, v171, s51, v168
	v_med3_f32 v171, v180, s51, v168
	v_med3_f32 v180, v181, s51, v168
	v_mov_b32_e32 v173, 0
	v_cvt_pk_fp8_f32 v173, v171, v180
	v_pk_mul_f32 v[178:179], v[16:17], v[216:217]
	v_pk_mul_f32 v[176:177], v[34:35], v[210:211]
	v_pk_fma_f32 v[178:179], v[28:29], v[208:209], v[178:179] neg_lo:[0,0,1] neg_hi:[0,0,1]
	v_pk_mul_f32 v[174:175], v[36:37], v[212:213]
	v_pk_fma_f32 v[176:177], v[22:23], v[202:203], v[176:177]
	v_pk_mul_f32 v[184:185], v[26:27], v[214:215]
	v_cvt_pk_fp8_f32 v172, v161, v170 op_sel:[0,0,1]
	v_med3_f32 v161, v178, s51, v168
	v_med3_f32 v170, v179, s51, v168
	v_pk_fma_f32 v[174:175], v[24:25], v[204:205], v[174:175]
	v_pk_fma_f32 v[184:185], v[14:15], v[206:207], v[184:185]
	v_cvt_pk_fp8_f32 v173, v161, v170 op_sel:[0,0,1]
	v_med3_f32 v161, v176, s51, v168
	v_med3_f32 v171, v177, s51, v168
	v_mov_b32_e32 v170, 0
	v_cvt_pk_fp8_f32 v170, v161, v171
	v_med3_f32 v161, v174, s51, v168
	v_med3_f32 v174, v175, s51, v168
	v_med3_f32 v175, v184, s51, v168
	v_med3_f32 v176, v185, s51, v168
	v_mov_b32_e32 v171, 0
	v_cvt_pk_fp8_f32 v171, v175, v176
	v_pk_mul_f32 v[182:183], v[28:29], v[216:217]
	v_cvt_pk_fp8_f32 v170, v161, v174 op_sel:[0,0,1]
	v_pk_fma_f32 v[182:183], v[16:17], v[208:209], v[182:183]
	v_pk_mul_f32 v[178:179], v[4:5], v[136:137]
	v_med3_f32 v161, v182, s51, v168
	v_med3_f32 v174, v183, s51, v168
	v_cvt_pk_fp8_f32 v171, v161, v174 op_sel:[0,0,1]
	v_mad_i64_i32 v[174:175], s[0:1], v230, s52, v[156:157]
	v_lshl_add_u64 v[174:175], v[174:175], 0, v[158:159]
	flat_store_dwordx2 v[174:175], v[172:173] offset:128 nt
	flat_store_dwordx2 v[174:175], v[170:171] offset:160 nt
	v_pk_mul_f32 v[172:173], v[6:7], v[222:223]
	v_pk_mul_f32 v[170:171], v[8:9], v[224:225]
	v_pk_fma_f32 v[172:173], v[18:19], v[218:219], v[172:173] neg_lo:[0,0,1] neg_hi:[0,0,1]
	v_pk_mul_f32 v[180:181], v[2:3], v[134:135]
	v_pk_mul_f32 v[136:137], v[12:13], v[136:137]
	v_pk_mul_f32 v[134:135], v[10:11], v[134:135]
	v_pk_fma_f32 v[170:171], v[20:21], v[220:221], v[170:171] neg_lo:[0,0,1] neg_hi:[0,0,1]
	v_pk_fma_f32 v[178:179], v[12:13], v[132:133], v[178:179] neg_lo:[0,0,1] neg_hi:[0,0,1]
	v_pk_fma_f32 v[180:181], v[10:11], v[130:131], v[180:181] neg_lo:[0,0,1] neg_hi:[0,0,1]
	v_pk_fma_f32 v[132:133], v[4:5], v[132:133], v[136:137]
	v_pk_fma_f32 v[130:131], v[2:3], v[130:131], v[134:135]
	v_med3_f32 v135, v172, s51, v168
	v_med3_f32 v136, v173, s51, v168
	v_mov_b32_e32 v134, 0
	v_cvt_pk_fp8_f32 v134, v135, v136
	v_med3_f32 v136, v170, s51, v168
	v_med3_f32 v161, v180, s51, v168
	v_med3_f32 v170, v181, s51, v168
	v_mov_b32_e32 v135, 0
	v_cvt_pk_fp8_f32 v135, v161, v170
	v_pk_mul_f32 v[176:177], v[18:19], v[222:223]
	v_med3_f32 v137, v171, s51, v168
	v_pk_fma_f32 v[176:177], v[6:7], v[218:219], v[176:177]
	v_cvt_pk_fp8_f32 v134, v136, v137 op_sel:[0,0,1]
	v_med3_f32 v136, v178, s51, v168
	v_med3_f32 v137, v179, s51, v168
	v_cvt_pk_fp8_f32 v135, v136, v137 op_sel:[0,0,1]
	v_med3_f32 v137, v176, s51, v168
	v_med3_f32 v161, v177, s51, v168
	v_mov_b32_e32 v136, 0
	v_cvt_pk_fp8_f32 v136, v137, v161
	v_med3_f32 v130, v130, s51, v168
	v_med3_f32 v131, v131, s51, v168
	v_mov_b32_e32 v137, 0
	v_cvt_pk_fp8_f32 v137, v130, v131
	v_pk_mul_f32 v[174:175], v[20:21], v[224:225]
	v_med3_f32 v130, v132, s51, v168
	v_pk_fma_f32 v[174:175], v[8:9], v[220:221], v[174:175]
	v_med3_f32 v131, v133, s51, v168
	v_med3_f32 v161, v174, s51, v168
	v_med3_f32 v170, v175, s51, v168
	v_cvt_pk_fp8_f32 v136, v161, v170 op_sel:[0,0,1]
	v_cvt_pk_fp8_f32 v137, v130, v131 op_sel:[0,0,1]
	v_mad_i64_i32 v[130:131], s[0:1], v160, s52, v[156:157]
	v_lshl_add_u64 v[130:131], v[130:131], 0, v[158:159]
	flat_store_dwordx2 v[130:131], v[134:135] offset:128 nt
	flat_store_dwordx2 v[130:131], v[136:137] offset:160 nt
.LBB0_2328:
	s_andn2_b64 vcc, exec, s[34:35]
	s_cbranch_vccnz .LBB0_2317
	v_max_f32_e32 v126, v126, v126
	v_med3_f32 v132, v126, s51, v168
	v_max_f32_e32 v126, v127, v127
	v_med3_f32 v127, v126, s51, v168
	v_mov_b32_e32 v126, 0
	v_cvt_pk_fp8_f32 v126, v132, v127
	v_max_f32_e32 v127, v128, v128
	v_max_f32_e32 v128, v129, v129
	v_med3_f32 v127, v127, s51, v168
	v_med3_f32 v128, v128, s51, v168
	v_max_f32_e32 v118, v118, v118
	v_cvt_pk_fp8_f32 v126, v127, v128 op_sel:[0,0,1]
	v_med3_f32 v128, v118, s51, v168
	v_max_f32_e32 v118, v119, v119
	v_med3_f32 v119, v118, s51, v168
	v_mov_b32_e32 v118, 0
	v_cvt_pk_fp8_f32 v118, v128, v119
	v_max_f32_e32 v122, v122, v122
	v_max_f32_e32 v123, v123, v123
	v_med3_f32 v122, v122, s51, v168
	v_med3_f32 v123, v123, s51, v168
	v_mov_b32_e32 v127, 0
	v_max_f32_e32 v119, v120, v120
	v_max_f32_e32 v120, v121, v121
	v_cvt_pk_fp8_f32 v127, v122, v123
	v_med3_f32 v119, v119, s51, v168
	v_med3_f32 v120, v120, s51, v168
	v_max_f32_e32 v110, v110, v110
	v_max_f32_e32 v111, v111, v111
	s_lshl_b32 s0, s56, 8
	v_cvt_pk_fp8_f32 v118, v119, v120 op_sel:[0,0,1]
	v_med3_f32 v110, v110, s51, v168
	v_med3_f32 v111, v111, s51, v168
	v_mov_b32_e32 v119, 0
	s_add_i32 s0, s0, s45
	v_max_f32_e32 v122, v124, v124
	v_max_f32_e32 v123, v125, v125
	v_cvt_pk_fp8_f32 v119, v110, v111
	v_add_u32_e32 v130, s0, v169
	v_med3_f32 v122, v122, s51, v168
	v_med3_f32 v123, v123, s51, v168
	s_mul_i32 s34, s57, 0x180
	v_mov_b32_e32 v131, v130
	v_cvt_pk_fp8_f32 v127, v122, v123 op_sel:[0,0,1]
	v_mov_b64_e32 v[122:123], s[22:23]
	v_max_f32_e32 v110, v112, v112
	v_max_f32_e32 v111, v113, v113
	s_ashr_i32 s35, s34, 31
	v_med3_f32 v110, v110, s51, v168
	v_mad_i64_i32 v[124:125], s[0:1], v131, s52, v[122:123]
	v_med3_f32 v111, v111, s51, v168
	v_lshl_add_u64 v[124:125], v[124:125], 0, s[34:35]
	v_cvt_pk_fp8_f32 v119, v110, v111 op_sel:[0,0,1]
	v_lshl_add_u64 v[110:111], v[124:125], 0, s[28:29]
	v_lshl_add_u64 v[110:111], v[110:111], 0, v[154:155]
	flat_store_dwordx2 v[110:111], v[126:127] nt
	flat_store_dwordx2 v[110:111], v[118:119] offset:192 nt
	v_max_f32_e32 v110, v114, v114
	v_med3_f32 v111, v110, s51, v168
	v_max_f32_e32 v110, v115, v115
	v_med3_f32 v113, v110, s51, v168
	v_mov_b32_e32 v110, 0
	v_cvt_pk_fp8_f32 v110, v111, v113
	v_max_f32_e32 v111, v116, v116
	v_max_f32_e32 v113, v117, v117
	v_med3_f32 v111, v111, s51, v168
	v_med3_f32 v113, v113, s51, v168
	v_max_f32_e32 v106, v106, v106
	v_max_f32_e32 v107, v107, v107
	v_cvt_pk_fp8_f32 v110, v111, v113 op_sel:[0,0,1]
	v_med3_f32 v106, v106, s51, v168
	v_med3_f32 v107, v107, s51, v168
	v_mov_b32_e32 v111, 0
	v_max_f32_e32 v102, v102, v102
	v_cvt_pk_fp8_f32 v111, v106, v107
	v_max_f32_e32 v106, v108, v108
	v_med3_f32 v108, v102, s51, v168
	v_max_f32_e32 v102, v103, v103
	v_med3_f32 v103, v102, s51, v168
	v_mov_b32_e32 v102, 0
	v_cvt_pk_fp8_f32 v102, v108, v103
	v_max_f32_e32 v103, v104, v104
	v_max_f32_e32 v104, v105, v105
	v_med3_f32 v103, v103, s51, v168
	v_med3_f32 v104, v104, s51, v168
	v_max_f32_e32 v94, v94, v94
	v_max_f32_e32 v95, v95, v95
	v_cvt_pk_fp8_f32 v102, v103, v104 op_sel:[0,0,1]
	v_med3_f32 v94, v94, s51, v168
	v_med3_f32 v95, v95, s51, v168
	v_mov_b32_e32 v103, 0
	v_cvt_pk_fp8_f32 v103, v94, v95
	v_max_f32_e32 v107, v109, v109
	v_add_u32_e32 v112, 16, v130
	v_med3_f32 v106, v106, s51, v168
	v_med3_f32 v107, v107, s51, v168
	v_max_f32_e32 v94, v96, v96
	v_max_f32_e32 v95, v97, v97
	v_cvt_pk_fp8_f32 v111, v106, v107 op_sel:[0,0,1]
	v_mad_i64_i32 v[106:107], s[0:1], v112, s52, v[122:123]
	v_med3_f32 v94, v94, s51, v168
	v_med3_f32 v95, v95, s51, v168
	v_lshl_add_u64 v[106:107], v[106:107], 0, s[34:35]
	v_cvt_pk_fp8_f32 v103, v94, v95 op_sel:[0,0,1]
	v_lshl_add_u64 v[94:95], v[106:107], 0, s[28:29]
	v_lshl_add_u64 v[94:95], v[94:95], 0, v[154:155]
	flat_store_dwordx2 v[94:95], v[110:111] nt
	flat_store_dwordx2 v[94:95], v[102:103] offset:192 nt
	v_max_f32_e32 v94, v98, v98
	v_med3_f32 v95, v94, s51, v168
	v_max_f32_e32 v94, v99, v99
	v_med3_f32 v97, v94, s51, v168
	v_mov_b32_e32 v94, 0
	v_cvt_pk_fp8_f32 v94, v95, v97
	v_max_f32_e32 v95, v100, v100
	v_max_f32_e32 v97, v101, v101
	v_med3_f32 v95, v95, s51, v168
	v_med3_f32 v97, v97, s51, v168
	v_max_f32_e32 v90, v90, v90
	v_max_f32_e32 v91, v91, v91
	v_cvt_pk_fp8_f32 v94, v95, v97 op_sel:[0,0,1]
	v_med3_f32 v90, v90, s51, v168
	v_med3_f32 v91, v91, s51, v168
	v_mov_b32_e32 v95, 0
	v_max_f32_e32 v86, v86, v86
	v_cvt_pk_fp8_f32 v95, v90, v91
	v_max_f32_e32 v90, v92, v92
	v_med3_f32 v92, v86, s51, v168
	v_max_f32_e32 v86, v87, v87
	v_med3_f32 v87, v86, s51, v168
	v_mov_b32_e32 v86, 0
	v_cvt_pk_fp8_f32 v86, v92, v87
	v_max_f32_e32 v87, v88, v88
	v_max_f32_e32 v88, v89, v89
	v_med3_f32 v87, v87, s51, v168
	v_med3_f32 v88, v88, s51, v168
	v_max_f32_e32 v78, v78, v78
	v_max_f32_e32 v79, v79, v79
	v_cvt_pk_fp8_f32 v86, v87, v88 op_sel:[0,0,1]
	v_med3_f32 v78, v78, s51, v168
	v_med3_f32 v79, v79, s51, v168
	v_mov_b32_e32 v87, 0
	v_cvt_pk_fp8_f32 v87, v78, v79
	v_max_f32_e32 v91, v93, v93
	v_add_u32_e32 v96, 32, v130
	v_med3_f32 v90, v90, s51, v168
	v_med3_f32 v91, v91, s51, v168
	v_max_f32_e32 v78, v80, v80
	v_max_f32_e32 v79, v81, v81
	v_cvt_pk_fp8_f32 v95, v90, v91 op_sel:[0,0,1]
	v_mad_i64_i32 v[90:91], s[0:1], v96, s52, v[122:123]
	v_med3_f32 v78, v78, s51, v168
	v_med3_f32 v79, v79, s51, v168
	v_lshl_add_u64 v[90:91], v[90:91], 0, s[34:35]
	v_cvt_pk_fp8_f32 v87, v78, v79 op_sel:[0,0,1]
	v_lshl_add_u64 v[78:79], v[90:91], 0, s[28:29]
	v_lshl_add_u64 v[78:79], v[78:79], 0, v[154:155]
	flat_store_dwordx2 v[78:79], v[94:95] nt
	flat_store_dwordx2 v[78:79], v[86:87] offset:192 nt
	v_max_f32_e32 v78, v82, v82
	v_med3_f32 v79, v78, s51, v168
	v_max_f32_e32 v78, v83, v83
	v_med3_f32 v81, v78, s51, v168
	v_mov_b32_e32 v78, 0
	v_cvt_pk_fp8_f32 v78, v79, v81
	v_max_f32_e32 v79, v84, v84
	v_max_f32_e32 v81, v85, v85
	v_med3_f32 v79, v79, s51, v168
	v_med3_f32 v81, v81, s51, v168
	v_max_f32_e32 v74, v74, v74
	v_max_f32_e32 v75, v75, v75
	v_cvt_pk_fp8_f32 v78, v79, v81 op_sel:[0,0,1]
	v_med3_f32 v74, v74, s51, v168
	v_med3_f32 v75, v75, s51, v168
	v_mov_b32_e32 v79, 0
	v_max_f32_e32 v70, v70, v70
	v_cvt_pk_fp8_f32 v79, v74, v75
	v_max_f32_e32 v74, v76, v76
	v_med3_f32 v76, v70, s51, v168
	v_max_f32_e32 v70, v71, v71
	v_med3_f32 v71, v70, s51, v168
	v_mov_b32_e32 v70, 0
	v_cvt_pk_fp8_f32 v70, v76, v71
	v_max_f32_e32 v71, v72, v72
	v_max_f32_e32 v72, v73, v73
	v_med3_f32 v71, v71, s51, v168
	v_med3_f32 v72, v72, s51, v168
	v_max_f32_e32 v66, v66, v66
	v_max_f32_e32 v67, v67, v67
	v_cvt_pk_fp8_f32 v70, v71, v72 op_sel:[0,0,1]
	v_med3_f32 v66, v66, s51, v168
	v_med3_f32 v67, v67, s51, v168
	v_mov_b32_e32 v71, 0
	v_cvt_pk_fp8_f32 v71, v66, v67
	v_max_f32_e32 v75, v77, v77
	v_add_u32_e32 v80, 48, v130
	v_med3_f32 v74, v74, s51, v168
	v_med3_f32 v75, v75, s51, v168
	v_max_f32_e32 v66, v68, v68
	v_max_f32_e32 v67, v69, v69
	v_cvt_pk_fp8_f32 v79, v74, v75 op_sel:[0,0,1]
	v_mad_i64_i32 v[74:75], s[0:1], v80, s52, v[122:123]
	v_med3_f32 v66, v66, s51, v168
	v_med3_f32 v67, v67, s51, v168
	v_lshl_add_u64 v[74:75], v[74:75], 0, s[34:35]
	v_cvt_pk_fp8_f32 v71, v66, v67 op_sel:[0,0,1]
	v_lshl_add_u64 v[66:67], v[74:75], 0, s[28:29]
	v_lshl_add_u64 v[66:67], v[66:67], 0, v[154:155]
	v_max_f32_e32 v62, v62, v62
	flat_store_dwordx2 v[66:67], v[78:79] nt
	flat_store_dwordx2 v[66:67], v[70:71] offset:192 nt
	v_med3_f32 v67, v62, s51, v168
	v_max_f32_e32 v62, v63, v63
	v_med3_f32 v63, v62, s51, v168
	v_mov_b32_e32 v62, 0
	v_cvt_pk_fp8_f32 v62, v67, v63
	v_max_f32_e32 v63, v64, v64
	v_max_f32_e32 v64, v65, v65
	v_med3_f32 v63, v63, s51, v168
	v_med3_f32 v64, v64, s51, v168
	v_max_f32_e32 v58, v58, v58
	v_max_f32_e32 v59, v59, v59
	v_cvt_pk_fp8_f32 v62, v63, v64 op_sel:[0,0,1]
	v_med3_f32 v58, v58, s51, v168
	v_med3_f32 v59, v59, s51, v168
	v_mov_b32_e32 v63, 0
	v_max_f32_e32 v54, v54, v54
	v_cvt_pk_fp8_f32 v63, v58, v59
	v_max_f32_e32 v58, v60, v60
	v_med3_f32 v60, v54, s51, v168
	v_max_f32_e32 v54, v55, v55
	v_med3_f32 v55, v54, s51, v168
	v_mov_b32_e32 v54, 0
	v_cvt_pk_fp8_f32 v54, v60, v55
	v_max_f32_e32 v55, v56, v56
	v_max_f32_e32 v56, v57, v57
	v_med3_f32 v55, v55, s51, v168
	v_med3_f32 v56, v56, s51, v168
	v_max_f32_e32 v46, v46, v46
	v_max_f32_e32 v47, v47, v47
	v_cvt_pk_fp8_f32 v54, v55, v56 op_sel:[0,0,1]
	v_med3_f32 v46, v46, s51, v168
	v_med3_f32 v47, v47, s51, v168
	v_mov_b32_e32 v55, 0
	v_cvt_pk_fp8_f32 v55, v46, v47
	v_max_f32_e32 v59, v61, v61
	v_add_u32_e32 v66, 0x80, v130
	v_med3_f32 v58, v58, s51, v168
	v_med3_f32 v59, v59, s51, v168
	v_max_f32_e32 v46, v48, v48
	v_max_f32_e32 v47, v49, v49
	v_cvt_pk_fp8_f32 v63, v58, v59 op_sel:[0,0,1]
	v_mad_i64_i32 v[58:59], s[0:1], v66, s52, v[122:123]
	v_med3_f32 v46, v46, s51, v168
	v_med3_f32 v47, v47, s51, v168
	v_lshl_add_u64 v[58:59], v[58:59], 0, s[34:35]
	v_cvt_pk_fp8_f32 v55, v46, v47 op_sel:[0,0,1]
	v_lshl_add_u64 v[46:47], v[58:59], 0, s[28:29]
	v_lshl_add_u64 v[46:47], v[46:47], 0, v[154:155]
	flat_store_dwordx2 v[46:47], v[62:63] nt
	flat_store_dwordx2 v[46:47], v[54:55] offset:192 nt
	v_max_f32_e32 v46, v50, v50
	v_med3_f32 v47, v46, s51, v168
	v_max_f32_e32 v46, v51, v51
	v_med3_f32 v49, v46, s51, v168
	v_mov_b32_e32 v46, 0
	v_cvt_pk_fp8_f32 v46, v47, v49
	v_max_f32_e32 v47, v52, v52
	v_max_f32_e32 v49, v53, v53
	v_med3_f32 v47, v47, s51, v168
	v_med3_f32 v49, v49, s51, v168
	v_max_f32_e32 v42, v42, v42
	v_max_f32_e32 v43, v43, v43
	v_cvt_pk_fp8_f32 v46, v47, v49 op_sel:[0,0,1]
	v_med3_f32 v42, v42, s51, v168
	v_med3_f32 v43, v43, s51, v168
	v_mov_b32_e32 v47, 0
	v_max_f32_e32 v38, v38, v38
	v_cvt_pk_fp8_f32 v47, v42, v43
	v_max_f32_e32 v42, v44, v44
	v_med3_f32 v44, v38, s51, v168
	v_max_f32_e32 v38, v39, v39
	v_med3_f32 v39, v38, s51, v168
	v_mov_b32_e32 v38, 0
	v_cvt_pk_fp8_f32 v38, v44, v39
	v_max_f32_e32 v39, v40, v40
	v_max_f32_e32 v40, v41, v41
	v_med3_f32 v39, v39, s51, v168
	v_med3_f32 v40, v40, s51, v168
	v_max_f32_e32 v30, v30, v30
	v_max_f32_e32 v31, v31, v31
	v_cvt_pk_fp8_f32 v38, v39, v40 op_sel:[0,0,1]
	v_med3_f32 v30, v30, s51, v168
	v_med3_f32 v31, v31, s51, v168
	v_mov_b32_e32 v39, 0
	v_cvt_pk_fp8_f32 v39, v30, v31
	v_max_f32_e32 v43, v45, v45
	v_add_u32_e32 v48, 0x90, v130
	v_med3_f32 v42, v42, s51, v168
	v_med3_f32 v43, v43, s51, v168
	v_max_f32_e32 v30, v32, v32
	v_max_f32_e32 v31, v33, v33
	v_cvt_pk_fp8_f32 v47, v42, v43 op_sel:[0,0,1]
	v_mad_i64_i32 v[42:43], s[0:1], v48, s52, v[122:123]
	v_med3_f32 v30, v30, s51, v168
	v_med3_f32 v31, v31, s51, v168
	v_lshl_add_u64 v[42:43], v[42:43], 0, s[34:35]
	v_cvt_pk_fp8_f32 v39, v30, v31 op_sel:[0,0,1]
	v_lshl_add_u64 v[30:31], v[42:43], 0, s[28:29]
	v_lshl_add_u64 v[30:31], v[30:31], 0, v[154:155]
	flat_store_dwordx2 v[30:31], v[46:47] nt
	flat_store_dwordx2 v[30:31], v[38:39] offset:192 nt
	v_max_f32_e32 v30, v34, v34
	v_med3_f32 v31, v30, s51, v168
	v_max_f32_e32 v30, v35, v35
	v_med3_f32 v33, v30, s51, v168
	v_mov_b32_e32 v30, 0
	v_cvt_pk_fp8_f32 v30, v31, v33
	v_max_f32_e32 v31, v36, v36
	v_max_f32_e32 v33, v37, v37
	v_med3_f32 v31, v31, s51, v168
	v_med3_f32 v33, v33, s51, v168
	v_max_f32_e32 v26, v26, v26
	v_max_f32_e32 v27, v27, v27
	v_cvt_pk_fp8_f32 v30, v31, v33 op_sel:[0,0,1]
	v_med3_f32 v26, v26, s51, v168
	v_med3_f32 v27, v27, s51, v168
	v_mov_b32_e32 v31, 0
	v_max_f32_e32 v22, v22, v22
	v_cvt_pk_fp8_f32 v31, v26, v27
	v_max_f32_e32 v26, v28, v28
	v_med3_f32 v28, v22, s51, v168
	v_max_f32_e32 v22, v23, v23
	v_med3_f32 v23, v22, s51, v168
	v_mov_b32_e32 v22, 0
	v_cvt_pk_fp8_f32 v22, v28, v23
	v_max_f32_e32 v23, v24, v24
	v_max_f32_e32 v24, v25, v25
	v_med3_f32 v23, v23, s51, v168
	v_med3_f32 v24, v24, s51, v168
	v_max_f32_e32 v14, v14, v14
	v_max_f32_e32 v15, v15, v15
	v_cvt_pk_fp8_f32 v22, v23, v24 op_sel:[0,0,1]
	v_med3_f32 v14, v14, s51, v168
	v_med3_f32 v15, v15, s51, v168
	v_mov_b32_e32 v23, 0
	v_cvt_pk_fp8_f32 v23, v14, v15
	v_max_f32_e32 v27, v29, v29
	v_add_u32_e32 v32, 0xa0, v130
	v_med3_f32 v26, v26, s51, v168
	v_med3_f32 v27, v27, s51, v168
	v_max_f32_e32 v14, v16, v16
	v_max_f32_e32 v15, v17, v17
	v_cvt_pk_fp8_f32 v31, v26, v27 op_sel:[0,0,1]
	v_mad_i64_i32 v[26:27], s[0:1], v32, s52, v[122:123]
	v_med3_f32 v14, v14, s51, v168
	v_med3_f32 v15, v15, s51, v168
	v_lshl_add_u64 v[26:27], v[26:27], 0, s[34:35]
	v_cvt_pk_fp8_f32 v23, v14, v15 op_sel:[0,0,1]
	v_lshl_add_u64 v[14:15], v[26:27], 0, s[28:29]
	v_lshl_add_u64 v[14:15], v[14:15], 0, v[154:155]
	flat_store_dwordx2 v[14:15], v[30:31] nt
	flat_store_dwordx2 v[14:15], v[22:23] offset:192 nt
	v_max_f32_e32 v14, v18, v18
	v_med3_f32 v15, v14, s51, v168
	v_max_f32_e32 v14, v19, v19
	v_med3_f32 v17, v14, s51, v168
	v_mov_b32_e32 v14, 0
	v_cvt_pk_fp8_f32 v14, v15, v17
	v_max_f32_e32 v15, v20, v20
	v_max_f32_e32 v17, v21, v21
	v_med3_f32 v15, v15, s51, v168
	v_med3_f32 v17, v17, s51, v168
	v_max_f32_e32 v10, v10, v10
	v_max_f32_e32 v11, v11, v11
	v_cvt_pk_fp8_f32 v14, v15, v17 op_sel:[0,0,1]
	v_med3_f32 v10, v10, s51, v168
	v_med3_f32 v11, v11, s51, v168
	v_mov_b32_e32 v15, 0
	v_max_f32_e32 v6, v6, v6
	v_cvt_pk_fp8_f32 v15, v10, v11
	v_max_f32_e32 v10, v12, v12
	v_med3_f32 v12, v6, s51, v168
	v_max_f32_e32 v6, v7, v7
	v_med3_f32 v7, v6, s51, v168
	v_mov_b32_e32 v6, 0
	v_cvt_pk_fp8_f32 v6, v12, v7
	v_max_f32_e32 v7, v8, v8
	v_max_f32_e32 v8, v9, v9
	v_med3_f32 v7, v7, s51, v168
	v_med3_f32 v8, v8, s51, v168
	v_max_f32_e32 v2, v2, v2
	v_max_f32_e32 v3, v3, v3
	v_cvt_pk_fp8_f32 v6, v7, v8 op_sel:[0,0,1]
	v_med3_f32 v2, v2, s51, v168
	v_med3_f32 v3, v3, s51, v168
	v_mov_b32_e32 v7, 0
	v_cvt_pk_fp8_f32 v7, v2, v3
	v_max_f32_e32 v11, v13, v13
	v_add_u32_e32 v16, 0xb0, v130
	v_med3_f32 v10, v10, s51, v168
	v_med3_f32 v11, v11, s51, v168
	v_max_f32_e32 v2, v4, v4
	v_max_f32_e32 v3, v5, v5
	v_cvt_pk_fp8_f32 v15, v10, v11 op_sel:[0,0,1]
	v_mad_i64_i32 v[10:11], s[0:1], v16, s52, v[122:123]
	v_med3_f32 v2, v2, s51, v168
	v_med3_f32 v3, v3, s51, v168
	v_lshl_add_u64 v[10:11], v[10:11], 0, s[34:35]
	v_cvt_pk_fp8_f32 v7, v2, v3 op_sel:[0,0,1]
	v_lshl_add_u64 v[2:3], v[10:11], 0, s[28:29]
	v_lshl_add_u64 v[2:3], v[2:3], 0, v[154:155]
	flat_store_dwordx2 v[2:3], v[14:15] nt
	flat_store_dwordx2 v[2:3], v[6:7] offset:192 nt
	s_branch .LBB0_2317

.LBB0_2344:
	s_add_u32 s39, s30, s38
	s_addc_u32 s40, s31, 0
	s_add_u32 s41, s39, 0x100
	s_addc_u32 s42, s40, 0
	s_and_b64 s[0:1], s[36:37], exec
	s_cselect_b32 s43, s21, s42
	s_cselect_b32 s42, s62, s41
	s_add_u32 s0, s28, s38
	s_addc_u32 s1, s29, 0
	s_add_u32 s38, s0, 0x100
	s_addc_u32 s41, s1, 0
	s_and_b64 s[0:1], s[36:37], exec
	s_cselect_b32 s45, s19, s41
	s_cselect_b32 s44, s63, s38
	s_add_u32 s46, s39, 0x10080
	s_addc_u32 s47, s40, 0
	s_add_i32 s70, s58, s9
	s_add_i32 m0, s27, 0xc000
	s_add_i32 s71, s27, 0xe000
	s_add_i32 s0, s70, 0x2000
	s_add_u32 s40, s44, 0x10000
	s_addc_u32 s41, s45, 0
	s_add_i32 s77, s59, s9
	ds_read_b128 v[152:155], v147
	ds_read_b128 v[156:159], v147 offset:1024
	ds_read_b128 v[160:163], v147 offset:2048
	ds_read_b128 v[164:167], v147 offset:3072
	s_add_i32 s1, s77, 0x2000
	s_add_i32 s73, 0, 0x18000
	s_add_u32 s38, s42, 0x10000
	s_addc_u32 s39, s43, 0
	s_add_i32 s72, s73, s9
	s_add_i32 s69, 0, 0x1c000
	s_add_i32 s67, s72, 0x2000
	s_add_u32 s36, s44, 0x10080
	s_addc_u32 s37, s45, 0
	s_add_i32 s65, s69, s9
	s_add_i32 s64, s65, 0x2000
	v_lshl_add_u64 v[142:143], s[46:47], 0, v[136:137]
	ds_read_b128 v[168:171], v148
	ds_read_b128 v[172:175], v148 offset:1024
	ds_read_b128 v[176:179], v148 offset:2048
	ds_read_b128 v[180:183], v148 offset:3072
	ds_read_b128 v[184:187], v148 offset:4096
	ds_read_b128 v[188:191], v148 offset:5120
	ds_read_b128 v[192:195], v148 offset:6144
	ds_read_b128 v[196:199], v148 offset:7168
	global_load_lds_dwordx4 v[142:143], off
	v_lshl_add_u64 v[142:143], s[46:47], 0, v[132:133]
	s_mov_b32 m0, s71
	s_nop 0
	global_load_lds_dwordx4 v[142:143], off
	s_waitcnt lgkmcnt(8)
	s_waitcnt vmcnt(10)
	s_barrier
	s_waitcnt lgkmcnt(0)
	s_setprio 1
	s_waitcnt lgkmcnt(0)
	v_mfma_f32_16x16x32_bf16 v[126:129], v[152:155], v[168:171], v[126:129]
	v_mfma_f32_16x16x32_bf16 v[122:125], v[160:163], v[168:171], v[122:125]
	v_mfma_f32_16x16x32_bf16 v[110:113], v[152:155], v[176:179], v[110:113]
	v_mfma_f32_16x16x32_bf16 v[106:109], v[160:163], v[176:179], v[106:109]
	v_mfma_f32_16x16x32_bf16 v[94:97], v[152:155], v[184:187], v[94:97]
	v_mfma_f32_16x16x32_bf16 v[90:93], v[160:163], v[184:187], v[90:93]
	v_mfma_f32_16x16x32_bf16 v[78:81], v[152:155], v[192:195], v[78:81]
	v_mfma_f32_16x16x32_bf16 v[74:77], v[160:163], v[192:195], v[74:77]
	v_mfma_f32_16x16x32_bf16 v[126:129], v[156:159], v[172:175], v[126:129]
	v_mfma_f32_16x16x32_bf16 v[122:125], v[164:167], v[172:175], v[122:125]
	v_mfma_f32_16x16x32_bf16 v[110:113], v[156:159], v[180:183], v[110:113]
	v_mfma_f32_16x16x32_bf16 v[106:109], v[164:167], v[180:183], v[106:109]
	v_mfma_f32_16x16x32_bf16 v[94:97], v[156:159], v[188:191], v[94:97]
	v_mfma_f32_16x16x32_bf16 v[90:93], v[164:167], v[188:191], v[90:93]
	v_mfma_f32_16x16x32_bf16 v[78:81], v[156:159], v[196:199], v[78:81]
	v_mfma_f32_16x16x32_bf16 v[74:77], v[164:167], v[196:199], v[74:77]
	s_setprio 0
	s_barrier
	s_mov_b32 m0, s70
	v_lshl_add_u64 v[142:143], s[44:45], 0, v[134:135]
	ds_read_b128 v[200:203], v149
	ds_read_b128 v[204:207], v149 offset:1024
	ds_read_b128 v[208:211], v149 offset:2048
	ds_read_b128 v[212:215], v149 offset:3072
	global_load_lds_dwordx4 v[142:143], off
	v_lshl_add_u64 v[216:217], s[44:45], 0, v[130:131]
	s_mov_b32 m0, s0
	s_nop 0
	global_load_lds_dwordx4 v[216:217], off
	s_waitcnt vmcnt(10)
	s_barrier
	s_waitcnt lgkmcnt(0)
	s_setprio 1
	s_waitcnt lgkmcnt(0)
	v_mfma_f32_16x16x32_bf16 v[118:121], v[200:203], v[168:171], v[118:121]
	v_mfma_f32_16x16x32_bf16 v[114:117], v[208:211], v[168:171], v[114:117]
	v_mfma_f32_16x16x32_bf16 v[102:105], v[200:203], v[176:179], v[102:105]
	v_mfma_f32_16x16x32_bf16 v[98:101], v[208:211], v[176:179], v[98:101]
	v_mfma_f32_16x16x32_bf16 v[86:89], v[200:203], v[184:187], v[86:89]
	v_mfma_f32_16x16x32_bf16 v[82:85], v[208:211], v[184:187], v[82:85]
	v_mfma_f32_16x16x32_bf16 v[70:73], v[200:203], v[192:195], v[70:73]
	v_mfma_f32_16x16x32_bf16 v[66:69], v[208:211], v[192:195], v[66:69]
	v_mfma_f32_16x16x32_bf16 v[118:121], v[204:207], v[172:175], v[118:121]
	v_mfma_f32_16x16x32_bf16 v[114:117], v[212:215], v[172:175], v[114:117]
	v_mfma_f32_16x16x32_bf16 v[102:105], v[204:207], v[180:183], v[102:105]
	v_mfma_f32_16x16x32_bf16 v[98:101], v[212:215], v[180:183], v[98:101]
	v_mfma_f32_16x16x32_bf16 v[86:89], v[204:207], v[188:191], v[86:89]
	v_mfma_f32_16x16x32_bf16 v[82:85], v[212:215], v[188:191], v[82:85]
	v_mfma_f32_16x16x32_bf16 v[70:73], v[204:207], v[196:199], v[70:73]
	v_mfma_f32_16x16x32_bf16 v[66:69], v[212:215], v[196:199], v[66:69]
	s_setprio 0
	s_mov_b32 m0, s27
	v_lshl_add_u64 v[218:219], s[42:43], 0, v[136:137]
	s_barrier
	ds_read_b128 v[168:171], v148 offset:16384
	ds_read_b128 v[172:175], v148 offset:17408
	ds_read_b128 v[176:179], v148 offset:18432
	ds_read_b128 v[180:183], v148 offset:19456
	ds_read_b128 v[184:187], v148 offset:20480
	ds_read_b128 v[188:191], v148 offset:21504
	ds_read_b128 v[192:195], v148 offset:22528
	ds_read_b128 v[196:199], v148 offset:23552
	global_load_lds_dwordx4 v[218:219], off
	v_lshl_add_u64 v[220:221], s[42:43], 0, v[132:133]
	s_mov_b32 m0, s48
	s_nop 0
	global_load_lds_dwordx4 v[220:221], off
	s_waitcnt vmcnt(10)
	s_barrier
	s_waitcnt lgkmcnt(0)
	s_setprio 1
	s_waitcnt lgkmcnt(0)
	v_mfma_f32_16x16x32_bf16 v[62:65], v[152:155], v[168:171], v[62:65]
	v_mfma_f32_16x16x32_bf16 v[58:61], v[160:163], v[168:171], v[58:61]
	v_mfma_f32_16x16x32_bf16 v[46:49], v[152:155], v[176:179], v[46:49]
	v_mfma_f32_16x16x32_bf16 v[42:45], v[160:163], v[176:179], v[42:45]
	v_mfma_f32_16x16x32_bf16 v[30:33], v[152:155], v[184:187], v[30:33]
	v_mfma_f32_16x16x32_bf16 v[26:29], v[160:163], v[184:187], v[26:29]
	v_mfma_f32_16x16x32_bf16 v[14:17], v[152:155], v[192:195], v[14:17]
	v_mfma_f32_16x16x32_bf16 v[10:13], v[160:163], v[192:195], v[10:13]
	v_mfma_f32_16x16x32_bf16 v[62:65], v[156:159], v[172:175], v[62:65]
	v_mfma_f32_16x16x32_bf16 v[58:61], v[164:167], v[172:175], v[58:61]
	v_mfma_f32_16x16x32_bf16 v[46:49], v[156:159], v[180:183], v[46:49]
	v_mfma_f32_16x16x32_bf16 v[42:45], v[164:167], v[180:183], v[42:45]
	v_mfma_f32_16x16x32_bf16 v[30:33], v[156:159], v[188:191], v[30:33]
	v_mfma_f32_16x16x32_bf16 v[26:29], v[164:167], v[188:191], v[26:29]
	v_mfma_f32_16x16x32_bf16 v[14:17], v[156:159], v[196:199], v[14:17]
	v_mfma_f32_16x16x32_bf16 v[10:13], v[164:167], v[196:199], v[10:13]
	s_setprio 0
	s_barrier
	s_mov_b32 m0, s77
	v_lshl_add_u64 v[152:153], s[40:41], 0, v[134:135]
	global_load_lds_dwordx4 v[152:153], off
	v_lshl_add_u64 v[152:153], s[40:41], 0, v[130:131]
	s_mov_b32 m0, s1
	s_nop 0
	global_load_lds_dwordx4 v[152:153], off
	s_waitcnt vmcnt(10)
	s_barrier
	s_setprio 1
	v_mfma_f32_16x16x32_bf16 v[54:57], v[200:203], v[168:171], v[54:57]
	v_mfma_f32_16x16x32_bf16 v[50:53], v[208:211], v[168:171], v[50:53]
	v_mfma_f32_16x16x32_bf16 v[38:41], v[200:203], v[176:179], v[38:41]
	v_mfma_f32_16x16x32_bf16 v[34:37], v[208:211], v[176:179], v[34:37]
	v_mfma_f32_16x16x32_bf16 v[22:25], v[200:203], v[184:187], v[22:25]
	v_mfma_f32_16x16x32_bf16 v[18:21], v[208:211], v[184:187], v[18:21]
	v_mfma_f32_16x16x32_bf16 v[6:9], v[200:203], v[192:195], v[6:9]
	v_mfma_f32_16x16x32_bf16 v[2:5], v[208:211], v[192:195], v[2:5]
	v_mfma_f32_16x16x32_bf16 v[54:57], v[204:207], v[172:175], v[54:57]
	v_mfma_f32_16x16x32_bf16 v[50:53], v[212:215], v[172:175], v[50:53]
	v_mfma_f32_16x16x32_bf16 v[38:41], v[204:207], v[180:183], v[38:41]
	v_mfma_f32_16x16x32_bf16 v[34:37], v[212:215], v[180:183], v[34:37]
	v_mfma_f32_16x16x32_bf16 v[22:25], v[204:207], v[188:191], v[22:25]
	v_mfma_f32_16x16x32_bf16 v[18:21], v[212:215], v[188:191], v[18:21]
	v_mfma_f32_16x16x32_bf16 v[6:9], v[204:207], v[196:199], v[6:9]
	v_mfma_f32_16x16x32_bf16 v[2:5], v[212:215], v[196:199], v[2:5]
	s_setprio 0
	v_add_u32_e32 v151, s73, v146
	s_barrier
	ds_read_b128 v[152:155], v151
	ds_read_b128 v[156:159], v151 offset:1024
	ds_read_b128 v[160:163], v151 offset:2048
	ds_read_b128 v[164:167], v151 offset:3072
	s_mov_b32 m0, s49
	v_lshl_add_u64 v[200:201], s[38:39], 0, v[136:137]
	ds_read_b128 v[168:171], v148 offset:32768
	ds_read_b128 v[172:175], v148 offset:33792
	ds_read_b128 v[176:179], v148 offset:34816
	ds_read_b128 v[180:183], v148 offset:35840
	ds_read_b128 v[184:187], v148 offset:36864
	ds_read_b128 v[188:191], v148 offset:37888
	ds_read_b128 v[192:195], v148 offset:38912
	ds_read_b128 v[196:199], v148 offset:39936
	global_load_lds_dwordx4 v[200:201], off
	v_lshl_add_u64 v[200:201], s[38:39], 0, v[132:133]
	s_mov_b32 m0, s50
	s_nop 0
	global_load_lds_dwordx4 v[200:201], off
	s_waitcnt lgkmcnt(8)
	s_waitcnt vmcnt(10)
	s_barrier
	s_waitcnt lgkmcnt(0)
	s_setprio 1
	s_waitcnt lgkmcnt(0)
	v_mfma_f32_16x16x32_bf16 v[126:129], v[152:155], v[168:171], v[126:129]
	v_mfma_f32_16x16x32_bf16 v[122:125], v[160:163], v[168:171], v[122:125]
	v_mfma_f32_16x16x32_bf16 v[110:113], v[152:155], v[176:179], v[110:113]
	v_mfma_f32_16x16x32_bf16 v[106:109], v[160:163], v[176:179], v[106:109]
	v_mfma_f32_16x16x32_bf16 v[94:97], v[152:155], v[184:187], v[94:97]
	v_mfma_f32_16x16x32_bf16 v[90:93], v[160:163], v[184:187], v[90:93]
	v_mfma_f32_16x16x32_bf16 v[78:81], v[152:155], v[192:195], v[78:81]
	v_mfma_f32_16x16x32_bf16 v[74:77], v[160:163], v[192:195], v[74:77]
	v_mfma_f32_16x16x32_bf16 v[126:129], v[156:159], v[172:175], v[126:129]
	v_mfma_f32_16x16x32_bf16 v[122:125], v[164:167], v[172:175], v[122:125]
	v_mfma_f32_16x16x32_bf16 v[110:113], v[156:159], v[180:183], v[110:113]
	v_mfma_f32_16x16x32_bf16 v[106:109], v[164:167], v[180:183], v[106:109]
	v_mfma_f32_16x16x32_bf16 v[94:97], v[156:159], v[188:191], v[94:97]
	v_mfma_f32_16x16x32_bf16 v[90:93], v[164:167], v[188:191], v[90:93]
	v_mfma_f32_16x16x32_bf16 v[78:81], v[156:159], v[196:199], v[78:81]
	v_mfma_f32_16x16x32_bf16 v[74:77], v[164:167], v[196:199], v[74:77]
	s_setprio 0
	s_barrier
	s_mov_b32 m0, s72
	v_add_u32_e32 v151, s69, v146
	v_lshl_add_u64 v[142:143], v[142:143], 0, s[16:17]
	ds_read_b128 v[200:203], v151
	ds_read_b128 v[204:207], v151 offset:1024
	ds_read_b128 v[208:211], v151 offset:2048
	ds_read_b128 v[212:215], v151 offset:3072
	global_load_lds_dwordx4 v[142:143], off
	v_lshl_add_u64 v[142:143], v[216:217], 0, s[16:17]
	s_mov_b32 m0, s67
	s_nop 0
	global_load_lds_dwordx4 v[142:143], off
	s_waitcnt vmcnt(10)
	s_barrier
	s_waitcnt lgkmcnt(0)
	s_setprio 1
	s_waitcnt lgkmcnt(0)
	v_mfma_f32_16x16x32_bf16 v[118:121], v[200:203], v[168:171], v[118:121]
	v_mfma_f32_16x16x32_bf16 v[114:117], v[208:211], v[168:171], v[114:117]
	v_mfma_f32_16x16x32_bf16 v[102:105], v[200:203], v[176:179], v[102:105]
	v_mfma_f32_16x16x32_bf16 v[98:101], v[208:211], v[176:179], v[98:101]
	v_mfma_f32_16x16x32_bf16 v[86:89], v[200:203], v[184:187], v[86:89]
	v_mfma_f32_16x16x32_bf16 v[82:85], v[208:211], v[184:187], v[82:85]
	v_mfma_f32_16x16x32_bf16 v[70:73], v[200:203], v[192:195], v[70:73]
	v_mfma_f32_16x16x32_bf16 v[66:69], v[208:211], v[192:195], v[66:69]
	v_mfma_f32_16x16x32_bf16 v[118:121], v[204:207], v[172:175], v[118:121]
	v_mfma_f32_16x16x32_bf16 v[114:117], v[212:215], v[172:175], v[114:117]
	v_mfma_f32_16x16x32_bf16 v[102:105], v[204:207], v[180:183], v[102:105]
	v_mfma_f32_16x16x32_bf16 v[98:101], v[212:215], v[180:183], v[98:101]
	v_mfma_f32_16x16x32_bf16 v[86:89], v[204:207], v[188:191], v[86:89]
	v_mfma_f32_16x16x32_bf16 v[82:85], v[212:215], v[188:191], v[82:85]
	v_mfma_f32_16x16x32_bf16 v[70:73], v[204:207], v[196:199], v[70:73]
	v_mfma_f32_16x16x32_bf16 v[66:69], v[212:215], v[196:199], v[66:69]
	s_setprio 0
	s_mov_b32 m0, s56
	v_lshl_add_u64 v[142:143], v[218:219], 0, s[16:17]
	s_barrier
	ds_read_b128 v[168:171], v148 offset:49152
	ds_read_b128 v[172:175], v148 offset:50176
	ds_read_b128 v[176:179], v148 offset:51200
	ds_read_b128 v[180:183], v148 offset:52224
	ds_read_b128 v[184:187], v148 offset:53248
	ds_read_b128 v[188:191], v148 offset:54272
	ds_read_b128 v[192:195], v148 offset:55296
	ds_read_b128 v[196:199], v148 offset:56320
	global_load_lds_dwordx4 v[142:143], off
	v_lshl_add_u64 v[142:143], v[220:221], 0, s[16:17]
	s_mov_b32 m0, s57
	s_nop 0
	global_load_lds_dwordx4 v[142:143], off
	s_waitcnt vmcnt(10)
	s_barrier
	s_waitcnt lgkmcnt(0)
	s_setprio 1
	s_waitcnt lgkmcnt(0)
	v_mfma_f32_16x16x32_bf16 v[62:65], v[152:155], v[168:171], v[62:65]
	v_mfma_f32_16x16x32_bf16 v[58:61], v[160:163], v[168:171], v[58:61]
	v_mfma_f32_16x16x32_bf16 v[46:49], v[152:155], v[176:179], v[46:49]
	v_mfma_f32_16x16x32_bf16 v[42:45], v[160:163], v[176:179], v[42:45]
	v_mfma_f32_16x16x32_bf16 v[30:33], v[152:155], v[184:187], v[30:33]
	v_mfma_f32_16x16x32_bf16 v[26:29], v[160:163], v[184:187], v[26:29]
	v_mfma_f32_16x16x32_bf16 v[14:17], v[152:155], v[192:195], v[14:17]
	v_mfma_f32_16x16x32_bf16 v[10:13], v[160:163], v[192:195], v[10:13]
	v_mfma_f32_16x16x32_bf16 v[62:65], v[156:159], v[172:175], v[62:65]
	v_mfma_f32_16x16x32_bf16 v[58:61], v[164:167], v[172:175], v[58:61]
	v_mfma_f32_16x16x32_bf16 v[46:49], v[156:159], v[180:183], v[46:49]
	v_mfma_f32_16x16x32_bf16 v[42:45], v[164:167], v[180:183], v[42:45]
	v_mfma_f32_16x16x32_bf16 v[30:33], v[156:159], v[188:191], v[30:33]
	v_mfma_f32_16x16x32_bf16 v[26:29], v[164:167], v[188:191], v[26:29]
	v_mfma_f32_16x16x32_bf16 v[14:17], v[156:159], v[196:199], v[14:17]
	v_mfma_f32_16x16x32_bf16 v[10:13], v[164:167], v[196:199], v[10:13]
	s_setprio 0
	s_barrier
	s_mov_b32 m0, s65
	v_lshl_add_u64 v[142:143], s[36:37], 0, v[134:135]
	global_load_lds_dwordx4 v[142:143], off
	v_lshl_add_u64 v[142:143], s[36:37], 0, v[130:131]
	s_mov_b32 m0, s64
	s_nop 0
	global_load_lds_dwordx4 v[142:143], off
	s_waitcnt vmcnt(10)
	s_barrier
	s_setprio 1
	v_mfma_f32_16x16x32_bf16 v[54:57], v[200:203], v[168:171], v[54:57]
	v_mfma_f32_16x16x32_bf16 v[50:53], v[208:211], v[168:171], v[50:53]
	v_mfma_f32_16x16x32_bf16 v[38:41], v[200:203], v[176:179], v[38:41]
	v_mfma_f32_16x16x32_bf16 v[34:37], v[208:211], v[176:179], v[34:37]
	v_mfma_f32_16x16x32_bf16 v[22:25], v[200:203], v[184:187], v[22:25]
	v_mfma_f32_16x16x32_bf16 v[18:21], v[208:211], v[184:187], v[18:21]
	v_mfma_f32_16x16x32_bf16 v[6:9], v[200:203], v[192:195], v[6:9]
	v_mfma_f32_16x16x32_bf16 v[2:5], v[208:211], v[192:195], v[2:5]
	v_mfma_f32_16x16x32_bf16 v[54:57], v[204:207], v[172:175], v[54:57]
	v_mfma_f32_16x16x32_bf16 v[50:53], v[212:215], v[172:175], v[50:53]
	v_mfma_f32_16x16x32_bf16 v[38:41], v[204:207], v[180:183], v[38:41]
	v_mfma_f32_16x16x32_bf16 v[34:37], v[212:215], v[180:183], v[34:37]
	v_mfma_f32_16x16x32_bf16 v[22:25], v[204:207], v[188:191], v[22:25]
	v_mfma_f32_16x16x32_bf16 v[18:21], v[212:215], v[188:191], v[18:21]
	v_mfma_f32_16x16x32_bf16 v[6:9], v[204:207], v[196:199], v[6:9]
	v_mfma_f32_16x16x32_bf16 v[2:5], v[212:215], v[196:199], v[2:5]
	s_setprio 0
	s_movk_i32 s38, 0x100
	s_andn2_b64 vcc, exec, s[34:35]
	s_mov_b64 s[36:37], -1
	s_mov_b64 s[34:35], 0
	s_barrier
	s_cbranch_vccz .LBB0_2344
	s_lshl_b32 s0, s26, 8
	v_mov_b32_e32 v143, v144
	s_add_i32 s0, s0, s53
	v_mov_b32_e32 v142, v145
	v_add_u32_e32 v151, s0, v143
	v_mov_b32_e32 v154, v151
	v_max_f32_e32 v126, v126, v126
	v_ashrrev_i32_e32 v152, 8, v154
	v_and_b32_e32 v152, -8, v152
	v_add_u32_e32 v152, s55, v152
	v_ashrrev_i32_e32 v153, 31, v152
	v_lshlrev_b64 v[152:153], 11, v[152:153]
	v_and_or_b32 v152, v154, s60, v152
	v_med3_f32 v154, v126, s61, v150
	v_max_f32_e32 v126, v127, v127
	v_med3_f32 v127, v126, s61, v150
	v_mov_b32_e32 v126, 0
	v_cvt_pk_fp8_f32 v126, v154, v127
	v_max_f32_e32 v127, v128, v128
	v_max_f32_e32 v128, v129, v129
	v_med3_f32 v127, v127, s61, v150
	v_med3_f32 v128, v128, s61, v150
	v_max_f32_e32 v122, v122, v122
	v_max_f32_e32 v123, v123, v123
	v_cvt_pk_fp8_f32 v126, v127, v128 op_sel:[0,0,1]
	v_med3_f32 v122, v122, s61, v150
	v_med3_f32 v123, v123, s61, v150
	v_mov_b32_e32 v127, 0
	v_cvt_pk_fp8_f32 v127, v122, v123
	v_max_f32_e32 v122, v124, v124
	v_max_f32_e32 v123, v125, v125
	v_med3_f32 v122, v122, s61, v150
	v_med3_f32 v123, v123, s61, v150
	v_lshl_add_u32 v142, v142, 3, s54
	v_cvt_pk_fp8_f32 v127, v122, v123 op_sel:[0,0,1]
	v_mov_b64_e32 v[122:123], s[12:13]
	v_ashrrev_i32_e32 v143, 31, v142
	v_mad_u64_u32 v[124:125], s[0:1], v152, s51, v[122:123]
	v_cvt_pk_bf16_f32 v118, v118, v119
	v_cvt_pk_bf16_f32 v119, v120, v121
	v_cvt_pk_bf16_f32 v120, v114, v115
	v_lshlrev_b64 v[114:115], 8, v[152:153]
	v_mad_i32_i24 v125, v153, s51, v125
	v_cvt_pk_bf16_f32 v121, v116, v117
	v_lshl_add_u64 v[116:117], s[14:15], 0, v[114:115]
	v_lshlrev_b64 v[114:115], 1, v[142:143]
	v_lshl_add_u64 v[124:125], v[124:125], 0, v[142:143]
	v_lshl_add_u64 v[116:117], v[116:117], 0, v[114:115]
	flat_store_dwordx2 v[124:125], v[126:127] nt
	flat_store_dwordx4 v[116:117], v[118:121] nt
	v_max_f32_e32 v110, v110, v110
	v_max_f32_e32 v106, v106, v106
	v_add_u32_e32 v118, 16, v151
	v_max_f32_e32 v107, v107, v107
	v_ashrrev_i32_e32 v116, 8, v118
	v_and_b32_e32 v116, -8, v116
	v_add_u32_e32 v116, s55, v116
	v_ashrrev_i32_e32 v117, 31, v116
	v_lshlrev_b64 v[116:117], 11, v[116:117]
	v_and_or_b32 v116, v118, s60, v116
	v_med3_f32 v118, v110, s61, v150
	v_max_f32_e32 v110, v111, v111
	v_med3_f32 v111, v110, s61, v150
	v_mov_b32_e32 v110, 0
	v_cvt_pk_fp8_f32 v110, v118, v111
	v_max_f32_e32 v111, v112, v112
	v_max_f32_e32 v112, v113, v113
	v_med3_f32 v111, v111, s61, v150
	v_med3_f32 v112, v112, s61, v150
	v_cvt_pk_fp8_f32 v110, v111, v112 op_sel:[0,0,1]
	v_med3_f32 v106, v106, s61, v150
	v_med3_f32 v107, v107, s61, v150
	v_mov_b32_e32 v111, 0
	v_cvt_pk_fp8_f32 v111, v106, v107
	v_max_f32_e32 v106, v108, v108
	v_max_f32_e32 v107, v109, v109
	v_med3_f32 v106, v106, s61, v150
	v_med3_f32 v107, v107, s61, v150
	v_cvt_pk_fp8_f32 v111, v106, v107 op_sel:[0,0,1]
	v_mad_u64_u32 v[106:107], s[0:1], v116, s51, v[122:123]
	v_cvt_pk_bf16_f32 v102, v102, v103
	v_cvt_pk_bf16_f32 v103, v104, v105
	v_cvt_pk_bf16_f32 v104, v98, v99
	v_lshlrev_b64 v[98:99], 8, v[116:117]
	v_mad_i32_i24 v107, v117, s51, v107
	v_lshl_add_u64 v[98:99], s[14:15], 0, v[98:99]
	v_lshl_add_u64 v[106:107], v[106:107], 0, v[142:143]
	v_cvt_pk_bf16_f32 v105, v100, v101
	v_lshl_add_u64 v[98:99], v[98:99], 0, v[114:115]
	v_add_u32_e32 v100, 32, v151
	flat_store_dwordx2 v[106:107], v[110:111] nt
	flat_store_dwordx4 v[98:99], v[102:105] nt
	v_max_f32_e32 v94, v94, v94
	v_ashrrev_i32_e32 v98, 8, v100
	v_and_b32_e32 v98, -8, v98
	v_add_u32_e32 v98, s55, v98
	v_ashrrev_i32_e32 v99, 31, v98
	v_lshlrev_b64 v[98:99], 11, v[98:99]
	v_and_or_b32 v98, v100, s60, v98
	v_med3_f32 v100, v94, s61, v150
	v_max_f32_e32 v94, v95, v95
	v_med3_f32 v95, v94, s61, v150
	v_mov_b32_e32 v94, 0
	v_cvt_pk_fp8_f32 v94, v100, v95
	v_max_f32_e32 v95, v96, v96
	v_max_f32_e32 v96, v97, v97
	v_med3_f32 v95, v95, s61, v150
	v_med3_f32 v96, v96, s61, v150
	v_max_f32_e32 v90, v90, v90
	v_max_f32_e32 v91, v91, v91
	v_cvt_pk_fp8_f32 v94, v95, v96 op_sel:[0,0,1]
	v_med3_f32 v90, v90, s61, v150
	v_med3_f32 v91, v91, s61, v150
	v_mov_b32_e32 v95, 0
	v_cvt_pk_fp8_f32 v95, v90, v91
	v_max_f32_e32 v90, v92, v92
	v_max_f32_e32 v91, v93, v93
	v_med3_f32 v90, v90, s61, v150
	v_med3_f32 v91, v91, s61, v150
	v_cvt_pk_fp8_f32 v95, v90, v91 op_sel:[0,0,1]
	v_mad_u64_u32 v[90:91], s[0:1], v98, s51, v[122:123]
	v_cvt_pk_bf16_f32 v86, v86, v87
	v_cvt_pk_bf16_f32 v87, v88, v89
	v_cvt_pk_bf16_f32 v88, v82, v83
	v_lshlrev_b64 v[82:83], 8, v[98:99]
	v_mad_i32_i24 v91, v99, s51, v91
	v_lshl_add_u64 v[82:83], s[14:15], 0, v[82:83]
	v_lshl_add_u64 v[90:91], v[90:91], 0, v[142:143]
	v_cvt_pk_bf16_f32 v89, v84, v85
	v_lshl_add_u64 v[82:83], v[82:83], 0, v[114:115]
	v_add_u32_e32 v84, 48, v151
	flat_store_dwordx2 v[90:91], v[94:95] nt
	flat_store_dwordx4 v[82:83], v[86:89] nt
	v_max_f32_e32 v78, v78, v78
	v_ashrrev_i32_e32 v82, 8, v84
	v_and_b32_e32 v82, -8, v82
	v_add_u32_e32 v82, s55, v82
	v_ashrrev_i32_e32 v83, 31, v82
	v_lshlrev_b64 v[82:83], 11, v[82:83]
	v_and_or_b32 v82, v84, s60, v82
	v_med3_f32 v84, v78, s61, v150
	v_max_f32_e32 v78, v79, v79
	v_med3_f32 v79, v78, s61, v150
	v_mov_b32_e32 v78, 0
	v_cvt_pk_fp8_f32 v78, v84, v79
	v_max_f32_e32 v79, v80, v80
	v_max_f32_e32 v80, v81, v81
	v_med3_f32 v79, v79, s61, v150
	v_med3_f32 v80, v80, s61, v150
	v_max_f32_e32 v74, v74, v74
	v_max_f32_e32 v75, v75, v75
	v_cvt_pk_fp8_f32 v78, v79, v80 op_sel:[0,0,1]
	v_med3_f32 v74, v74, s61, v150
	v_med3_f32 v75, v75, s61, v150
	v_mov_b32_e32 v79, 0
	v_cvt_pk_fp8_f32 v79, v74, v75
	v_max_f32_e32 v74, v76, v76
	v_max_f32_e32 v75, v77, v77
	v_med3_f32 v74, v74, s61, v150
	v_med3_f32 v75, v75, s61, v150
	v_cvt_pk_fp8_f32 v79, v74, v75 op_sel:[0,0,1]
	v_mad_u64_u32 v[74:75], s[0:1], v82, s51, v[122:123]
	v_cvt_pk_bf16_f32 v70, v70, v71
	v_cvt_pk_bf16_f32 v71, v72, v73
	v_cvt_pk_bf16_f32 v72, v66, v67
	v_lshlrev_b64 v[66:67], 8, v[82:83]
	v_mad_i32_i24 v75, v83, s51, v75
	v_lshl_add_u64 v[66:67], s[14:15], 0, v[66:67]
	v_lshl_add_u64 v[74:75], v[74:75], 0, v[142:143]
	v_cvt_pk_bf16_f32 v73, v68, v69
	v_lshl_add_u64 v[66:67], v[66:67], 0, v[114:115]
	v_add_u32_e32 v68, 0x80, v151
	flat_store_dwordx2 v[74:75], v[78:79] nt
	flat_store_dwordx4 v[66:67], v[70:73] nt
	v_max_f32_e32 v62, v62, v62
	v_ashrrev_i32_e32 v66, 8, v68
	v_and_b32_e32 v66, -8, v66
	v_add_u32_e32 v66, s55, v66
	v_ashrrev_i32_e32 v67, 31, v66
	v_lshlrev_b64 v[66:67], 11, v[66:67]
	v_and_or_b32 v66, v68, s60, v66
	v_med3_f32 v68, v62, s61, v150
	v_max_f32_e32 v62, v63, v63
	v_med3_f32 v63, v62, s61, v150
	v_mov_b32_e32 v62, 0
	v_cvt_pk_fp8_f32 v62, v68, v63
	v_max_f32_e32 v63, v64, v64
	v_max_f32_e32 v64, v65, v65
	v_med3_f32 v63, v63, s61, v150
	v_med3_f32 v64, v64, s61, v150
	v_max_f32_e32 v58, v58, v58
	v_max_f32_e32 v59, v59, v59
	v_cvt_pk_fp8_f32 v62, v63, v64 op_sel:[0,0,1]
	v_med3_f32 v58, v58, s61, v150
	v_med3_f32 v59, v59, s61, v150
	v_mov_b32_e32 v63, 0
	v_cvt_pk_fp8_f32 v63, v58, v59
	v_max_f32_e32 v58, v60, v60
	v_max_f32_e32 v59, v61, v61
	v_med3_f32 v58, v58, s61, v150
	v_med3_f32 v59, v59, s61, v150
	v_cvt_pk_fp8_f32 v63, v58, v59 op_sel:[0,0,1]
	v_mad_u64_u32 v[58:59], s[0:1], v66, s51, v[122:123]
	v_cvt_pk_bf16_f32 v54, v54, v55
	v_cvt_pk_bf16_f32 v55, v56, v57
	v_cvt_pk_bf16_f32 v56, v50, v51
	v_lshlrev_b64 v[50:51], 8, v[66:67]
	v_mad_i32_i24 v59, v67, s51, v59
	v_lshl_add_u64 v[50:51], s[14:15], 0, v[50:51]
	v_lshl_add_u64 v[58:59], v[58:59], 0, v[142:143]
	v_cvt_pk_bf16_f32 v57, v52, v53
	v_lshl_add_u64 v[50:51], v[50:51], 0, v[114:115]
	v_add_u32_e32 v52, 0x90, v151
	flat_store_dwordx2 v[58:59], v[62:63] nt
	flat_store_dwordx4 v[50:51], v[54:57] nt
	v_max_f32_e32 v46, v46, v46
	v_ashrrev_i32_e32 v50, 8, v52
	v_and_b32_e32 v50, -8, v50
	v_add_u32_e32 v50, s55, v50
	v_ashrrev_i32_e32 v51, 31, v50
	v_lshlrev_b64 v[50:51], 11, v[50:51]
	v_and_or_b32 v50, v52, s60, v50
	v_med3_f32 v52, v46, s61, v150
	v_max_f32_e32 v46, v47, v47
	v_med3_f32 v47, v46, s61, v150
	v_mov_b32_e32 v46, 0
	v_cvt_pk_fp8_f32 v46, v52, v47
	v_max_f32_e32 v47, v48, v48
	v_max_f32_e32 v48, v49, v49
	v_med3_f32 v47, v47, s61, v150
	v_med3_f32 v48, v48, s61, v150
	v_max_f32_e32 v42, v42, v42
	v_max_f32_e32 v43, v43, v43
	v_cvt_pk_fp8_f32 v46, v47, v48 op_sel:[0,0,1]
	v_med3_f32 v42, v42, s61, v150
	v_med3_f32 v43, v43, s61, v150
	v_mov_b32_e32 v47, 0
	v_cvt_pk_fp8_f32 v47, v42, v43
	v_max_f32_e32 v42, v44, v44
	v_max_f32_e32 v43, v45, v45
	v_med3_f32 v42, v42, s61, v150
	v_med3_f32 v43, v43, s61, v150
	v_cvt_pk_fp8_f32 v47, v42, v43 op_sel:[0,0,1]
	v_mad_u64_u32 v[42:43], s[0:1], v50, s51, v[122:123]
	v_cvt_pk_bf16_f32 v38, v38, v39
	v_cvt_pk_bf16_f32 v39, v40, v41
	v_cvt_pk_bf16_f32 v40, v34, v35
	v_lshlrev_b64 v[34:35], 8, v[50:51]
	v_mad_i32_i24 v43, v51, s51, v43
	v_lshl_add_u64 v[34:35], s[14:15], 0, v[34:35]
	v_lshl_add_u64 v[42:43], v[42:43], 0, v[142:143]
	v_cvt_pk_bf16_f32 v41, v36, v37
	v_lshl_add_u64 v[34:35], v[34:35], 0, v[114:115]
	v_add_u32_e32 v36, 0xa0, v151
	flat_store_dwordx2 v[42:43], v[46:47] nt
	flat_store_dwordx4 v[34:35], v[38:41] nt
	v_max_f32_e32 v30, v30, v30
	v_ashrrev_i32_e32 v34, 8, v36
	v_and_b32_e32 v34, -8, v34
	v_add_u32_e32 v34, s55, v34
	v_ashrrev_i32_e32 v35, 31, v34
	v_lshlrev_b64 v[34:35], 11, v[34:35]
	v_and_or_b32 v34, v36, s60, v34
	v_med3_f32 v36, v30, s61, v150
	v_max_f32_e32 v30, v31, v31
	v_med3_f32 v31, v30, s61, v150
	v_mov_b32_e32 v30, 0
	v_cvt_pk_fp8_f32 v30, v36, v31
	v_max_f32_e32 v31, v32, v32
	v_max_f32_e32 v32, v33, v33
	v_med3_f32 v31, v31, s61, v150
	v_med3_f32 v32, v32, s61, v150
	v_max_f32_e32 v26, v26, v26
	v_max_f32_e32 v27, v27, v27
	v_cvt_pk_fp8_f32 v30, v31, v32 op_sel:[0,0,1]
	v_med3_f32 v26, v26, s61, v150
	v_med3_f32 v27, v27, s61, v150
	v_mov_b32_e32 v31, 0
	v_cvt_pk_fp8_f32 v31, v26, v27
	v_max_f32_e32 v26, v28, v28
	v_max_f32_e32 v27, v29, v29
	v_med3_f32 v26, v26, s61, v150
	v_med3_f32 v27, v27, s61, v150
	v_cvt_pk_fp8_f32 v31, v26, v27 op_sel:[0,0,1]
	v_mad_u64_u32 v[26:27], s[0:1], v34, s51, v[122:123]
	v_cvt_pk_bf16_f32 v22, v22, v23
	v_cvt_pk_bf16_f32 v23, v24, v25
	v_cvt_pk_bf16_f32 v24, v18, v19
	v_lshlrev_b64 v[18:19], 8, v[34:35]
	v_mad_i32_i24 v27, v35, s51, v27
	v_lshl_add_u64 v[18:19], s[14:15], 0, v[18:19]
	v_lshl_add_u64 v[26:27], v[26:27], 0, v[142:143]
	v_cvt_pk_bf16_f32 v25, v20, v21
	v_lshl_add_u64 v[18:19], v[18:19], 0, v[114:115]
	v_add_u32_e32 v20, 0xb0, v151
	flat_store_dwordx2 v[26:27], v[30:31] nt
	flat_store_dwordx4 v[18:19], v[22:25] nt
	v_max_f32_e32 v14, v14, v14
	v_ashrrev_i32_e32 v18, 8, v20
	v_and_b32_e32 v18, -8, v18
	v_add_u32_e32 v18, s55, v18
	v_ashrrev_i32_e32 v19, 31, v18
	v_lshlrev_b64 v[18:19], 11, v[18:19]
	v_and_or_b32 v18, v20, s60, v18
	v_med3_f32 v20, v14, s61, v150
	v_max_f32_e32 v14, v15, v15
	v_med3_f32 v15, v14, s61, v150
	v_mov_b32_e32 v14, 0
	v_cvt_pk_fp8_f32 v14, v20, v15
	v_max_f32_e32 v15, v16, v16
	v_max_f32_e32 v16, v17, v17
	v_med3_f32 v15, v15, s61, v150
	v_med3_f32 v16, v16, s61, v150
	v_max_f32_e32 v10, v10, v10
	v_max_f32_e32 v11, v11, v11
	v_cvt_pk_fp8_f32 v14, v15, v16 op_sel:[0,0,1]
	v_med3_f32 v10, v10, s61, v150
	v_med3_f32 v11, v11, s61, v150
	v_mov_b32_e32 v15, 0
	v_cvt_pk_fp8_f32 v15, v10, v11
	v_max_f32_e32 v10, v12, v12
	v_max_f32_e32 v11, v13, v13
	v_med3_f32 v10, v10, s61, v150
	v_med3_f32 v11, v11, s61, v150
	v_cvt_pk_fp8_f32 v15, v10, v11 op_sel:[0,0,1]
	v_mad_u64_u32 v[10:11], s[0:1], v18, s51, v[122:123]
	v_cvt_pk_bf16_f32 v6, v6, v7
	v_cvt_pk_bf16_f32 v7, v8, v9
	v_cvt_pk_bf16_f32 v8, v2, v3
	v_lshlrev_b64 v[2:3], 8, v[18:19]
	v_mad_i32_i24 v11, v19, s51, v11
	v_lshl_add_u64 v[2:3], s[14:15], 0, v[2:3]
	v_readlane_b32 s72, v254, 2
	v_lshl_add_u64 v[10:11], v[10:11], 0, v[142:143]
	v_cvt_pk_bf16_f32 v9, v4, v5
	v_lshl_add_u64 v[2:3], v[2:3], 0, v[114:115]
	s_and_b64 vcc, exec, s[10:11]
	s_mov_b32 s55, s18
	s_mov_b32 s26, s20
	s_mov_b64 s[28:29], s[24:25]
	s_mov_b64 s[30:31], s[22:23]
	v_readlane_b32 s73, v254, 3
	flat_store_dwordx2 v[10:11], v[14:15] nt
	flat_store_dwordx4 v[2:3], v[6:9] nt
	s_cbranch_vccz .LBB0_2337
	s_waitcnt vmcnt(0)
	s_cmpk_gt_u32 s5, 0xff
	s_cbranch_scc1 .LBB0_2348
	s_barrier

.LBB0_2749:
	s_add_u32 s10, s34, 0x100
	s_addc_u32 s11, s35, 0
	s_add_u32 s30, s29, s34
	s_addc_u32 s31, s55, s35
	s_cmpk_eq_i32 s34, 0x300
	s_cselect_b64 vcc, -1, 0
	s_and_b64 s[0:1], vcc, exec
	s_cselect_b32 s1, 0, s10
	s_cselect_b32 s0, 0, s11
	s_cselect_b32 s30, s27, s30
	s_cselect_b32 s31, s25, s31
	s_add_u32 s36, s14, s1
	s_addc_u32 s37, s15, s0
	s_add_i32 s1, 0, 0x10000
	v_add_u32_e32 v14, s1, v196
	ds_read_b128 v[2:5], v14
	ds_read_b128 v[6:9], v14 offset:1024
	ds_read_b128 v[10:13], v14 offset:2048
	ds_read_b128 v[14:17], v14 offset:3072
	v_cndmask_b32_e32 v162, v168, v171, vcc
	v_cndmask_b32_e32 v184, v170, v197, vcc
	v_cndmask_b32_e32 v175, v172, v198, vcc
	v_cndmask_b32_e32 v173, v174, v199, vcc
	v_lshl_add_u64 v[18:19], v[178:179], 0, s[34:35]
	s_add_i32 m0, s45, 0xc000
	ds_read_b128 v[200:203], v169
	ds_read_b128 v[204:207], v169 offset:1024
	ds_read_b128 v[208:211], v169 offset:2048
	ds_read_b128 v[212:215], v169 offset:3072
	ds_read_b128 v[216:219], v169 offset:4096
	ds_read_b128 v[220:223], v169 offset:5120
	ds_read_b128 v[224:227], v169 offset:6144
	ds_read_b128 v[228:231], v169 offset:7168
	global_load_lds_dwordx4 v[18:19], off
	v_lshl_add_u64 v[18:19], v[176:177], 0, s[34:35]
	s_add_i32 m0, s45, 0xe000
	s_nop 0
	global_load_lds_dwordx4 v[18:19], off
	s_waitcnt lgkmcnt(8)
	s_waitcnt vmcnt(10)
	s_barrier
	s_waitcnt lgkmcnt(0)
	s_setprio 1
	s_waitcnt lgkmcnt(0)
	v_mfma_scale_f32_16x16x128_f8f6f4 v[158:161], v[2:9], v[200:207], v[158:161], v1, v1 op_sel_hi:[0,0,0]
	v_mfma_scale_f32_16x16x128_f8f6f4 v[150:153], v[10:17], v[200:207], v[150:153], v1, v1 op_sel_hi:[0,0,0]
	v_mfma_scale_f32_16x16x128_f8f6f4 v[142:145], v[2:9], v[208:215], v[142:145], v1, v1 op_sel_hi:[0,0,0]
	v_mfma_scale_f32_16x16x128_f8f6f4 v[134:137], v[10:17], v[208:215], v[134:137], v1, v1 op_sel_hi:[0,0,0]
	v_mfma_scale_f32_16x16x128_f8f6f4 v[126:129], v[2:9], v[216:223], v[126:129], v1, v1 op_sel_hi:[0,0,0]
	v_mfma_scale_f32_16x16x128_f8f6f4 v[118:121], v[10:17], v[216:223], v[118:121], v1, v1 op_sel_hi:[0,0,0]
	v_mfma_scale_f32_16x16x128_f8f6f4 v[110:113], v[2:9], v[224:231], v[110:113], v1, v1 op_sel_hi:[0,0,0]
	v_mfma_scale_f32_16x16x128_f8f6f4 v[102:105], v[10:17], v[224:231], v[102:105], v1, v1 op_sel_hi:[0,0,0]
	s_setprio 0
	s_barrier
	s_add_i32 s0, 0, 0x14000
	s_add_i32 s1, s1, s43
	v_add_u32_e32 v30, s0, v196
	v_lshl_add_u64 v[180:181], s[30:31], 0, v[164:165]
	s_mov_b32 m0, s1
	ds_read_b128 v[18:21], v30
	ds_read_b128 v[22:25], v30 offset:1024
	ds_read_b128 v[26:29], v30 offset:2048
	ds_read_b128 v[30:33], v30 offset:3072
	global_load_lds_dwordx4 v[180:181], off
	v_lshl_add_u64 v[182:183], s[30:31], 0, v[166:167]
	s_add_i32 m0, s1, 0x2000
	s_nop 0
	global_load_lds_dwordx4 v[182:183], off
	s_waitcnt vmcnt(10)
	s_barrier
	s_waitcnt lgkmcnt(0)
	s_setprio 1
	s_waitcnt lgkmcnt(0)
	v_mfma_scale_f32_16x16x128_f8f6f4 v[154:157], v[18:25], v[200:207], v[154:157], v1, v1 op_sel_hi:[0,0,0]
	v_mfma_scale_f32_16x16x128_f8f6f4 v[146:149], v[26:33], v[200:207], v[146:149], v1, v1 op_sel_hi:[0,0,0]
	v_mfma_scale_f32_16x16x128_f8f6f4 v[138:141], v[18:25], v[208:215], v[138:141], v1, v1 op_sel_hi:[0,0,0]
	v_mfma_scale_f32_16x16x128_f8f6f4 v[130:133], v[26:33], v[208:215], v[130:133], v1, v1 op_sel_hi:[0,0,0]
	v_mfma_scale_f32_16x16x128_f8f6f4 v[122:125], v[18:25], v[216:223], v[122:125], v1, v1 op_sel_hi:[0,0,0]
	v_mfma_scale_f32_16x16x128_f8f6f4 v[114:117], v[26:33], v[216:223], v[114:117], v1, v1 op_sel_hi:[0,0,0]
	v_mfma_scale_f32_16x16x128_f8f6f4 v[106:109], v[18:25], v[224:231], v[106:109], v1, v1 op_sel_hi:[0,0,0]
	v_mfma_scale_f32_16x16x128_f8f6f4 v[98:101], v[26:33], v[224:231], v[98:101], v1, v1 op_sel_hi:[0,0,0]
	s_setprio 0
	s_mov_b32 m0, s45
	s_barrier
	ds_read_b128 v[200:203], v169 offset:16384
	ds_read_b128 v[204:207], v169 offset:17408
	ds_read_b128 v[208:211], v169 offset:18432
	ds_read_b128 v[212:215], v169 offset:19456
	ds_read_b128 v[216:219], v169 offset:20480
	ds_read_b128 v[220:223], v169 offset:21504
	ds_read_b128 v[224:227], v169 offset:22528
	ds_read_b128 v[228:231], v169 offset:23552
	global_load_lds_dwordx4 v162, s[36:37]
	s_mov_b32 m0, s46
	v_mov_b32_e32 v185, v163
	global_load_lds_dwordx4 v184, s[36:37]
	s_waitcnt vmcnt(10)
	s_barrier
	s_waitcnt lgkmcnt(0)
	v_lshl_add_u64 v[186:187], s[36:37], 0, v[162:163]
	v_lshl_add_u64 v[184:185], s[36:37], 0, v[184:185]
	s_setprio 1
	s_waitcnt lgkmcnt(0)
	v_mfma_scale_f32_16x16x128_f8f6f4 v[94:97], v[2:9], v[200:207], v[94:97], v1, v1 op_sel_hi:[0,0,0]
	v_mfma_scale_f32_16x16x128_f8f6f4 v[86:89], v[10:17], v[200:207], v[86:89], v1, v1 op_sel_hi:[0,0,0]
	v_mfma_scale_f32_16x16x128_f8f6f4 v[78:81], v[2:9], v[208:215], v[78:81], v1, v1 op_sel_hi:[0,0,0]
	v_mfma_scale_f32_16x16x128_f8f6f4 v[70:73], v[10:17], v[208:215], v[70:73], v1, v1 op_sel_hi:[0,0,0]
	v_mfma_scale_f32_16x16x128_f8f6f4 v[62:65], v[2:9], v[216:223], v[62:65], v1, v1 op_sel_hi:[0,0,0]
	v_mfma_scale_f32_16x16x128_f8f6f4 v[54:57], v[10:17], v[216:223], v[54:57], v1, v1 op_sel_hi:[0,0,0]
	v_mfma_scale_f32_16x16x128_f8f6f4 v[46:49], v[2:9], v[224:231], v[46:49], v1, v1 op_sel_hi:[0,0,0]
	v_mfma_scale_f32_16x16x128_f8f6f4 v[38:41], v[10:17], v[224:231], v[38:41], v1, v1 op_sel_hi:[0,0,0]
	s_setprio 0
	s_barrier
	s_add_u32 s34, s30, 0x20000
	s_addc_u32 s35, s31, 0
	s_add_i32 s0, s0, s43
	v_lshl_add_u64 v[2:3], s[34:35], 0, v[164:165]
	s_mov_b32 m0, s0
	s_nop 0
	global_load_lds_dwordx4 v[2:3], off
	v_lshl_add_u64 v[2:3], s[34:35], 0, v[166:167]
	s_add_i32 m0, s0, 0x2000
	s_nop 0
	global_load_lds_dwordx4 v[2:3], off
	s_waitcnt vmcnt(10)
	s_barrier
	s_setprio 1
	v_mfma_scale_f32_16x16x128_f8f6f4 v[90:93], v[18:25], v[200:207], v[90:93], v1, v1 op_sel_hi:[0,0,0]
	v_mfma_scale_f32_16x16x128_f8f6f4 v[82:85], v[26:33], v[200:207], v[82:85], v1, v1 op_sel_hi:[0,0,0]
	v_mfma_scale_f32_16x16x128_f8f6f4 v[74:77], v[18:25], v[208:215], v[74:77], v1, v1 op_sel_hi:[0,0,0]
	v_mfma_scale_f32_16x16x128_f8f6f4 v[66:69], v[26:33], v[208:215], v[66:69], v1, v1 op_sel_hi:[0,0,0]
	v_mfma_scale_f32_16x16x128_f8f6f4 v[58:61], v[18:25], v[216:223], v[58:61], v1, v1 op_sel_hi:[0,0,0]
	v_mfma_scale_f32_16x16x128_f8f6f4 v[50:53], v[26:33], v[216:223], v[50:53], v1, v1 op_sel_hi:[0,0,0]
	v_mfma_scale_f32_16x16x128_f8f6f4 v[42:45], v[18:25], v[224:231], v[42:45], v1, v1 op_sel_hi:[0,0,0]
	v_mfma_scale_f32_16x16x128_f8f6f4 v[34:37], v[26:33], v[224:231], v[34:37], v1, v1 op_sel_hi:[0,0,0]
	s_setprio 0
	s_add_i32 s0, 0, 0x18000
	v_add_u32_e32 v14, s0, v196
	s_barrier
	ds_read_b128 v[2:5], v14
	ds_read_b128 v[6:9], v14 offset:1024
	ds_read_b128 v[10:13], v14 offset:2048
	ds_read_b128 v[14:17], v14 offset:3072
	s_mov_b32 m0, s47
	ds_read_b128 v[18:21], v169 offset:32768
	ds_read_b128 v[22:25], v169 offset:33792
	ds_read_b128 v[26:29], v169 offset:34816
	ds_read_b128 v[30:33], v169 offset:35840
	ds_read_b128 v[200:203], v169 offset:36864
	ds_read_b128 v[204:207], v169 offset:37888
	ds_read_b128 v[208:211], v169 offset:38912
	ds_read_b128 v[212:215], v169 offset:39936
	global_load_lds_dwordx4 v175, s[36:37]
	s_mov_b32 m0, s48
	s_nop 0
	global_load_lds_dwordx4 v173, s[36:37]
	s_waitcnt lgkmcnt(8)
	s_waitcnt vmcnt(10)
	s_barrier
	s_waitcnt lgkmcnt(0)
	s_setprio 1
	s_waitcnt lgkmcnt(0)
	v_mfma_scale_f32_16x16x128_f8f6f4 v[158:161], v[2:9], v[18:25], v[158:161], v1, v1 op_sel_hi:[0,0,0]
	v_mfma_scale_f32_16x16x128_f8f6f4 v[150:153], v[10:17], v[18:25], v[150:153], v1, v1 op_sel_hi:[0,0,0]
	v_mfma_scale_f32_16x16x128_f8f6f4 v[142:145], v[2:9], v[26:33], v[142:145], v1, v1 op_sel_hi:[0,0,0]
	v_mfma_scale_f32_16x16x128_f8f6f4 v[134:137], v[10:17], v[26:33], v[134:137], v1, v1 op_sel_hi:[0,0,0]
	v_mfma_scale_f32_16x16x128_f8f6f4 v[126:129], v[2:9], v[200:207], v[126:129], v1, v1 op_sel_hi:[0,0,0]
	v_mfma_scale_f32_16x16x128_f8f6f4 v[118:121], v[10:17], v[200:207], v[118:121], v1, v1 op_sel_hi:[0,0,0]
	v_mfma_scale_f32_16x16x128_f8f6f4 v[110:113], v[2:9], v[208:215], v[110:113], v1, v1 op_sel_hi:[0,0,0]
	v_mfma_scale_f32_16x16x128_f8f6f4 v[102:105], v[10:17], v[208:215], v[102:105], v1, v1 op_sel_hi:[0,0,0]
	s_setprio 0
	s_barrier
	s_add_i32 s34, 0, 0x1c000
	s_add_i32 s0, s0, s43
	v_add_u32_e32 v162, s34, v196
	v_lshl_add_u64 v[180:181], v[180:181], 0, s[20:21]
	s_mov_b32 m0, s0
	ds_read_b128 v[216:219], v162
	ds_read_b128 v[220:223], v162 offset:1024
	ds_read_b128 v[224:227], v162 offset:2048
	ds_read_b128 v[228:231], v162 offset:3072
	global_load_lds_dwordx4 v[180:181], off
	v_lshl_add_u64 v[180:181], v[182:183], 0, s[20:21]
	s_add_i32 m0, s0, 0x2000
	s_nop 0
	global_load_lds_dwordx4 v[180:181], off
	s_waitcnt vmcnt(10)
	s_barrier
	s_waitcnt lgkmcnt(0)
	s_setprio 1
	s_waitcnt lgkmcnt(0)
	v_mfma_scale_f32_16x16x128_f8f6f4 v[154:157], v[216:223], v[18:25], v[154:157], v1, v1 op_sel_hi:[0,0,0]
	v_mfma_scale_f32_16x16x128_f8f6f4 v[146:149], v[224:231], v[18:25], v[146:149], v1, v1 op_sel_hi:[0,0,0]
	v_mfma_scale_f32_16x16x128_f8f6f4 v[138:141], v[216:223], v[26:33], v[138:141], v1, v1 op_sel_hi:[0,0,0]
	v_mfma_scale_f32_16x16x128_f8f6f4 v[130:133], v[224:231], v[26:33], v[130:133], v1, v1 op_sel_hi:[0,0,0]
	v_mfma_scale_f32_16x16x128_f8f6f4 v[122:125], v[216:223], v[200:207], v[122:125], v1, v1 op_sel_hi:[0,0,0]
	v_mfma_scale_f32_16x16x128_f8f6f4 v[114:117], v[224:231], v[200:207], v[114:117], v1, v1 op_sel_hi:[0,0,0]
	v_mfma_scale_f32_16x16x128_f8f6f4 v[106:109], v[216:223], v[208:215], v[106:109], v1, v1 op_sel_hi:[0,0,0]
	v_mfma_scale_f32_16x16x128_f8f6f4 v[98:101], v[224:231], v[208:215], v[98:101], v1, v1 op_sel_hi:[0,0,0]
	s_setprio 0
	s_mov_b32 m0, s51
	v_lshl_add_u64 v[180:181], v[186:187], 0, s[20:21]
	s_barrier
	ds_read_b128 v[18:21], v169 offset:49152
	ds_read_b128 v[22:25], v169 offset:50176
	ds_read_b128 v[26:29], v169 offset:51200
	ds_read_b128 v[30:33], v169 offset:52224
	ds_read_b128 v[200:203], v169 offset:53248
	ds_read_b128 v[204:207], v169 offset:54272
	ds_read_b128 v[208:211], v169 offset:55296
	ds_read_b128 v[212:215], v169 offset:56320
	global_load_lds_dwordx4 v[180:181], off
	v_lshl_add_u64 v[180:181], v[184:185], 0, s[20:21]
	s_mov_b32 m0, s52
	s_nop 0
	global_load_lds_dwordx4 v[180:181], off
	s_waitcnt vmcnt(10)
	s_barrier
	s_waitcnt lgkmcnt(0)
	s_setprio 1
	s_waitcnt lgkmcnt(0)
	v_mfma_scale_f32_16x16x128_f8f6f4 v[94:97], v[2:9], v[18:25], v[94:97], v1, v1 op_sel_hi:[0,0,0]
	v_mfma_scale_f32_16x16x128_f8f6f4 v[86:89], v[10:17], v[18:25], v[86:89], v1, v1 op_sel_hi:[0,0,0]
	v_mfma_scale_f32_16x16x128_f8f6f4 v[78:81], v[2:9], v[26:33], v[78:81], v1, v1 op_sel_hi:[0,0,0]
	v_mfma_scale_f32_16x16x128_f8f6f4 v[70:73], v[10:17], v[26:33], v[70:73], v1, v1 op_sel_hi:[0,0,0]
	v_mfma_scale_f32_16x16x128_f8f6f4 v[62:65], v[2:9], v[200:207], v[62:65], v1, v1 op_sel_hi:[0,0,0]
	v_mfma_scale_f32_16x16x128_f8f6f4 v[54:57], v[10:17], v[200:207], v[54:57], v1, v1 op_sel_hi:[0,0,0]
	v_mfma_scale_f32_16x16x128_f8f6f4 v[46:49], v[2:9], v[208:215], v[46:49], v1, v1 op_sel_hi:[0,0,0]
	v_mfma_scale_f32_16x16x128_f8f6f4 v[38:41], v[10:17], v[208:215], v[38:41], v1, v1 op_sel_hi:[0,0,0]
	s_setprio 0
	s_barrier
	s_add_u32 s0, s30, 0x20080
	s_addc_u32 s1, s31, 0
	s_add_i32 s30, s34, s43
	v_lshl_add_u64 v[2:3], s[0:1], 0, v[164:165]
	s_mov_b32 m0, s30
	s_nop 0
	global_load_lds_dwordx4 v[2:3], off
	v_lshl_add_u64 v[2:3], s[0:1], 0, v[166:167]
	s_add_i32 m0, s30, 0x2000
	s_nop 0
	global_load_lds_dwordx4 v[2:3], off
	s_waitcnt vmcnt(10)
	s_barrier
	s_setprio 1
	v_mfma_scale_f32_16x16x128_f8f6f4 v[90:93], v[216:223], v[18:25], v[90:93], v1, v1 op_sel_hi:[0,0,0]
	v_mfma_scale_f32_16x16x128_f8f6f4 v[82:85], v[224:231], v[18:25], v[82:85], v1, v1 op_sel_hi:[0,0,0]
	v_mfma_scale_f32_16x16x128_f8f6f4 v[74:77], v[216:223], v[26:33], v[74:77], v1, v1 op_sel_hi:[0,0,0]
	v_mfma_scale_f32_16x16x128_f8f6f4 v[66:69], v[224:231], v[26:33], v[66:69], v1, v1 op_sel_hi:[0,0,0]
	v_mfma_scale_f32_16x16x128_f8f6f4 v[58:61], v[216:223], v[200:207], v[58:61], v1, v1 op_sel_hi:[0,0,0]
	v_mfma_scale_f32_16x16x128_f8f6f4 v[50:53], v[224:231], v[200:207], v[50:53], v1, v1 op_sel_hi:[0,0,0]
	v_mfma_scale_f32_16x16x128_f8f6f4 v[42:45], v[216:223], v[208:215], v[42:45], v1, v1 op_sel_hi:[0,0,0]
	v_mfma_scale_f32_16x16x128_f8f6f4 v[34:37], v[224:231], v[208:215], v[34:37], v1, v1 op_sel_hi:[0,0,0]
	s_setprio 0
	s_add_i32 s56, s56, 2
	s_cmp_gt_u32 s56, 5
	s_mov_b64 s[34:35], s[10:11]
	s_barrier
	s_cbranch_scc0 .LBB0_2749
	v_mul_f32_e32 v5, 0x3c800000, v158
	v_mul_f32_e32 v6, 0xbfb8aa3b, v5
	v_exp_f32_e32 v6, v6
	s_ashr_i32 s29, s28, 31
	s_ashr_i32 s27, s26, 31
	s_lshl_b64 s[10:11], s[28:29], 18
	v_add_f32_e32 v6, 1.0, v6
	v_rcp_f32_e32 v6, v6
	s_lshl_b64 s[26:27], s[26:27], 15
	v_mov_b32_e32 v3, v194
	s_add_u32 s0, s8, s10
	v_mul_f32_e32 v5, v5, v6
	v_mul_f32_e32 v6, 0x3c800000, v159
	v_mul_f32_e32 v7, 0xbfb8aa3b, v6
	v_exp_f32_e32 v7, v7
	v_mul_f32_e32 v5, v5, v154
	v_mul_f32_e32 v5, 0x3e000000, v5
	v_med3_f32 v5, v5, s40, v189
	v_add_f32_e32 v7, 1.0, v7
	v_rcp_f32_e32 v7, v7
	s_nop 15
	s_nop 15
	v_mov_b32_e32 v2, v195
	v_mul_f32_e32 v6, v6, v7
	v_mul_f32_e32 v7, 0x3c800000, v160
	v_mul_f32_e32 v8, 0xbfb8aa3b, v7
	v_exp_f32_e32 v8, v8
	v_mul_f32_e32 v6, v6, v155
	v_mul_f32_e32 v6, 0x3e000000, v6
	v_add_u32_e32 v4, s49, v3
	v_add_f32_e32 v8, 1.0, v8
	v_rcp_f32_e32 v8, v8
	s_addc_u32 s1, s9, s11
	s_add_u32 s10, s0, s26
	v_mul_f32_e32 v7, v7, v8
	v_mul_f32_e32 v8, 0x3c800000, v161
	v_mul_f32_e32 v9, 0xbfb8aa3b, v8
	v_exp_f32_e32 v9, v9
	v_mul_f32_e32 v7, v7, v156
	v_mul_f32_e32 v7, 0x3e000000, v7
	v_lshl_add_u32 v2, v2, 3, s50
	v_add_f32_e32 v9, 1.0, v9
	v_rcp_f32_e32 v9, v9
	s_addc_u32 s11, s1, s27
	v_ashrrev_i32_e32 v3, 31, v2
	s_and_b64 vcc, exec, s[6:7]
	v_mul_f32_e32 v8, v8, v9
	v_mul_f32_e32 v9, 0x3c800000, v150
	v_mul_f32_e32 v10, 0xbfb8aa3b, v9
	v_exp_f32_e32 v10, v10
	v_mul_f32_e32 v8, v8, v157
	v_mul_f32_e32 v8, 0x3e000000, v8
	v_mov_b32_e32 v174, v199
	v_add_f32_e32 v10, 1.0, v10
	v_rcp_f32_e32 v10, v10
	v_mov_b32_e32 v172, v198
	v_mov_b32_e32 v170, v197
	v_mov_b32_e32 v168, v171
	v_mul_f32_e32 v9, v9, v10
	v_mul_f32_e32 v10, 0x3c800000, v151
	v_mul_f32_e32 v11, 0xbfb8aa3b, v10
	v_exp_f32_e32 v11, v11
	v_mul_f32_e32 v9, v9, v146
	v_mul_f32_e32 v9, 0x3e000000, v9
	s_mov_b32 s26, s24
	v_add_f32_e32 v11, 1.0, v11
	v_rcp_f32_e32 v11, v11
	s_mov_b32 s28, s54
	s_mov_b64 s[30:31], s[12:13]
	v_mul_f32_e32 v10, v10, v11
	v_mul_f32_e32 v11, 0x3c800000, v152
	v_mul_f32_e32 v12, 0xbfb8aa3b, v11
	v_exp_f32_e32 v12, v12
	v_mul_f32_e32 v10, v10, v147
	v_mul_f32_e32 v10, 0x3e000000, v10
	v_add_f32_e32 v12, 1.0, v12
	v_rcp_f32_e32 v12, v12
	s_nop 0
	v_mul_f32_e32 v11, v11, v12
	v_mul_f32_e32 v12, 0x3c800000, v153
	v_mul_f32_e32 v13, 0xbfb8aa3b, v12
	v_exp_f32_e32 v13, v13
	v_mul_f32_e32 v11, v11, v148
	v_mul_f32_e32 v11, 0x3e000000, v11
	v_add_f32_e32 v13, 1.0, v13
	v_rcp_f32_e32 v13, v13
	s_nop 0
	v_mul_f32_e32 v12, v12, v13
	v_med3_f32 v13, v6, s40, v189
	v_mov_b32_e32 v6, v163
	v_cvt_pk_fp8_f32 v6, v5, v13
	v_med3_f32 v5, v7, s40, v189
	v_med3_f32 v7, v8, s40, v189
	v_med3_f32 v8, v10, s40, v189
	v_cvt_pk_fp8_f32 v6, v5, v7 op_sel:[0,0,1]
	v_med3_f32 v5, v9, s40, v189
	v_mov_b32_e32 v7, v163
	v_cvt_pk_fp8_f32 v7, v5, v8
	v_mul_f32_e32 v12, v12, v149
	v_mul_f32_e32 v12, 0x3e000000, v12
	v_med3_f32 v5, v11, s40, v189
	v_med3_f32 v8, v12, s40, v189
	v_cvt_pk_fp8_f32 v7, v5, v8 op_sel:[0,0,1]
	v_ashrrev_i32_e32 v5, 31, v4
	v_lshlrev_b64 v[8:9], 7, v[4:5]
	v_lshl_add_u64 v[8:9], s[10:11], 0, v[8:9]
	v_lshl_add_u64 v[8:9], v[8:9], 0, v[2:3]
	v_mul_f32_e32 v5, 0x3c800000, v142
	flat_store_dwordx2 v[8:9], v[6:7] nt
	v_mul_f32_e32 v6, 0xbfb8aa3b, v5
	v_exp_f32_e32 v6, v6
	s_nop 0
	v_add_f32_e32 v6, 1.0, v6
	v_rcp_f32_e32 v6, v6
	s_nop 0
	v_mul_f32_e32 v5, v5, v6
	v_mul_f32_e32 v6, 0x3c800000, v143
	v_mul_f32_e32 v7, 0xbfb8aa3b, v6
	v_exp_f32_e32 v7, v7
	v_mul_f32_e32 v5, v5, v138
	v_mul_f32_e32 v5, 0x3e000000, v5
	v_med3_f32 v5, v5, s40, v189
	v_add_f32_e32 v7, 1.0, v7
	v_rcp_f32_e32 v7, v7
	s_nop 0
	v_mul_f32_e32 v6, v6, v7
	v_mul_f32_e32 v6, v6, v139
	v_mul_f32_e32 v7, 0x3e000000, v6
	v_mul_f32_e32 v6, 0x3c800000, v144
	v_mul_f32_e32 v8, 0xbfb8aa3b, v6
	v_exp_f32_e32 v8, v8
	v_med3_f32 v7, v7, s40, v189
	v_add_f32_e32 v8, 1.0, v8
	v_rcp_f32_e32 v8, v8
	s_nop 0
	v_mul_f32_e32 v6, v6, v8
	v_mul_f32_e32 v6, v6, v140
	v_mul_f32_e32 v9, 0x3e000000, v6
	v_mul_f32_e32 v6, 0x3c800000, v145
	v_mul_f32_e32 v8, 0xbfb8aa3b, v6
	v_exp_f32_e32 v8, v8
	s_nop 0
	v_add_f32_e32 v8, 1.0, v8
	v_rcp_f32_e32 v8, v8
	s_nop 0
	v_mul_f32_e32 v6, v6, v8
	v_mul_f32_e32 v6, v6, v141
	v_mul_f32_e32 v10, 0x3e000000, v6
	v_mul_f32_e32 v6, 0x3c800000, v134
	v_mul_f32_e32 v8, 0xbfb8aa3b, v6
	v_exp_f32_e32 v8, v8
	s_nop 0
	v_add_f32_e32 v8, 1.0, v8
	v_rcp_f32_e32 v8, v8
	s_nop 0
	v_mul_f32_e32 v6, v6, v8
	v_mul_f32_e32 v6, v6, v130
	v_mul_f32_e32 v11, 0x3e000000, v6
	v_mul_f32_e32 v6, 0x3c800000, v135
	v_mul_f32_e32 v8, 0xbfb8aa3b, v6
	v_exp_f32_e32 v8, v8
	s_nop 0
	v_add_f32_e32 v8, 1.0, v8
	v_rcp_f32_e32 v8, v8
	s_nop 0
	v_mul_f32_e32 v6, v6, v8
	v_mul_f32_e32 v6, v6, v131
	v_mul_f32_e32 v12, 0x3e000000, v6
	v_mul_f32_e32 v6, 0x3c800000, v136
	v_mul_f32_e32 v8, 0xbfb8aa3b, v6
	v_exp_f32_e32 v8, v8
	s_nop 0
	v_add_f32_e32 v8, 1.0, v8
	v_rcp_f32_e32 v8, v8
	s_nop 0
	v_mul_f32_e32 v6, v6, v8
	v_mul_f32_e32 v6, v6, v132
	v_mul_f32_e32 v13, 0x3e000000, v6
	v_mul_f32_e32 v6, 0x3c800000, v137
	v_mul_f32_e32 v8, 0xbfb8aa3b, v6
	v_exp_f32_e32 v8, v8
	s_nop 0
	v_add_f32_e32 v8, 1.0, v8
	v_rcp_f32_e32 v8, v8
	s_nop 0
	v_mul_f32_e32 v6, v6, v8
	v_mov_b32_e32 v8, v163
	v_cvt_pk_fp8_f32 v8, v5, v7
	v_med3_f32 v5, v9, s40, v189
	v_med3_f32 v7, v10, s40, v189
	v_mov_b32_e32 v9, v163
	v_cvt_pk_fp8_f32 v8, v5, v7 op_sel:[0,0,1]
	v_med3_f32 v5, v11, s40, v189
	v_med3_f32 v7, v12, s40, v189
	v_cvt_pk_fp8_f32 v9, v5, v7
	v_mul_f32_e32 v6, v6, v133
	v_mul_f32_e32 v14, 0x3e000000, v6
	v_add_u32_e32 v6, 16, v4
	v_med3_f32 v5, v13, s40, v189
	v_med3_f32 v7, v14, s40, v189
	v_cvt_pk_fp8_f32 v9, v5, v7 op_sel:[0,0,1]
	v_ashrrev_i32_e32 v7, 31, v6
	v_lshlrev_b64 v[6:7], 7, v[6:7]
	v_lshl_add_u64 v[6:7], s[10:11], 0, v[6:7]
	v_lshl_add_u64 v[6:7], v[6:7], 0, v[2:3]
	v_mul_f32_e32 v5, 0x3c800000, v126
	flat_store_dwordx2 v[6:7], v[8:9] nt
	v_mul_f32_e32 v6, 0xbfb8aa3b, v5
	v_exp_f32_e32 v6, v6
	s_nop 0
	v_add_f32_e32 v6, 1.0, v6
	v_rcp_f32_e32 v6, v6
	s_nop 0
	v_mul_f32_e32 v5, v5, v6
	v_mul_f32_e32 v6, 0x3c800000, v127
	v_mul_f32_e32 v7, 0xbfb8aa3b, v6
	v_exp_f32_e32 v7, v7
	v_mul_f32_e32 v5, v5, v122
	v_mul_f32_e32 v5, 0x3e000000, v5
	v_med3_f32 v5, v5, s40, v189
	v_add_f32_e32 v7, 1.0, v7
	v_rcp_f32_e32 v7, v7
	s_nop 0
	v_mul_f32_e32 v6, v6, v7
	v_mul_f32_e32 v6, v6, v123
	v_mul_f32_e32 v7, 0x3e000000, v6
	v_mul_f32_e32 v6, 0x3c800000, v128
	v_mul_f32_e32 v8, 0xbfb8aa3b, v6
	v_exp_f32_e32 v8, v8
	v_med3_f32 v7, v7, s40, v189
	v_add_f32_e32 v8, 1.0, v8
	v_rcp_f32_e32 v8, v8
	s_nop 0
	v_mul_f32_e32 v6, v6, v8
	v_mul_f32_e32 v6, v6, v124
	v_mul_f32_e32 v9, 0x3e000000, v6
	v_mul_f32_e32 v6, 0x3c800000, v129
	v_mul_f32_e32 v8, 0xbfb8aa3b, v6
	v_exp_f32_e32 v8, v8
	s_nop 0
	v_add_f32_e32 v8, 1.0, v8
	v_rcp_f32_e32 v8, v8
	s_nop 0
	v_mul_f32_e32 v6, v6, v8
	v_mul_f32_e32 v6, v6, v125
	v_mul_f32_e32 v10, 0x3e000000, v6
	v_mul_f32_e32 v6, 0x3c800000, v118
	v_mul_f32_e32 v8, 0xbfb8aa3b, v6
	v_exp_f32_e32 v8, v8
	s_nop 0
	v_add_f32_e32 v8, 1.0, v8
	v_rcp_f32_e32 v8, v8
	s_nop 0
	v_mul_f32_e32 v6, v6, v8
	v_mul_f32_e32 v6, v6, v114
	v_mul_f32_e32 v11, 0x3e000000, v6
	v_mul_f32_e32 v6, 0x3c800000, v119
	v_mul_f32_e32 v8, 0xbfb8aa3b, v6
	v_exp_f32_e32 v8, v8
	s_nop 0
	v_add_f32_e32 v8, 1.0, v8
	v_rcp_f32_e32 v8, v8
	s_nop 0
	v_mul_f32_e32 v6, v6, v8
	v_mul_f32_e32 v6, v6, v115
	v_mul_f32_e32 v12, 0x3e000000, v6
	v_mul_f32_e32 v6, 0x3c800000, v120
	v_mul_f32_e32 v8, 0xbfb8aa3b, v6
	v_exp_f32_e32 v8, v8
	s_nop 0
	v_add_f32_e32 v8, 1.0, v8
	v_rcp_f32_e32 v8, v8
	s_nop 0
	v_mul_f32_e32 v6, v6, v8
	v_mul_f32_e32 v6, v6, v116
	v_mul_f32_e32 v13, 0x3e000000, v6
	v_mul_f32_e32 v6, 0x3c800000, v121
	v_mul_f32_e32 v8, 0xbfb8aa3b, v6
	v_exp_f32_e32 v8, v8
	s_nop 0
	v_add_f32_e32 v8, 1.0, v8
	v_rcp_f32_e32 v8, v8
	s_nop 0
	v_mul_f32_e32 v6, v6, v8
	v_mov_b32_e32 v8, v163
	v_cvt_pk_fp8_f32 v8, v5, v7
	v_med3_f32 v5, v9, s40, v189
	v_med3_f32 v7, v10, s40, v189
	v_mov_b32_e32 v9, v163
	v_cvt_pk_fp8_f32 v8, v5, v7 op_sel:[0,0,1]
	v_med3_f32 v5, v11, s40, v189
	v_med3_f32 v7, v12, s40, v189
	v_cvt_pk_fp8_f32 v9, v5, v7
	v_mul_f32_e32 v6, v6, v117
	v_mul_f32_e32 v14, 0x3e000000, v6
	v_add_u32_e32 v6, 32, v4
	v_med3_f32 v5, v13, s40, v189
	v_med3_f32 v7, v14, s40, v189
	v_cvt_pk_fp8_f32 v9, v5, v7 op_sel:[0,0,1]
	v_ashrrev_i32_e32 v7, 31, v6
	v_lshlrev_b64 v[6:7], 7, v[6:7]
	v_lshl_add_u64 v[6:7], s[10:11], 0, v[6:7]
	v_lshl_add_u64 v[6:7], v[6:7], 0, v[2:3]
	v_mul_f32_e32 v5, 0x3c800000, v110
	flat_store_dwordx2 v[6:7], v[8:9] nt
	v_mul_f32_e32 v6, 0xbfb8aa3b, v5
	v_exp_f32_e32 v6, v6
	s_nop 0
	v_add_f32_e32 v6, 1.0, v6
	v_rcp_f32_e32 v6, v6
	s_nop 0
	v_mul_f32_e32 v5, v5, v6
	v_mul_f32_e32 v6, 0x3c800000, v111
	v_mul_f32_e32 v7, 0xbfb8aa3b, v6
	v_exp_f32_e32 v7, v7
	v_mul_f32_e32 v5, v5, v106
	v_mul_f32_e32 v5, 0x3e000000, v5
	v_med3_f32 v5, v5, s40, v189
	v_add_f32_e32 v7, 1.0, v7
	v_rcp_f32_e32 v7, v7
	s_nop 0
	v_mul_f32_e32 v6, v6, v7
	v_mul_f32_e32 v6, v6, v107
	v_mul_f32_e32 v7, 0x3e000000, v6
	v_mul_f32_e32 v6, 0x3c800000, v112
	v_mul_f32_e32 v8, 0xbfb8aa3b, v6
	v_exp_f32_e32 v8, v8
	v_med3_f32 v7, v7, s40, v189
	v_add_f32_e32 v8, 1.0, v8
	v_rcp_f32_e32 v8, v8
	s_nop 0
	v_mul_f32_e32 v6, v6, v8
	v_mul_f32_e32 v6, v6, v108
	v_mul_f32_e32 v9, 0x3e000000, v6
	v_mul_f32_e32 v6, 0x3c800000, v113
	v_mul_f32_e32 v8, 0xbfb8aa3b, v6
	v_exp_f32_e32 v8, v8
	s_nop 0
	v_add_f32_e32 v8, 1.0, v8
	v_rcp_f32_e32 v8, v8
	s_nop 0
	v_mul_f32_e32 v6, v6, v8
	v_mul_f32_e32 v6, v6, v109
	v_mul_f32_e32 v10, 0x3e000000, v6
	v_mul_f32_e32 v6, 0x3c800000, v102
	v_mul_f32_e32 v8, 0xbfb8aa3b, v6
	v_exp_f32_e32 v8, v8
	s_nop 0
	v_add_f32_e32 v8, 1.0, v8
	v_rcp_f32_e32 v8, v8
	s_nop 0
	v_mul_f32_e32 v6, v6, v8
	v_mul_f32_e32 v6, v6, v98
	v_mul_f32_e32 v11, 0x3e000000, v6
	v_mul_f32_e32 v6, 0x3c800000, v103
	v_mul_f32_e32 v8, 0xbfb8aa3b, v6
	v_exp_f32_e32 v8, v8
	s_nop 0
	v_add_f32_e32 v8, 1.0, v8
	v_rcp_f32_e32 v8, v8
	s_nop 0
	v_mul_f32_e32 v6, v6, v8
	v_mul_f32_e32 v6, v6, v99
	v_mul_f32_e32 v12, 0x3e000000, v6
	v_mul_f32_e32 v6, 0x3c800000, v104
	v_mul_f32_e32 v8, 0xbfb8aa3b, v6
	v_exp_f32_e32 v8, v8
	s_nop 0
	v_add_f32_e32 v8, 1.0, v8
	v_rcp_f32_e32 v8, v8
	s_nop 0
	v_mul_f32_e32 v6, v6, v8
	v_mul_f32_e32 v6, v6, v100
	v_mul_f32_e32 v13, 0x3e000000, v6
	v_mul_f32_e32 v6, 0x3c800000, v105
	v_mul_f32_e32 v8, 0xbfb8aa3b, v6
	v_exp_f32_e32 v8, v8
	s_nop 0
	v_add_f32_e32 v8, 1.0, v8
	v_rcp_f32_e32 v8, v8
	s_nop 0
	v_mul_f32_e32 v6, v6, v8
	v_mov_b32_e32 v8, v163
	v_cvt_pk_fp8_f32 v8, v5, v7
	v_med3_f32 v5, v9, s40, v189
	v_med3_f32 v7, v10, s40, v189
	v_mov_b32_e32 v9, v163
	v_cvt_pk_fp8_f32 v8, v5, v7 op_sel:[0,0,1]
	v_med3_f32 v5, v11, s40, v189
	v_med3_f32 v7, v12, s40, v189
	v_cvt_pk_fp8_f32 v9, v5, v7
	v_mul_f32_e32 v6, v6, v101
	v_mul_f32_e32 v14, 0x3e000000, v6
	v_add_u32_e32 v6, 48, v4
	v_med3_f32 v5, v13, s40, v189
	v_med3_f32 v7, v14, s40, v189
	v_cvt_pk_fp8_f32 v9, v5, v7 op_sel:[0,0,1]
	v_ashrrev_i32_e32 v7, 31, v6
	v_lshlrev_b64 v[6:7], 7, v[6:7]
	v_lshl_add_u64 v[6:7], s[10:11], 0, v[6:7]
	v_lshl_add_u64 v[6:7], v[6:7], 0, v[2:3]
	v_mul_f32_e32 v5, 0x3c800000, v94
	flat_store_dwordx2 v[6:7], v[8:9] nt
	v_mul_f32_e32 v7, 0xbfb8aa3b, v5
	v_exp_f32_e32 v7, v7
	v_add_u32_e32 v6, 0x80, v4
	v_add_f32_e32 v7, 1.0, v7
	v_rcp_f32_e32 v7, v7
	s_nop 0
	v_mul_f32_e32 v5, v5, v7
	v_mul_f32_e32 v7, 0x3c800000, v95
	v_mul_f32_e32 v8, 0xbfb8aa3b, v7
	v_exp_f32_e32 v8, v8
	v_mul_f32_e32 v5, v5, v90
	v_mul_f32_e32 v5, 0x3e000000, v5
	v_med3_f32 v5, v5, s40, v189
	v_add_f32_e32 v8, 1.0, v8
	v_rcp_f32_e32 v8, v8
	s_nop 0
	v_mul_f32_e32 v7, v7, v8
	v_mul_f32_e32 v8, 0x3c800000, v96
	v_mul_f32_e32 v9, 0xbfb8aa3b, v8
	v_exp_f32_e32 v9, v9
	v_mul_f32_e32 v7, v7, v91
	v_mul_f32_e32 v7, 0x3e000000, v7
	v_med3_f32 v7, v7, s40, v189
	v_add_f32_e32 v9, 1.0, v9
	v_rcp_f32_e32 v9, v9
	s_nop 0
	v_mul_f32_e32 v8, v8, v9
	v_mul_f32_e32 v8, v8, v92
	v_mul_f32_e32 v9, 0x3e000000, v8
	v_mul_f32_e32 v8, 0x3c800000, v97
	v_mul_f32_e32 v10, 0xbfb8aa3b, v8
	v_exp_f32_e32 v10, v10
	s_nop 0
	v_add_f32_e32 v10, 1.0, v10
	v_rcp_f32_e32 v10, v10
	s_nop 0
	v_mul_f32_e32 v8, v8, v10
	v_mul_f32_e32 v8, v8, v93
	v_mul_f32_e32 v10, 0x3e000000, v8
	v_mul_f32_e32 v8, 0x3c800000, v86
	v_mul_f32_e32 v11, 0xbfb8aa3b, v8
	v_exp_f32_e32 v11, v11
	s_nop 0
	v_add_f32_e32 v11, 1.0, v11
	v_rcp_f32_e32 v11, v11
	s_nop 0
	v_mul_f32_e32 v8, v8, v11
	v_mul_f32_e32 v8, v8, v82
	v_mul_f32_e32 v11, 0x3e000000, v8
	v_mul_f32_e32 v8, 0x3c800000, v87
	v_mul_f32_e32 v12, 0xbfb8aa3b, v8
	v_exp_f32_e32 v12, v12
	s_nop 0
	v_add_f32_e32 v12, 1.0, v12
	v_rcp_f32_e32 v12, v12
	s_nop 0
	v_mul_f32_e32 v8, v8, v12
	v_mul_f32_e32 v8, v8, v83
	v_mul_f32_e32 v12, 0x3e000000, v8
	v_mul_f32_e32 v8, 0x3c800000, v88
	v_mul_f32_e32 v13, 0xbfb8aa3b, v8
	v_exp_f32_e32 v13, v13
	s_nop 0
	v_add_f32_e32 v13, 1.0, v13
	v_rcp_f32_e32 v13, v13
	s_nop 0
	v_mul_f32_e32 v8, v8, v13
	v_mul_f32_e32 v8, v8, v84
	v_mul_f32_e32 v13, 0x3e000000, v8
	v_mul_f32_e32 v8, 0x3c800000, v89
	v_mul_f32_e32 v14, 0xbfb8aa3b, v8
	v_exp_f32_e32 v14, v14
	s_nop 0
	v_add_f32_e32 v14, 1.0, v14
	v_rcp_f32_e32 v14, v14
	s_nop 0
	v_mul_f32_e32 v8, v8, v14
	v_mul_f32_e32 v8, v8, v85
	v_mul_f32_e32 v14, 0x3e000000, v8
	v_mov_b32_e32 v8, v163
	v_cvt_pk_fp8_f32 v8, v5, v7
	v_med3_f32 v5, v9, s40, v189
	v_med3_f32 v7, v10, s40, v189
	v_mov_b32_e32 v9, v163
	v_cvt_pk_fp8_f32 v8, v5, v7 op_sel:[0,0,1]
	v_med3_f32 v5, v11, s40, v189
	v_med3_f32 v7, v12, s40, v189
	v_cvt_pk_fp8_f32 v9, v5, v7
	v_med3_f32 v5, v13, s40, v189
	v_med3_f32 v7, v14, s40, v189
	v_cvt_pk_fp8_f32 v9, v5, v7 op_sel:[0,0,1]
	v_ashrrev_i32_e32 v7, 31, v6
	v_lshlrev_b64 v[6:7], 7, v[6:7]
	v_lshl_add_u64 v[6:7], s[10:11], 0, v[6:7]
	v_lshl_add_u64 v[6:7], v[6:7], 0, v[2:3]
	v_mul_f32_e32 v5, 0x3c800000, v78
	flat_store_dwordx2 v[6:7], v[8:9] nt
	v_mul_f32_e32 v6, 0xbfb8aa3b, v5
	v_exp_f32_e32 v6, v6
	s_nop 0
	v_add_f32_e32 v6, 1.0, v6
	v_rcp_f32_e32 v6, v6
	s_nop 0
	v_mul_f32_e32 v5, v5, v6
	v_mul_f32_e32 v6, 0x3c800000, v79
	v_mul_f32_e32 v7, 0xbfb8aa3b, v6
	v_exp_f32_e32 v7, v7
	v_mul_f32_e32 v5, v5, v74
	v_mul_f32_e32 v5, 0x3e000000, v5
	v_med3_f32 v5, v5, s40, v189
	v_add_f32_e32 v7, 1.0, v7
	v_rcp_f32_e32 v7, v7
	s_nop 0
	v_mul_f32_e32 v6, v6, v7
	v_mul_f32_e32 v6, v6, v75
	v_mul_f32_e32 v7, 0x3e000000, v6
	v_mul_f32_e32 v6, 0x3c800000, v80
	v_mul_f32_e32 v8, 0xbfb8aa3b, v6
	v_exp_f32_e32 v8, v8
	v_med3_f32 v7, v7, s40, v189
	v_add_f32_e32 v8, 1.0, v8
	v_rcp_f32_e32 v8, v8
	s_nop 0
	v_mul_f32_e32 v6, v6, v8
	v_mul_f32_e32 v6, v6, v76
	v_mul_f32_e32 v9, 0x3e000000, v6
	v_mul_f32_e32 v6, 0x3c800000, v81
	v_mul_f32_e32 v8, 0xbfb8aa3b, v6
	v_exp_f32_e32 v8, v8
	s_nop 0
	v_add_f32_e32 v8, 1.0, v8
	v_rcp_f32_e32 v8, v8
	s_nop 0
	v_mul_f32_e32 v6, v6, v8
	v_mul_f32_e32 v6, v6, v77
	v_mul_f32_e32 v10, 0x3e000000, v6
	v_mul_f32_e32 v6, 0x3c800000, v70
	v_mul_f32_e32 v8, 0xbfb8aa3b, v6
	v_exp_f32_e32 v8, v8
	s_nop 0
	v_add_f32_e32 v8, 1.0, v8
	v_rcp_f32_e32 v8, v8
	s_nop 0
	v_mul_f32_e32 v6, v6, v8
	v_mul_f32_e32 v6, v6, v66
	v_mul_f32_e32 v11, 0x3e000000, v6
	v_mul_f32_e32 v6, 0x3c800000, v71
	v_mul_f32_e32 v8, 0xbfb8aa3b, v6
	v_exp_f32_e32 v8, v8
	s_nop 0
	v_add_f32_e32 v8, 1.0, v8
	v_rcp_f32_e32 v8, v8
	s_nop 0
	v_mul_f32_e32 v6, v6, v8
	v_mul_f32_e32 v6, v6, v67
	v_mul_f32_e32 v12, 0x3e000000, v6
	v_mul_f32_e32 v6, 0x3c800000, v72
	v_mul_f32_e32 v8, 0xbfb8aa3b, v6
	v_exp_f32_e32 v8, v8
	s_nop 0
	v_add_f32_e32 v8, 1.0, v8
	v_rcp_f32_e32 v8, v8
	s_nop 0
	v_mul_f32_e32 v6, v6, v8
	v_mul_f32_e32 v6, v6, v68
	v_mul_f32_e32 v13, 0x3e000000, v6
	v_mul_f32_e32 v6, 0x3c800000, v73
	v_mul_f32_e32 v8, 0xbfb8aa3b, v6
	v_exp_f32_e32 v8, v8
	s_nop 0
	v_add_f32_e32 v8, 1.0, v8
	v_rcp_f32_e32 v8, v8
	s_nop 0
	v_mul_f32_e32 v6, v6, v8
	v_mov_b32_e32 v8, v163
	v_cvt_pk_fp8_f32 v8, v5, v7
	v_med3_f32 v5, v9, s40, v189
	v_med3_f32 v7, v10, s40, v189
	v_mov_b32_e32 v9, v163
	v_cvt_pk_fp8_f32 v8, v5, v7 op_sel:[0,0,1]
	v_med3_f32 v5, v11, s40, v189
	v_med3_f32 v7, v12, s40, v189
	v_cvt_pk_fp8_f32 v9, v5, v7
	v_mul_f32_e32 v6, v6, v69
	v_mul_f32_e32 v14, 0x3e000000, v6
	v_add_u32_e32 v6, 0x90, v4
	v_med3_f32 v5, v13, s40, v189
	v_med3_f32 v7, v14, s40, v189
	v_cvt_pk_fp8_f32 v9, v5, v7 op_sel:[0,0,1]
	v_ashrrev_i32_e32 v7, 31, v6
	v_lshlrev_b64 v[6:7], 7, v[6:7]
	v_lshl_add_u64 v[6:7], s[10:11], 0, v[6:7]
	v_lshl_add_u64 v[6:7], v[6:7], 0, v[2:3]
	v_mul_f32_e32 v5, 0x3c800000, v62
	flat_store_dwordx2 v[6:7], v[8:9] nt
	v_mul_f32_e32 v6, 0xbfb8aa3b, v5
	v_exp_f32_e32 v6, v6
	s_nop 0
	v_add_f32_e32 v6, 1.0, v6
	v_rcp_f32_e32 v6, v6
	s_nop 0
	v_mul_f32_e32 v5, v5, v6
	v_mul_f32_e32 v6, 0x3c800000, v63
	v_mul_f32_e32 v7, 0xbfb8aa3b, v6
	v_exp_f32_e32 v7, v7
	v_mul_f32_e32 v5, v5, v58
	v_mul_f32_e32 v5, 0x3e000000, v5
	v_med3_f32 v5, v5, s40, v189
	v_add_f32_e32 v7, 1.0, v7
	v_rcp_f32_e32 v7, v7
	s_nop 0
	v_mul_f32_e32 v6, v6, v7
	v_mul_f32_e32 v6, v6, v59
	v_mul_f32_e32 v7, 0x3e000000, v6
	v_mul_f32_e32 v6, 0x3c800000, v64
	v_mul_f32_e32 v8, 0xbfb8aa3b, v6
	v_exp_f32_e32 v8, v8
	v_med3_f32 v7, v7, s40, v189
	v_add_f32_e32 v8, 1.0, v8
	v_rcp_f32_e32 v8, v8
	s_nop 0
	v_mul_f32_e32 v6, v6, v8
	v_mul_f32_e32 v6, v6, v60
	v_mul_f32_e32 v9, 0x3e000000, v6
	v_mul_f32_e32 v6, 0x3c800000, v65
	v_mul_f32_e32 v8, 0xbfb8aa3b, v6
	v_exp_f32_e32 v8, v8
	s_nop 0
	v_add_f32_e32 v8, 1.0, v8
	v_rcp_f32_e32 v8, v8
	s_nop 0
	v_mul_f32_e32 v6, v6, v8
	v_mul_f32_e32 v6, v6, v61
	v_mul_f32_e32 v10, 0x3e000000, v6
	v_mul_f32_e32 v6, 0x3c800000, v54
	v_mul_f32_e32 v8, 0xbfb8aa3b, v6
	v_exp_f32_e32 v8, v8
	s_nop 0
	v_add_f32_e32 v8, 1.0, v8
	v_rcp_f32_e32 v8, v8
	s_nop 0
	v_mul_f32_e32 v6, v6, v8
	v_mul_f32_e32 v6, v6, v50
	v_mul_f32_e32 v11, 0x3e000000, v6
	v_mul_f32_e32 v6, 0x3c800000, v55
	v_mul_f32_e32 v8, 0xbfb8aa3b, v6
	v_exp_f32_e32 v8, v8
	s_nop 0
	v_add_f32_e32 v8, 1.0, v8
	v_rcp_f32_e32 v8, v8
	s_nop 0
	v_mul_f32_e32 v6, v6, v8
	v_mul_f32_e32 v6, v6, v51
	v_mul_f32_e32 v12, 0x3e000000, v6
	v_mul_f32_e32 v6, 0x3c800000, v56
	v_mul_f32_e32 v8, 0xbfb8aa3b, v6
	v_exp_f32_e32 v8, v8
	s_nop 0
	v_add_f32_e32 v8, 1.0, v8
	v_rcp_f32_e32 v8, v8
	s_nop 0
	v_mul_f32_e32 v6, v6, v8
	v_mul_f32_e32 v6, v6, v52
	v_mul_f32_e32 v13, 0x3e000000, v6
	v_mul_f32_e32 v6, 0x3c800000, v57
	v_mul_f32_e32 v8, 0xbfb8aa3b, v6
	v_exp_f32_e32 v8, v8
	s_nop 0
	v_add_f32_e32 v8, 1.0, v8
	v_rcp_f32_e32 v8, v8
	s_nop 0
	v_mul_f32_e32 v6, v6, v8
	v_mov_b32_e32 v8, v163
	v_cvt_pk_fp8_f32 v8, v5, v7
	v_med3_f32 v5, v9, s40, v189
	v_med3_f32 v7, v10, s40, v189
	v_mov_b32_e32 v9, v163
	v_cvt_pk_fp8_f32 v8, v5, v7 op_sel:[0,0,1]
	v_med3_f32 v5, v11, s40, v189
	v_med3_f32 v7, v12, s40, v189
	v_cvt_pk_fp8_f32 v9, v5, v7
	v_mul_f32_e32 v6, v6, v53
	v_mul_f32_e32 v14, 0x3e000000, v6
	v_add_u32_e32 v6, 0xa0, v4
	v_med3_f32 v5, v13, s40, v189
	v_med3_f32 v7, v14, s40, v189
	v_cvt_pk_fp8_f32 v9, v5, v7 op_sel:[0,0,1]
	v_ashrrev_i32_e32 v7, 31, v6
	v_lshlrev_b64 v[6:7], 7, v[6:7]
	v_lshl_add_u64 v[6:7], s[10:11], 0, v[6:7]
	v_lshl_add_u64 v[6:7], v[6:7], 0, v[2:3]
	v_mul_f32_e32 v5, 0x3c800000, v46
	flat_store_dwordx2 v[6:7], v[8:9] nt
	v_mul_f32_e32 v6, 0xbfb8aa3b, v5
	v_exp_f32_e32 v6, v6
	v_add_u32_e32 v4, 0xb0, v4
	v_add_f32_e32 v6, 1.0, v6
	v_rcp_f32_e32 v6, v6
	s_nop 0
	v_mul_f32_e32 v5, v5, v6
	v_mul_f32_e32 v6, 0x3c800000, v47
	v_mul_f32_e32 v7, 0xbfb8aa3b, v6
	v_exp_f32_e32 v7, v7
	v_mul_f32_e32 v5, v5, v42
	v_mul_f32_e32 v5, 0x3e000000, v5
	v_med3_f32 v5, v5, s40, v189
	v_add_f32_e32 v7, 1.0, v7
	v_rcp_f32_e32 v7, v7
	s_nop 0
	v_mul_f32_e32 v6, v6, v7
	v_mul_f32_e32 v7, 0x3c800000, v48
	v_mul_f32_e32 v8, 0xbfb8aa3b, v7
	v_exp_f32_e32 v8, v8
	v_mul_f32_e32 v6, v6, v43
	v_mul_f32_e32 v6, 0x3e000000, v6
	v_add_f32_e32 v8, 1.0, v8
	v_rcp_f32_e32 v8, v8
	s_nop 0
	v_mul_f32_e32 v7, v7, v8
	v_mul_f32_e32 v8, 0x3c800000, v49
	v_mul_f32_e32 v9, 0xbfb8aa3b, v8
	v_exp_f32_e32 v9, v9
	v_mul_f32_e32 v7, v7, v44
	v_mul_f32_e32 v7, 0x3e000000, v7
	v_add_f32_e32 v9, 1.0, v9
	v_rcp_f32_e32 v9, v9
	s_nop 0
	v_mul_f32_e32 v8, v8, v9
	v_mul_f32_e32 v9, 0x3c800000, v38
	v_mul_f32_e32 v10, 0xbfb8aa3b, v9
	v_exp_f32_e32 v10, v10
	v_mul_f32_e32 v8, v8, v45
	v_mul_f32_e32 v8, 0x3e000000, v8
	v_add_f32_e32 v10, 1.0, v10
	v_rcp_f32_e32 v10, v10
	s_nop 0
	v_mul_f32_e32 v9, v9, v10
	v_mul_f32_e32 v10, 0x3c800000, v39
	v_mul_f32_e32 v11, 0xbfb8aa3b, v10
	v_exp_f32_e32 v11, v11
	v_mul_f32_e32 v9, v9, v34
	v_mul_f32_e32 v9, 0x3e000000, v9
	v_add_f32_e32 v11, 1.0, v11
	v_rcp_f32_e32 v11, v11
	s_nop 0
	v_mul_f32_e32 v10, v10, v11
	v_mul_f32_e32 v11, 0x3c800000, v40
	v_mul_f32_e32 v12, 0xbfb8aa3b, v11
	v_exp_f32_e32 v12, v12
	v_mul_f32_e32 v10, v10, v35
	v_mul_f32_e32 v10, 0x3e000000, v10
	v_add_f32_e32 v12, 1.0, v12
	v_rcp_f32_e32 v12, v12
	s_nop 0
	v_mul_f32_e32 v11, v11, v12
	v_mul_f32_e32 v12, 0x3c800000, v41
	v_mul_f32_e32 v13, 0xbfb8aa3b, v12
	v_exp_f32_e32 v13, v13
	v_mul_f32_e32 v11, v11, v36
	v_mul_f32_e32 v11, 0x3e000000, v11
	v_add_f32_e32 v13, 1.0, v13
	v_rcp_f32_e32 v13, v13
	s_nop 0
	v_mul_f32_e32 v12, v12, v13
	v_med3_f32 v13, v6, s40, v189
	v_mov_b32_e32 v6, v163
	v_cvt_pk_fp8_f32 v6, v5, v13
	v_med3_f32 v5, v7, s40, v189
	v_med3_f32 v7, v8, s40, v189
	v_med3_f32 v8, v10, s40, v189
	v_cvt_pk_fp8_f32 v6, v5, v7 op_sel:[0,0,1]
	v_med3_f32 v5, v9, s40, v189
	v_mov_b32_e32 v7, v163
	v_cvt_pk_fp8_f32 v7, v5, v8
	v_mul_f32_e32 v12, v12, v37
	v_mul_f32_e32 v12, 0x3e000000, v12
	v_med3_f32 v5, v11, s40, v189
	v_med3_f32 v8, v12, s40, v189
	v_cvt_pk_fp8_f32 v7, v5, v8 op_sel:[0,0,1]
	v_ashrrev_i32_e32 v5, 31, v4
	v_lshlrev_b64 v[4:5], 7, v[4:5]
	v_lshl_add_u64 v[4:5], s[10:11], 0, v[4:5]
	v_lshl_add_u64 v[2:3], v[4:5], 0, v[2:3]
	flat_store_dwordx2 v[2:3], v[6:7] nt
	s_cbranch_vccz .LBB0_2738
	s_waitcnt vmcnt(0)
	s_cmpk_gt_u32 s42, 0xff
	s_cbranch_scc1 .LBB0_2684
	s_barrier
	s_branch .LBB0_2684

.LBB0_2816:
	ds_read_b128 v[2:5], v168
	ds_read_b128 v[6:9], v168 offset:1024
	ds_read_b128 v[10:13], v168 offset:2048
	ds_read_b128 v[14:17], v168 offset:3072
	s_add_u32 s0, s26, 0x4000
	s_addc_u32 s1, s27, 0
	s_cmp_eq_u32 s53, 4
	s_cselect_b32 s34, s49, s0
	s_cselect_b32 s35, s19, s1
	s_cselect_b32 s28, s50, s51
	s_cselect_b32 s29, s17, s52
	s_add_u32 s30, s34, 0x8000
	s_addc_u32 s31, s35, 0
	v_lshl_add_u64 v[162:163], s[26:27], 0, v[156:157]
	s_add_i32 m0, s25, 0xc000
	ds_read_b128 v[174:177], v169
	ds_read_b128 v[178:181], v169 offset:1024
	ds_read_b128 v[182:185], v169 offset:2048
	ds_read_b128 v[186:189], v169 offset:3072
	ds_read_b128 v[190:193], v169 offset:4096
	ds_read_b128 v[194:197], v169 offset:5120
	ds_read_b128 v[198:201], v169 offset:6144
	ds_read_b128 v[202:205], v169 offset:7168
	global_load_lds_dwordx4 v[162:163], off
	v_lshl_add_u64 v[162:163], s[26:27], 0, v[154:155]
	s_add_i32 m0, s25, 0xe000
	s_nop 0
	global_load_lds_dwordx4 v[162:163], off
	s_waitcnt lgkmcnt(8)
	s_waitcnt vmcnt(10)
	s_barrier
	s_waitcnt lgkmcnt(0)
	s_setprio 1
	s_waitcnt lgkmcnt(0)
	v_mfma_scale_f32_16x16x128_f8f6f4 v[142:145], v[2:9], v[174:181], v[142:145], v170, v170 op_sel_hi:[0,0,0]
	v_mfma_scale_f32_16x16x128_f8f6f4 v[138:141], v[10:17], v[174:181], v[138:141], v170, v170 op_sel_hi:[0,0,0]
	v_mfma_scale_f32_16x16x128_f8f6f4 v[126:129], v[2:9], v[182:189], v[126:129], v170, v170 op_sel_hi:[0,0,0]
	v_mfma_scale_f32_16x16x128_f8f6f4 v[122:125], v[10:17], v[182:189], v[122:125], v170, v170 op_sel_hi:[0,0,0]
	v_mfma_scale_f32_16x16x128_f8f6f4 v[110:113], v[2:9], v[190:197], v[110:113], v170, v170 op_sel_hi:[0,0,0]
	v_mfma_scale_f32_16x16x128_f8f6f4 v[106:109], v[10:17], v[190:197], v[106:109], v170, v170 op_sel_hi:[0,0,0]
	v_mfma_scale_f32_16x16x128_f8f6f4 v[94:97], v[2:9], v[198:205], v[94:97], v170, v170 op_sel_hi:[0,0,0]
	v_mfma_scale_f32_16x16x128_f8f6f4 v[90:93], v[10:17], v[198:205], v[90:93], v170, v170 op_sel_hi:[0,0,0]
	s_setprio 0
	s_barrier
	s_add_i32 s0, s45, s37
	v_lshl_add_u64 v[162:163], s[28:29], 0, v[150:151]
	s_mov_b32 m0, s0
	ds_read_b128 v[206:209], v171
	ds_read_b128 v[210:213], v171 offset:1024
	ds_read_b128 v[214:217], v171 offset:2048
	ds_read_b128 v[218:221], v171 offset:3072
	global_load_lds_dwordx4 v[162:163], off
	v_lshl_add_u64 v[164:165], s[28:29], 0, v[146:147]
	s_add_i32 m0, s0, 0x2000
	s_nop 0
	global_load_lds_dwordx4 v[164:165], off
	s_waitcnt vmcnt(10)
	s_barrier
	s_waitcnt lgkmcnt(0)
	s_setprio 1
	s_waitcnt lgkmcnt(0)
	v_mfma_scale_f32_16x16x128_f8f6f4 v[134:137], v[206:213], v[174:181], v[134:137], v170, v170 op_sel_hi:[0,0,0]
	v_mfma_scale_f32_16x16x128_f8f6f4 v[130:133], v[214:221], v[174:181], v[130:133], v170, v170 op_sel_hi:[0,0,0]
	v_mfma_scale_f32_16x16x128_f8f6f4 v[118:121], v[206:213], v[182:189], v[118:121], v170, v170 op_sel_hi:[0,0,0]
	v_mfma_scale_f32_16x16x128_f8f6f4 v[114:117], v[214:221], v[182:189], v[114:117], v170, v170 op_sel_hi:[0,0,0]
	v_mfma_scale_f32_16x16x128_f8f6f4 v[102:105], v[206:213], v[190:197], v[102:105], v170, v170 op_sel_hi:[0,0,0]
	v_mfma_scale_f32_16x16x128_f8f6f4 v[98:101], v[214:221], v[190:197], v[98:101], v170, v170 op_sel_hi:[0,0,0]
	v_mfma_scale_f32_16x16x128_f8f6f4 v[86:89], v[206:213], v[198:205], v[86:89], v170, v170 op_sel_hi:[0,0,0]
	v_mfma_scale_f32_16x16x128_f8f6f4 v[82:85], v[214:221], v[198:205], v[82:85], v170, v170 op_sel_hi:[0,0,0]
	s_setprio 0
	s_mov_b32 m0, s25
	v_lshl_add_u64 v[222:223], s[34:35], 0, v[152:153]
	s_barrier
	ds_read_b128 v[174:177], v169 offset:16384
	ds_read_b128 v[178:181], v169 offset:17408
	ds_read_b128 v[182:185], v169 offset:18432
	ds_read_b128 v[186:189], v169 offset:19456
	ds_read_b128 v[190:193], v169 offset:20480
	ds_read_b128 v[194:197], v169 offset:21504
	ds_read_b128 v[198:201], v169 offset:22528
	ds_read_b128 v[202:205], v169 offset:23552
	global_load_lds_dwordx4 v[222:223], off
	v_lshl_add_u64 v[222:223], s[34:35], 0, v[148:149]
	s_mov_b32 m0, s38
	s_nop 0
	global_load_lds_dwordx4 v[222:223], off
	s_waitcnt vmcnt(10)
	s_barrier
	s_waitcnt lgkmcnt(0)
	s_setprio 1
	s_waitcnt lgkmcnt(0)
	v_mfma_scale_f32_16x16x128_f8f6f4 v[78:81], v[2:9], v[174:181], v[78:81], v170, v170 op_sel_hi:[0,0,0]
	v_mfma_scale_f32_16x16x128_f8f6f4 v[74:77], v[10:17], v[174:181], v[74:77], v170, v170 op_sel_hi:[0,0,0]
	v_mfma_scale_f32_16x16x128_f8f6f4 v[62:65], v[2:9], v[182:189], v[62:65], v170, v170 op_sel_hi:[0,0,0]
	v_mfma_scale_f32_16x16x128_f8f6f4 v[58:61], v[10:17], v[182:189], v[58:61], v170, v170 op_sel_hi:[0,0,0]
	v_mfma_scale_f32_16x16x128_f8f6f4 v[46:49], v[2:9], v[190:197], v[46:49], v170, v170 op_sel_hi:[0,0,0]
	v_mfma_scale_f32_16x16x128_f8f6f4 v[42:45], v[10:17], v[190:197], v[42:45], v170, v170 op_sel_hi:[0,0,0]
	v_mfma_scale_f32_16x16x128_f8f6f4 v[30:33], v[2:9], v[198:205], v[30:33], v170, v170 op_sel_hi:[0,0,0]
	v_mfma_scale_f32_16x16x128_f8f6f4 v[26:29], v[10:17], v[198:205], v[26:29], v170, v170 op_sel_hi:[0,0,0]
	s_setprio 0
	s_barrier
	s_add_u32 s0, s28, 0x20000
	s_addc_u32 s1, s29, 0
	s_add_i32 s54, s46, s37
	v_lshl_add_u64 v[2:3], s[0:1], 0, v[150:151]
	s_mov_b32 m0, s54
	s_nop 0
	global_load_lds_dwordx4 v[2:3], off
	v_lshl_add_u64 v[2:3], s[0:1], 0, v[146:147]
	s_add_i32 m0, s54, 0x2000
	s_nop 0
	global_load_lds_dwordx4 v[2:3], off
	s_waitcnt vmcnt(10)
	s_barrier
	s_setprio 1
	v_mfma_scale_f32_16x16x128_f8f6f4 v[70:73], v[206:213], v[174:181], v[70:73], v170, v170 op_sel_hi:[0,0,0]
	v_mfma_scale_f32_16x16x128_f8f6f4 v[66:69], v[214:221], v[174:181], v[66:69], v170, v170 op_sel_hi:[0,0,0]
	v_mfma_scale_f32_16x16x128_f8f6f4 v[54:57], v[206:213], v[182:189], v[54:57], v170, v170 op_sel_hi:[0,0,0]
	v_mfma_scale_f32_16x16x128_f8f6f4 v[50:53], v[214:221], v[182:189], v[50:53], v170, v170 op_sel_hi:[0,0,0]
	v_mfma_scale_f32_16x16x128_f8f6f4 v[38:41], v[206:213], v[190:197], v[38:41], v170, v170 op_sel_hi:[0,0,0]
	v_mfma_scale_f32_16x16x128_f8f6f4 v[34:37], v[214:221], v[190:197], v[34:37], v170, v170 op_sel_hi:[0,0,0]
	v_mfma_scale_f32_16x16x128_f8f6f4 v[22:25], v[206:213], v[198:205], v[22:25], v170, v170 op_sel_hi:[0,0,0]
	v_mfma_scale_f32_16x16x128_f8f6f4 v[18:21], v[214:221], v[198:205], v[18:21], v170, v170 op_sel_hi:[0,0,0]
	s_setprio 0
	s_add_i32 s54, 0, 0x18000
	v_add_u32_e32 v14, s54, v167
	s_barrier
	ds_read_b128 v[2:5], v14
	ds_read_b128 v[6:9], v14 offset:1024
	ds_read_b128 v[10:13], v14 offset:2048
	ds_read_b128 v[14:17], v14 offset:3072
	s_add_u32 s0, s34, 0x4000
	s_addc_u32 s1, s35, 0
	s_mov_b32 m0, s39
	v_lshl_add_u64 v[206:207], s[0:1], 0, v[152:153]
	ds_read_b128 v[174:177], v169 offset:32768
	ds_read_b128 v[178:181], v169 offset:33792
	ds_read_b128 v[182:185], v169 offset:34816
	ds_read_b128 v[186:189], v169 offset:35840
	ds_read_b128 v[190:193], v169 offset:36864
	ds_read_b128 v[194:197], v169 offset:37888
	ds_read_b128 v[198:201], v169 offset:38912
	ds_read_b128 v[202:205], v169 offset:39936
	global_load_lds_dwordx4 v[206:207], off
	v_lshl_add_u64 v[206:207], s[0:1], 0, v[148:149]
	s_mov_b32 m0, s40
	s_nop 0
	global_load_lds_dwordx4 v[206:207], off
	s_waitcnt lgkmcnt(8)
	s_waitcnt vmcnt(10)
	s_barrier
	s_waitcnt lgkmcnt(0)
	s_setprio 1
	s_waitcnt lgkmcnt(0)
	v_mfma_scale_f32_16x16x128_f8f6f4 v[142:145], v[2:9], v[174:181], v[142:145], v170, v170 op_sel_hi:[0,0,0]
	v_mfma_scale_f32_16x16x128_f8f6f4 v[138:141], v[10:17], v[174:181], v[138:141], v170, v170 op_sel_hi:[0,0,0]
	v_mfma_scale_f32_16x16x128_f8f6f4 v[126:129], v[2:9], v[182:189], v[126:129], v170, v170 op_sel_hi:[0,0,0]
	v_mfma_scale_f32_16x16x128_f8f6f4 v[122:125], v[10:17], v[182:189], v[122:125], v170, v170 op_sel_hi:[0,0,0]
	v_mfma_scale_f32_16x16x128_f8f6f4 v[110:113], v[2:9], v[190:197], v[110:113], v170, v170 op_sel_hi:[0,0,0]
	v_mfma_scale_f32_16x16x128_f8f6f4 v[106:109], v[10:17], v[190:197], v[106:109], v170, v170 op_sel_hi:[0,0,0]
	v_mfma_scale_f32_16x16x128_f8f6f4 v[94:97], v[2:9], v[198:205], v[94:97], v170, v170 op_sel_hi:[0,0,0]
	v_mfma_scale_f32_16x16x128_f8f6f4 v[90:93], v[10:17], v[198:205], v[90:93], v170, v170 op_sel_hi:[0,0,0]
	s_setprio 0
	s_barrier
	s_add_i32 s34, 0, 0x1c000
	s_add_i32 s0, s54, s37
	v_add_u32_e32 v173, s34, v167
	v_lshl_add_u64 v[162:163], v[162:163], 0, s[12:13]
	s_mov_b32 m0, s0
	ds_read_b128 v[206:209], v173
	ds_read_b128 v[210:213], v173 offset:1024
	ds_read_b128 v[214:217], v173 offset:2048
	ds_read_b128 v[218:221], v173 offset:3072
	global_load_lds_dwordx4 v[162:163], off
	v_lshl_add_u64 v[162:163], v[164:165], 0, s[12:13]
	s_add_i32 m0, s0, 0x2000
	s_nop 0
	global_load_lds_dwordx4 v[162:163], off
	s_waitcnt vmcnt(10)
	s_barrier
	s_waitcnt lgkmcnt(0)
	s_setprio 1
	s_waitcnt lgkmcnt(0)
	v_mfma_scale_f32_16x16x128_f8f6f4 v[134:137], v[206:213], v[174:181], v[134:137], v170, v170 op_sel_hi:[0,0,0]
	v_mfma_scale_f32_16x16x128_f8f6f4 v[130:133], v[214:221], v[174:181], v[130:133], v170, v170 op_sel_hi:[0,0,0]
	v_mfma_scale_f32_16x16x128_f8f6f4 v[118:121], v[206:213], v[182:189], v[118:121], v170, v170 op_sel_hi:[0,0,0]
	v_mfma_scale_f32_16x16x128_f8f6f4 v[114:117], v[214:221], v[182:189], v[114:117], v170, v170 op_sel_hi:[0,0,0]
	v_mfma_scale_f32_16x16x128_f8f6f4 v[102:105], v[206:213], v[190:197], v[102:105], v170, v170 op_sel_hi:[0,0,0]
	v_mfma_scale_f32_16x16x128_f8f6f4 v[98:101], v[214:221], v[190:197], v[98:101], v170, v170 op_sel_hi:[0,0,0]
	v_mfma_scale_f32_16x16x128_f8f6f4 v[86:89], v[206:213], v[198:205], v[86:89], v170, v170 op_sel_hi:[0,0,0]
	v_mfma_scale_f32_16x16x128_f8f6f4 v[82:85], v[214:221], v[198:205], v[82:85], v170, v170 op_sel_hi:[0,0,0]
	s_setprio 0
	s_mov_b32 m0, s43
	v_lshl_add_u64 v[162:163], s[30:31], 0, v[152:153]
	s_barrier
	ds_read_b128 v[174:177], v169 offset:49152
	ds_read_b128 v[178:181], v169 offset:50176
	ds_read_b128 v[182:185], v169 offset:51200
	ds_read_b128 v[186:189], v169 offset:52224
	ds_read_b128 v[190:193], v169 offset:53248
	ds_read_b128 v[194:197], v169 offset:54272
	ds_read_b128 v[198:201], v169 offset:55296
	ds_read_b128 v[202:205], v169 offset:56320
	global_load_lds_dwordx4 v[162:163], off
	v_lshl_add_u64 v[162:163], s[30:31], 0, v[148:149]
	s_mov_b32 m0, s44
	s_nop 0
	global_load_lds_dwordx4 v[162:163], off
	s_waitcnt vmcnt(10)
	s_barrier
	s_waitcnt lgkmcnt(0)
	s_setprio 1
	s_waitcnt lgkmcnt(0)
	v_mfma_scale_f32_16x16x128_f8f6f4 v[78:81], v[2:9], v[174:181], v[78:81], v170, v170 op_sel_hi:[0,0,0]
	v_mfma_scale_f32_16x16x128_f8f6f4 v[74:77], v[10:17], v[174:181], v[74:77], v170, v170 op_sel_hi:[0,0,0]
	v_mfma_scale_f32_16x16x128_f8f6f4 v[62:65], v[2:9], v[182:189], v[62:65], v170, v170 op_sel_hi:[0,0,0]
	v_mfma_scale_f32_16x16x128_f8f6f4 v[58:61], v[10:17], v[182:189], v[58:61], v170, v170 op_sel_hi:[0,0,0]
	v_mfma_scale_f32_16x16x128_f8f6f4 v[46:49], v[2:9], v[190:197], v[46:49], v170, v170 op_sel_hi:[0,0,0]
	v_mfma_scale_f32_16x16x128_f8f6f4 v[42:45], v[10:17], v[190:197], v[42:45], v170, v170 op_sel_hi:[0,0,0]
	v_mfma_scale_f32_16x16x128_f8f6f4 v[30:33], v[2:9], v[198:205], v[30:33], v170, v170 op_sel_hi:[0,0,0]
	v_mfma_scale_f32_16x16x128_f8f6f4 v[26:29], v[10:17], v[198:205], v[26:29], v170, v170 op_sel_hi:[0,0,0]
	s_setprio 0
	s_barrier
	s_add_u32 s0, s28, 0x20080
	s_addc_u32 s1, s29, 0
	s_add_i32 s28, s34, s37
	v_lshl_add_u64 v[2:3], s[0:1], 0, v[150:151]
	s_mov_b32 m0, s28
	s_nop 0
	global_load_lds_dwordx4 v[2:3], off
	v_lshl_add_u64 v[2:3], s[0:1], 0, v[146:147]
	s_add_i32 m0, s28, 0x2000
	s_nop 0
	global_load_lds_dwordx4 v[2:3], off
	s_waitcnt vmcnt(10)
	s_barrier
	s_setprio 1
	v_mfma_scale_f32_16x16x128_f8f6f4 v[70:73], v[206:213], v[174:181], v[70:73], v170, v170 op_sel_hi:[0,0,0]
	v_mfma_scale_f32_16x16x128_f8f6f4 v[66:69], v[214:221], v[174:181], v[66:69], v170, v170 op_sel_hi:[0,0,0]
	v_mfma_scale_f32_16x16x128_f8f6f4 v[54:57], v[206:213], v[182:189], v[54:57], v170, v170 op_sel_hi:[0,0,0]
	v_mfma_scale_f32_16x16x128_f8f6f4 v[50:53], v[214:221], v[182:189], v[50:53], v170, v170 op_sel_hi:[0,0,0]
	v_mfma_scale_f32_16x16x128_f8f6f4 v[38:41], v[206:213], v[190:197], v[38:41], v170, v170 op_sel_hi:[0,0,0]
	v_mfma_scale_f32_16x16x128_f8f6f4 v[34:37], v[214:221], v[190:197], v[34:37], v170, v170 op_sel_hi:[0,0,0]
	v_mfma_scale_f32_16x16x128_f8f6f4 v[22:25], v[206:213], v[198:205], v[22:25], v170, v170 op_sel_hi:[0,0,0]
	v_mfma_scale_f32_16x16x128_f8f6f4 v[18:21], v[214:221], v[198:205], v[18:21], v170, v170 op_sel_hi:[0,0,0]
	s_setprio 0
	s_add_i32 s53, s53, 2
	s_add_u32 s51, s51, 0x100
	s_addc_u32 s52, s52, 0
	s_add_u32 s26, s26, 0x10000
	s_addc_u32 s27, s27, 0
	s_cmp_gt_u32 s53, 5
	s_barrier
	s_cbranch_scc0 .LBB0_2816
	v_pk_mul_f32 v[8:9], v[142:143], s[14:15] op_sel_hi:[1,0]
	v_pk_mul_f32 v[6:7], v[144:145], s[14:15] op_sel_hi:[1,0]
	v_med3_f32 v14, v8, s47, v172
	v_med3_f32 v9, v9, s47, v172
	v_mov_b32_e32 v8, 0
	v_cvt_pk_fp8_f32 v8, v14, v9
	v_pk_mul_f32 v[12:13], v[138:139], s[14:15] op_sel_hi:[1,0]
	v_pk_mul_f32 v[10:11], v[140:141], s[14:15] op_sel_hi:[1,0]
	v_med3_f32 v6, v6, s47, v172
	v_med3_f32 v7, v7, s47, v172
	v_med3_f32 v12, v12, s47, v172
	v_med3_f32 v13, v13, s47, v172
	v_mov_b32_e32 v9, 0
	v_mov_b32_e32 v3, v1
	v_mov_b32_e32 v2, v166
	s_lshl_b32 s0, s48, 8
	v_cvt_pk_fp8_f32 v9, v12, v13
	v_cvt_pk_fp8_f32 v8, v6, v7 op_sel:[0,0,1]
	v_med3_f32 v6, v10, s47, v172
	v_med3_f32 v7, v11, s47, v172
	v_pk_mul_f32 v[10:11], v[134:135], s[14:15] op_sel_hi:[1,0]
	s_nop 15
	s_nop 15
	s_or_b32 s0, s0, s42
	v_pk_mul_f32 v[14:15], v[130:131], s[14:15] op_sel_hi:[1,0]
	v_med3_f32 v17, v10, s47, v172
	v_med3_f32 v11, v11, s47, v172
	v_mov_b32_e32 v10, 0
	v_lshl_add_u32 v2, v2, 3, s0
	s_lshl_b32 s0, s24, 8
	v_cvt_pk_fp8_f32 v10, v17, v11
	v_med3_f32 v14, v14, s47, v172
	v_med3_f32 v15, v15, s47, v172
	v_mov_b32_e32 v11, 0
	s_add_i32 s0, s0, s15
	v_cvt_pk_fp8_f32 v11, v14, v15
	v_add_u32_e32 v16, s0, v3
	v_cvt_pk_fp8_f32 v9, v6, v7 op_sel:[0,0,1]
	v_pk_mul_f32 v[6:7], v[136:137], s[14:15] op_sel_hi:[1,0]
	v_mov_b32_e32 v4, v16
	v_pk_mul_f32 v[12:13], v[132:133], s[14:15] op_sel_hi:[1,0]
	v_med3_f32 v6, v6, s47, v172
	v_med3_f32 v7, v7, s47, v172
	v_cvt_pk_fp8_f32 v10, v6, v7 op_sel:[0,0,1]
	v_ashrrev_i32_e32 v5, 31, v4
	v_med3_f32 v6, v12, s47, v172
	v_med3_f32 v7, v13, s47, v172
	v_lshlrev_b64 v[4:5], 10, v[4:5]
	v_cvt_pk_fp8_f32 v11, v6, v7 op_sel:[0,0,1]
	v_ashrrev_i32_e32 v3, 31, v2
	v_lshl_add_u64 v[4:5], s[10:11], 0, v[4:5]
	v_lshl_add_u64 v[4:5], v[4:5], 0, v[2:3]
	flat_store_dwordx2 v[4:5], v[8:9] nt
	flat_store_dwordx2 v[4:5], v[10:11] offset:128 nt
	v_pk_mul_f32 v[8:9], v[126:127], s[14:15] op_sel_hi:[1,0]
	v_pk_mul_f32 v[6:7], v[128:129], s[14:15] op_sel_hi:[1,0]
	v_med3_f32 v14, v8, s47, v172
	v_med3_f32 v9, v9, s47, v172
	v_mov_b32_e32 v8, 0
	v_cvt_pk_fp8_f32 v8, v14, v9
	v_pk_mul_f32 v[12:13], v[122:123], s[14:15] op_sel_hi:[1,0]
	v_pk_mul_f32 v[10:11], v[124:125], s[14:15] op_sel_hi:[1,0]
	v_med3_f32 v6, v6, s47, v172
	v_med3_f32 v7, v7, s47, v172
	v_med3_f32 v12, v12, s47, v172
	v_med3_f32 v13, v13, s47, v172
	v_mov_b32_e32 v9, 0
	v_cvt_pk_fp8_f32 v9, v12, v13
	v_cvt_pk_fp8_f32 v8, v6, v7 op_sel:[0,0,1]
	v_med3_f32 v6, v10, s47, v172
	v_med3_f32 v7, v11, s47, v172
	v_pk_mul_f32 v[10:11], v[118:119], s[14:15] op_sel_hi:[1,0]
	v_pk_mul_f32 v[14:15], v[114:115], s[14:15] op_sel_hi:[1,0]
	v_med3_f32 v17, v10, s47, v172
	v_med3_f32 v11, v11, s47, v172
	v_mov_b32_e32 v10, 0
	v_cvt_pk_fp8_f32 v10, v17, v11
	v_med3_f32 v14, v14, s47, v172
	v_med3_f32 v15, v15, s47, v172
	v_mov_b32_e32 v11, 0
	v_cvt_pk_fp8_f32 v11, v14, v15
	v_cvt_pk_fp8_f32 v9, v6, v7 op_sel:[0,0,1]
	v_pk_mul_f32 v[6:7], v[120:121], s[14:15] op_sel_hi:[1,0]
	v_add_u32_e32 v4, 16, v16
	v_pk_mul_f32 v[12:13], v[116:117], s[14:15] op_sel_hi:[1,0]
	v_med3_f32 v6, v6, s47, v172
	v_med3_f32 v7, v7, s47, v172
	v_cvt_pk_fp8_f32 v10, v6, v7 op_sel:[0,0,1]
	v_ashrrev_i32_e32 v5, 31, v4
	v_med3_f32 v6, v12, s47, v172
	v_med3_f32 v7, v13, s47, v172
	v_lshlrev_b64 v[4:5], 10, v[4:5]
	v_cvt_pk_fp8_f32 v11, v6, v7 op_sel:[0,0,1]
	v_lshl_add_u64 v[4:5], s[10:11], 0, v[4:5]
	v_lshl_add_u64 v[4:5], v[4:5], 0, v[2:3]
	flat_store_dwordx2 v[4:5], v[8:9] nt
	flat_store_dwordx2 v[4:5], v[10:11] offset:128 nt
	v_pk_mul_f32 v[8:9], v[110:111], s[14:15] op_sel_hi:[1,0]
	v_pk_mul_f32 v[6:7], v[112:113], s[14:15] op_sel_hi:[1,0]
	v_med3_f32 v14, v8, s47, v172
	v_med3_f32 v9, v9, s47, v172
	v_mov_b32_e32 v8, 0
	v_cvt_pk_fp8_f32 v8, v14, v9
	v_pk_mul_f32 v[12:13], v[106:107], s[14:15] op_sel_hi:[1,0]
	v_pk_mul_f32 v[10:11], v[108:109], s[14:15] op_sel_hi:[1,0]
	v_med3_f32 v6, v6, s47, v172
	v_med3_f32 v7, v7, s47, v172
	v_med3_f32 v12, v12, s47, v172
	v_med3_f32 v13, v13, s47, v172
	v_mov_b32_e32 v9, 0
	v_cvt_pk_fp8_f32 v9, v12, v13
	v_cvt_pk_fp8_f32 v8, v6, v7 op_sel:[0,0,1]
	v_med3_f32 v6, v10, s47, v172
	v_med3_f32 v7, v11, s47, v172
	v_pk_mul_f32 v[10:11], v[102:103], s[14:15] op_sel_hi:[1,0]
	v_pk_mul_f32 v[14:15], v[98:99], s[14:15] op_sel_hi:[1,0]
	v_med3_f32 v17, v10, s47, v172
	v_med3_f32 v11, v11, s47, v172
	v_mov_b32_e32 v10, 0
	v_cvt_pk_fp8_f32 v10, v17, v11
	v_med3_f32 v14, v14, s47, v172
	v_med3_f32 v15, v15, s47, v172
	v_mov_b32_e32 v11, 0
	v_cvt_pk_fp8_f32 v11, v14, v15
	v_cvt_pk_fp8_f32 v9, v6, v7 op_sel:[0,0,1]
	v_pk_mul_f32 v[6:7], v[104:105], s[14:15] op_sel_hi:[1,0]
	v_add_u32_e32 v4, 32, v16
	v_pk_mul_f32 v[12:13], v[100:101], s[14:15] op_sel_hi:[1,0]
	v_med3_f32 v6, v6, s47, v172
	v_med3_f32 v7, v7, s47, v172
	v_cvt_pk_fp8_f32 v10, v6, v7 op_sel:[0,0,1]
	v_ashrrev_i32_e32 v5, 31, v4
	v_med3_f32 v6, v12, s47, v172
	v_med3_f32 v7, v13, s47, v172
	v_lshlrev_b64 v[4:5], 10, v[4:5]
	v_cvt_pk_fp8_f32 v11, v6, v7 op_sel:[0,0,1]
	v_lshl_add_u64 v[4:5], s[10:11], 0, v[4:5]
	v_lshl_add_u64 v[4:5], v[4:5], 0, v[2:3]
	flat_store_dwordx2 v[4:5], v[8:9] nt
	flat_store_dwordx2 v[4:5], v[10:11] offset:128 nt
	v_pk_mul_f32 v[8:9], v[94:95], s[14:15] op_sel_hi:[1,0]
	v_pk_mul_f32 v[6:7], v[96:97], s[14:15] op_sel_hi:[1,0]
	v_med3_f32 v14, v8, s47, v172
	v_med3_f32 v9, v9, s47, v172
	v_mov_b32_e32 v8, 0
	v_cvt_pk_fp8_f32 v8, v14, v9
	v_pk_mul_f32 v[12:13], v[90:91], s[14:15] op_sel_hi:[1,0]
	v_pk_mul_f32 v[10:11], v[92:93], s[14:15] op_sel_hi:[1,0]
	v_med3_f32 v6, v6, s47, v172
	v_med3_f32 v7, v7, s47, v172
	v_med3_f32 v12, v12, s47, v172
	v_med3_f32 v13, v13, s47, v172
	v_mov_b32_e32 v9, 0
	v_cvt_pk_fp8_f32 v9, v12, v13
	v_cvt_pk_fp8_f32 v8, v6, v7 op_sel:[0,0,1]
	v_med3_f32 v6, v10, s47, v172
	v_med3_f32 v7, v11, s47, v172
	v_pk_mul_f32 v[10:11], v[86:87], s[14:15] op_sel_hi:[1,0]
	v_pk_mul_f32 v[14:15], v[82:83], s[14:15] op_sel_hi:[1,0]
	v_med3_f32 v17, v10, s47, v172
	v_med3_f32 v11, v11, s47, v172
	v_mov_b32_e32 v10, 0
	v_cvt_pk_fp8_f32 v10, v17, v11
	v_med3_f32 v14, v14, s47, v172
	v_med3_f32 v15, v15, s47, v172
	v_mov_b32_e32 v11, 0
	v_cvt_pk_fp8_f32 v11, v14, v15
	v_cvt_pk_fp8_f32 v9, v6, v7 op_sel:[0,0,1]
	v_pk_mul_f32 v[6:7], v[88:89], s[14:15] op_sel_hi:[1,0]
	v_add_u32_e32 v4, 48, v16
	v_pk_mul_f32 v[12:13], v[84:85], s[14:15] op_sel_hi:[1,0]
	v_med3_f32 v6, v6, s47, v172
	v_med3_f32 v7, v7, s47, v172
	v_cvt_pk_fp8_f32 v10, v6, v7 op_sel:[0,0,1]
	v_ashrrev_i32_e32 v5, 31, v4
	v_med3_f32 v6, v12, s47, v172
	v_med3_f32 v7, v13, s47, v172
	v_lshlrev_b64 v[4:5], 10, v[4:5]
	v_cvt_pk_fp8_f32 v11, v6, v7 op_sel:[0,0,1]
	v_lshl_add_u64 v[4:5], s[10:11], 0, v[4:5]
	v_lshl_add_u64 v[4:5], v[4:5], 0, v[2:3]
	flat_store_dwordx2 v[4:5], v[8:9] nt
	flat_store_dwordx2 v[4:5], v[10:11] offset:128 nt
	v_pk_mul_f32 v[8:9], v[78:79], s[14:15] op_sel_hi:[1,0]
	v_pk_mul_f32 v[6:7], v[80:81], s[14:15] op_sel_hi:[1,0]
	v_med3_f32 v14, v8, s47, v172
	v_med3_f32 v9, v9, s47, v172
	v_mov_b32_e32 v8, 0
	v_cvt_pk_fp8_f32 v8, v14, v9
	v_pk_mul_f32 v[12:13], v[74:75], s[14:15] op_sel_hi:[1,0]
	v_pk_mul_f32 v[10:11], v[76:77], s[14:15] op_sel_hi:[1,0]
	v_med3_f32 v6, v6, s47, v172
	v_med3_f32 v7, v7, s47, v172
	v_med3_f32 v12, v12, s47, v172
	v_med3_f32 v13, v13, s47, v172
	v_mov_b32_e32 v9, 0
	v_cvt_pk_fp8_f32 v9, v12, v13
	v_cvt_pk_fp8_f32 v8, v6, v7 op_sel:[0,0,1]
	v_med3_f32 v6, v10, s47, v172
	v_med3_f32 v7, v11, s47, v172
	v_pk_mul_f32 v[10:11], v[70:71], s[14:15] op_sel_hi:[1,0]
	v_pk_mul_f32 v[14:15], v[66:67], s[14:15] op_sel_hi:[1,0]
	v_med3_f32 v17, v10, s47, v172
	v_med3_f32 v11, v11, s47, v172
	v_mov_b32_e32 v10, 0
	v_cvt_pk_fp8_f32 v10, v17, v11
	v_med3_f32 v14, v14, s47, v172
	v_med3_f32 v15, v15, s47, v172
	v_mov_b32_e32 v11, 0
	v_cvt_pk_fp8_f32 v11, v14, v15
	v_cvt_pk_fp8_f32 v9, v6, v7 op_sel:[0,0,1]
	v_pk_mul_f32 v[6:7], v[72:73], s[14:15] op_sel_hi:[1,0]
	v_add_u32_e32 v4, 0x80, v16
	v_pk_mul_f32 v[12:13], v[68:69], s[14:15] op_sel_hi:[1,0]
	v_med3_f32 v6, v6, s47, v172
	v_med3_f32 v7, v7, s47, v172
	v_cvt_pk_fp8_f32 v10, v6, v7 op_sel:[0,0,1]
	v_ashrrev_i32_e32 v5, 31, v4
	v_med3_f32 v6, v12, s47, v172
	v_med3_f32 v7, v13, s47, v172
	v_lshlrev_b64 v[4:5], 10, v[4:5]
	v_cvt_pk_fp8_f32 v11, v6, v7 op_sel:[0,0,1]
	v_lshl_add_u64 v[4:5], s[10:11], 0, v[4:5]
	v_lshl_add_u64 v[4:5], v[4:5], 0, v[2:3]
	flat_store_dwordx2 v[4:5], v[8:9] nt
	flat_store_dwordx2 v[4:5], v[10:11] offset:128 nt
	v_pk_mul_f32 v[8:9], v[62:63], s[14:15] op_sel_hi:[1,0]
	v_pk_mul_f32 v[6:7], v[64:65], s[14:15] op_sel_hi:[1,0]
	v_med3_f32 v14, v8, s47, v172
	v_med3_f32 v9, v9, s47, v172
	v_mov_b32_e32 v8, 0
	v_cvt_pk_fp8_f32 v8, v14, v9
	v_pk_mul_f32 v[12:13], v[58:59], s[14:15] op_sel_hi:[1,0]
	v_pk_mul_f32 v[10:11], v[60:61], s[14:15] op_sel_hi:[1,0]
	v_med3_f32 v6, v6, s47, v172
	v_med3_f32 v7, v7, s47, v172
	v_med3_f32 v12, v12, s47, v172
	v_med3_f32 v13, v13, s47, v172
	v_mov_b32_e32 v9, 0
	v_cvt_pk_fp8_f32 v9, v12, v13
	v_cvt_pk_fp8_f32 v8, v6, v7 op_sel:[0,0,1]
	v_med3_f32 v6, v10, s47, v172
	v_med3_f32 v7, v11, s47, v172
	v_pk_mul_f32 v[10:11], v[54:55], s[14:15] op_sel_hi:[1,0]
	v_pk_mul_f32 v[14:15], v[50:51], s[14:15] op_sel_hi:[1,0]
	v_med3_f32 v17, v10, s47, v172
	v_med3_f32 v11, v11, s47, v172
	v_mov_b32_e32 v10, 0
	v_cvt_pk_fp8_f32 v10, v17, v11
	v_med3_f32 v14, v14, s47, v172
	v_med3_f32 v15, v15, s47, v172
	v_mov_b32_e32 v11, 0
	v_cvt_pk_fp8_f32 v11, v14, v15
	v_cvt_pk_fp8_f32 v9, v6, v7 op_sel:[0,0,1]
	v_pk_mul_f32 v[6:7], v[56:57], s[14:15] op_sel_hi:[1,0]
	v_add_u32_e32 v4, 0x90, v16
	v_pk_mul_f32 v[12:13], v[52:53], s[14:15] op_sel_hi:[1,0]
	v_med3_f32 v6, v6, s47, v172
	v_med3_f32 v7, v7, s47, v172
	v_cvt_pk_fp8_f32 v10, v6, v7 op_sel:[0,0,1]
	v_ashrrev_i32_e32 v5, 31, v4
	v_med3_f32 v6, v12, s47, v172
	v_med3_f32 v7, v13, s47, v172
	v_lshlrev_b64 v[4:5], 10, v[4:5]
	v_cvt_pk_fp8_f32 v11, v6, v7 op_sel:[0,0,1]
	v_lshl_add_u64 v[4:5], s[10:11], 0, v[4:5]
	v_lshl_add_u64 v[4:5], v[4:5], 0, v[2:3]
	flat_store_dwordx2 v[4:5], v[8:9] nt
	flat_store_dwordx2 v[4:5], v[10:11] offset:128 nt
	v_pk_mul_f32 v[8:9], v[46:47], s[14:15] op_sel_hi:[1,0]
	v_pk_mul_f32 v[6:7], v[48:49], s[14:15] op_sel_hi:[1,0]
	v_med3_f32 v14, v8, s47, v172
	v_med3_f32 v9, v9, s47, v172
	v_mov_b32_e32 v8, 0
	v_cvt_pk_fp8_f32 v8, v14, v9
	v_pk_mul_f32 v[12:13], v[42:43], s[14:15] op_sel_hi:[1,0]
	v_pk_mul_f32 v[10:11], v[44:45], s[14:15] op_sel_hi:[1,0]
	v_med3_f32 v6, v6, s47, v172
	v_med3_f32 v7, v7, s47, v172
	v_med3_f32 v12, v12, s47, v172
	v_med3_f32 v13, v13, s47, v172
	v_mov_b32_e32 v9, 0
	v_cvt_pk_fp8_f32 v9, v12, v13
	v_cvt_pk_fp8_f32 v8, v6, v7 op_sel:[0,0,1]
	v_med3_f32 v6, v10, s47, v172
	v_med3_f32 v7, v11, s47, v172
	v_pk_mul_f32 v[10:11], v[38:39], s[14:15] op_sel_hi:[1,0]
	v_pk_mul_f32 v[14:15], v[34:35], s[14:15] op_sel_hi:[1,0]
	v_med3_f32 v17, v10, s47, v172
	v_med3_f32 v11, v11, s47, v172
	v_mov_b32_e32 v10, 0
	v_cvt_pk_fp8_f32 v10, v17, v11
	v_med3_f32 v14, v14, s47, v172
	v_med3_f32 v15, v15, s47, v172
	v_mov_b32_e32 v11, 0
	v_cvt_pk_fp8_f32 v11, v14, v15
	v_cvt_pk_fp8_f32 v9, v6, v7 op_sel:[0,0,1]
	v_pk_mul_f32 v[6:7], v[40:41], s[14:15] op_sel_hi:[1,0]
	v_add_u32_e32 v4, 0xa0, v16
	v_pk_mul_f32 v[12:13], v[36:37], s[14:15] op_sel_hi:[1,0]
	v_med3_f32 v6, v6, s47, v172
	v_med3_f32 v7, v7, s47, v172
	v_cvt_pk_fp8_f32 v10, v6, v7 op_sel:[0,0,1]
	v_ashrrev_i32_e32 v5, 31, v4
	v_med3_f32 v6, v12, s47, v172
	v_med3_f32 v7, v13, s47, v172
	v_lshlrev_b64 v[4:5], 10, v[4:5]
	v_cvt_pk_fp8_f32 v11, v6, v7 op_sel:[0,0,1]
	v_lshl_add_u64 v[4:5], s[10:11], 0, v[4:5]
	v_lshl_add_u64 v[4:5], v[4:5], 0, v[2:3]
	flat_store_dwordx2 v[4:5], v[8:9] nt
	flat_store_dwordx2 v[4:5], v[10:11] offset:128 nt
	v_pk_mul_f32 v[8:9], v[30:31], s[14:15] op_sel_hi:[1,0]
	v_pk_mul_f32 v[6:7], v[32:33], s[14:15] op_sel_hi:[1,0]
	v_med3_f32 v14, v8, s47, v172
	v_med3_f32 v9, v9, s47, v172
	v_mov_b32_e32 v8, 0
	v_cvt_pk_fp8_f32 v8, v14, v9
	v_pk_mul_f32 v[12:13], v[26:27], s[14:15] op_sel_hi:[1,0]
	v_pk_mul_f32 v[10:11], v[28:29], s[14:15] op_sel_hi:[1,0]
	v_med3_f32 v6, v6, s47, v172
	v_med3_f32 v7, v7, s47, v172
	v_med3_f32 v12, v12, s47, v172
	v_med3_f32 v13, v13, s47, v172
	v_mov_b32_e32 v9, 0
	v_cvt_pk_fp8_f32 v9, v12, v13
	v_cvt_pk_fp8_f32 v8, v6, v7 op_sel:[0,0,1]
	v_med3_f32 v6, v10, s47, v172
	v_med3_f32 v7, v11, s47, v172
	v_pk_mul_f32 v[10:11], v[22:23], s[14:15] op_sel_hi:[1,0]
	v_add_u32_e32 v4, 0xb0, v16
	v_pk_mul_f32 v[14:15], v[18:19], s[14:15] op_sel_hi:[1,0]
	v_med3_f32 v16, v10, s47, v172
	v_med3_f32 v11, v11, s47, v172
	v_mov_b32_e32 v10, 0
	v_cvt_pk_fp8_f32 v10, v16, v11
	v_med3_f32 v14, v14, s47, v172
	v_med3_f32 v15, v15, s47, v172
	v_mov_b32_e32 v11, 0
	v_cvt_pk_fp8_f32 v11, v14, v15
	v_cvt_pk_fp8_f32 v9, v6, v7 op_sel:[0,0,1]
	v_pk_mul_f32 v[6:7], v[24:25], s[14:15] op_sel_hi:[1,0]
	v_pk_mul_f32 v[12:13], v[20:21], s[14:15] op_sel_hi:[1,0]
	v_med3_f32 v6, v6, s47, v172
	v_med3_f32 v7, v7, s47, v172
	v_cvt_pk_fp8_f32 v10, v6, v7 op_sel:[0,0,1]
	v_ashrrev_i32_e32 v5, 31, v4
	v_med3_f32 v6, v12, s47, v172
	v_med3_f32 v7, v13, s47, v172
	v_lshlrev_b64 v[4:5], 10, v[4:5]
	v_cvt_pk_fp8_f32 v11, v6, v7 op_sel:[0,0,1]
	v_lshl_add_u64 v[4:5], s[10:11], 0, v[4:5]
	v_lshl_add_u64 v[2:3], v[4:5], 0, v[2:3]
	s_and_b64 vcc, exec, s[6:7]
	s_mov_b32 s48, s16
	s_mov_b32 s24, s18
	s_mov_b64 s[26:27], s[22:23]
	s_mov_b64 s[28:29], s[20:21]
	flat_store_dwordx2 v[2:3], v[8:9] nt
	flat_store_dwordx2 v[2:3], v[10:11] offset:128 nt
	s_cbranch_vccz .LBB0_2809
	s_waitcnt vmcnt(0)
	s_cmpk_gt_u32 s4, 0xff
	s_cbranch_scc1 .LBB0_2820
	s_barrier
